# v84 + GEMM K-loops: first eight fragment reads of each K-tile via one loop-invariant LDS base register + immediate offsets (4 VALU adds per iteration removed)
# speedup vs baseline: 1.0016x; 1.0016x over previous
;     __device__ __forceinline__ bool next(int i, Unit& u) const { if (i >= n) return false; u.pm = pm; u.pn = pn0 + i; return true; }
;     __device__ __forceinline__ bool next(int i, Unit& u) const { if (i) return false; u.pm = pm; u.pn = pn; return true; }
; #define PG8_STAGE(bufoff, gbase, voff) do { _Pragma("unroll") for (int _i = 0; _i < 2; ++_i) \
;         __builtin_amdgcn_global_load_lds((const unsigned*)((const char*)(gbase) + (voff)[_i]), (PG8_LAS unsigned*)(lds + (bufoff) + ldsw + _i * 8192), 16, 0, 0); } while (0)
; #define PG8_LDA(dst, b, h) do { _Pragma("unroll") for (int m = 0; m < 4; ++m) _Pragma("unroll") for (int k = 0; k < 2; ++k) dst[m][k] = *(const PG8_LAS bf16x8*)(lds + PG8_SA(b, h) + aoff + m * 2048 + k * 1024); } while (0)
; #define PG8_LDB(dst, b, h) do { _Pragma("unroll") for (int n = 0; n < 2; ++n) _Pragma("unroll") for (int k = 0; k < 2; ++k) dst[n][k] = *(const PG8_LAS bf16x8*)(lds + PG8_SB(b, h) + boff + n * 2048 + k * 1024); } while (0)
; #define PG8_WAIT_V(n) asm volatile("s_waitcnt vmcnt(" #n ")" ::: "memory")
;     ...
;         const bool has_next = S.next(ui + 1, nxt);
;         const char* nA = has_next ? (const char*)g.A + (size_t)nxt.pm * tstep : cA; const char* nB = has_next ? (const char*)g.Bt + (size_t)nxt.pn * tstep : cB;
;         for (int t = 0; t < nt; t += 2) {
;             const bool last = (t == nt - 2);
;             const char* a1 = cA + (size_t)(t + 1) * kstep;
;             const char* a2 = last ? nA : cA + (size_t)(t + 2) * kstep; const char* b2 = last ? nB : cB + (size_t)(t + 2) * kstep;
;             const char* a3 = a2 + kstep; const char* b3 = b2 + kstep;
;             if (last && has_next) S.a_ready(nxt);
;             if (t == 0) E.pre_issue(pre, cur, tid, ui); else if (t == 2) E.pre_finish(pre, tid, ui);
;             if constexpr (SP2) {
;             PG8_LDB(B0, 0, 0); PG8_LDB(B1, 0, 1); PG8_SCHED; PG8_LDA(At, 0, 0); PG8_STAGE(PG8_SA(1, 1), a1 + hstep, voffA);
;             PG8_WAIT_V(8); PG8_WAIT_L(0); PG8_BAR; PG8_MMA(0, 0, At, B0); PG8_MMA(0, 1, At, B1); PG8_BAR; PG8_SCHED;
;     ...
;         for (int a = 0; a < 2; ++a)
; #pragma unroll
;             for (int b = 0; b < 2; ++b)
; #pragma unroll
;                 for (int m = 0; m < 4; ++m)
; #pragma unroll
;                     for (int n = 0; n < 2; ++n) acc[a][b][m][n] = (f32x4){0.f, 0.f, 0.f, 0.f};
;         cur = nxt; cA = nA; cB = nB; ++ui;
.LBB0_197:
	s_ashr_i32 s25, s24, 31
	s_lshl_b64 s[50:51], s[24:25], 20
	s_add_u32 s50, s36, s50
	s_addc_u32 s51, s37, s51
	s_and_b64 s[58:59], s[4:5], exec
	s_cselect_b32 s25, s51, s61
	s_cselect_b32 s81, s50, s60
	s_ashr_i32 s15, s14, 31
	s_lshl_b64 s[58:59], s[14:15], 20
	s_add_u32 s58, s75, s58
	s_addc_u32 s59, s82, s59
	s_and_b64 s[68:69], s[4:5], exec
	s_cselect_b32 s15, s59, s63
	s_cselect_b32 s83, s58, s62
	s_add_u32 s60, s60, 0x80080
	s_addc_u32 s61, s61, 0
	s_add_u32 s84, s62, 0x100
	v_mov_b32_e32 v4, 0
	s_addc_u32 s85, s63, 0
	s_mov_b32 s86, -2
	v_mov_b32_e32 v5, v4
	v_mov_b32_e32 v6, v4
	v_mov_b32_e32 v7, v4
	v_mov_b32_e32 v8, v4
	v_mov_b32_e32 v9, v4
	v_mov_b32_e32 v10, v4
	v_mov_b32_e32 v11, v4
	v_mov_b32_e32 v20, v4
	v_mov_b32_e32 v21, v4
	v_mov_b32_e32 v22, v4
	v_mov_b32_e32 v23, v4
	s_waitcnt vmcnt(0)
	v_mov_b32_e32 v24, v4
	v_mov_b32_e32 v25, v4
	v_mov_b32_e32 v26, v4
	v_mov_b32_e32 v27, v4
	v_mov_b32_e32 v36, v4
	v_mov_b32_e32 v37, v4
	v_mov_b32_e32 v38, v4
	v_mov_b32_e32 v39, v4
	v_mov_b32_e32 v40, v4
	v_mov_b32_e32 v41, v4
	v_mov_b32_e32 v42, v4
	v_mov_b32_e32 v43, v4
	v_mov_b32_e32 v52, v4
	v_mov_b32_e32 v53, v4
	v_mov_b32_e32 v54, v4
	v_mov_b32_e32 v55, v4
	v_mov_b32_e32 v56, v4
	v_mov_b32_e32 v57, v4
	v_mov_b32_e32 v58, v4
	v_mov_b32_e32 v59, v4
	v_mov_b32_e32 v12, v4
	v_mov_b32_e32 v13, v4
	v_mov_b32_e32 v14, v4
	v_mov_b32_e32 v15, v4
	v_mov_b32_e32 v16, v4
	v_mov_b32_e32 v17, v4
	v_mov_b32_e32 v18, v4
	v_mov_b32_e32 v19, v4
	v_mov_b32_e32 v28, v4
	v_mov_b32_e32 v29, v4
	v_mov_b32_e32 v30, v4
	v_mov_b32_e32 v31, v4
	v_mov_b32_e32 v32, v4
	v_mov_b32_e32 v33, v4
	v_mov_b32_e32 v34, v4
	v_mov_b32_e32 v35, v4
	v_mov_b32_e32 v44, v4
	v_mov_b32_e32 v45, v4
	v_mov_b32_e32 v46, v4
	v_mov_b32_e32 v47, v4
	v_mov_b32_e32 v48, v4
	v_mov_b32_e32 v49, v4
	v_mov_b32_e32 v50, v4
	v_mov_b32_e32 v51, v4
	v_mov_b32_e32 v60, v4
	v_mov_b32_e32 v61, v4
	v_mov_b32_e32 v62, v4
	v_mov_b32_e32 v63, v4
	v_mov_b32_e32 v64, v4
	v_mov_b32_e32 v65, v4
	v_mov_b32_e32 v66, v4
	v_mov_b32_e32 v67, v4
	v_mov_b32_e32 v68, v4
	v_mov_b32_e32 v69, v4
	v_mov_b32_e32 v70, v4
	v_mov_b32_e32 v71, v4
	v_mov_b32_e32 v72, v4
	v_mov_b32_e32 v73, v4
	v_mov_b32_e32 v74, v4
	v_mov_b32_e32 v75, v4
	v_mov_b32_e32 v84, v4
	v_mov_b32_e32 v85, v4
	v_mov_b32_e32 v86, v4
	v_mov_b32_e32 v87, v4
	v_mov_b32_e32 v88, v4
	v_mov_b32_e32 v89, v4
	v_mov_b32_e32 v90, v4
	v_mov_b32_e32 v91, v4
	v_mov_b32_e32 v100, v4
	v_mov_b32_e32 v101, v4
	v_mov_b32_e32 v102, v4
	v_mov_b32_e32 v103, v4
	v_mov_b32_e32 v104, v4
	v_mov_b32_e32 v105, v4
	v_mov_b32_e32 v106, v4
	v_mov_b32_e32 v107, v4
	v_mov_b32_e32 v116, v4
	v_mov_b32_e32 v117, v4
	v_mov_b32_e32 v118, v4
	v_mov_b32_e32 v119, v4
	v_mov_b32_e32 v120, v4
	v_mov_b32_e32 v121, v4
	v_mov_b32_e32 v122, v4
	v_mov_b32_e32 v123, v4
	v_mov_b32_e32 v76, v4
	v_mov_b32_e32 v77, v4
	v_mov_b32_e32 v78, v4
	v_mov_b32_e32 v79, v4
	v_mov_b32_e32 v80, v4
	v_mov_b32_e32 v81, v4
	v_mov_b32_e32 v82, v4
	v_mov_b32_e32 v83, v4
	v_mov_b32_e32 v92, v4
	v_mov_b32_e32 v93, v4
	v_mov_b32_e32 v94, v4
	v_mov_b32_e32 v95, v4
	v_mov_b32_e32 v96, v4
	v_mov_b32_e32 v97, v4
	v_mov_b32_e32 v98, v4
	v_mov_b32_e32 v99, v4
	v_mov_b32_e32 v108, v4
	v_mov_b32_e32 v109, v4
	v_mov_b32_e32 v110, v4
	v_mov_b32_e32 v111, v4
	v_mov_b32_e32 v112, v4
	v_mov_b32_e32 v113, v4
	v_mov_b32_e32 v114, v4
	v_mov_b32_e32 v115, v4
	v_mov_b32_e32 v124, v4
	v_mov_b32_e32 v125, v4
	v_mov_b32_e32 v126, v4
	v_mov_b32_e32 v127, v4
	v_mov_b32_e32 v128, v4
	v_mov_b32_e32 v129, v4
	v_mov_b32_e32 v130, v4
	v_mov_b32_e32 v131, v4
	v_add_u32_e32 v251, 0x10000, v155
.LBB0_198:
	s_add_u32 s48, s60, 0xfff80080
	s_addc_u32 s49, s61, -1
	s_add_i32 s87, 0, 0x10000
	s_cmp_eq_u32 s86, 28
	s_cselect_b32 s69, s25, s49
	s_cselect_b32 s68, s81, s48
	s_cselect_b32 s63, s15, s85
	s_cselect_b32 s62, s83, s84
	s_add_i32 s48, 0, 0x14000
	ds_read_b128 v[142:145], v251
	ds_read_b128 v[146:149], v251 offset:1024
	ds_read_b128 v[150:153], v251 offset:2048
	ds_read_b128 v[158:161], v251 offset:3072
	ds_read_b128 v[162:165], v251 offset:16384
	ds_read_b128 v[166:169], v251 offset:17408
	ds_read_b128 v[170:173], v251 offset:18432
	ds_read_b128 v[174:177], v251 offset:19456
	v_lshl_add_u64 v[198:199], s[60:61], 0, v[138:139]
	s_add_i32 m0, s20, 0xc000
	ds_read_b128 v[178:181], v156
	ds_read_b128 v[182:185], v156 offset:1024
	ds_read_b128 v[186:189], v156 offset:2048
	ds_read_b128 v[190:193], v156 offset:3072
	ds_read_b128 v[194:197], v156 offset:4096
	ds_read_b128 v[210:213], v156 offset:5120
	ds_read_b128 v[214:217], v156 offset:6144
	ds_read_b128 v[218:221], v156 offset:7168
	global_load_lds_dwordx4 v[198:199], off
	v_lshl_add_u64 v[198:199], s[60:61], 0, v[140:141]
	s_add_i32 m0, s20, 0xe000
	s_nop 0
	global_load_lds_dwordx4 v[198:199], off
	s_waitcnt vmcnt(8)
	s_waitcnt lgkmcnt(0)
	s_setprio 1
	s_barrier
; #define PG8_STAGE(bufoff, gbase, voff) do { _Pragma("unroll") for (int _i = 0; _i < 2; ++_i) \
;         __builtin_amdgcn_global_load_lds((const unsigned*)((const char*)(gbase) + (voff)[_i]), (PG8_LAS unsigned*)(lds + (bufoff) + ldsw + _i * 8192), 16, 0, 0); } while (0)
; #define PG8_LDA(dst, b, h) do { _Pragma("unroll") for (int m = 0; m < 4; ++m) _Pragma("unroll") for (int k = 0; k < 2; ++k) dst[m][k] = *(const PG8_LAS bf16x8*)(lds + PG8_SA(b, h) + aoff + m * 2048 + k * 1024); } while (0)
; #define PG8_MMA(ai, bj, At, Bt) do { __builtin_amdgcn_s_setprio(1); _Pragma("unroll") for (int m = 0; m < 4; ++m) _Pragma("unroll") for (int n = 0; n < 2; ++n) _Pragma("unroll") for (int k = 0; k < 2; ++k) \
;         acc[ai][bj][m][n] = __builtin_amdgcn_mfma_f32_16x16x32_bf16(Bt[n][k], At[m][k], acc[ai][bj][m][n], 0, 0, 0); __builtin_amdgcn_s_setprio(0); } while (0)
; #define PG8_WAIT_V(n) asm volatile("s_waitcnt vmcnt(" #n ")" ::: "memory")
; #define PG8_WAIT_L(n) asm volatile("s_waitcnt lgkmcnt(" #n ")" ::: "memory")
; #define PG8_BAR __builtin_amdgcn_s_barrier()
; #define PG8_SCHED __builtin_amdgcn_sched_barrier(0)
;     ...
;             PG8_WAIT_V(8); PG8_WAIT_L(0); PG8_BAR; PG8_MMA(0, 0, At, B0); PG8_MMA(0, 1, At, B1); PG8_BAR; PG8_SCHED;
;             PG8_LDA(At, 0, 1); PG8_STAGE(PG8_SB(0, 0), b2, voffB); PG8_STAGE(PG8_SB(0, 1), b2 + hstep, voffB); PG8_STAGE(PG8_SA(0, 0), a2, voffA);
;             PG8_WAIT_V(8); PG8_WAIT_L(0); PG8_BAR; PG8_MMA(1, 0, At, B0); PG8_MMA(1, 1, At, B1); PG8_BAR; PG8_SCHED;
	v_mfma_f32_16x16x32_bf16 v[128:131], v[142:145], v[178:181], v[128:131]
	v_mfma_f32_16x16x32_bf16 v[124:127], v[150:153], v[178:181], v[124:127]
	v_mfma_f32_16x16x32_bf16 v[112:115], v[142:145], v[186:189], v[112:115]
	v_mfma_f32_16x16x32_bf16 v[108:111], v[150:153], v[186:189], v[108:111]
	v_mfma_f32_16x16x32_bf16 v[96:99], v[142:145], v[194:197], v[96:99]
	v_mfma_f32_16x16x32_bf16 v[92:95], v[150:153], v[194:197], v[92:95]
	v_mfma_f32_16x16x32_bf16 v[80:83], v[142:145], v[214:217], v[80:83]
	v_mfma_f32_16x16x32_bf16 v[76:79], v[150:153], v[214:217], v[76:79]
	v_mfma_f32_16x16x32_bf16 v[128:131], v[146:149], v[182:185], v[128:131]
	v_mfma_f32_16x16x32_bf16 v[124:127], v[158:161], v[182:185], v[124:127]
	v_mfma_f32_16x16x32_bf16 v[112:115], v[146:149], v[190:193], v[112:115]
	v_mfma_f32_16x16x32_bf16 v[108:111], v[158:161], v[190:193], v[108:111]
	v_mfma_f32_16x16x32_bf16 v[96:99], v[146:149], v[210:213], v[96:99]
	v_mfma_f32_16x16x32_bf16 v[92:95], v[158:161], v[210:213], v[92:95]
	v_mfma_f32_16x16x32_bf16 v[80:83], v[146:149], v[218:221], v[80:83]
	v_mfma_f32_16x16x32_bf16 v[76:79], v[158:161], v[218:221], v[76:79]
	s_setprio 0
	s_setprio 1
	v_mfma_f32_16x16x32_bf16 v[120:123], v[162:165], v[178:181], v[120:123]
	v_mfma_f32_16x16x32_bf16 v[116:119], v[170:173], v[178:181], v[116:119]
	v_mfma_f32_16x16x32_bf16 v[104:107], v[162:165], v[186:189], v[104:107]
	v_mfma_f32_16x16x32_bf16 v[100:103], v[170:173], v[186:189], v[100:103]
	v_mfma_f32_16x16x32_bf16 v[88:91], v[162:165], v[194:197], v[88:91]
	v_mfma_f32_16x16x32_bf16 v[84:87], v[170:173], v[194:197], v[84:87]
	v_mfma_f32_16x16x32_bf16 v[72:75], v[162:165], v[214:217], v[72:75]
	v_mfma_f32_16x16x32_bf16 v[68:71], v[170:173], v[214:217], v[68:71]
	v_mfma_f32_16x16x32_bf16 v[120:123], v[166:169], v[182:185], v[120:123]
	v_mfma_f32_16x16x32_bf16 v[116:119], v[174:177], v[182:185], v[116:119]
	v_mfma_f32_16x16x32_bf16 v[104:107], v[166:169], v[190:193], v[104:107]
	v_mfma_f32_16x16x32_bf16 v[100:103], v[174:177], v[190:193], v[100:103]
	v_mfma_f32_16x16x32_bf16 v[88:91], v[166:169], v[210:213], v[88:91]
	v_mfma_f32_16x16x32_bf16 v[84:87], v[174:177], v[210:213], v[84:87]
	v_mfma_f32_16x16x32_bf16 v[72:75], v[166:169], v[218:221], v[72:75]
	v_mfma_f32_16x16x32_bf16 v[68:71], v[174:177], v[218:221], v[68:71]
	s_barrier
	s_setprio 0
	s_add_i32 s49, s87, s1
	v_lshl_add_u64 v[198:199], s[62:63], 0, v[200:201]
	s_mov_b32 m0, s49
	ds_read_b128 v[178:181], v156 offset:16384
	ds_read_b128 v[182:185], v156 offset:17408
	ds_read_b128 v[186:189], v156 offset:18432
	ds_read_b128 v[190:193], v156 offset:19456
	ds_read_b128 v[194:197], v156 offset:20480
	ds_read_b128 v[210:213], v156 offset:21504
	ds_read_b128 v[214:217], v156 offset:22528
	ds_read_b128 v[218:221], v156 offset:23552
	global_load_lds_dwordx4 v[198:199], off
	s_add_i32 m0, s49, 0x2000
	s_add_u32 s88, s62, 0x80000
	v_lshl_add_u64 v[206:207], s[62:63], 0, v[132:133]
	s_addc_u32 s89, s63, 0
	s_add_i32 s48, s48, s1
	global_load_lds_dwordx4 v[206:207], off
	v_lshl_add_u64 v[208:209], s[88:89], 0, v[200:201]
	s_mov_b32 m0, s48
	v_lshl_add_u64 v[222:223], s[68:69], 0, v[134:135]
	global_load_lds_dwordx4 v[208:209], off
	v_lshl_add_u64 v[208:209], s[88:89], 0, v[132:133]
	s_add_i32 m0, s48, 0x2000
	s_nop 0
	global_load_lds_dwordx4 v[208:209], off
	v_lshl_add_u64 v[208:209], s[68:69], 0, v[136:137]
	s_mov_b32 m0, s20
	s_nop 0
	global_load_lds_dwordx4 v[208:209], off
	s_mov_b32 m0, s21
	s_nop 0
	global_load_lds_dwordx4 v[222:223], off
	s_waitcnt vmcnt(8)
	s_waitcnt lgkmcnt(0)
	s_setprio 1
	s_barrier
	v_mfma_f32_16x16x32_bf16 v[64:67], v[142:145], v[178:181], v[64:67]
	v_mfma_f32_16x16x32_bf16 v[60:63], v[150:153], v[178:181], v[60:63]
	v_mfma_f32_16x16x32_bf16 v[48:51], v[142:145], v[186:189], v[48:51]
	v_mfma_f32_16x16x32_bf16 v[44:47], v[150:153], v[186:189], v[44:47]
	v_mfma_f32_16x16x32_bf16 v[32:35], v[142:145], v[194:197], v[32:35]
	v_mfma_f32_16x16x32_bf16 v[28:31], v[150:153], v[194:197], v[28:31]
	v_mfma_f32_16x16x32_bf16 v[16:19], v[142:145], v[214:217], v[16:19]
	v_mfma_f32_16x16x32_bf16 v[12:15], v[150:153], v[214:217], v[12:15]
	v_mfma_f32_16x16x32_bf16 v[64:67], v[146:149], v[182:185], v[64:67]
	v_mfma_f32_16x16x32_bf16 v[60:63], v[158:161], v[182:185], v[60:63]
	v_mfma_f32_16x16x32_bf16 v[48:51], v[146:149], v[190:193], v[48:51]
	v_mfma_f32_16x16x32_bf16 v[44:47], v[158:161], v[190:193], v[44:47]
	v_mfma_f32_16x16x32_bf16 v[32:35], v[146:149], v[210:213], v[32:35]
	v_mfma_f32_16x16x32_bf16 v[28:31], v[158:161], v[210:213], v[28:31]
	v_mfma_f32_16x16x32_bf16 v[16:19], v[146:149], v[218:221], v[16:19]
	v_mfma_f32_16x16x32_bf16 v[12:15], v[158:161], v[218:221], v[12:15]
	s_setprio 0
	s_setprio 1
	v_mfma_f32_16x16x32_bf16 v[56:59], v[162:165], v[178:181], v[56:59]
	v_mfma_f32_16x16x32_bf16 v[52:55], v[170:173], v[178:181], v[52:55]
	v_mfma_f32_16x16x32_bf16 v[40:43], v[162:165], v[186:189], v[40:43]
	v_mfma_f32_16x16x32_bf16 v[36:39], v[170:173], v[186:189], v[36:39]
	v_mfma_f32_16x16x32_bf16 v[24:27], v[162:165], v[194:197], v[24:27]
	v_mfma_f32_16x16x32_bf16 v[20:23], v[170:173], v[194:197], v[20:23]
	v_mfma_f32_16x16x32_bf16 v[8:11], v[162:165], v[214:217], v[8:11]
	v_mfma_f32_16x16x32_bf16 v[4:7], v[170:173], v[214:217], v[4:7]
	v_mfma_f32_16x16x32_bf16 v[56:59], v[166:169], v[182:185], v[56:59]
	v_mfma_f32_16x16x32_bf16 v[52:55], v[174:177], v[182:185], v[52:55]
	v_mfma_f32_16x16x32_bf16 v[40:43], v[166:169], v[190:193], v[40:43]
	v_mfma_f32_16x16x32_bf16 v[36:39], v[174:177], v[190:193], v[36:39]
	v_mfma_f32_16x16x32_bf16 v[24:27], v[166:169], v[210:213], v[24:27]
	v_mfma_f32_16x16x32_bf16 v[20:23], v[174:177], v[210:213], v[20:23]
	v_mfma_f32_16x16x32_bf16 v[8:11], v[166:169], v[218:221], v[8:11]
	v_mfma_f32_16x16x32_bf16 v[4:7], v[174:177], v[218:221], v[4:7]
	s_barrier
; #define PG8_STAGE(bufoff, gbase, voff) do { _Pragma("unroll") for (int _i = 0; _i < 2; ++_i) \
;         __builtin_amdgcn_global_load_lds((const unsigned*)((const char*)(gbase) + (voff)[_i]), (PG8_LAS unsigned*)(lds + (bufoff) + ldsw + _i * 8192), 16, 0, 0); } while (0)
; #define PG8_LDA(dst, b, h) do { _Pragma("unroll") for (int m = 0; m < 4; ++m) _Pragma("unroll") for (int k = 0; k < 2; ++k) dst[m][k] = *(const PG8_LAS bf16x8*)(lds + PG8_SA(b, h) + aoff + m * 2048 + k * 1024); } while (0)
; #define PG8_LDB(dst, b, h) do { _Pragma("unroll") for (int n = 0; n < 2; ++n) _Pragma("unroll") for (int k = 0; k < 2; ++k) dst[n][k] = *(const PG8_LAS bf16x8*)(lds + PG8_SB(b, h) + boff + n * 2048 + k * 1024); } while (0)
; #define PG8_MMA(ai, bj, At, Bt) do { __builtin_amdgcn_s_setprio(1); _Pragma("unroll") for (int m = 0; m < 4; ++m) _Pragma("unroll") for (int n = 0; n < 2; ++n) _Pragma("unroll") for (int k = 0; k < 2; ++k) \
;         acc[ai][bj][m][n] = __builtin_amdgcn_mfma_f32_16x16x32_bf16(Bt[n][k], At[m][k], acc[ai][bj][m][n], 0, 0, 0); __builtin_amdgcn_s_setprio(0); } while (0)
; #define PG8_WAIT_V(n) asm volatile("s_waitcnt vmcnt(" #n ")" ::: "memory")
; #define PG8_WAIT_L(n) asm volatile("s_waitcnt lgkmcnt(" #n ")" ::: "memory")
; #define PG8_BAR __builtin_amdgcn_s_barrier()
; #define PG8_SCHED __builtin_amdgcn_sched_barrier(0)
;     ...
;             PG8_LDB(B0, 1, 0); PG8_LDB(B1, 1, 1); PG8_SCHED; PG8_LDA(At, 1, 0); PG8_STAGE(PG8_SA(0, 1), a2 + hstep, voffA);
;             PG8_WAIT_V(8); PG8_WAIT_L(0); PG8_BAR; PG8_MMA(0, 0, At, B0); PG8_MMA(0, 1, At, B1); PG8_BAR; PG8_SCHED;
	s_setprio 0
	s_add_i32 s48, 0, 0x18000
	s_add_i32 s49, 0, 0x1c000
	ds_read_b128 v[142:145], v251 offset:32768
	ds_read_b128 v[146:149], v251 offset:33792
	ds_read_b128 v[150:153], v251 offset:34816
	ds_read_b128 v[158:161], v251 offset:35840
	ds_read_b128 v[162:165], v251 offset:49152
	ds_read_b128 v[166:169], v251 offset:50176
	ds_read_b128 v[170:173], v251 offset:51200
	ds_read_b128 v[174:177], v251 offset:52224
	s_add_u32 s68, s68, 0x80000
	s_addc_u32 s69, s69, 0
	s_mov_b32 m0, s23
	v_lshl_add_u64 v[224:225], s[68:69], 0, v[136:137]
	ds_read_b128 v[178:181], v156 offset:32768
	ds_read_b128 v[182:185], v156 offset:33792
	ds_read_b128 v[186:189], v156 offset:34816
	ds_read_b128 v[190:193], v156 offset:35840
	ds_read_b128 v[194:197], v156 offset:36864
	ds_read_b128 v[210:213], v156 offset:37888
	ds_read_b128 v[214:217], v156 offset:38912
	ds_read_b128 v[218:221], v156 offset:39936
	global_load_lds_dwordx4 v[224:225], off
	v_lshl_add_u64 v[224:225], s[68:69], 0, v[134:135]
	s_mov_b32 m0, s42
	s_nop 0
	global_load_lds_dwordx4 v[224:225], off
	s_waitcnt vmcnt(8)
	s_waitcnt lgkmcnt(0)
	s_setprio 1
	s_barrier
	v_mfma_f32_16x16x32_bf16 v[128:131], v[142:145], v[178:181], v[128:131]
	v_mfma_f32_16x16x32_bf16 v[124:127], v[150:153], v[178:181], v[124:127]
	v_mfma_f32_16x16x32_bf16 v[112:115], v[142:145], v[186:189], v[112:115]
	v_mfma_f32_16x16x32_bf16 v[108:111], v[150:153], v[186:189], v[108:111]
	v_mfma_f32_16x16x32_bf16 v[96:99], v[142:145], v[194:197], v[96:99]
	v_mfma_f32_16x16x32_bf16 v[92:95], v[150:153], v[194:197], v[92:95]
	v_mfma_f32_16x16x32_bf16 v[80:83], v[142:145], v[214:217], v[80:83]
	v_mfma_f32_16x16x32_bf16 v[76:79], v[150:153], v[214:217], v[76:79]
	v_mfma_f32_16x16x32_bf16 v[128:131], v[146:149], v[182:185], v[128:131]
	v_mfma_f32_16x16x32_bf16 v[124:127], v[158:161], v[182:185], v[124:127]
	v_mfma_f32_16x16x32_bf16 v[112:115], v[146:149], v[190:193], v[112:115]
	v_mfma_f32_16x16x32_bf16 v[108:111], v[158:161], v[190:193], v[108:111]
	v_mfma_f32_16x16x32_bf16 v[96:99], v[146:149], v[210:213], v[96:99]
	v_mfma_f32_16x16x32_bf16 v[92:95], v[158:161], v[210:213], v[92:95]
	v_mfma_f32_16x16x32_bf16 v[80:83], v[146:149], v[218:221], v[80:83]
	v_mfma_f32_16x16x32_bf16 v[76:79], v[158:161], v[218:221], v[76:79]
	s_setprio 0
	s_setprio 1
	v_mfma_f32_16x16x32_bf16 v[120:123], v[162:165], v[178:181], v[120:123]
	v_mfma_f32_16x16x32_bf16 v[116:119], v[170:173], v[178:181], v[116:119]
	v_mfma_f32_16x16x32_bf16 v[104:107], v[162:165], v[186:189], v[104:107]
	v_mfma_f32_16x16x32_bf16 v[100:103], v[170:173], v[186:189], v[100:103]
	v_mfma_f32_16x16x32_bf16 v[88:91], v[162:165], v[194:197], v[88:91]
	v_mfma_f32_16x16x32_bf16 v[84:87], v[170:173], v[194:197], v[84:87]
	v_mfma_f32_16x16x32_bf16 v[72:75], v[162:165], v[214:217], v[72:75]
	v_mfma_f32_16x16x32_bf16 v[68:71], v[170:173], v[214:217], v[68:71]
	v_mfma_f32_16x16x32_bf16 v[120:123], v[166:169], v[182:185], v[120:123]
	v_mfma_f32_16x16x32_bf16 v[116:119], v[174:177], v[182:185], v[116:119]
	v_mfma_f32_16x16x32_bf16 v[104:107], v[166:169], v[190:193], v[104:107]
	v_mfma_f32_16x16x32_bf16 v[100:103], v[174:177], v[190:193], v[100:103]
	v_mfma_f32_16x16x32_bf16 v[88:91], v[166:169], v[210:213], v[88:91]
	v_mfma_f32_16x16x32_bf16 v[84:87], v[174:177], v[210:213], v[84:87]
	v_mfma_f32_16x16x32_bf16 v[72:75], v[166:169], v[218:221], v[72:75]
	v_mfma_f32_16x16x32_bf16 v[68:71], v[174:177], v[218:221], v[68:71]
	s_barrier
; #define PG8_STAGE(bufoff, gbase, voff) do { _Pragma("unroll") for (int _i = 0; _i < 2; ++_i) \
;         __builtin_amdgcn_global_load_lds((const unsigned*)((const char*)(gbase) + (voff)[_i]), (PG8_LAS unsigned*)(lds + (bufoff) + ldsw + _i * 8192), 16, 0, 0); } while (0)
; #define PG8_LDA(dst, b, h) do { _Pragma("unroll") for (int m = 0; m < 4; ++m) _Pragma("unroll") for (int k = 0; k < 2; ++k) dst[m][k] = *(const PG8_LAS bf16x8*)(lds + PG8_SA(b, h) + aoff + m * 2048 + k * 1024); } while (0)
; #define PG8_LDB(dst, b, h) do { _Pragma("unroll") for (int n = 0; n < 2; ++n) _Pragma("unroll") for (int k = 0; k < 2; ++k) dst[n][k] = *(const PG8_LAS bf16x8*)(lds + PG8_SB(b, h) + boff + n * 2048 + k * 1024); } while (0)
; #define PG8_WAIT_V(n) asm volatile("s_waitcnt vmcnt(" #n ")" ::: "memory")
;     ...
;         for (int t = 0; t < nt; t += 2) {
;             const bool last = (t == nt - 2);
;             const char* a1 = cA + (size_t)(t + 1) * kstep;
;             const char* a2 = last ? nA : cA + (size_t)(t + 2) * kstep; const char* b2 = last ? nB : cB + (size_t)(t + 2) * kstep;
;             const char* a3 = a2 + kstep; const char* b3 = b2 + kstep;
;             if (last && has_next) S.a_ready(nxt);
;             if (t == 0) E.pre_issue(pre, cur, tid, ui); else if (t == 2) E.pre_finish(pre, tid, ui);
;             if constexpr (SP2) {
;             PG8_LDB(B0, 0, 0); PG8_LDB(B1, 0, 1); PG8_SCHED; PG8_LDA(At, 0, 0); PG8_STAGE(PG8_SA(1, 1), a1 + hstep, voffA);
;             PG8_WAIT_V(8); PG8_WAIT_L(0); PG8_BAR; PG8_MMA(0, 0, At, B0); PG8_MMA(0, 1, At, B1); PG8_BAR; PG8_SCHED;
;             PG8_LDA(At, 0, 1); PG8_STAGE(PG8_SB(0, 0), b2, voffB); PG8_STAGE(PG8_SB(0, 1), b2 + hstep, voffB); PG8_STAGE(PG8_SA(0, 0), a2, voffA);
;             PG8_WAIT_V(8); PG8_WAIT_L(0); PG8_BAR; PG8_MMA(1, 0, At, B0); PG8_MMA(1, 1, At, B1); PG8_BAR; PG8_SCHED;
;             PG8_LDB(B0, 1, 0); PG8_LDB(B1, 1, 1); PG8_SCHED; PG8_LDA(At, 1, 0); PG8_STAGE(PG8_SA(0, 1), a2 + hstep, voffA);
;             PG8_WAIT_V(8); PG8_WAIT_L(0); PG8_BAR; PG8_MMA(0, 0, At, B0); PG8_MMA(0, 1, At, B1); PG8_BAR; PG8_SCHED;
;             PG8_LDA(At, 1, 1); PG8_STAGE(PG8_SB(1, 0), b3, voffB); PG8_STAGE(PG8_SB(1, 1), b3 + hstep, voffB); PG8_STAGE(PG8_SA(1, 0), a3, voffA);
;             PG8_WAIT_V(8); PG8_WAIT_L(0); PG8_BAR; PG8_MMA(1, 0, At, B0); PG8_MMA(1, 1, At, B1); PG8_BAR; PG8_SCHED;
	s_setprio 0
	s_add_i32 s48, s48, s1
	v_lshl_add_u64 v[198:199], v[198:199], 0, s[66:67]
	s_mov_b32 m0, s48
	ds_read_b128 v[178:181], v156 offset:49152
	ds_read_b128 v[182:185], v156 offset:50176
	ds_read_b128 v[186:189], v156 offset:51200
	ds_read_b128 v[190:193], v156 offset:52224
	ds_read_b128 v[194:197], v156 offset:53248
	ds_read_b128 v[210:213], v156 offset:54272
	ds_read_b128 v[214:217], v156 offset:55296
	ds_read_b128 v[218:221], v156 offset:56320
	global_load_lds_dwordx4 v[198:199], off
	s_add_i32 m0, s48, 0x2000
	s_add_u32 s62, s62, 0x80080
	v_lshl_add_u64 v[198:199], v[206:207], 0, s[66:67]
	s_addc_u32 s63, s63, 0
	s_add_i32 s48, s49, s1
	global_load_lds_dwordx4 v[198:199], off
	v_lshl_add_u64 v[198:199], s[62:63], 0, v[200:201]
	s_mov_b32 m0, s48
	s_nop 0
	global_load_lds_dwordx4 v[198:199], off
	v_lshl_add_u64 v[198:199], s[62:63], 0, v[132:133]
	s_add_i32 m0, s48, 0x2000
	s_nop 0
	global_load_lds_dwordx4 v[198:199], off
	v_lshl_add_u64 v[198:199], v[208:209], 0, s[66:67]
	s_mov_b32 m0, s55
	s_nop 0
	global_load_lds_dwordx4 v[198:199], off
	v_lshl_add_u64 v[198:199], v[222:223], 0, s[66:67]
	s_mov_b32 m0, s56
	s_nop 0
	global_load_lds_dwordx4 v[198:199], off
	s_waitcnt vmcnt(8)
	s_waitcnt lgkmcnt(0)
	s_setprio 1
	s_barrier
	v_mfma_f32_16x16x32_bf16 v[64:67], v[142:145], v[178:181], v[64:67]
	v_mfma_f32_16x16x32_bf16 v[60:63], v[150:153], v[178:181], v[60:63]
	v_mfma_f32_16x16x32_bf16 v[48:51], v[142:145], v[186:189], v[48:51]
	v_mfma_f32_16x16x32_bf16 v[44:47], v[150:153], v[186:189], v[44:47]
	v_mfma_f32_16x16x32_bf16 v[32:35], v[142:145], v[194:197], v[32:35]
	v_mfma_f32_16x16x32_bf16 v[28:31], v[150:153], v[194:197], v[28:31]
	v_mfma_f32_16x16x32_bf16 v[16:19], v[142:145], v[214:217], v[16:19]
	v_mfma_f32_16x16x32_bf16 v[12:15], v[150:153], v[214:217], v[12:15]
	v_mfma_f32_16x16x32_bf16 v[64:67], v[146:149], v[182:185], v[64:67]
	v_mfma_f32_16x16x32_bf16 v[60:63], v[158:161], v[182:185], v[60:63]
	v_mfma_f32_16x16x32_bf16 v[48:51], v[146:149], v[190:193], v[48:51]
	v_mfma_f32_16x16x32_bf16 v[44:47], v[158:161], v[190:193], v[44:47]
	v_mfma_f32_16x16x32_bf16 v[32:35], v[146:149], v[210:213], v[32:35]
	v_mfma_f32_16x16x32_bf16 v[28:31], v[158:161], v[210:213], v[28:31]
	v_mfma_f32_16x16x32_bf16 v[16:19], v[146:149], v[218:221], v[16:19]
	v_mfma_f32_16x16x32_bf16 v[12:15], v[158:161], v[218:221], v[12:15]
	s_setprio 0
	s_setprio 1
	v_mfma_f32_16x16x32_bf16 v[56:59], v[162:165], v[178:181], v[56:59]
	v_mfma_f32_16x16x32_bf16 v[52:55], v[170:173], v[178:181], v[52:55]
	v_mfma_f32_16x16x32_bf16 v[40:43], v[162:165], v[186:189], v[40:43]
	v_mfma_f32_16x16x32_bf16 v[36:39], v[170:173], v[186:189], v[36:39]
	v_mfma_f32_16x16x32_bf16 v[24:27], v[162:165], v[194:197], v[24:27]
	v_mfma_f32_16x16x32_bf16 v[20:23], v[170:173], v[194:197], v[20:23]
	v_mfma_f32_16x16x32_bf16 v[8:11], v[162:165], v[214:217], v[8:11]
	v_mfma_f32_16x16x32_bf16 v[4:7], v[170:173], v[214:217], v[4:7]
	v_mfma_f32_16x16x32_bf16 v[56:59], v[166:169], v[182:185], v[56:59]
	v_mfma_f32_16x16x32_bf16 v[52:55], v[174:177], v[182:185], v[52:55]
	v_mfma_f32_16x16x32_bf16 v[40:43], v[166:169], v[190:193], v[40:43]
	v_mfma_f32_16x16x32_bf16 v[36:39], v[174:177], v[190:193], v[36:39]
	v_mfma_f32_16x16x32_bf16 v[24:27], v[166:169], v[210:213], v[24:27]
	v_mfma_f32_16x16x32_bf16 v[20:23], v[174:177], v[210:213], v[20:23]
	v_mfma_f32_16x16x32_bf16 v[8:11], v[166:169], v[218:221], v[8:11]
	v_mfma_f32_16x16x32_bf16 v[4:7], v[174:177], v[218:221], v[4:7]
	s_barrier
	s_setprio 0
	s_add_i32 s86, s86, 2
	s_add_u32 s60, s60, 0x100
	s_addc_u32 s61, s61, 0
	s_add_u32 s84, s84, 0x100
	s_addc_u32 s85, s85, 0
	s_cmp_gt_u32 s86, 29
	s_cbranch_scc0 .LBB0_198
	s_and_b64 vcc, exec, s[12:13]
	s_cbranch_vccz .LBB0_201
	s_barrier

;     __device__ __forceinline__ bool next(int i, Unit& u) const { if (i >= n) return false; u.pm = pm; u.pn = pn0 + i; return true; }
;     __device__ __forceinline__ bool next(int i, Unit& u) const { if (i) return false; u.pm = pm; u.pn = pn; return true; }
; #define PG8_STAGE(bufoff, gbase, voff) do { _Pragma("unroll") for (int _i = 0; _i < 2; ++_i) \
;         __builtin_amdgcn_global_load_lds((const unsigned*)((const char*)(gbase) + (voff)[_i]), (PG8_LAS unsigned*)(lds + (bufoff) + ldsw + _i * 8192), 16, 0, 0); } while (0)
; #define PG8_WAIT_V(n) asm volatile("s_waitcnt vmcnt(" #n ")" ::: "memory")
; #define PG8_BAR __builtin_amdgcn_s_barrier()
;     ...
;     for (int i = 0; i < 2; ++i) { int R, C; stage_rc(tid * 16 + i * 8192, R, C); const int Rb = Epi::PERM ? ((R & ~31) + perm32(R & 31)) : R;
;         voffA[i] = (unsigned)(R * K + C) * 2u; voffB[i] = (unsigned)(Rb * K + C) * 2u; }
;     const size_t kstep = (size_t)(BK * 2);
;     const size_t hstep = (size_t)HALF * K * 2;
;     const size_t tstep = 2 * hstep;
;     const unsigned ldsw = (unsigned)wid * 1024u;
;     const int aoff = lds_byte(wr * 64 + fr, fq * 8), boff = lds_byte(wc * 32 + fr, fq * 8);
;     ...
;     Unit cur, nxt; int ui = 0;
;     typename Epi::Pre pre;
;     if (!S.next(0, cur)) return;
;     f32x4 acc[2][2][4][2];
; #pragma unroll
;     for (int a = 0; a < 2; ++a)
; #pragma unroll
;         for (int b = 0; b < 2; ++b)
; #pragma unroll
;             for (int m = 0; m < 4; ++m)
; #pragma unroll
;                 for (int n = 0; n < 2; ++n) acc[a][b][m][n] = (f32x4){0.f, 0.f, 0.f, 0.f};
;     bf16x8 At[4][2], B0[2][2], B1[2][2];
;     const char* cA = (const char*)g.A + (size_t)cur.pm * tstep; const char* cB = (const char*)g.Bt + (size_t)cur.pn * tstep;
;     S.a_ready(cur);
;     if constexpr (SP2) {
;         PG8_STAGE(PG8_SB(0, 0), cB, voffB); PG8_STAGE(PG8_SB(0, 1), cB + hstep, voffB); PG8_STAGE(PG8_SA(0, 0), cA, voffA); PG8_STAGE(PG8_SA(0, 1), cA + hstep, voffA);
;         if (wr == 1) PG8_BAR;
;         PG8_WAIT_V(2); PG8_BAR;
;         PG8_STAGE(PG8_SB(1, 0), cB + kstep, voffB); PG8_STAGE(PG8_SA(1, 0), cA + kstep, voffA); PG8_STAGE(PG8_SB(1, 1), cB + hstep + kstep, voffB);
;         PG8_WAIT_V(6); PG8_BAR;
.LBB0_278:
	v_bfe_u32 v142, v9, 4, 2
	s_and_b32 s25, s6, 3
	v_and_b32_e32 v3, 15, v9
	v_lshlrev_b32_e32 v11, 4, v142
	v_lshlrev_b32_e32 v9, 2, v9
	s_lshl_b32 s24, s7, 6
	v_lshl_or_b32 v11, v3, 6, v11
	v_and_b32_e32 v9, 32, v9
	s_lshl_b32 s6, s7, 13
	s_lshl_b32 s7, s25, 12
	v_bitop3_b32 v143, v11, s7, v9 bitop3:0xde
	v_bitop3_b32 v9, v11, s6, v9 bitop3:0xde
	s_add_u32 s6, s75, 0x400080
	s_addc_u32 s7, s82, 0
	v_mov_b32_e32 v137, v201
	v_mov_b32_e32 v133, v201
	s_add_i32 m0, s15, 0x18000
	v_lshl_add_u64 v[16:17], s[6:7], 0, v[200:201]
	v_lshl_add_u64 v[12:13], s[54:55], 0, v[132:133]
	v_mov_b32_e32 v135, v201
	s_waitcnt vmcnt(2)
	s_barrier
	global_load_lds_dwordx4 v[16:17], off
	v_lshl_add_u64 v[16:17], s[6:7], 0, v[136:137]
	s_add_i32 m0, s15, 0x1a000
	s_add_i32 s42, s15, 0x8000
	s_add_i32 s44, s15, 0xa000
	v_lshl_add_u64 v[14:15], s[54:55], 0, v[134:135]
	global_load_lds_dwordx4 v[16:17], off
	v_lshl_add_u64 v[12:13], v[12:13], 0, s[66:67]
	s_mov_b32 m0, s42
	s_add_u32 s6, s75, 0x480080
	global_load_lds_dwordx4 v[12:13], off
	v_lshl_add_u64 v[12:13], v[14:15], 0, s[66:67]
	s_mov_b32 m0, s44
	s_addc_u32 s7, s82, 0
	global_load_lds_dwordx4 v[12:13], off
	s_add_i32 m0, s15, 0x1c000
	v_lshl_add_u64 v[12:13], s[6:7], 0, v[200:201]
	global_load_lds_dwordx4 v[12:13], off
	v_lshl_add_u64 v[12:13], s[6:7], 0, v[136:137]
	s_add_i32 m0, s15, 0x1e000
	v_lshlrev_b32_e32 v11, 15, v4
	global_load_lds_dwordx4 v[12:13], off
	v_and_b32_e32 v11, 0xffff0000, v11
	v_lshl_add_u32 v5, v5, 12, v11
	v_and_b32_e32 v4, 1, v4
	v_lshl_or_b32 v4, v4, 6, v5
	v_readlane_b32 s6, v255, 14
	v_lshl_add_u32 v4, v6, 1, v4
	v_mov_b32_e32 v5, v201
	v_readlane_b32 s7, v255, 15
	s_add_u32 s0, s28, s0
	s_waitcnt vmcnt(6)
	s_mov_b32 s51, -2
	v_lshl_add_u64 v[138:139], s[6:7], 0, v[4:5]
	v_lshlrev_b32_e32 v4, 15, v7
	v_and_b32_e32 v4, 0xffff0000, v4
	v_lshl_add_u32 v4, v8, 12, v4
	v_and_b32_e32 v5, 1, v7
	v_lshl_or_b32 v4, v5, 6, v4
	v_lshl_add_u32 v4, v10, 1, v4
	v_mov_b32_e32 v5, v201
	v_lshl_add_u64 v[140:141], s[6:7], 0, v[4:5]
	s_addc_u32 s6, s29, 0
	s_add_u32 s0, s0, 0xc00100
	v_mov_b32_e32 v4, 0
	s_addc_u32 s50, s6, 0
	s_mov_b64 s[6:7], 0
	v_add_u32_e32 v144, 0, v9
	v_mov_b32_e32 v5, v4
	v_mov_b32_e32 v6, v4
	v_mov_b32_e32 v7, v4
	v_mov_b32_e32 v8, v4
	v_mov_b32_e32 v9, v4
	v_mov_b32_e32 v10, v4
	v_mov_b32_e32 v11, v4
	v_mov_b32_e32 v20, v4
	v_mov_b32_e32 v21, v4
	v_mov_b32_e32 v22, v4
	v_mov_b32_e32 v23, v4
	v_mov_b32_e32 v24, v4
	v_mov_b32_e32 v25, v4
	v_mov_b32_e32 v26, v4
	v_mov_b32_e32 v27, v4
	v_mov_b32_e32 v36, v4
	v_mov_b32_e32 v37, v4
	v_mov_b32_e32 v38, v4
	v_mov_b32_e32 v39, v4
	v_mov_b32_e32 v40, v4
	v_mov_b32_e32 v41, v4
	v_mov_b32_e32 v42, v4
	v_mov_b32_e32 v43, v4
	v_mov_b32_e32 v52, v4
	v_mov_b32_e32 v53, v4
	v_mov_b32_e32 v54, v4
	v_mov_b32_e32 v55, v4
	v_mov_b32_e32 v56, v4
	v_mov_b32_e32 v57, v4
	v_mov_b32_e32 v58, v4
	v_mov_b32_e32 v59, v4
	v_mov_b32_e32 v12, v4
	v_mov_b32_e32 v13, v4
	v_mov_b32_e32 v14, v4
	v_mov_b32_e32 v15, v4
	v_mov_b32_e32 v16, v4
	v_mov_b32_e32 v17, v4
	v_mov_b32_e32 v18, v4
	v_mov_b32_e32 v19, v4
	v_mov_b32_e32 v28, v4
	v_mov_b32_e32 v29, v4
	v_mov_b32_e32 v30, v4
	v_mov_b32_e32 v31, v4
	v_mov_b32_e32 v32, v4
	v_mov_b32_e32 v33, v4
	v_mov_b32_e32 v34, v4
	v_mov_b32_e32 v35, v4
	v_mov_b32_e32 v44, v4
	v_mov_b32_e32 v45, v4
	v_mov_b32_e32 v46, v4
	v_mov_b32_e32 v47, v4
	v_mov_b32_e32 v48, v4
	v_mov_b32_e32 v49, v4
	v_mov_b32_e32 v50, v4
	v_mov_b32_e32 v51, v4
	v_mov_b32_e32 v60, v4
	v_mov_b32_e32 v61, v4
	v_mov_b32_e32 v62, v4
	v_mov_b32_e32 v63, v4
	v_mov_b32_e32 v64, v4
	v_mov_b32_e32 v65, v4
	v_mov_b32_e32 v66, v4
	v_mov_b32_e32 v67, v4
	v_mov_b32_e32 v68, v4
	v_mov_b32_e32 v69, v4
	v_mov_b32_e32 v70, v4
	v_mov_b32_e32 v71, v4
	v_mov_b32_e32 v72, v4
	v_mov_b32_e32 v73, v4
	v_mov_b32_e32 v74, v4
	v_mov_b32_e32 v75, v4
	v_mov_b32_e32 v84, v4
	v_mov_b32_e32 v85, v4
	v_mov_b32_e32 v86, v4
	v_mov_b32_e32 v87, v4
	v_mov_b32_e32 v88, v4
	v_mov_b32_e32 v89, v4
	v_mov_b32_e32 v90, v4
	v_mov_b32_e32 v91, v4
	v_mov_b32_e32 v100, v4
	v_mov_b32_e32 v101, v4
	v_mov_b32_e32 v102, v4
	v_mov_b32_e32 v103, v4
	v_mov_b32_e32 v104, v4
	v_mov_b32_e32 v105, v4
	v_mov_b32_e32 v106, v4
	v_mov_b32_e32 v107, v4
	v_mov_b32_e32 v116, v4
	v_mov_b32_e32 v117, v4
	v_mov_b32_e32 v118, v4
	v_mov_b32_e32 v119, v4
	v_mov_b32_e32 v120, v4
	v_mov_b32_e32 v121, v4
	v_mov_b32_e32 v122, v4
	v_mov_b32_e32 v123, v4
	v_mov_b32_e32 v76, v4
	v_mov_b32_e32 v77, v4
	v_mov_b32_e32 v78, v4
	v_mov_b32_e32 v79, v4
	v_mov_b32_e32 v80, v4
	v_mov_b32_e32 v81, v4
	v_mov_b32_e32 v82, v4
	v_mov_b32_e32 v83, v4
	v_mov_b32_e32 v92, v4
	v_mov_b32_e32 v93, v4
	v_mov_b32_e32 v94, v4
	v_mov_b32_e32 v95, v4
	v_mov_b32_e32 v96, v4
	v_mov_b32_e32 v97, v4
	v_mov_b32_e32 v98, v4
	v_mov_b32_e32 v99, v4
	v_mov_b32_e32 v108, v4
	v_mov_b32_e32 v109, v4
	v_mov_b32_e32 v110, v4
	v_mov_b32_e32 v111, v4
	v_mov_b32_e32 v112, v4
	v_mov_b32_e32 v113, v4
	v_mov_b32_e32 v114, v4
	v_mov_b32_e32 v115, v4
	v_mov_b32_e32 v124, v4
	v_mov_b32_e32 v125, v4
	v_mov_b32_e32 v126, v4
	v_mov_b32_e32 v127, v4
	v_mov_b32_e32 v128, v4
	v_mov_b32_e32 v129, v4
	v_mov_b32_e32 v130, v4
	v_mov_b32_e32 v131, v4
	s_barrier
	v_add_u32_e32 v251, 0x10000, v143
;     __device__ __forceinline__ bool next(int i, Unit& u) const { if (i >= n) return false; u.pm = pm; u.pn = pn0 + i; return true; }
;     __device__ __forceinline__ bool next(int i, Unit& u) const { if (i) return false; u.pm = pm; u.pn = pn; return true; }
; #define PG8_STAGE(bufoff, gbase, voff) do { _Pragma("unroll") for (int _i = 0; _i < 2; ++_i) \
;         __builtin_amdgcn_global_load_lds((const unsigned*)((const char*)(gbase) + (voff)[_i]), (PG8_LAS unsigned*)(lds + (bufoff) + ldsw + _i * 8192), 16, 0, 0); } while (0)
; #define PG8_LDA(dst, b, h) do { _Pragma("unroll") for (int m = 0; m < 4; ++m) _Pragma("unroll") for (int k = 0; k < 2; ++k) dst[m][k] = *(const PG8_LAS bf16x8*)(lds + PG8_SA(b, h) + aoff + m * 2048 + k * 1024); } while (0)
; #define PG8_LDB(dst, b, h) do { _Pragma("unroll") for (int n = 0; n < 2; ++n) _Pragma("unroll") for (int k = 0; k < 2; ++k) dst[n][k] = *(const PG8_LAS bf16x8*)(lds + PG8_SB(b, h) + boff + n * 2048 + k * 1024); } while (0)
; #define PG8_MMA(ai, bj, At, Bt) do { __builtin_amdgcn_s_setprio(1); _Pragma("unroll") for (int m = 0; m < 4; ++m) _Pragma("unroll") for (int n = 0; n < 2; ++n) _Pragma("unroll") for (int k = 0; k < 2; ++k) \
;         acc[ai][bj][m][n] = __builtin_amdgcn_mfma_f32_16x16x32_bf16(Bt[n][k], At[m][k], acc[ai][bj][m][n], 0, 0, 0); __builtin_amdgcn_s_setprio(0); } while (0)
;     ...
;         const bool has_next = S.next(ui + 1, nxt);
;         const char* nA = has_next ? (const char*)g.A + (size_t)nxt.pm * tstep : cA; const char* nB = has_next ? (const char*)g.Bt + (size_t)nxt.pn * tstep : cB;
;         for (int t = 0; t < nt; t += 2) {
;             const bool last = (t == nt - 2);
;             const char* a1 = cA + (size_t)(t + 1) * kstep;
;             const char* a2 = last ? nA : cA + (size_t)(t + 2) * kstep; const char* b2 = last ? nB : cB + (size_t)(t + 2) * kstep;
;             const char* a3 = a2 + kstep; const char* b3 = b2 + kstep;
;             if (last && has_next) S.a_ready(nxt);
;             if (t == 0) E.pre_issue(pre, cur, tid, ui); else if (t == 2) E.pre_finish(pre, tid, ui);
;             if constexpr (SP2) {
;             PG8_LDB(B0, 0, 0); PG8_LDB(B1, 0, 1); PG8_SCHED; PG8_LDA(At, 0, 0); PG8_STAGE(PG8_SA(1, 1), a1 + hstep, voffA);
;             PG8_WAIT_V(8); PG8_WAIT_L(0); PG8_BAR; PG8_MMA(0, 0, At, B0); PG8_MMA(0, 1, At, B1); PG8_BAR; PG8_SCHED;
.LBB0_279:
	s_add_u32 s10, s56, s6
	s_addc_u32 s11, s73, s7
	s_add_u32 s10, s10, 0x1d800100
	s_addc_u32 s11, s11, 0
	s_add_u32 s48, s0, s6
	s_addc_u32 s49, s50, s7
	s_add_i32 s52, 0, 0x10000
	s_cmpk_eq_i32 s6, 0xf00
	s_cselect_b32 s13, s55, s11
	s_cselect_b32 s12, s54, s10
	s_cselect_b32 s11, s5, s49
	s_cselect_b32 s10, s4, s48
	s_add_i32 s48, 0, 0x14000
	ds_read_b128 v[146:149], v251
	ds_read_b128 v[150:153], v251 offset:1024
	ds_read_b128 v[154:157], v251 offset:2048
	ds_read_b128 v[158:161], v251 offset:3072
	ds_read_b128 v[162:165], v251 offset:16384
	ds_read_b128 v[166:169], v251 offset:17408
	ds_read_b128 v[170:173], v251 offset:18432
	ds_read_b128 v[174:177], v251 offset:19456
	v_lshl_add_u64 v[198:199], v[138:139], 0, s[6:7]
	s_add_i32 m0, s15, 0xc000
	ds_read_b128 v[178:181], v144
	ds_read_b128 v[182:185], v144 offset:1024
	ds_read_b128 v[186:189], v144 offset:2048
	ds_read_b128 v[190:193], v144 offset:3072
	ds_read_b128 v[194:197], v144 offset:4096
	ds_read_b128 v[210:213], v144 offset:5120
	ds_read_b128 v[214:217], v144 offset:6144
	ds_read_b128 v[218:221], v144 offset:7168
	global_load_lds_dwordx4 v[198:199], off
	v_lshl_add_u64 v[198:199], v[140:141], 0, s[6:7]
	s_add_i32 m0, s15, 0xe000
	s_nop 0
	global_load_lds_dwordx4 v[198:199], off
	s_waitcnt vmcnt(8)
	s_waitcnt lgkmcnt(0)
	s_setprio 1
	s_barrier
	v_mfma_f32_16x16x32_bf16 v[128:131], v[146:149], v[178:181], v[128:131]
	v_mfma_f32_16x16x32_bf16 v[124:127], v[154:157], v[178:181], v[124:127]
	v_mfma_f32_16x16x32_bf16 v[112:115], v[146:149], v[186:189], v[112:115]
	v_mfma_f32_16x16x32_bf16 v[108:111], v[154:157], v[186:189], v[108:111]
	v_mfma_f32_16x16x32_bf16 v[96:99], v[146:149], v[194:197], v[96:99]
	v_mfma_f32_16x16x32_bf16 v[92:95], v[154:157], v[194:197], v[92:95]
	v_mfma_f32_16x16x32_bf16 v[80:83], v[146:149], v[214:217], v[80:83]
	v_mfma_f32_16x16x32_bf16 v[76:79], v[154:157], v[214:217], v[76:79]
	v_mfma_f32_16x16x32_bf16 v[128:131], v[150:153], v[182:185], v[128:131]
	v_mfma_f32_16x16x32_bf16 v[124:127], v[158:161], v[182:185], v[124:127]
	v_mfma_f32_16x16x32_bf16 v[112:115], v[150:153], v[190:193], v[112:115]
	v_mfma_f32_16x16x32_bf16 v[108:111], v[158:161], v[190:193], v[108:111]
	v_mfma_f32_16x16x32_bf16 v[96:99], v[150:153], v[210:213], v[96:99]
	v_mfma_f32_16x16x32_bf16 v[92:95], v[158:161], v[210:213], v[92:95]
	v_mfma_f32_16x16x32_bf16 v[80:83], v[150:153], v[218:221], v[80:83]
	v_mfma_f32_16x16x32_bf16 v[76:79], v[158:161], v[218:221], v[76:79]
	s_setprio 0
	s_setprio 1
	v_mfma_f32_16x16x32_bf16 v[120:123], v[162:165], v[178:181], v[120:123]
	v_mfma_f32_16x16x32_bf16 v[116:119], v[170:173], v[178:181], v[116:119]
	v_mfma_f32_16x16x32_bf16 v[104:107], v[162:165], v[186:189], v[104:107]
	v_mfma_f32_16x16x32_bf16 v[100:103], v[170:173], v[186:189], v[100:103]
	v_mfma_f32_16x16x32_bf16 v[88:91], v[162:165], v[194:197], v[88:91]
	v_mfma_f32_16x16x32_bf16 v[84:87], v[170:173], v[194:197], v[84:87]
	v_mfma_f32_16x16x32_bf16 v[72:75], v[162:165], v[214:217], v[72:75]
	v_mfma_f32_16x16x32_bf16 v[68:71], v[170:173], v[214:217], v[68:71]
	v_mfma_f32_16x16x32_bf16 v[120:123], v[166:169], v[182:185], v[120:123]
	v_mfma_f32_16x16x32_bf16 v[116:119], v[174:177], v[182:185], v[116:119]
	v_mfma_f32_16x16x32_bf16 v[104:107], v[166:169], v[190:193], v[104:107]
	v_mfma_f32_16x16x32_bf16 v[100:103], v[174:177], v[190:193], v[100:103]
	v_mfma_f32_16x16x32_bf16 v[88:91], v[166:169], v[210:213], v[88:91]
	v_mfma_f32_16x16x32_bf16 v[84:87], v[174:177], v[210:213], v[84:87]
	v_mfma_f32_16x16x32_bf16 v[72:75], v[166:169], v[218:221], v[72:75]
	v_mfma_f32_16x16x32_bf16 v[68:71], v[174:177], v[218:221], v[68:71]
	s_barrier
	s_setprio 0
	s_add_i32 s49, s52, s14
	v_lshl_add_u64 v[198:199], s[10:11], 0, v[200:201]
	s_mov_b32 m0, s49
	ds_read_b128 v[178:181], v144 offset:16384
	ds_read_b128 v[182:185], v144 offset:17408
	ds_read_b128 v[186:189], v144 offset:18432
	ds_read_b128 v[190:193], v144 offset:19456
	ds_read_b128 v[194:197], v144 offset:20480
	ds_read_b128 v[210:213], v144 offset:21504
	ds_read_b128 v[214:217], v144 offset:22528
	ds_read_b128 v[218:221], v144 offset:23552
	global_load_lds_dwordx4 v[198:199], off
	s_add_i32 m0, s49, 0x2000
	s_add_u32 s52, s10, 0x80000
	v_lshl_add_u64 v[206:207], s[10:11], 0, v[136:137]
	s_addc_u32 s53, s11, 0
	s_add_i32 s48, s48, s14
	global_load_lds_dwordx4 v[206:207], off
	v_lshl_add_u64 v[208:209], s[52:53], 0, v[200:201]
	s_mov_b32 m0, s48
	v_lshl_add_u64 v[222:223], s[12:13], 0, v[134:135]
	global_load_lds_dwordx4 v[208:209], off
	v_lshl_add_u64 v[208:209], s[52:53], 0, v[136:137]
	s_add_i32 m0, s48, 0x2000
	s_nop 0
	global_load_lds_dwordx4 v[208:209], off
	v_lshl_add_u64 v[208:209], s[12:13], 0, v[132:133]
	s_mov_b32 m0, s15
	s_nop 0
	global_load_lds_dwordx4 v[208:209], off
	s_mov_b32 m0, s20
	s_nop 0
	global_load_lds_dwordx4 v[222:223], off
	s_waitcnt vmcnt(8)
	s_waitcnt lgkmcnt(0)
	s_setprio 1
	s_barrier
; #define PG8_STAGE(bufoff, gbase, voff) do { _Pragma("unroll") for (int _i = 0; _i < 2; ++_i) \
;         __builtin_amdgcn_global_load_lds((const unsigned*)((const char*)(gbase) + (voff)[_i]), (PG8_LAS unsigned*)(lds + (bufoff) + ldsw + _i * 8192), 16, 0, 0); } while (0)
; #define PG8_LDA(dst, b, h) do { _Pragma("unroll") for (int m = 0; m < 4; ++m) _Pragma("unroll") for (int k = 0; k < 2; ++k) dst[m][k] = *(const PG8_LAS bf16x8*)(lds + PG8_SA(b, h) + aoff + m * 2048 + k * 1024); } while (0)
; #define PG8_LDB(dst, b, h) do { _Pragma("unroll") for (int n = 0; n < 2; ++n) _Pragma("unroll") for (int k = 0; k < 2; ++k) dst[n][k] = *(const PG8_LAS bf16x8*)(lds + PG8_SB(b, h) + boff + n * 2048 + k * 1024); } while (0)
; #define PG8_MMA(ai, bj, At, Bt) do { __builtin_amdgcn_s_setprio(1); _Pragma("unroll") for (int m = 0; m < 4; ++m) _Pragma("unroll") for (int n = 0; n < 2; ++n) _Pragma("unroll") for (int k = 0; k < 2; ++k) \
;         acc[ai][bj][m][n] = __builtin_amdgcn_mfma_f32_16x16x32_bf16(Bt[n][k], At[m][k], acc[ai][bj][m][n], 0, 0, 0); __builtin_amdgcn_s_setprio(0); } while (0)
; #define PG8_WAIT_V(n) asm volatile("s_waitcnt vmcnt(" #n ")" ::: "memory")
; #define PG8_WAIT_L(n) asm volatile("s_waitcnt lgkmcnt(" #n ")" ::: "memory")
; #define PG8_BAR __builtin_amdgcn_s_barrier()
; #define PG8_SCHED __builtin_amdgcn_sched_barrier(0)
;     ...
;             PG8_WAIT_V(8); PG8_WAIT_L(0); PG8_BAR; PG8_MMA(1, 0, At, B0); PG8_MMA(1, 1, At, B1); PG8_BAR; PG8_SCHED;
;             PG8_LDB(B0, 1, 0); PG8_LDB(B1, 1, 1); PG8_SCHED; PG8_LDA(At, 1, 0); PG8_STAGE(PG8_SA(0, 1), a2 + hstep, voffA);
;             PG8_WAIT_V(8); PG8_WAIT_L(0); PG8_BAR; PG8_MMA(0, 0, At, B0); PG8_MMA(0, 1, At, B1); PG8_BAR; PG8_SCHED;
	v_mfma_f32_16x16x32_bf16 v[64:67], v[146:149], v[178:181], v[64:67]
	v_mfma_f32_16x16x32_bf16 v[60:63], v[154:157], v[178:181], v[60:63]
	v_mfma_f32_16x16x32_bf16 v[48:51], v[146:149], v[186:189], v[48:51]
	v_mfma_f32_16x16x32_bf16 v[44:47], v[154:157], v[186:189], v[44:47]
	v_mfma_f32_16x16x32_bf16 v[32:35], v[146:149], v[194:197], v[32:35]
	v_mfma_f32_16x16x32_bf16 v[28:31], v[154:157], v[194:197], v[28:31]
	v_mfma_f32_16x16x32_bf16 v[16:19], v[146:149], v[214:217], v[16:19]
	v_mfma_f32_16x16x32_bf16 v[12:15], v[154:157], v[214:217], v[12:15]
	v_mfma_f32_16x16x32_bf16 v[64:67], v[150:153], v[182:185], v[64:67]
	v_mfma_f32_16x16x32_bf16 v[60:63], v[158:161], v[182:185], v[60:63]
	v_mfma_f32_16x16x32_bf16 v[48:51], v[150:153], v[190:193], v[48:51]
	v_mfma_f32_16x16x32_bf16 v[44:47], v[158:161], v[190:193], v[44:47]
	v_mfma_f32_16x16x32_bf16 v[32:35], v[150:153], v[210:213], v[32:35]
	v_mfma_f32_16x16x32_bf16 v[28:31], v[158:161], v[210:213], v[28:31]
	v_mfma_f32_16x16x32_bf16 v[16:19], v[150:153], v[218:221], v[16:19]
	v_mfma_f32_16x16x32_bf16 v[12:15], v[158:161], v[218:221], v[12:15]
	s_setprio 0
	s_setprio 1
	v_mfma_f32_16x16x32_bf16 v[56:59], v[162:165], v[178:181], v[56:59]
	v_mfma_f32_16x16x32_bf16 v[52:55], v[170:173], v[178:181], v[52:55]
	v_mfma_f32_16x16x32_bf16 v[40:43], v[162:165], v[186:189], v[40:43]
	v_mfma_f32_16x16x32_bf16 v[36:39], v[170:173], v[186:189], v[36:39]
	v_mfma_f32_16x16x32_bf16 v[24:27], v[162:165], v[194:197], v[24:27]
	v_mfma_f32_16x16x32_bf16 v[20:23], v[170:173], v[194:197], v[20:23]
	v_mfma_f32_16x16x32_bf16 v[8:11], v[162:165], v[214:217], v[8:11]
	v_mfma_f32_16x16x32_bf16 v[4:7], v[170:173], v[214:217], v[4:7]
	v_mfma_f32_16x16x32_bf16 v[56:59], v[166:169], v[182:185], v[56:59]
	v_mfma_f32_16x16x32_bf16 v[52:55], v[174:177], v[182:185], v[52:55]
	v_mfma_f32_16x16x32_bf16 v[40:43], v[166:169], v[190:193], v[40:43]
	v_mfma_f32_16x16x32_bf16 v[36:39], v[174:177], v[190:193], v[36:39]
	v_mfma_f32_16x16x32_bf16 v[24:27], v[166:169], v[210:213], v[24:27]
	v_mfma_f32_16x16x32_bf16 v[20:23], v[174:177], v[210:213], v[20:23]
	v_mfma_f32_16x16x32_bf16 v[8:11], v[166:169], v[218:221], v[8:11]
	v_mfma_f32_16x16x32_bf16 v[4:7], v[174:177], v[218:221], v[4:7]
	s_barrier
	s_setprio 0
	s_add_i32 s48, 0, 0x18000
	s_add_i32 s49, 0, 0x1c000
	ds_read_b128 v[146:149], v251 offset:32768
	ds_read_b128 v[150:153], v251 offset:33792
	ds_read_b128 v[154:157], v251 offset:34816
	ds_read_b128 v[158:161], v251 offset:35840
	ds_read_b128 v[162:165], v251 offset:49152
	ds_read_b128 v[166:169], v251 offset:50176
	ds_read_b128 v[170:173], v251 offset:51200
	ds_read_b128 v[174:177], v251 offset:52224
	s_add_u32 s12, s12, 0x80000
	s_addc_u32 s13, s13, 0
	s_mov_b32 m0, s21
	v_lshl_add_u64 v[224:225], s[12:13], 0, v[132:133]
	ds_read_b128 v[178:181], v144 offset:32768
	ds_read_b128 v[182:185], v144 offset:33792
	ds_read_b128 v[186:189], v144 offset:34816
	ds_read_b128 v[190:193], v144 offset:35840
	ds_read_b128 v[194:197], v144 offset:36864
	ds_read_b128 v[210:213], v144 offset:37888
	ds_read_b128 v[214:217], v144 offset:38912
	ds_read_b128 v[218:221], v144 offset:39936
	global_load_lds_dwordx4 v[224:225], off
	v_lshl_add_u64 v[224:225], s[12:13], 0, v[134:135]
	s_mov_b32 m0, s23
	s_nop 0
	global_load_lds_dwordx4 v[224:225], off
	s_waitcnt vmcnt(8)
	s_waitcnt lgkmcnt(0)
	s_setprio 1
	s_barrier
	v_mfma_f32_16x16x32_bf16 v[128:131], v[146:149], v[178:181], v[128:131]
	v_mfma_f32_16x16x32_bf16 v[124:127], v[154:157], v[178:181], v[124:127]
	v_mfma_f32_16x16x32_bf16 v[112:115], v[146:149], v[186:189], v[112:115]
	v_mfma_f32_16x16x32_bf16 v[108:111], v[154:157], v[186:189], v[108:111]
	v_mfma_f32_16x16x32_bf16 v[96:99], v[146:149], v[194:197], v[96:99]
	v_mfma_f32_16x16x32_bf16 v[92:95], v[154:157], v[194:197], v[92:95]
	v_mfma_f32_16x16x32_bf16 v[80:83], v[146:149], v[214:217], v[80:83]
	v_mfma_f32_16x16x32_bf16 v[76:79], v[154:157], v[214:217], v[76:79]
	v_mfma_f32_16x16x32_bf16 v[128:131], v[150:153], v[182:185], v[128:131]
	v_mfma_f32_16x16x32_bf16 v[124:127], v[158:161], v[182:185], v[124:127]
	v_mfma_f32_16x16x32_bf16 v[112:115], v[150:153], v[190:193], v[112:115]
	v_mfma_f32_16x16x32_bf16 v[108:111], v[158:161], v[190:193], v[108:111]
	v_mfma_f32_16x16x32_bf16 v[96:99], v[150:153], v[210:213], v[96:99]
	v_mfma_f32_16x16x32_bf16 v[92:95], v[158:161], v[210:213], v[92:95]
	v_mfma_f32_16x16x32_bf16 v[80:83], v[150:153], v[218:221], v[80:83]
	v_mfma_f32_16x16x32_bf16 v[76:79], v[158:161], v[218:221], v[76:79]
	s_setprio 0
	s_setprio 1
	v_mfma_f32_16x16x32_bf16 v[120:123], v[162:165], v[178:181], v[120:123]
	v_mfma_f32_16x16x32_bf16 v[116:119], v[170:173], v[178:181], v[116:119]
	v_mfma_f32_16x16x32_bf16 v[104:107], v[162:165], v[186:189], v[104:107]
	v_mfma_f32_16x16x32_bf16 v[100:103], v[170:173], v[186:189], v[100:103]
	v_mfma_f32_16x16x32_bf16 v[88:91], v[162:165], v[194:197], v[88:91]
	v_mfma_f32_16x16x32_bf16 v[84:87], v[170:173], v[194:197], v[84:87]
	v_mfma_f32_16x16x32_bf16 v[72:75], v[162:165], v[214:217], v[72:75]
	v_mfma_f32_16x16x32_bf16 v[68:71], v[170:173], v[214:217], v[68:71]
	v_mfma_f32_16x16x32_bf16 v[120:123], v[166:169], v[182:185], v[120:123]
	v_mfma_f32_16x16x32_bf16 v[116:119], v[174:177], v[182:185], v[116:119]
	v_mfma_f32_16x16x32_bf16 v[104:107], v[166:169], v[190:193], v[104:107]
	v_mfma_f32_16x16x32_bf16 v[100:103], v[174:177], v[190:193], v[100:103]
	v_mfma_f32_16x16x32_bf16 v[88:91], v[166:169], v[210:213], v[88:91]
	v_mfma_f32_16x16x32_bf16 v[84:87], v[174:177], v[210:213], v[84:87]
	v_mfma_f32_16x16x32_bf16 v[72:75], v[166:169], v[218:221], v[72:75]
	v_mfma_f32_16x16x32_bf16 v[68:71], v[174:177], v[218:221], v[68:71]
	s_barrier
; #define PG8_STAGE(bufoff, gbase, voff) do { _Pragma("unroll") for (int _i = 0; _i < 2; ++_i) \
;         __builtin_amdgcn_global_load_lds((const unsigned*)((const char*)(gbase) + (voff)[_i]), (PG8_LAS unsigned*)(lds + (bufoff) + ldsw + _i * 8192), 16, 0, 0); } while (0)
; #define PG8_LDA(dst, b, h) do { _Pragma("unroll") for (int m = 0; m < 4; ++m) _Pragma("unroll") for (int k = 0; k < 2; ++k) dst[m][k] = *(const PG8_LAS bf16x8*)(lds + PG8_SA(b, h) + aoff + m * 2048 + k * 1024); } while (0)
; #define PG8_MMA(ai, bj, At, Bt) do { __builtin_amdgcn_s_setprio(1); _Pragma("unroll") for (int m = 0; m < 4; ++m) _Pragma("unroll") for (int n = 0; n < 2; ++n) _Pragma("unroll") for (int k = 0; k < 2; ++k) \
;         acc[ai][bj][m][n] = __builtin_amdgcn_mfma_f32_16x16x32_bf16(Bt[n][k], At[m][k], acc[ai][bj][m][n], 0, 0, 0); __builtin_amdgcn_s_setprio(0); } while (0)
; #define PG8_WAIT_V(n) asm volatile("s_waitcnt vmcnt(" #n ")" ::: "memory")
; #define PG8_WAIT_L(n) asm volatile("s_waitcnt lgkmcnt(" #n ")" ::: "memory")
; #define PG8_BAR __builtin_amdgcn_s_barrier()
; #define PG8_SCHED __builtin_amdgcn_sched_barrier(0)
;     ...
;             PG8_LDA(At, 1, 1); PG8_STAGE(PG8_SB(1, 0), b3, voffB); PG8_STAGE(PG8_SB(1, 1), b3 + hstep, voffB); PG8_STAGE(PG8_SA(1, 0), a3, voffA);
;             PG8_WAIT_V(8); PG8_WAIT_L(0); PG8_BAR; PG8_MMA(1, 0, At, B0); PG8_MMA(1, 1, At, B1); PG8_BAR; PG8_SCHED;
;     ...
;         if constexpr (ALIGN_EPI) { if (wr == 0) PG8_BAR; }
	s_setprio 0
	s_add_i32 s12, s48, s14
	v_lshl_add_u64 v[198:199], v[198:199], 0, s[66:67]
	s_mov_b32 m0, s12
	ds_read_b128 v[178:181], v144 offset:49152
	ds_read_b128 v[182:185], v144 offset:50176
	ds_read_b128 v[186:189], v144 offset:51200
	ds_read_b128 v[190:193], v144 offset:52224
	ds_read_b128 v[194:197], v144 offset:53248
	ds_read_b128 v[210:213], v144 offset:54272
	ds_read_b128 v[214:217], v144 offset:55296
	ds_read_b128 v[218:221], v144 offset:56320
	global_load_lds_dwordx4 v[198:199], off
	s_add_i32 m0, s12, 0x2000
	s_add_u32 s10, s10, 0x80080
	v_lshl_add_u64 v[198:199], v[206:207], 0, s[66:67]
	s_addc_u32 s11, s11, 0
	s_add_i32 s12, s49, s14
	global_load_lds_dwordx4 v[198:199], off
	v_lshl_add_u64 v[198:199], s[10:11], 0, v[200:201]
	s_mov_b32 m0, s12
	s_nop 0
	global_load_lds_dwordx4 v[198:199], off
	v_lshl_add_u64 v[198:199], s[10:11], 0, v[136:137]
	s_add_i32 m0, s12, 0x2000
	s_nop 0
	global_load_lds_dwordx4 v[198:199], off
	v_lshl_add_u64 v[198:199], v[208:209], 0, s[66:67]
	s_mov_b32 m0, s42
	s_nop 0
	global_load_lds_dwordx4 v[198:199], off
	v_lshl_add_u64 v[198:199], v[222:223], 0, s[66:67]
	s_mov_b32 m0, s44
	s_nop 0
	global_load_lds_dwordx4 v[198:199], off
	s_waitcnt vmcnt(8)
	s_waitcnt lgkmcnt(0)
	s_setprio 1
	s_barrier
	v_mfma_f32_16x16x32_bf16 v[64:67], v[146:149], v[178:181], v[64:67]
	v_mfma_f32_16x16x32_bf16 v[60:63], v[154:157], v[178:181], v[60:63]
	v_mfma_f32_16x16x32_bf16 v[48:51], v[146:149], v[186:189], v[48:51]
	v_mfma_f32_16x16x32_bf16 v[44:47], v[154:157], v[186:189], v[44:47]
	v_mfma_f32_16x16x32_bf16 v[32:35], v[146:149], v[194:197], v[32:35]
	v_mfma_f32_16x16x32_bf16 v[28:31], v[154:157], v[194:197], v[28:31]
	v_mfma_f32_16x16x32_bf16 v[16:19], v[146:149], v[214:217], v[16:19]
	v_mfma_f32_16x16x32_bf16 v[12:15], v[154:157], v[214:217], v[12:15]
	v_mfma_f32_16x16x32_bf16 v[64:67], v[150:153], v[182:185], v[64:67]
	v_mfma_f32_16x16x32_bf16 v[60:63], v[158:161], v[182:185], v[60:63]
	v_mfma_f32_16x16x32_bf16 v[48:51], v[150:153], v[190:193], v[48:51]
	v_mfma_f32_16x16x32_bf16 v[44:47], v[158:161], v[190:193], v[44:47]
	v_mfma_f32_16x16x32_bf16 v[32:35], v[150:153], v[210:213], v[32:35]
	v_mfma_f32_16x16x32_bf16 v[28:31], v[158:161], v[210:213], v[28:31]
	v_mfma_f32_16x16x32_bf16 v[16:19], v[150:153], v[218:221], v[16:19]
	v_mfma_f32_16x16x32_bf16 v[12:15], v[158:161], v[218:221], v[12:15]
	s_setprio 0
	s_setprio 1
	v_mfma_f32_16x16x32_bf16 v[56:59], v[162:165], v[178:181], v[56:59]
	v_mfma_f32_16x16x32_bf16 v[52:55], v[170:173], v[178:181], v[52:55]
	v_mfma_f32_16x16x32_bf16 v[40:43], v[162:165], v[186:189], v[40:43]
	v_mfma_f32_16x16x32_bf16 v[36:39], v[170:173], v[186:189], v[36:39]
	v_mfma_f32_16x16x32_bf16 v[24:27], v[162:165], v[194:197], v[24:27]
	v_mfma_f32_16x16x32_bf16 v[20:23], v[170:173], v[194:197], v[20:23]
	v_mfma_f32_16x16x32_bf16 v[8:11], v[162:165], v[214:217], v[8:11]
	v_mfma_f32_16x16x32_bf16 v[4:7], v[170:173], v[214:217], v[4:7]
	v_mfma_f32_16x16x32_bf16 v[56:59], v[166:169], v[182:185], v[56:59]
	v_mfma_f32_16x16x32_bf16 v[52:55], v[174:177], v[182:185], v[52:55]
	v_mfma_f32_16x16x32_bf16 v[40:43], v[166:169], v[190:193], v[40:43]
	v_mfma_f32_16x16x32_bf16 v[36:39], v[174:177], v[190:193], v[36:39]
	v_mfma_f32_16x16x32_bf16 v[24:27], v[166:169], v[210:213], v[24:27]
	v_mfma_f32_16x16x32_bf16 v[20:23], v[174:177], v[210:213], v[20:23]
	v_mfma_f32_16x16x32_bf16 v[8:11], v[166:169], v[218:221], v[8:11]
	v_mfma_f32_16x16x32_bf16 v[4:7], v[174:177], v[218:221], v[4:7]
	s_barrier
	s_setprio 0
	s_add_i32 s51, s51, 2
	s_add_u32 s6, s6, 0x100
	s_addc_u32 s7, s7, 0
	s_cmp_gt_u32 s51, 29
	s_cbranch_scc0 .LBB0_279
	s_cmpk_lt_u32 s1, 0x100
	s_cbranch_scc0 .LBB0_282
	s_barrier

;     __device__ __forceinline__ bool next(int i, Unit& u) const { if (i >= n) return false; u.pm = pm; u.pn = pn0 + i; return true; }
;     __device__ __forceinline__ bool next(int i, Unit& u) const { if (i) return false; u.pm = pm; u.pn = pn; return true; }
; #define PG8_STAGE(bufoff, gbase, voff) do { _Pragma("unroll") for (int _i = 0; _i < 2; ++_i) \
;         __builtin_amdgcn_global_load_lds((const unsigned*)((const char*)(gbase) + (voff)[_i]), (PG8_LAS unsigned*)(lds + (bufoff) + ldsw + _i * 8192), 16, 0, 0); } while (0)
; #define PG8_LDA(dst, b, h) do { _Pragma("unroll") for (int m = 0; m < 4; ++m) _Pragma("unroll") for (int k = 0; k < 2; ++k) dst[m][k] = *(const PG8_LAS bf16x8*)(lds + PG8_SA(b, h) + aoff + m * 2048 + k * 1024); } while (0)
; #define PG8_LDB(dst, b, h) do { _Pragma("unroll") for (int n = 0; n < 2; ++n) _Pragma("unroll") for (int k = 0; k < 2; ++k) dst[n][k] = *(const PG8_LAS bf16x8*)(lds + PG8_SB(b, h) + boff + n * 2048 + k * 1024); } while (0)
; #define PG8_SCHED __builtin_amdgcn_sched_barrier(0)
;     ...
;         const bool has_next = S.next(ui + 1, nxt);
;         const char* nA = has_next ? (const char*)g.A + (size_t)nxt.pm * tstep : cA; const char* nB = has_next ? (const char*)g.Bt + (size_t)nxt.pn * tstep : cB;
;         for (int t = 0; t < nt; t += 2) {
;             const bool last = (t == nt - 2);
;             const char* a1 = cA + (size_t)(t + 1) * kstep;
;             const char* a2 = last ? nA : cA + (size_t)(t + 2) * kstep; const char* b2 = last ? nB : cB + (size_t)(t + 2) * kstep;
;             const char* a3 = a2 + kstep; const char* b3 = b2 + kstep;
;             if (last && has_next) S.a_ready(nxt);
;             if (t == 0) E.pre_issue(pre, cur, tid, ui); else if (t == 2) E.pre_finish(pre, tid, ui);
;             if constexpr (SP2) {
;             PG8_LDB(B0, 0, 0); PG8_LDB(B1, 0, 1); PG8_SCHED; PG8_LDA(At, 0, 0); PG8_STAGE(PG8_SA(1, 1), a1 + hstep, voffA);
;     ...
;         for (int a = 0; a < 2; ++a)
; #pragma unroll
;             for (int b = 0; b < 2; ++b)
; #pragma unroll
;                 for (int m = 0; m < 4; ++m)
; #pragma unroll
;                     for (int n = 0; n < 2; ++n) acc[a][b][m][n] = (f32x4){0.f, 0.f, 0.f, 0.f};
;         cur = nxt; cA = nA; cB = nB; ++ui;
.LBB0_289:
	s_add_i32 s62, s63, 1
	s_cmp_lt_u32 s63, 7
	s_mov_b64 s[24:25], s[6:7]
	s_mov_b32 s6, s59
	s_cselect_b64 s[60:61], -1, 0
	s_add_i32 s59, s62, s84
	s_mov_b64 s[50:51], s[4:5]
	s_and_b64 s[4:5], s[60:61], exec
	v_readlane_b32 s5, v254, 23
	s_cselect_b32 s4, s59, s6
	s_cselect_b32 s6, s5, s5
	s_ashr_i32 s7, s6, 31
	s_lshl_b64 s[6:7], s[6:7], 18
	s_add_u32 s6, s78, s6
	s_addc_u32 s7, s79, s7
	s_and_b64 s[68:69], s[60:61], exec
	s_cselect_b32 s68, s7, s25
	s_cselect_b32 s69, s6, s24
	s_ashr_i32 s5, s4, 31
	s_lshl_b64 s[4:5], s[4:5], 18
	s_add_u32 s4, s0, s4
	s_addc_u32 s5, s1, s5
	s_and_b64 s[60:61], s[60:61], exec
	s_cselect_b32 s70, s5, s51
	s_cselect_b32 s71, s4, s50
	s_add_u32 s73, s50, 0x100
	s_addc_u32 s81, s51, 0
	s_add_u32 s24, s24, 0x20080
	v_mov_b32_e32 v4, 0
	s_addc_u32 s25, s25, 0
	s_mov_b32 s83, -2
	v_mov_b32_e32 v5, v4
	v_mov_b32_e32 v6, v4
	v_mov_b32_e32 v7, v4
	v_mov_b32_e32 v8, v4
	v_mov_b32_e32 v9, v4
	v_mov_b32_e32 v10, v4
	v_mov_b32_e32 v11, v4
	v_mov_b32_e32 v20, v4
	v_mov_b32_e32 v21, v4
	v_mov_b32_e32 v22, v4
	v_mov_b32_e32 v23, v4
	v_mov_b32_e32 v24, v4
	v_mov_b32_e32 v25, v4
	v_mov_b32_e32 v26, v4
	v_mov_b32_e32 v27, v4
	v_mov_b32_e32 v36, v4
	v_mov_b32_e32 v37, v4
	v_mov_b32_e32 v38, v4
	v_mov_b32_e32 v39, v4
	v_mov_b32_e32 v40, v4
	v_mov_b32_e32 v41, v4
	v_mov_b32_e32 v42, v4
	v_mov_b32_e32 v43, v4
	v_mov_b32_e32 v52, v4
	v_mov_b32_e32 v53, v4
	v_mov_b32_e32 v54, v4
	v_mov_b32_e32 v55, v4
	v_mov_b32_e32 v56, v4
	v_mov_b32_e32 v57, v4
	v_mov_b32_e32 v58, v4
	v_mov_b32_e32 v59, v4
	v_mov_b32_e32 v12, v4
	v_mov_b32_e32 v13, v4
	v_mov_b32_e32 v14, v4
	v_mov_b32_e32 v15, v4
	v_mov_b32_e32 v16, v4
	v_mov_b32_e32 v17, v4
	v_mov_b32_e32 v18, v4
	v_mov_b32_e32 v19, v4
	v_mov_b32_e32 v28, v4
	v_mov_b32_e32 v29, v4
	v_mov_b32_e32 v30, v4
	v_mov_b32_e32 v31, v4
	v_mov_b32_e32 v32, v4
	v_mov_b32_e32 v33, v4
	v_mov_b32_e32 v34, v4
	v_mov_b32_e32 v35, v4
	v_mov_b32_e32 v44, v4
	v_mov_b32_e32 v45, v4
	v_mov_b32_e32 v46, v4
	v_mov_b32_e32 v47, v4
	v_mov_b32_e32 v48, v4
	v_mov_b32_e32 v49, v4
	v_mov_b32_e32 v50, v4
	v_mov_b32_e32 v51, v4
	v_mov_b32_e32 v60, v4
	v_mov_b32_e32 v61, v4
	v_mov_b32_e32 v62, v4
	v_mov_b32_e32 v63, v4
	v_mov_b32_e32 v64, v4
	v_mov_b32_e32 v65, v4
	v_mov_b32_e32 v66, v4
	v_mov_b32_e32 v67, v4
	v_mov_b32_e32 v68, v4
	v_mov_b32_e32 v69, v4
	v_mov_b32_e32 v70, v4
	v_mov_b32_e32 v71, v4
	v_mov_b32_e32 v72, v4
	v_mov_b32_e32 v73, v4
	v_mov_b32_e32 v74, v4
	v_mov_b32_e32 v75, v4
	v_mov_b32_e32 v84, v4
	v_mov_b32_e32 v85, v4
	v_mov_b32_e32 v86, v4
	v_mov_b32_e32 v87, v4
	v_mov_b32_e32 v88, v4
	v_mov_b32_e32 v89, v4
	v_mov_b32_e32 v90, v4
	v_mov_b32_e32 v91, v4
	v_mov_b32_e32 v100, v4
	v_mov_b32_e32 v101, v4
	v_mov_b32_e32 v102, v4
	v_mov_b32_e32 v103, v4
	v_mov_b32_e32 v104, v4
	v_mov_b32_e32 v105, v4
	v_mov_b32_e32 v106, v4
	v_mov_b32_e32 v107, v4
	v_mov_b32_e32 v116, v4
	v_mov_b32_e32 v117, v4
	v_mov_b32_e32 v118, v4
	v_mov_b32_e32 v119, v4
	v_mov_b32_e32 v120, v4
	v_mov_b32_e32 v121, v4
	v_mov_b32_e32 v122, v4
	v_mov_b32_e32 v123, v4
	v_mov_b32_e32 v76, v4
	v_mov_b32_e32 v77, v4
	v_mov_b32_e32 v78, v4
	v_mov_b32_e32 v79, v4
	v_mov_b32_e32 v80, v4
	v_mov_b32_e32 v81, v4
	v_mov_b32_e32 v82, v4
	v_mov_b32_e32 v83, v4
	v_mov_b32_e32 v92, v4
	v_mov_b32_e32 v93, v4
	v_mov_b32_e32 v94, v4
	v_mov_b32_e32 v95, v4
	v_mov_b32_e32 v96, v4
	v_mov_b32_e32 v97, v4
	v_mov_b32_e32 v98, v4
	v_mov_b32_e32 v99, v4
	v_mov_b32_e32 v108, v4
	v_mov_b32_e32 v109, v4
	v_mov_b32_e32 v110, v4
	v_mov_b32_e32 v111, v4
	v_mov_b32_e32 v112, v4
	v_mov_b32_e32 v113, v4
	v_mov_b32_e32 v114, v4
	v_mov_b32_e32 v115, v4
	v_mov_b32_e32 v124, v4
	v_mov_b32_e32 v125, v4
	v_mov_b32_e32 v126, v4
	v_mov_b32_e32 v127, v4
	v_mov_b32_e32 v128, v4
	v_mov_b32_e32 v129, v4
	v_mov_b32_e32 v130, v4
	v_mov_b32_e32 v131, v4
	v_add_u32_e32 v251, 0x10000, v149
.LBB0_290:
	s_add_u32 s48, s24, 0xfffe0080
	s_addc_u32 s49, s25, -1
	s_add_i32 s84, 0, 0x10000
	s_cmp_eq_u32 s83, 4
	s_cselect_b32 s61, s68, s49
	s_cselect_b32 s60, s69, s48
	s_cselect_b32 s51, s70, s81
	s_cselect_b32 s50, s71, s73
	s_add_i32 s48, 0, 0x14000
	ds_read_b128 v[142:145], v251
	ds_read_b128 v[152:155], v251 offset:1024
	ds_read_b128 v[156:159], v251 offset:2048
	ds_read_b128 v[160:163], v251 offset:3072
	ds_read_b128 v[164:167], v251 offset:16384
	ds_read_b128 v[168:171], v251 offset:17408
	ds_read_b128 v[172:175], v251 offset:18432
	ds_read_b128 v[176:179], v251 offset:19456
	v_lshl_add_u64 v[146:147], s[24:25], 0, v[140:141]
	s_add_i32 m0, s23, 0xc000
	ds_read_b128 v[180:183], v150
	ds_read_b128 v[184:187], v150 offset:1024
	ds_read_b128 v[188:191], v150 offset:2048
	ds_read_b128 v[192:195], v150 offset:3072
	ds_read_b128 v[196:199], v150 offset:4096
	ds_read_b128 v[210:213], v150 offset:5120
	ds_read_b128 v[214:217], v150 offset:6144
	ds_read_b128 v[218:221], v150 offset:7168
	global_load_lds_dwordx4 v[146:147], off
	v_lshl_add_u64 v[146:147], s[24:25], 0, v[138:139]
	s_add_i32 m0, s23, 0xe000
	s_nop 0
	global_load_lds_dwordx4 v[146:147], off
	s_waitcnt vmcnt(8)
	s_waitcnt lgkmcnt(0)
	s_setprio 1
	s_barrier
; #define PG8_STAGE(bufoff, gbase, voff) do { _Pragma("unroll") for (int _i = 0; _i < 2; ++_i) \
;         __builtin_amdgcn_global_load_lds((const unsigned*)((const char*)(gbase) + (voff)[_i]), (PG8_LAS unsigned*)(lds + (bufoff) + ldsw + _i * 8192), 16, 0, 0); } while (0)
; #define PG8_LDA(dst, b, h) do { _Pragma("unroll") for (int m = 0; m < 4; ++m) _Pragma("unroll") for (int k = 0; k < 2; ++k) dst[m][k] = *(const PG8_LAS bf16x8*)(lds + PG8_SA(b, h) + aoff + m * 2048 + k * 1024); } while (0)
; #define PG8_MMA(ai, bj, At, Bt) do { __builtin_amdgcn_s_setprio(1); _Pragma("unroll") for (int m = 0; m < 4; ++m) _Pragma("unroll") for (int n = 0; n < 2; ++n) _Pragma("unroll") for (int k = 0; k < 2; ++k) \
;         acc[ai][bj][m][n] = __builtin_amdgcn_mfma_f32_16x16x32_bf16(Bt[n][k], At[m][k], acc[ai][bj][m][n], 0, 0, 0); __builtin_amdgcn_s_setprio(0); } while (0)
; #define PG8_WAIT_V(n) asm volatile("s_waitcnt vmcnt(" #n ")" ::: "memory")
; #define PG8_WAIT_L(n) asm volatile("s_waitcnt lgkmcnt(" #n ")" ::: "memory")
; #define PG8_BAR __builtin_amdgcn_s_barrier()
; #define PG8_SCHED __builtin_amdgcn_sched_barrier(0)
;     ...
;             PG8_WAIT_V(8); PG8_WAIT_L(0); PG8_BAR; PG8_MMA(0, 0, At, B0); PG8_MMA(0, 1, At, B1); PG8_BAR; PG8_SCHED;
;             PG8_LDA(At, 0, 1); PG8_STAGE(PG8_SB(0, 0), b2, voffB); PG8_STAGE(PG8_SB(0, 1), b2 + hstep, voffB); PG8_STAGE(PG8_SA(0, 0), a2, voffA);
;             PG8_WAIT_V(8); PG8_WAIT_L(0); PG8_BAR; PG8_MMA(1, 0, At, B0); PG8_MMA(1, 1, At, B1); PG8_BAR; PG8_SCHED;
	v_mfma_f32_16x16x32_bf16 v[128:131], v[142:145], v[180:183], v[128:131]
	v_mfma_f32_16x16x32_bf16 v[124:127], v[156:159], v[180:183], v[124:127]
	v_mfma_f32_16x16x32_bf16 v[112:115], v[142:145], v[188:191], v[112:115]
	v_mfma_f32_16x16x32_bf16 v[108:111], v[156:159], v[188:191], v[108:111]
	v_mfma_f32_16x16x32_bf16 v[96:99], v[142:145], v[196:199], v[96:99]
	v_mfma_f32_16x16x32_bf16 v[92:95], v[156:159], v[196:199], v[92:95]
	v_mfma_f32_16x16x32_bf16 v[80:83], v[142:145], v[214:217], v[80:83]
	v_mfma_f32_16x16x32_bf16 v[76:79], v[156:159], v[214:217], v[76:79]
	v_mfma_f32_16x16x32_bf16 v[128:131], v[152:155], v[184:187], v[128:131]
	v_mfma_f32_16x16x32_bf16 v[124:127], v[160:163], v[184:187], v[124:127]
	v_mfma_f32_16x16x32_bf16 v[112:115], v[152:155], v[192:195], v[112:115]
	v_mfma_f32_16x16x32_bf16 v[108:111], v[160:163], v[192:195], v[108:111]
	v_mfma_f32_16x16x32_bf16 v[96:99], v[152:155], v[210:213], v[96:99]
	v_mfma_f32_16x16x32_bf16 v[92:95], v[160:163], v[210:213], v[92:95]
	v_mfma_f32_16x16x32_bf16 v[80:83], v[152:155], v[218:221], v[80:83]
	v_mfma_f32_16x16x32_bf16 v[76:79], v[160:163], v[218:221], v[76:79]
	s_setprio 0
	s_setprio 1
	v_mfma_f32_16x16x32_bf16 v[120:123], v[164:167], v[180:183], v[120:123]
	v_mfma_f32_16x16x32_bf16 v[116:119], v[172:175], v[180:183], v[116:119]
	v_mfma_f32_16x16x32_bf16 v[104:107], v[164:167], v[188:191], v[104:107]
	v_mfma_f32_16x16x32_bf16 v[100:103], v[172:175], v[188:191], v[100:103]
	v_mfma_f32_16x16x32_bf16 v[88:91], v[164:167], v[196:199], v[88:91]
	v_mfma_f32_16x16x32_bf16 v[84:87], v[172:175], v[196:199], v[84:87]
	v_mfma_f32_16x16x32_bf16 v[72:75], v[164:167], v[214:217], v[72:75]
	v_mfma_f32_16x16x32_bf16 v[68:71], v[172:175], v[214:217], v[68:71]
	v_mfma_f32_16x16x32_bf16 v[120:123], v[168:171], v[184:187], v[120:123]
	v_mfma_f32_16x16x32_bf16 v[116:119], v[176:179], v[184:187], v[116:119]
	v_mfma_f32_16x16x32_bf16 v[104:107], v[168:171], v[192:195], v[104:107]
	v_mfma_f32_16x16x32_bf16 v[100:103], v[176:179], v[192:195], v[100:103]
	v_mfma_f32_16x16x32_bf16 v[88:91], v[168:171], v[210:213], v[88:91]
	v_mfma_f32_16x16x32_bf16 v[84:87], v[176:179], v[210:213], v[84:87]
	v_mfma_f32_16x16x32_bf16 v[72:75], v[168:171], v[218:221], v[72:75]
	v_mfma_f32_16x16x32_bf16 v[68:71], v[176:179], v[218:221], v[68:71]
	s_barrier
	s_setprio 0
	s_add_i32 s49, s84, s21
	v_lshl_add_u64 v[146:147], s[50:51], 0, v[200:201]
	s_mov_b32 m0, s49
	ds_read_b128 v[180:183], v150 offset:16384
	ds_read_b128 v[184:187], v150 offset:17408
	ds_read_b128 v[188:191], v150 offset:18432
	ds_read_b128 v[192:195], v150 offset:19456
	ds_read_b128 v[196:199], v150 offset:20480
	ds_read_b128 v[210:213], v150 offset:21504
	ds_read_b128 v[214:217], v150 offset:22528
	ds_read_b128 v[218:221], v150 offset:23552
	global_load_lds_dwordx4 v[146:147], off
	s_add_i32 m0, s49, 0x2000
	s_add_u32 s84, s50, 0x20000
	v_lshl_add_u64 v[206:207], s[50:51], 0, v[132:133]
	s_addc_u32 s85, s51, 0
	s_add_i32 s48, s48, s21
	global_load_lds_dwordx4 v[206:207], off
	v_lshl_add_u64 v[208:209], s[84:85], 0, v[200:201]
	s_mov_b32 m0, s48
	v_lshl_add_u64 v[222:223], s[60:61], 0, v[134:135]
	global_load_lds_dwordx4 v[208:209], off
	v_lshl_add_u64 v[208:209], s[84:85], 0, v[132:133]
	s_add_i32 m0, s48, 0x2000
	s_nop 0
	global_load_lds_dwordx4 v[208:209], off
	v_lshl_add_u64 v[208:209], s[60:61], 0, v[136:137]
	s_mov_b32 m0, s23
	s_nop 0
	global_load_lds_dwordx4 v[208:209], off
	s_mov_b32 m0, s42
	s_nop 0
	global_load_lds_dwordx4 v[222:223], off
	s_waitcnt vmcnt(8)
	s_waitcnt lgkmcnt(0)
	s_setprio 1
	s_barrier
	v_mfma_f32_16x16x32_bf16 v[64:67], v[142:145], v[180:183], v[64:67]
	v_mfma_f32_16x16x32_bf16 v[60:63], v[156:159], v[180:183], v[60:63]
	v_mfma_f32_16x16x32_bf16 v[48:51], v[142:145], v[188:191], v[48:51]
	v_mfma_f32_16x16x32_bf16 v[44:47], v[156:159], v[188:191], v[44:47]
	v_mfma_f32_16x16x32_bf16 v[32:35], v[142:145], v[196:199], v[32:35]
	v_mfma_f32_16x16x32_bf16 v[28:31], v[156:159], v[196:199], v[28:31]
	v_mfma_f32_16x16x32_bf16 v[16:19], v[142:145], v[214:217], v[16:19]
	v_mfma_f32_16x16x32_bf16 v[12:15], v[156:159], v[214:217], v[12:15]
	v_mfma_f32_16x16x32_bf16 v[64:67], v[152:155], v[184:187], v[64:67]
	v_mfma_f32_16x16x32_bf16 v[60:63], v[160:163], v[184:187], v[60:63]
	v_mfma_f32_16x16x32_bf16 v[48:51], v[152:155], v[192:195], v[48:51]
	v_mfma_f32_16x16x32_bf16 v[44:47], v[160:163], v[192:195], v[44:47]
	v_mfma_f32_16x16x32_bf16 v[32:35], v[152:155], v[210:213], v[32:35]
	v_mfma_f32_16x16x32_bf16 v[28:31], v[160:163], v[210:213], v[28:31]
	v_mfma_f32_16x16x32_bf16 v[16:19], v[152:155], v[218:221], v[16:19]
	v_mfma_f32_16x16x32_bf16 v[12:15], v[160:163], v[218:221], v[12:15]
	s_setprio 0
	s_setprio 1
	v_mfma_f32_16x16x32_bf16 v[56:59], v[164:167], v[180:183], v[56:59]
	v_mfma_f32_16x16x32_bf16 v[52:55], v[172:175], v[180:183], v[52:55]
	v_mfma_f32_16x16x32_bf16 v[40:43], v[164:167], v[188:191], v[40:43]
	v_mfma_f32_16x16x32_bf16 v[36:39], v[172:175], v[188:191], v[36:39]
	v_mfma_f32_16x16x32_bf16 v[24:27], v[164:167], v[196:199], v[24:27]
	v_mfma_f32_16x16x32_bf16 v[20:23], v[172:175], v[196:199], v[20:23]
	v_mfma_f32_16x16x32_bf16 v[8:11], v[164:167], v[214:217], v[8:11]
	v_mfma_f32_16x16x32_bf16 v[4:7], v[172:175], v[214:217], v[4:7]
	v_mfma_f32_16x16x32_bf16 v[56:59], v[168:171], v[184:187], v[56:59]
	v_mfma_f32_16x16x32_bf16 v[52:55], v[176:179], v[184:187], v[52:55]
	v_mfma_f32_16x16x32_bf16 v[40:43], v[168:171], v[192:195], v[40:43]
	v_mfma_f32_16x16x32_bf16 v[36:39], v[176:179], v[192:195], v[36:39]
	v_mfma_f32_16x16x32_bf16 v[24:27], v[168:171], v[210:213], v[24:27]
	v_mfma_f32_16x16x32_bf16 v[20:23], v[176:179], v[210:213], v[20:23]
	v_mfma_f32_16x16x32_bf16 v[8:11], v[168:171], v[218:221], v[8:11]
	v_mfma_f32_16x16x32_bf16 v[4:7], v[176:179], v[218:221], v[4:7]
	s_barrier
; #define PG8_STAGE(bufoff, gbase, voff) do { _Pragma("unroll") for (int _i = 0; _i < 2; ++_i) \
;         __builtin_amdgcn_global_load_lds((const unsigned*)((const char*)(gbase) + (voff)[_i]), (PG8_LAS unsigned*)(lds + (bufoff) + ldsw + _i * 8192), 16, 0, 0); } while (0)
; #define PG8_LDA(dst, b, h) do { _Pragma("unroll") for (int m = 0; m < 4; ++m) _Pragma("unroll") for (int k = 0; k < 2; ++k) dst[m][k] = *(const PG8_LAS bf16x8*)(lds + PG8_SA(b, h) + aoff + m * 2048 + k * 1024); } while (0)
; #define PG8_LDB(dst, b, h) do { _Pragma("unroll") for (int n = 0; n < 2; ++n) _Pragma("unroll") for (int k = 0; k < 2; ++k) dst[n][k] = *(const PG8_LAS bf16x8*)(lds + PG8_SB(b, h) + boff + n * 2048 + k * 1024); } while (0)
; #define PG8_MMA(ai, bj, At, Bt) do { __builtin_amdgcn_s_setprio(1); _Pragma("unroll") for (int m = 0; m < 4; ++m) _Pragma("unroll") for (int n = 0; n < 2; ++n) _Pragma("unroll") for (int k = 0; k < 2; ++k) \
;         acc[ai][bj][m][n] = __builtin_amdgcn_mfma_f32_16x16x32_bf16(Bt[n][k], At[m][k], acc[ai][bj][m][n], 0, 0, 0); __builtin_amdgcn_s_setprio(0); } while (0)
; #define PG8_WAIT_V(n) asm volatile("s_waitcnt vmcnt(" #n ")" ::: "memory")
; #define PG8_WAIT_L(n) asm volatile("s_waitcnt lgkmcnt(" #n ")" ::: "memory")
; #define PG8_BAR __builtin_amdgcn_s_barrier()
; #define PG8_SCHED __builtin_amdgcn_sched_barrier(0)
;     ...
;             PG8_LDB(B0, 1, 0); PG8_LDB(B1, 1, 1); PG8_SCHED; PG8_LDA(At, 1, 0); PG8_STAGE(PG8_SA(0, 1), a2 + hstep, voffA);
;             PG8_WAIT_V(8); PG8_WAIT_L(0); PG8_BAR; PG8_MMA(0, 0, At, B0); PG8_MMA(0, 1, At, B1); PG8_BAR; PG8_SCHED;
;             PG8_LDA(At, 1, 1); PG8_STAGE(PG8_SB(1, 0), b3, voffB); PG8_STAGE(PG8_SB(1, 1), b3 + hstep, voffB); PG8_STAGE(PG8_SA(1, 0), a3, voffA);
	s_setprio 0
	s_add_i32 s48, 0, 0x18000
	s_add_i32 s49, 0, 0x1c000
	ds_read_b128 v[142:145], v251 offset:32768
	ds_read_b128 v[152:155], v251 offset:33792
	ds_read_b128 v[156:159], v251 offset:34816
	ds_read_b128 v[160:163], v251 offset:35840
	ds_read_b128 v[164:167], v251 offset:49152
	ds_read_b128 v[168:171], v251 offset:50176
	ds_read_b128 v[172:175], v251 offset:51200
	ds_read_b128 v[176:179], v251 offset:52224
	s_add_u32 s60, s60, 0x20000
	s_addc_u32 s61, s61, 0
	s_mov_b32 m0, s44
	v_lshl_add_u64 v[224:225], s[60:61], 0, v[136:137]
	ds_read_b128 v[180:183], v150 offset:32768
	ds_read_b128 v[184:187], v150 offset:33792
	ds_read_b128 v[188:191], v150 offset:34816
	ds_read_b128 v[192:195], v150 offset:35840
	ds_read_b128 v[196:199], v150 offset:36864
	ds_read_b128 v[210:213], v150 offset:37888
	ds_read_b128 v[214:217], v150 offset:38912
	ds_read_b128 v[218:221], v150 offset:39936
	global_load_lds_dwordx4 v[224:225], off
	v_lshl_add_u64 v[224:225], s[60:61], 0, v[134:135]
	s_mov_b32 m0, s52
	s_nop 0
	global_load_lds_dwordx4 v[224:225], off
	s_waitcnt vmcnt(8)
	s_waitcnt lgkmcnt(0)
	s_setprio 1
	s_barrier
	v_mfma_f32_16x16x32_bf16 v[128:131], v[142:145], v[180:183], v[128:131]
	v_mfma_f32_16x16x32_bf16 v[124:127], v[156:159], v[180:183], v[124:127]
	v_mfma_f32_16x16x32_bf16 v[112:115], v[142:145], v[188:191], v[112:115]
	v_mfma_f32_16x16x32_bf16 v[108:111], v[156:159], v[188:191], v[108:111]
	v_mfma_f32_16x16x32_bf16 v[96:99], v[142:145], v[196:199], v[96:99]
	v_mfma_f32_16x16x32_bf16 v[92:95], v[156:159], v[196:199], v[92:95]
	v_mfma_f32_16x16x32_bf16 v[80:83], v[142:145], v[214:217], v[80:83]
	v_mfma_f32_16x16x32_bf16 v[76:79], v[156:159], v[214:217], v[76:79]
	v_mfma_f32_16x16x32_bf16 v[128:131], v[152:155], v[184:187], v[128:131]
	v_mfma_f32_16x16x32_bf16 v[124:127], v[160:163], v[184:187], v[124:127]
	v_mfma_f32_16x16x32_bf16 v[112:115], v[152:155], v[192:195], v[112:115]
	v_mfma_f32_16x16x32_bf16 v[108:111], v[160:163], v[192:195], v[108:111]
	v_mfma_f32_16x16x32_bf16 v[96:99], v[152:155], v[210:213], v[96:99]
	v_mfma_f32_16x16x32_bf16 v[92:95], v[160:163], v[210:213], v[92:95]
	v_mfma_f32_16x16x32_bf16 v[80:83], v[152:155], v[218:221], v[80:83]
	v_mfma_f32_16x16x32_bf16 v[76:79], v[160:163], v[218:221], v[76:79]
	s_setprio 0
	s_setprio 1
	v_mfma_f32_16x16x32_bf16 v[120:123], v[164:167], v[180:183], v[120:123]
	v_mfma_f32_16x16x32_bf16 v[116:119], v[172:175], v[180:183], v[116:119]
	v_mfma_f32_16x16x32_bf16 v[104:107], v[164:167], v[188:191], v[104:107]
	v_mfma_f32_16x16x32_bf16 v[100:103], v[172:175], v[188:191], v[100:103]
	v_mfma_f32_16x16x32_bf16 v[88:91], v[164:167], v[196:199], v[88:91]
	v_mfma_f32_16x16x32_bf16 v[84:87], v[172:175], v[196:199], v[84:87]
	v_mfma_f32_16x16x32_bf16 v[72:75], v[164:167], v[214:217], v[72:75]
	v_mfma_f32_16x16x32_bf16 v[68:71], v[172:175], v[214:217], v[68:71]
	v_mfma_f32_16x16x32_bf16 v[120:123], v[168:171], v[184:187], v[120:123]
	v_mfma_f32_16x16x32_bf16 v[116:119], v[176:179], v[184:187], v[116:119]
	v_mfma_f32_16x16x32_bf16 v[104:107], v[168:171], v[192:195], v[104:107]
	v_mfma_f32_16x16x32_bf16 v[100:103], v[176:179], v[192:195], v[100:103]
	v_mfma_f32_16x16x32_bf16 v[88:91], v[168:171], v[210:213], v[88:91]
	v_mfma_f32_16x16x32_bf16 v[84:87], v[176:179], v[210:213], v[84:87]
	v_mfma_f32_16x16x32_bf16 v[72:75], v[168:171], v[218:221], v[72:75]
	v_mfma_f32_16x16x32_bf16 v[68:71], v[176:179], v[218:221], v[68:71]
	s_barrier
	s_setprio 0
	s_add_i32 s48, s48, s21
	v_lshl_add_u64 v[146:147], v[146:147], 0, s[66:67]
	s_mov_b32 m0, s48
	ds_read_b128 v[180:183], v150 offset:49152
	ds_read_b128 v[184:187], v150 offset:50176
	ds_read_b128 v[188:191], v150 offset:51200
	ds_read_b128 v[192:195], v150 offset:52224
	ds_read_b128 v[196:199], v150 offset:53248
	ds_read_b128 v[210:213], v150 offset:54272
	ds_read_b128 v[214:217], v150 offset:55296
	ds_read_b128 v[218:221], v150 offset:56320
	global_load_lds_dwordx4 v[146:147], off
	s_add_i32 m0, s48, 0x2000
	s_add_u32 s50, s50, 0x20080
	v_lshl_add_u64 v[146:147], v[206:207], 0, s[66:67]
	s_addc_u32 s51, s51, 0
	s_add_i32 s48, s49, s21
	global_load_lds_dwordx4 v[146:147], off
	v_lshl_add_u64 v[146:147], s[50:51], 0, v[200:201]
	s_mov_b32 m0, s48
	s_nop 0
	global_load_lds_dwordx4 v[146:147], off
	v_lshl_add_u64 v[146:147], s[50:51], 0, v[132:133]
	s_add_i32 m0, s48, 0x2000
	s_nop 0
	global_load_lds_dwordx4 v[146:147], off
	v_lshl_add_u64 v[146:147], v[208:209], 0, s[66:67]
	s_mov_b32 m0, s54
	s_nop 0
	global_load_lds_dwordx4 v[146:147], off
	v_lshl_add_u64 v[146:147], v[222:223], 0, s[66:67]
	s_mov_b32 m0, s55
	s_nop 0
	global_load_lds_dwordx4 v[146:147], off
	s_waitcnt vmcnt(8)
	s_waitcnt lgkmcnt(0)
	s_setprio 1
	s_barrier
; #define PG8_G __attribute__((address_space(1)))
; __device__ __forceinline__ u32x4 pack8bf(const f32x4 a, const f32x4 b) { u32x4 w; w.x = cvt_pk_bf16(a[0], a[1]); w.y = cvt_pk_bf16(a[2], a[3]); w.z = cvt_pk_bf16(b[0], b[1]); w.w = cvt_pk_bf16(b[2], b[3]); return w; }
; #define PG8_STAGE(bufoff, gbase, voff) do { _Pragma("unroll") for (int _i = 0; _i < 2; ++_i) \
;         __builtin_amdgcn_global_load_lds((const unsigned*)((const char*)(gbase) + (voff)[_i]), (PG8_LAS unsigned*)(lds + (bufoff) + ldsw + _i * 8192), 16, 0, 0); } while (0)
; #define PG8_LDA(dst, b, h) do { _Pragma("unroll") for (int m = 0; m < 4; ++m) _Pragma("unroll") for (int k = 0; k < 2; ++k) dst[m][k] = *(const PG8_LAS bf16x8*)(lds + PG8_SA(b, h) + aoff + m * 2048 + k * 1024); } while (0)
; #define PG8_MMA(ai, bj, At, Bt) do { __builtin_amdgcn_s_setprio(1); _Pragma("unroll") for (int m = 0; m < 4; ++m) _Pragma("unroll") for (int n = 0; n < 2; ++n) _Pragma("unroll") for (int k = 0; k < 2; ++k) \
;         acc[ai][bj][m][n] = __builtin_amdgcn_mfma_f32_16x16x32_bf16(Bt[n][k], At[m][k], acc[ai][bj][m][n], 0, 0, 0); __builtin_amdgcn_s_setprio(0); } while (0)
;     __device__ __forceinline__ void operator()(const f32x4 (&acc)[2][2][4][2], const Unit& u, int wr, int wc, int fr_, int fq_, int ui) const {
;         int fr = fr_, fq = fq_; asm volatile("" : "+v"(fr), "+v"(fq));
;         const int row0 = u.pm * BM + wr * 64 + fr, dim0 = wc * 32 + 8 * fq;
;         float r[2][4]; load_rs(r, rsl, wr, fr);
; #pragma unroll
;         for (int ai = 0; ai < 2; ++ai)
; #pragma unroll
;             for (int m = 0; m < 4; ++m) { const int row = row0 + ai * HALF + m * 16, b = row >> 12, s = row & 4095;
;                 const size_t o = (((size_t)b * 16 + u.pn) * 4096 + s) * 128 + dim0;
;                 *(PG8_G u32x4*)(KH + o) = pack8bf(acc[ai][0][m][0] * r[ai][m], acc[ai][0][m][1] * r[ai][m]); *(PG8_G u32x4*)(VH + o) = pack8bf(acc[ai][1][m][0] * r[ai][m], acc[ai][1][m][1] * r[ai][m]); }
;     ...
;             PG8_WAIT_V(8); PG8_WAIT_L(0); PG8_BAR; PG8_MMA(0, 0, At, B0); PG8_MMA(0, 1, At, B1); PG8_BAR; PG8_SCHED;
;             PG8_LDA(At, 1, 1); PG8_STAGE(PG8_SB(1, 0), b3, voffB); PG8_STAGE(PG8_SB(1, 1), b3 + hstep, voffB); PG8_STAGE(PG8_SA(1, 0), a3, voffA);
;             PG8_WAIT_V(8); PG8_WAIT_L(0); PG8_BAR; PG8_MMA(1, 0, At, B0); PG8_MMA(1, 1, At, B1); PG8_BAR; PG8_SCHED;
	v_mfma_f32_16x16x32_bf16 v[64:67], v[142:145], v[180:183], v[64:67]
	v_mfma_f32_16x16x32_bf16 v[60:63], v[156:159], v[180:183], v[60:63]
	v_mfma_f32_16x16x32_bf16 v[48:51], v[142:145], v[188:191], v[48:51]
	v_mfma_f32_16x16x32_bf16 v[44:47], v[156:159], v[188:191], v[44:47]
	v_mfma_f32_16x16x32_bf16 v[32:35], v[142:145], v[196:199], v[32:35]
	v_mfma_f32_16x16x32_bf16 v[28:31], v[156:159], v[196:199], v[28:31]
	v_mfma_f32_16x16x32_bf16 v[16:19], v[142:145], v[214:217], v[16:19]
	v_mfma_f32_16x16x32_bf16 v[12:15], v[156:159], v[214:217], v[12:15]
	v_mfma_f32_16x16x32_bf16 v[64:67], v[152:155], v[184:187], v[64:67]
	v_mfma_f32_16x16x32_bf16 v[60:63], v[160:163], v[184:187], v[60:63]
	v_mfma_f32_16x16x32_bf16 v[48:51], v[152:155], v[192:195], v[48:51]
	v_mfma_f32_16x16x32_bf16 v[44:47], v[160:163], v[192:195], v[44:47]
	v_mfma_f32_16x16x32_bf16 v[32:35], v[152:155], v[210:213], v[32:35]
	v_mfma_f32_16x16x32_bf16 v[28:31], v[160:163], v[210:213], v[28:31]
	v_mfma_f32_16x16x32_bf16 v[16:19], v[152:155], v[218:221], v[16:19]
	v_mfma_f32_16x16x32_bf16 v[12:15], v[160:163], v[218:221], v[12:15]
	s_setprio 0
	s_setprio 1
	v_mfma_f32_16x16x32_bf16 v[56:59], v[164:167], v[180:183], v[56:59]
	v_mfma_f32_16x16x32_bf16 v[52:55], v[172:175], v[180:183], v[52:55]
	v_mfma_f32_16x16x32_bf16 v[40:43], v[164:167], v[188:191], v[40:43]
	v_mfma_f32_16x16x32_bf16 v[36:39], v[172:175], v[188:191], v[36:39]
	v_mfma_f32_16x16x32_bf16 v[24:27], v[164:167], v[196:199], v[24:27]
	v_mfma_f32_16x16x32_bf16 v[20:23], v[172:175], v[196:199], v[20:23]
	v_mfma_f32_16x16x32_bf16 v[8:11], v[164:167], v[214:217], v[8:11]
	v_mfma_f32_16x16x32_bf16 v[4:7], v[172:175], v[214:217], v[4:7]
	v_mfma_f32_16x16x32_bf16 v[56:59], v[168:171], v[184:187], v[56:59]
	v_mfma_f32_16x16x32_bf16 v[52:55], v[176:179], v[184:187], v[52:55]
	v_mfma_f32_16x16x32_bf16 v[40:43], v[168:171], v[192:195], v[40:43]
	v_mfma_f32_16x16x32_bf16 v[36:39], v[176:179], v[192:195], v[36:39]
	v_mfma_f32_16x16x32_bf16 v[24:27], v[168:171], v[210:213], v[24:27]
	v_mfma_f32_16x16x32_bf16 v[20:23], v[176:179], v[210:213], v[20:23]
	v_mfma_f32_16x16x32_bf16 v[8:11], v[168:171], v[218:221], v[8:11]
	v_mfma_f32_16x16x32_bf16 v[4:7], v[176:179], v[218:221], v[4:7]
	s_barrier
	s_setprio 0
	s_add_i32 s83, s83, 2
	s_add_u32 s73, s73, 0x100
	s_addc_u32 s81, s81, 0
	s_add_u32 s24, s24, 0x100
	s_addc_u32 s25, s25, 0
	s_cmp_gt_u32 s83, 5
	s_cbranch_scc0 .LBB0_290
	v_mov_b32_e32 v142, v148
	v_mov_b32_e32 v143, v3
	v_readlane_b32 s84, v255, 29
	s_add_i32 s24, s63, s84
	v_add_u32_e32 v151, s56, v143
	v_ashrrev_i32_e32 v156, 12, v151
	s_ashr_i32 s25, s24, 31
	v_ashrrev_i32_e32 v157, 31, v156
	s_lshl_b64 s[24:25], s[24:25], 12
	v_lshlrev_b64 v[156:157], 16, v[156:157]
	v_lshl_add_u32 v143, v143, 2, s58
	v_lshl_add_u64 v[156:157], v[156:157], 0, s[24:25]
	v_lshl_add_u32 v142, v142, 3, s53
	ds_read2_b32 v[152:153], v143 offset1:16
	ds_read2_b32 v[154:155], v143 offset0:32 offset1:48
	ds_read2_b32 v[146:147], v143 offset0:128 offset1:144
	ds_read2_b32 v[144:145], v143 offset0:160 offset1:176
	v_and_or_b32 v156, v151, s17, v156
	v_ashrrev_i32_e32 v143, 31, v142
	v_lshlrev_b64 v[156:157], 7, v[156:157]
	v_lshl_add_u64 v[156:157], v[156:157], 0, v[142:143]
	s_waitcnt lgkmcnt(0)
	v_pk_mul_f32 v[128:129], v[128:129], v[152:153] op_sel_hi:[1,0]
	v_pk_mul_f32 v[130:131], v[130:131], v[152:153] op_sel_hi:[1,0]
	v_pk_mul_f32 v[158:159], v[126:127], v[152:153] op_sel_hi:[1,0]
	v_pk_mul_f32 v[126:127], v[124:125], v[152:153] op_sel_hi:[1,0]
	v_cvt_pk_bf16_f32 v124, v128, v129
	v_lshlrev_b64 v[128:129], 1, v[156:157]
	v_cvt_pk_bf16_f32 v125, v130, v131
	v_lshl_add_u64 v[130:131], s[12:13], 0, v[128:129]
	v_cvt_pk_bf16_f32 v126, v126, v127
	v_cvt_pk_bf16_f32 v127, v158, v159
	global_store_dwordx4 v[130:131], v[124:127], off
	v_pk_mul_f32 v[120:121], v[120:121], v[152:153] op_sel_hi:[1,0]
	v_pk_mul_f32 v[122:123], v[122:123], v[152:153] op_sel_hi:[1,0]
	v_pk_mul_f32 v[124:125], v[118:119], v[152:153] op_sel_hi:[1,0]
	v_pk_mul_f32 v[118:119], v[116:117], v[152:153] op_sel_hi:[1,0]
	v_cvt_pk_bf16_f32 v116, v120, v121
	v_cvt_pk_bf16_f32 v117, v122, v123
	v_lshl_add_u64 v[120:121], s[14:15], 0, v[128:129]
	v_cvt_pk_bf16_f32 v118, v118, v119
	v_cvt_pk_bf16_f32 v119, v124, v125
	global_store_dwordx4 v[120:121], v[116:119], off
	v_pk_mul_f32 v[96:97], v[96:97], v[154:155] op_sel_hi:[1,0]
	v_pk_mul_f32 v[98:99], v[98:99], v[154:155] op_sel_hi:[1,0]
	v_add_u32_e32 v118, 16, v151
	v_ashrrev_i32_e32 v116, 12, v118
	v_ashrrev_i32_e32 v117, 31, v116
	v_lshlrev_b64 v[116:117], 16, v[116:117]
	v_lshl_add_u64 v[116:117], v[116:117], 0, s[24:25]
	v_and_or_b32 v116, v118, s17, v116
	v_lshlrev_b64 v[116:117], 7, v[116:117]
	v_mov_b32_e32 v118, v153
	v_lshl_add_u64 v[116:117], v[116:117], 0, v[142:143]
	v_pk_mul_f32 v[112:113], v[112:113], v[118:119] op_sel_hi:[1,0]
	v_pk_mul_f32 v[114:115], v[114:115], v[118:119] op_sel_hi:[1,0]
	v_pk_mul_f32 v[120:121], v[110:111], v[118:119] op_sel_hi:[1,0]
	v_pk_mul_f32 v[110:111], v[108:109], v[118:119] op_sel_hi:[1,0]
	v_cvt_pk_bf16_f32 v108, v112, v113
	v_lshlrev_b64 v[112:113], 1, v[116:117]
	v_cvt_pk_bf16_f32 v109, v114, v115
	v_lshl_add_u64 v[114:115], s[12:13], 0, v[112:113]
	v_cvt_pk_bf16_f32 v110, v110, v111
	v_cvt_pk_bf16_f32 v111, v120, v121
	global_store_dwordx4 v[114:115], v[108:111], off
	v_pk_mul_f32 v[104:105], v[104:105], v[118:119] op_sel_hi:[1,0]
	v_pk_mul_f32 v[106:107], v[106:107], v[118:119] op_sel_hi:[1,0]
	v_pk_mul_f32 v[108:109], v[102:103], v[118:119] op_sel_hi:[1,0]
	v_pk_mul_f32 v[102:103], v[100:101], v[118:119] op_sel_hi:[1,0]
	v_cvt_pk_bf16_f32 v100, v104, v105
	v_cvt_pk_bf16_f32 v101, v106, v107
; #define PG8_G __attribute__((address_space(1)))
; __device__ __forceinline__ u32x4 pack8bf(const f32x4 a, const f32x4 b) { u32x4 w; w.x = cvt_pk_bf16(a[0], a[1]); w.y = cvt_pk_bf16(a[2], a[3]); w.z = cvt_pk_bf16(b[0], b[1]); w.w = cvt_pk_bf16(b[2], b[3]); return w; }
;     __device__ __forceinline__ void operator()(const f32x4 (&acc)[2][2][4][2], const Unit& u, int wr, int wc, int fr_, int fq_, int ui) const {
;     ...
; #pragma unroll
;         for (int ai = 0; ai < 2; ++ai)
; #pragma unroll
;             for (int m = 0; m < 4; ++m) { const int row = row0 + ai * HALF + m * 16, b = row >> 12, s = row & 4095;
;                 const size_t o = (((size_t)b * 16 + u.pn) * 4096 + s) * 128 + dim0;
;                 *(PG8_G u32x4*)(KH + o) = pack8bf(acc[ai][0][m][0] * r[ai][m], acc[ai][0][m][1] * r[ai][m]); *(PG8_G u32x4*)(VH + o) = pack8bf(acc[ai][1][m][0] * r[ai][m], acc[ai][1][m][1] * r[ai][m]); }
	v_lshl_add_u64 v[104:105], s[14:15], 0, v[112:113]
	v_cvt_pk_bf16_f32 v102, v102, v103
	v_cvt_pk_bf16_f32 v103, v108, v109
	global_store_dwordx4 v[104:105], v[100:103], off
	v_pk_mul_f32 v[88:89], v[88:89], v[154:155] op_sel_hi:[1,0]
	v_pk_mul_f32 v[90:91], v[90:91], v[154:155] op_sel_hi:[1,0]
	v_add_u32_e32 v102, 32, v151
	v_ashrrev_i32_e32 v100, 12, v102
	v_ashrrev_i32_e32 v101, 31, v100
	v_lshlrev_b64 v[100:101], 16, v[100:101]
	v_lshl_add_u64 v[100:101], v[100:101], 0, s[24:25]
	v_and_or_b32 v100, v102, s17, v100
	v_lshlrev_b64 v[100:101], 7, v[100:101]
	v_lshl_add_u64 v[100:101], v[100:101], 0, v[142:143]
	v_pk_mul_f32 v[102:103], v[94:95], v[154:155] op_sel_hi:[1,0]
	v_pk_mul_f32 v[94:95], v[92:93], v[154:155] op_sel_hi:[1,0]
	v_cvt_pk_bf16_f32 v92, v96, v97
	v_lshlrev_b64 v[96:97], 1, v[100:101]
	v_cvt_pk_bf16_f32 v93, v98, v99
	v_lshl_add_u64 v[98:99], s[12:13], 0, v[96:97]
	v_cvt_pk_bf16_f32 v94, v94, v95
	v_cvt_pk_bf16_f32 v95, v102, v103
	global_store_dwordx4 v[98:99], v[92:95], off
	v_pk_mul_f32 v[64:65], v[64:65], v[146:147] op_sel_hi:[1,0]
	v_pk_mul_f32 v[66:67], v[66:67], v[146:147] op_sel_hi:[1,0]
	v_pk_mul_f32 v[92:93], v[86:87], v[154:155] op_sel_hi:[1,0]
	v_pk_mul_f32 v[86:87], v[84:85], v[154:155] op_sel_hi:[1,0]
	v_cvt_pk_bf16_f32 v84, v88, v89
	v_cvt_pk_bf16_f32 v85, v90, v91
	v_lshl_add_u64 v[88:89], s[14:15], 0, v[96:97]
	v_cvt_pk_bf16_f32 v86, v86, v87
	v_cvt_pk_bf16_f32 v87, v92, v93
	global_store_dwordx4 v[88:89], v[84:87], off
	v_pk_mul_f32 v[56:57], v[56:57], v[146:147] op_sel_hi:[1,0]
	v_pk_mul_f32 v[58:59], v[58:59], v[146:147] op_sel_hi:[1,0]
	v_add_u32_e32 v86, 48, v151
	v_ashrrev_i32_e32 v84, 12, v86
	v_ashrrev_i32_e32 v85, 31, v84
	v_lshlrev_b64 v[84:85], 16, v[84:85]
	v_lshl_add_u64 v[84:85], v[84:85], 0, s[24:25]
	v_and_or_b32 v84, v86, s17, v84
	v_lshlrev_b64 v[84:85], 7, v[84:85]
	v_mov_b32_e32 v86, v155
	v_lshl_add_u64 v[84:85], v[84:85], 0, v[142:143]
	v_pk_mul_f32 v[80:81], v[80:81], v[86:87] op_sel_hi:[1,0]
	v_pk_mul_f32 v[82:83], v[82:83], v[86:87] op_sel_hi:[1,0]
	v_pk_mul_f32 v[88:89], v[78:79], v[86:87] op_sel_hi:[1,0]
	v_pk_mul_f32 v[78:79], v[76:77], v[86:87] op_sel_hi:[1,0]
	v_cvt_pk_bf16_f32 v76, v80, v81
	v_lshlrev_b64 v[80:81], 1, v[84:85]
	v_cvt_pk_bf16_f32 v77, v82, v83
	v_lshl_add_u64 v[82:83], s[12:13], 0, v[80:81]
	v_cvt_pk_bf16_f32 v78, v78, v79
	v_cvt_pk_bf16_f32 v79, v88, v89
	global_store_dwordx4 v[82:83], v[76:79], off
	v_pk_mul_f32 v[72:73], v[72:73], v[86:87] op_sel_hi:[1,0]
	v_pk_mul_f32 v[74:75], v[74:75], v[86:87] op_sel_hi:[1,0]
	v_pk_mul_f32 v[76:77], v[70:71], v[86:87] op_sel_hi:[1,0]
	v_pk_mul_f32 v[70:71], v[68:69], v[86:87] op_sel_hi:[1,0]
	v_cvt_pk_bf16_f32 v68, v72, v73
	v_cvt_pk_bf16_f32 v69, v74, v75
	v_lshl_add_u64 v[72:73], s[14:15], 0, v[80:81]
	v_cvt_pk_bf16_f32 v70, v70, v71
	v_cvt_pk_bf16_f32 v71, v76, v77
	global_store_dwordx4 v[72:73], v[68:71], off
	v_pk_mul_f32 v[32:33], v[32:33], v[144:145] op_sel_hi:[1,0]
	v_pk_mul_f32 v[34:35], v[34:35], v[144:145] op_sel_hi:[1,0]
	v_add_u32_e32 v70, 0x80, v151
	v_ashrrev_i32_e32 v68, 12, v70
	v_ashrrev_i32_e32 v69, 31, v68
	v_lshlrev_b64 v[68:69], 16, v[68:69]
	v_lshl_add_u64 v[68:69], v[68:69], 0, s[24:25]
	v_and_or_b32 v68, v70, s17, v68
	v_lshlrev_b64 v[68:69], 7, v[68:69]
	v_lshl_add_u64 v[68:69], v[68:69], 0, v[142:143]
	v_pk_mul_f32 v[70:71], v[62:63], v[146:147] op_sel_hi:[1,0]
	v_pk_mul_f32 v[62:63], v[60:61], v[146:147] op_sel_hi:[1,0]
	v_cvt_pk_bf16_f32 v60, v64, v65
	v_lshlrev_b64 v[64:65], 1, v[68:69]
	v_cvt_pk_bf16_f32 v61, v66, v67
	v_lshl_add_u64 v[66:67], s[12:13], 0, v[64:65]
	v_cvt_pk_bf16_f32 v62, v62, v63
	v_cvt_pk_bf16_f32 v63, v70, v71
	global_store_dwordx4 v[66:67], v[60:63], off
	v_pk_mul_f32 v[24:25], v[24:25], v[144:145] op_sel_hi:[1,0]
	v_pk_mul_f32 v[26:27], v[26:27], v[144:145] op_sel_hi:[1,0]
	v_pk_mul_f32 v[60:61], v[54:55], v[146:147] op_sel_hi:[1,0]
	v_pk_mul_f32 v[54:55], v[52:53], v[146:147] op_sel_hi:[1,0]
	v_cvt_pk_bf16_f32 v52, v56, v57
; #define PG8_G __attribute__((address_space(1)))
; __device__ __forceinline__ u32x4 pack8bf(const f32x4 a, const f32x4 b) { u32x4 w; w.x = cvt_pk_bf16(a[0], a[1]); w.y = cvt_pk_bf16(a[2], a[3]); w.z = cvt_pk_bf16(b[0], b[1]); w.w = cvt_pk_bf16(b[2], b[3]); return w; }
; #define PG8_WAIT_V(n) asm volatile("s_waitcnt vmcnt(" #n ")" ::: "memory")
; #define PG8_BAR __builtin_amdgcn_s_barrier()
;     __device__ __forceinline__ void operator()(const f32x4 (&acc)[2][2][4][2], const Unit& u, int wr, int wc, int fr_, int fq_, int ui) const {
;     ...
; #pragma unroll
;         for (int ai = 0; ai < 2; ++ai)
; #pragma unroll
;             for (int m = 0; m < 4; ++m) { const int row = row0 + ai * HALF + m * 16, b = row >> 12, s = row & 4095;
;                 const size_t o = (((size_t)b * 16 + u.pn) * 4096 + s) * 128 + dim0;
;                 *(PG8_G u32x4*)(KH + o) = pack8bf(acc[ai][0][m][0] * r[ai][m], acc[ai][0][m][1] * r[ai][m]); *(PG8_G u32x4*)(VH + o) = pack8bf(acc[ai][1][m][0] * r[ai][m], acc[ai][1][m][1] * r[ai][m]); }
;     }
;     ...
;     PG8_WAIT_V(0);
;     if constexpr (!ALIGN_EPI) { if (wr == 0) PG8_BAR; }
	v_cvt_pk_bf16_f32 v53, v58, v59
	v_lshl_add_u64 v[56:57], s[14:15], 0, v[64:65]
	v_cvt_pk_bf16_f32 v54, v54, v55
	v_cvt_pk_bf16_f32 v55, v60, v61
	global_store_dwordx4 v[56:57], v[52:55], off
	s_cmp_eq_u32 s62, 8
	s_mov_b32 s63, s62
	v_add_u32_e32 v54, 0x90, v151
	v_ashrrev_i32_e32 v52, 12, v54
	v_ashrrev_i32_e32 v53, 31, v52
	v_lshlrev_b64 v[52:53], 16, v[52:53]
	v_lshl_add_u64 v[52:53], v[52:53], 0, s[24:25]
	v_and_or_b32 v52, v54, s17, v52
	v_lshlrev_b64 v[52:53], 7, v[52:53]
	v_mov_b32_e32 v54, v147
	v_lshl_add_u64 v[52:53], v[52:53], 0, v[142:143]
	v_pk_mul_f32 v[48:49], v[48:49], v[54:55] op_sel_hi:[1,0]
	v_pk_mul_f32 v[50:51], v[50:51], v[54:55] op_sel_hi:[1,0]
	v_pk_mul_f32 v[56:57], v[46:47], v[54:55] op_sel_hi:[1,0]
	v_pk_mul_f32 v[46:47], v[44:45], v[54:55] op_sel_hi:[1,0]
	v_cvt_pk_bf16_f32 v44, v48, v49
	v_lshlrev_b64 v[48:49], 1, v[52:53]
	v_cvt_pk_bf16_f32 v45, v50, v51
	v_lshl_add_u64 v[50:51], s[12:13], 0, v[48:49]
	v_cvt_pk_bf16_f32 v46, v46, v47
	v_cvt_pk_bf16_f32 v47, v56, v57
	global_store_dwordx4 v[50:51], v[44:47], off
	v_pk_mul_f32 v[40:41], v[40:41], v[54:55] op_sel_hi:[1,0]
	v_pk_mul_f32 v[42:43], v[42:43], v[54:55] op_sel_hi:[1,0]
	v_pk_mul_f32 v[44:45], v[38:39], v[54:55] op_sel_hi:[1,0]
	v_pk_mul_f32 v[38:39], v[36:37], v[54:55] op_sel_hi:[1,0]
	v_cvt_pk_bf16_f32 v36, v40, v41
	v_cvt_pk_bf16_f32 v37, v42, v43
	v_lshl_add_u64 v[40:41], s[14:15], 0, v[48:49]
	v_cvt_pk_bf16_f32 v38, v38, v39
	v_cvt_pk_bf16_f32 v39, v44, v45
	global_store_dwordx4 v[40:41], v[36:39], off
	v_readlane_b32 s85, v255, 30
	s_nop 0
	v_add_u32_e32 v38, 0xa0, v151
	v_ashrrev_i32_e32 v36, 12, v38
	v_ashrrev_i32_e32 v37, 31, v36
	v_lshlrev_b64 v[36:37], 16, v[36:37]
	v_lshl_add_u64 v[36:37], v[36:37], 0, s[24:25]
	v_and_or_b32 v36, v38, s17, v36
	v_lshlrev_b64 v[36:37], 7, v[36:37]
	v_lshl_add_u64 v[36:37], v[36:37], 0, v[142:143]
	v_pk_mul_f32 v[38:39], v[30:31], v[144:145] op_sel_hi:[1,0]
	v_pk_mul_f32 v[30:31], v[28:29], v[144:145] op_sel_hi:[1,0]
	v_cvt_pk_bf16_f32 v28, v32, v33
	v_lshlrev_b64 v[32:33], 1, v[36:37]
	v_cvt_pk_bf16_f32 v29, v34, v35
	v_lshl_add_u64 v[34:35], s[12:13], 0, v[32:33]
	v_cvt_pk_bf16_f32 v30, v30, v31
	v_cvt_pk_bf16_f32 v31, v38, v39
	global_store_dwordx4 v[34:35], v[28:31], off
	s_nop 1
	v_pk_mul_f32 v[28:29], v[22:23], v[144:145] op_sel_hi:[1,0]
	v_pk_mul_f32 v[22:23], v[20:21], v[144:145] op_sel_hi:[1,0]
	v_cvt_pk_bf16_f32 v20, v24, v25
	v_cvt_pk_bf16_f32 v21, v26, v27
	v_lshl_add_u64 v[24:25], s[14:15], 0, v[32:33]
	v_cvt_pk_bf16_f32 v22, v22, v23
	v_cvt_pk_bf16_f32 v23, v28, v29
	global_store_dwordx4 v[24:25], v[20:23], off
	s_nop 1
	v_add_u32_e32 v22, 0xb0, v151
	v_ashrrev_i32_e32 v20, 12, v22
	v_ashrrev_i32_e32 v21, 31, v20
	v_lshlrev_b64 v[20:21], 16, v[20:21]
	v_lshl_add_u64 v[20:21], v[20:21], 0, s[24:25]
	v_and_or_b32 v20, v22, s17, v20
	v_lshlrev_b64 v[20:21], 7, v[20:21]
	v_mov_b32_e32 v22, v145
	v_lshl_add_u64 v[20:21], v[20:21], 0, v[142:143]
	v_pk_mul_f32 v[16:17], v[16:17], v[22:23] op_sel_hi:[1,0]
	v_pk_mul_f32 v[18:19], v[18:19], v[22:23] op_sel_hi:[1,0]
	v_pk_mul_f32 v[24:25], v[14:15], v[22:23] op_sel_hi:[1,0]
	v_pk_mul_f32 v[14:15], v[12:13], v[22:23] op_sel_hi:[1,0]
	v_cvt_pk_bf16_f32 v12, v16, v17
	v_lshlrev_b64 v[16:17], 1, v[20:21]
	v_cvt_pk_bf16_f32 v13, v18, v19
	v_lshl_add_u64 v[18:19], s[12:13], 0, v[16:17]
	v_pk_mul_f32 v[8:9], v[8:9], v[22:23] op_sel_hi:[1,0]
	v_cvt_pk_bf16_f32 v14, v14, v15
	v_cvt_pk_bf16_f32 v15, v24, v25
	global_store_dwordx4 v[18:19], v[12:15], off
	v_pk_mul_f32 v[10:11], v[10:11], v[22:23] op_sel_hi:[1,0]
	s_nop 0
	v_pk_mul_f32 v[12:13], v[6:7], v[22:23] op_sel_hi:[1,0]
	v_pk_mul_f32 v[6:7], v[4:5], v[22:23] op_sel_hi:[1,0]
	v_cvt_pk_bf16_f32 v4, v8, v9
	v_lshl_add_u64 v[8:9], s[14:15], 0, v[16:17]
	v_cvt_pk_bf16_f32 v5, v10, v11
	v_cvt_pk_bf16_f32 v6, v6, v7
	v_cvt_pk_bf16_f32 v7, v12, v13
	global_store_dwordx4 v[8:9], v[4:7], off
	s_cbranch_scc0 .LBB0_289
	s_waitcnt vmcnt(0)
	s_cmpk_gt_u32 s20, 0xff
	s_cbranch_scc1 .LBB0_294
	s_barrier

;     __device__ __forceinline__ bool next(int i, Unit& u) const { if (i >= n) return false; u.pm = pm; u.pn = pn0 + i; return true; }
;     __device__ __forceinline__ bool next(int i, Unit& u) const { if (i) return false; u.pm = pm; u.pn = pn; return true; }
; #define PG8_STAGE(bufoff, gbase, voff) do { _Pragma("unroll") for (int _i = 0; _i < 2; ++_i) \
;         __builtin_amdgcn_global_load_lds((const unsigned*)((const char*)(gbase) + (voff)[_i]), (PG8_LAS unsigned*)(lds + (bufoff) + ldsw + _i * 8192), 16, 0, 0); } while (0)
; #define PG8_LDA(dst, b, h) do { _Pragma("unroll") for (int m = 0; m < 4; ++m) _Pragma("unroll") for (int k = 0; k < 2; ++k) dst[m][k] = *(const PG8_LAS bf16x8*)(lds + PG8_SA(b, h) + aoff + m * 2048 + k * 1024); } while (0)
; #define PG8_LDB(dst, b, h) do { _Pragma("unroll") for (int n = 0; n < 2; ++n) _Pragma("unroll") for (int k = 0; k < 2; ++k) dst[n][k] = *(const PG8_LAS bf16x8*)(lds + PG8_SB(b, h) + boff + n * 2048 + k * 1024); } while (0)
; #define PG8_SCHED __builtin_amdgcn_sched_barrier(0)
;     ...
;         const bool has_next = S.next(ui + 1, nxt);
;         const char* nA = has_next ? (const char*)g.A + (size_t)nxt.pm * tstep : cA; const char* nB = has_next ? (const char*)g.Bt + (size_t)nxt.pn * tstep : cB;
;         for (int t = 0; t < nt; t += 2) {
;             const bool last = (t == nt - 2);
;             const char* a1 = cA + (size_t)(t + 1) * kstep;
;             const char* a2 = last ? nA : cA + (size_t)(t + 2) * kstep; const char* b2 = last ? nB : cB + (size_t)(t + 2) * kstep;
;             const char* a3 = a2 + kstep; const char* b3 = b2 + kstep;
;             if (last && has_next) S.a_ready(nxt);
;             if (t == 0) E.pre_issue(pre, cur, tid, ui); else if (t == 2) E.pre_finish(pre, tid, ui);
;             if constexpr (SP2) {
;             PG8_LDB(B0, 0, 0); PG8_LDB(B1, 0, 1); PG8_SCHED; PG8_LDA(At, 0, 0); PG8_STAGE(PG8_SA(1, 1), a1 + hstep, voffA);
;     ...
;         for (int a = 0; a < 2; ++a)
; #pragma unroll
;             for (int b = 0; b < 2; ++b)
; #pragma unroll
;                 for (int m = 0; m < 4; ++m)
; #pragma unroll
;                     for (int n = 0; n < 2; ++n) acc[a][b][m][n] = (f32x4){0.f, 0.f, 0.f, 0.f};
;         cur = nxt; cA = nA; cB = nB; ++ui;
.LBB0_300:
	s_mov_b32 s20, s79
	s_add_i32 s79, s79, 1
	s_mov_b64 s[24:25], s[4:5]
	s_cmp_lt_u32 s79, s21
	v_readlane_b32 s4, v254, 30
	s_mov_b64 s[14:15], s[6:7]
	s_mov_b32 s6, s83
	s_cselect_b64 s[50:51], -1, 0
	s_add_i32 s83, s79, s4
	s_and_b64 s[4:5], s[50:51], exec
	v_readlane_b32 s5, v254, 23
	s_cselect_b32 s4, s83, s6
	s_cselect_b32 s6, s5, s5
	s_ashr_i32 s7, s6, 31
	s_lshl_b64 s[6:7], s[6:7], 18
	s_add_u32 s6, s76, s6
	s_addc_u32 s7, s77, s7
	s_and_b64 s[52:53], s[50:51], exec
	s_cselect_b32 s21, s7, s15
	s_cselect_b32 s23, s6, s14
	s_ashr_i32 s5, s4, 31
	s_lshl_b64 s[4:5], s[4:5], 18
	s_add_u32 s4, s58, s4
	s_addc_u32 s5, s59, s5
	s_and_b64 s[50:51], s[50:51], exec
	s_cselect_b32 s42, s5, s25
	s_cselect_b32 s44, s4, s24
	s_add_u32 s52, s24, 0x100
	s_addc_u32 s53, s25, 0
	s_add_u32 s14, s14, 0x20080
	v_mov_b32_e32 v4, 0
	s_addc_u32 s15, s15, 0
	s_mov_b32 s54, -2
	v_mov_b32_e32 v5, v4
	v_mov_b32_e32 v6, v4
	v_mov_b32_e32 v7, v4
	v_mov_b32_e32 v8, v4
	v_mov_b32_e32 v9, v4
	v_mov_b32_e32 v10, v4
	v_mov_b32_e32 v11, v4
	v_mov_b32_e32 v16, v4
	v_mov_b32_e32 v17, v4
	v_mov_b32_e32 v18, v4
	v_mov_b32_e32 v19, v4
	v_mov_b32_e32 v24, v4
	v_mov_b32_e32 v25, v4
	v_mov_b32_e32 v26, v4
	v_mov_b32_e32 v27, v4
	v_mov_b32_e32 v32, v4
	v_mov_b32_e32 v33, v4
	v_mov_b32_e32 v34, v4
	v_mov_b32_e32 v35, v4
	v_mov_b32_e32 v40, v4
	v_mov_b32_e32 v41, v4
	v_mov_b32_e32 v42, v4
	v_mov_b32_e32 v43, v4
	v_mov_b32_e32 v48, v4
	v_mov_b32_e32 v49, v4
	v_mov_b32_e32 v50, v4
	v_mov_b32_e32 v51, v4
	v_mov_b32_e32 v56, v4
	v_mov_b32_e32 v57, v4
	v_mov_b32_e32 v58, v4
	v_mov_b32_e32 v59, v4
	v_mov_b32_e32 v12, v4
	v_mov_b32_e32 v13, v4
	v_mov_b32_e32 v14, v4
	v_mov_b32_e32 v15, v4
	v_mov_b32_e32 v20, v4
	v_mov_b32_e32 v21, v4
	v_mov_b32_e32 v22, v4
	v_mov_b32_e32 v23, v4
	v_mov_b32_e32 v28, v4
	v_mov_b32_e32 v29, v4
	v_mov_b32_e32 v30, v4
	v_mov_b32_e32 v31, v4
	v_mov_b32_e32 v36, v4
	v_mov_b32_e32 v37, v4
	v_mov_b32_e32 v38, v4
	v_mov_b32_e32 v39, v4
	v_mov_b32_e32 v44, v4
	v_mov_b32_e32 v45, v4
	v_mov_b32_e32 v46, v4
	v_mov_b32_e32 v47, v4
	v_mov_b32_e32 v52, v4
	v_mov_b32_e32 v53, v4
	v_mov_b32_e32 v54, v4
	v_mov_b32_e32 v55, v4
	v_mov_b32_e32 v60, v4
	v_mov_b32_e32 v61, v4
	v_mov_b32_e32 v62, v4
	v_mov_b32_e32 v63, v4
	v_mov_b32_e32 v64, v4
	v_mov_b32_e32 v65, v4
	v_mov_b32_e32 v66, v4
	v_mov_b32_e32 v67, v4
	v_mov_b32_e32 v68, v4
	v_mov_b32_e32 v69, v4
	v_mov_b32_e32 v70, v4
	v_mov_b32_e32 v71, v4
	v_mov_b32_e32 v72, v4
	v_mov_b32_e32 v73, v4
	v_mov_b32_e32 v74, v4
	v_mov_b32_e32 v75, v4
	v_mov_b32_e32 v80, v4
	v_mov_b32_e32 v81, v4
	v_mov_b32_e32 v82, v4
	v_mov_b32_e32 v83, v4
	v_mov_b32_e32 v88, v4
	v_mov_b32_e32 v89, v4
	v_mov_b32_e32 v90, v4
	v_mov_b32_e32 v91, v4
	v_mov_b32_e32 v96, v4
	v_mov_b32_e32 v97, v4
	v_mov_b32_e32 v98, v4
	v_mov_b32_e32 v99, v4
	v_mov_b32_e32 v104, v4
	v_mov_b32_e32 v105, v4
	v_mov_b32_e32 v106, v4
	v_mov_b32_e32 v107, v4
	v_mov_b32_e32 v112, v4
	v_mov_b32_e32 v113, v4
	v_mov_b32_e32 v114, v4
	v_mov_b32_e32 v115, v4
	v_mov_b32_e32 v120, v4
	v_mov_b32_e32 v121, v4
	v_mov_b32_e32 v122, v4
	v_mov_b32_e32 v123, v4
	v_mov_b32_e32 v76, v4
	v_mov_b32_e32 v77, v4
	v_mov_b32_e32 v78, v4
	v_mov_b32_e32 v79, v4
	v_mov_b32_e32 v84, v4
	v_mov_b32_e32 v85, v4
	v_mov_b32_e32 v86, v4
	v_mov_b32_e32 v87, v4
	v_mov_b32_e32 v92, v4
	v_mov_b32_e32 v93, v4
	v_mov_b32_e32 v94, v4
	v_mov_b32_e32 v95, v4
	v_mov_b32_e32 v100, v4
	v_mov_b32_e32 v101, v4
	v_mov_b32_e32 v102, v4
	v_mov_b32_e32 v103, v4
	v_mov_b32_e32 v108, v4
	v_mov_b32_e32 v109, v4
	v_mov_b32_e32 v110, v4
	v_mov_b32_e32 v111, v4
	v_mov_b32_e32 v116, v4
	v_mov_b32_e32 v117, v4
	v_mov_b32_e32 v118, v4
	v_mov_b32_e32 v119, v4
	v_mov_b32_e32 v124, v4
	v_mov_b32_e32 v125, v4
	v_mov_b32_e32 v126, v4
	v_mov_b32_e32 v127, v4
	v_mov_b32_e32 v128, v4
	v_mov_b32_e32 v129, v4
	v_mov_b32_e32 v130, v4
	v_mov_b32_e32 v131, v4
	s_waitcnt lgkmcnt(0)
	v_add_u32_e32 v251, 0x10000, v173
.LBB0_301:
	s_add_u32 s24, s14, 0xfffe0080
	s_addc_u32 s25, s15, -1
	s_add_i32 s48, 0, 0x10000
	s_cmp_eq_u32 s54, 4
	s_cselect_b32 s51, s21, s25
	s_cselect_b32 s50, s23, s24
	s_cselect_b32 s25, s42, s53
	s_cselect_b32 s24, s44, s52
	s_add_i32 s49, 0, 0x14000
	ds_read_b128 v[132:135], v251
	ds_read_b128 v[146:149], v251 offset:1024
	ds_read_b128 v[150:153], v251 offset:2048
	ds_read_b128 v[154:157], v251 offset:3072
	ds_read_b128 v[158:161], v251 offset:16384
	ds_read_b128 v[162:165], v251 offset:17408
	ds_read_b128 v[166:169], v251 offset:18432
	ds_read_b128 v[176:179], v251 offset:19456
	v_lshl_add_u64 v[170:171], s[14:15], 0, v[144:145]
	s_add_i32 m0, s62, 0xc000
	ds_read_b128 v[180:183], v174
	ds_read_b128 v[184:187], v174 offset:1024
	ds_read_b128 v[188:191], v174 offset:2048
	ds_read_b128 v[192:195], v174 offset:3072
	ds_read_b128 v[196:199], v174 offset:4096
	ds_read_b128 v[210:213], v174 offset:5120
	ds_read_b128 v[214:217], v174 offset:6144
	ds_read_b128 v[218:221], v174 offset:7168
	global_load_lds_dwordx4 v[170:171], off
	v_lshl_add_u64 v[170:171], s[14:15], 0, v[142:143]
	s_add_i32 m0, s62, 0xe000
	s_nop 0
	global_load_lds_dwordx4 v[170:171], off
	s_waitcnt vmcnt(8)
	s_waitcnt lgkmcnt(0)
	s_setprio 1
	s_barrier
; #define PG8_STAGE(bufoff, gbase, voff) do { _Pragma("unroll") for (int _i = 0; _i < 2; ++_i) \
;         __builtin_amdgcn_global_load_lds((const unsigned*)((const char*)(gbase) + (voff)[_i]), (PG8_LAS unsigned*)(lds + (bufoff) + ldsw + _i * 8192), 16, 0, 0); } while (0)
; #define PG8_LDA(dst, b, h) do { _Pragma("unroll") for (int m = 0; m < 4; ++m) _Pragma("unroll") for (int k = 0; k < 2; ++k) dst[m][k] = *(const PG8_LAS bf16x8*)(lds + PG8_SA(b, h) + aoff + m * 2048 + k * 1024); } while (0)
; #define PG8_MMA(ai, bj, At, Bt) do { __builtin_amdgcn_s_setprio(1); _Pragma("unroll") for (int m = 0; m < 4; ++m) _Pragma("unroll") for (int n = 0; n < 2; ++n) _Pragma("unroll") for (int k = 0; k < 2; ++k) \
;         acc[ai][bj][m][n] = __builtin_amdgcn_mfma_f32_16x16x32_bf16(Bt[n][k], At[m][k], acc[ai][bj][m][n], 0, 0, 0); __builtin_amdgcn_s_setprio(0); } while (0)
; #define PG8_WAIT_V(n) asm volatile("s_waitcnt vmcnt(" #n ")" ::: "memory")
; #define PG8_WAIT_L(n) asm volatile("s_waitcnt lgkmcnt(" #n ")" ::: "memory")
; #define PG8_BAR __builtin_amdgcn_s_barrier()
; #define PG8_SCHED __builtin_amdgcn_sched_barrier(0)
;     ...
;             PG8_WAIT_V(8); PG8_WAIT_L(0); PG8_BAR; PG8_MMA(0, 0, At, B0); PG8_MMA(0, 1, At, B1); PG8_BAR; PG8_SCHED;
;             PG8_LDA(At, 0, 1); PG8_STAGE(PG8_SB(0, 0), b2, voffB); PG8_STAGE(PG8_SB(0, 1), b2 + hstep, voffB); PG8_STAGE(PG8_SA(0, 0), a2, voffA);
;             PG8_WAIT_V(8); PG8_WAIT_L(0); PG8_BAR; PG8_MMA(1, 0, At, B0); PG8_MMA(1, 1, At, B1); PG8_BAR; PG8_SCHED;
	v_mfma_f32_16x16x32_bf16 v[128:131], v[132:135], v[180:183], v[128:131]
	v_mfma_f32_16x16x32_bf16 v[124:127], v[150:153], v[180:183], v[124:127]
	v_mfma_f32_16x16x32_bf16 v[116:119], v[132:135], v[188:191], v[116:119]
	v_mfma_f32_16x16x32_bf16 v[108:111], v[150:153], v[188:191], v[108:111]
	v_mfma_f32_16x16x32_bf16 v[100:103], v[132:135], v[196:199], v[100:103]
	v_mfma_f32_16x16x32_bf16 v[92:95], v[150:153], v[196:199], v[92:95]
	v_mfma_f32_16x16x32_bf16 v[84:87], v[132:135], v[214:217], v[84:87]
	v_mfma_f32_16x16x32_bf16 v[76:79], v[150:153], v[214:217], v[76:79]
	v_mfma_f32_16x16x32_bf16 v[128:131], v[146:149], v[184:187], v[128:131]
	v_mfma_f32_16x16x32_bf16 v[124:127], v[154:157], v[184:187], v[124:127]
	v_mfma_f32_16x16x32_bf16 v[116:119], v[146:149], v[192:195], v[116:119]
	v_mfma_f32_16x16x32_bf16 v[108:111], v[154:157], v[192:195], v[108:111]
	v_mfma_f32_16x16x32_bf16 v[100:103], v[146:149], v[210:213], v[100:103]
	v_mfma_f32_16x16x32_bf16 v[92:95], v[154:157], v[210:213], v[92:95]
	v_mfma_f32_16x16x32_bf16 v[84:87], v[146:149], v[218:221], v[84:87]
	v_mfma_f32_16x16x32_bf16 v[76:79], v[154:157], v[218:221], v[76:79]
	s_setprio 0
	s_setprio 1
	v_mfma_f32_16x16x32_bf16 v[120:123], v[158:161], v[180:183], v[120:123]
	v_mfma_f32_16x16x32_bf16 v[112:115], v[166:169], v[180:183], v[112:115]
	v_mfma_f32_16x16x32_bf16 v[104:107], v[158:161], v[188:191], v[104:107]
	v_mfma_f32_16x16x32_bf16 v[96:99], v[166:169], v[188:191], v[96:99]
	v_mfma_f32_16x16x32_bf16 v[88:91], v[158:161], v[196:199], v[88:91]
	v_mfma_f32_16x16x32_bf16 v[80:83], v[166:169], v[196:199], v[80:83]
	v_mfma_f32_16x16x32_bf16 v[72:75], v[158:161], v[214:217], v[72:75]
	v_mfma_f32_16x16x32_bf16 v[68:71], v[166:169], v[214:217], v[68:71]
	v_mfma_f32_16x16x32_bf16 v[120:123], v[162:165], v[184:187], v[120:123]
	v_mfma_f32_16x16x32_bf16 v[112:115], v[176:179], v[184:187], v[112:115]
	v_mfma_f32_16x16x32_bf16 v[104:107], v[162:165], v[192:195], v[104:107]
	v_mfma_f32_16x16x32_bf16 v[96:99], v[176:179], v[192:195], v[96:99]
	v_mfma_f32_16x16x32_bf16 v[88:91], v[162:165], v[210:213], v[88:91]
	v_mfma_f32_16x16x32_bf16 v[80:83], v[176:179], v[210:213], v[80:83]
	v_mfma_f32_16x16x32_bf16 v[72:75], v[162:165], v[218:221], v[72:75]
	v_mfma_f32_16x16x32_bf16 v[68:71], v[176:179], v[218:221], v[68:71]
	s_barrier
	s_setprio 0
	s_add_i32 s48, s48, s61
	v_lshl_add_u64 v[170:171], s[24:25], 0, v[200:201]
	s_mov_b32 m0, s48
	ds_read_b128 v[180:183], v174 offset:16384
	ds_read_b128 v[184:187], v174 offset:17408
	ds_read_b128 v[188:191], v174 offset:18432
	ds_read_b128 v[192:195], v174 offset:19456
	ds_read_b128 v[196:199], v174 offset:20480
	ds_read_b128 v[210:213], v174 offset:21504
	ds_read_b128 v[214:217], v174 offset:22528
	ds_read_b128 v[218:221], v174 offset:23552
	global_load_lds_dwordx4 v[170:171], off
	s_add_i32 m0, s48, 0x2000
	s_add_u32 s84, s24, 0x20000
	v_lshl_add_u64 v[206:207], s[24:25], 0, v[136:137]
	s_addc_u32 s85, s25, 0
	s_add_i32 s48, s49, s61
	global_load_lds_dwordx4 v[206:207], off
	v_lshl_add_u64 v[208:209], s[84:85], 0, v[200:201]
	s_mov_b32 m0, s48
	v_lshl_add_u64 v[222:223], s[50:51], 0, v[138:139]
	global_load_lds_dwordx4 v[208:209], off
	v_lshl_add_u64 v[208:209], s[84:85], 0, v[136:137]
	s_add_i32 m0, s48, 0x2000
	s_nop 0
	global_load_lds_dwordx4 v[208:209], off
	v_lshl_add_u64 v[208:209], s[50:51], 0, v[140:141]
	s_mov_b32 m0, s62
	s_nop 0
	global_load_lds_dwordx4 v[208:209], off
	s_mov_b32 m0, s63
	s_nop 0
	global_load_lds_dwordx4 v[222:223], off
	s_waitcnt vmcnt(8)
	s_waitcnt lgkmcnt(0)
	s_setprio 1
	s_barrier
	v_mfma_f32_16x16x32_bf16 v[64:67], v[132:135], v[180:183], v[64:67]
	v_mfma_f32_16x16x32_bf16 v[60:63], v[150:153], v[180:183], v[60:63]
	v_mfma_f32_16x16x32_bf16 v[52:55], v[132:135], v[188:191], v[52:55]
	v_mfma_f32_16x16x32_bf16 v[44:47], v[150:153], v[188:191], v[44:47]
	v_mfma_f32_16x16x32_bf16 v[36:39], v[132:135], v[196:199], v[36:39]
	v_mfma_f32_16x16x32_bf16 v[28:31], v[150:153], v[196:199], v[28:31]
	v_mfma_f32_16x16x32_bf16 v[20:23], v[132:135], v[214:217], v[20:23]
	v_mfma_f32_16x16x32_bf16 v[12:15], v[150:153], v[214:217], v[12:15]
	v_mfma_f32_16x16x32_bf16 v[64:67], v[146:149], v[184:187], v[64:67]
	v_mfma_f32_16x16x32_bf16 v[60:63], v[154:157], v[184:187], v[60:63]
	v_mfma_f32_16x16x32_bf16 v[52:55], v[146:149], v[192:195], v[52:55]
	v_mfma_f32_16x16x32_bf16 v[44:47], v[154:157], v[192:195], v[44:47]
	v_mfma_f32_16x16x32_bf16 v[36:39], v[146:149], v[210:213], v[36:39]
	v_mfma_f32_16x16x32_bf16 v[28:31], v[154:157], v[210:213], v[28:31]
	v_mfma_f32_16x16x32_bf16 v[20:23], v[146:149], v[218:221], v[20:23]
	v_mfma_f32_16x16x32_bf16 v[12:15], v[154:157], v[218:221], v[12:15]
	s_setprio 0
	s_setprio 1
	v_mfma_f32_16x16x32_bf16 v[56:59], v[158:161], v[180:183], v[56:59]
	v_mfma_f32_16x16x32_bf16 v[48:51], v[166:169], v[180:183], v[48:51]
	v_mfma_f32_16x16x32_bf16 v[40:43], v[158:161], v[188:191], v[40:43]
	v_mfma_f32_16x16x32_bf16 v[32:35], v[166:169], v[188:191], v[32:35]
	v_mfma_f32_16x16x32_bf16 v[24:27], v[158:161], v[196:199], v[24:27]
	v_mfma_f32_16x16x32_bf16 v[16:19], v[166:169], v[196:199], v[16:19]
	v_mfma_f32_16x16x32_bf16 v[8:11], v[158:161], v[214:217], v[8:11]
	v_mfma_f32_16x16x32_bf16 v[4:7], v[166:169], v[214:217], v[4:7]
	v_mfma_f32_16x16x32_bf16 v[56:59], v[162:165], v[184:187], v[56:59]
	v_mfma_f32_16x16x32_bf16 v[48:51], v[176:179], v[184:187], v[48:51]
	v_mfma_f32_16x16x32_bf16 v[40:43], v[162:165], v[192:195], v[40:43]
	v_mfma_f32_16x16x32_bf16 v[32:35], v[176:179], v[192:195], v[32:35]
	v_mfma_f32_16x16x32_bf16 v[24:27], v[162:165], v[210:213], v[24:27]
	v_mfma_f32_16x16x32_bf16 v[16:19], v[176:179], v[210:213], v[16:19]
	v_mfma_f32_16x16x32_bf16 v[8:11], v[162:165], v[218:221], v[8:11]
	v_mfma_f32_16x16x32_bf16 v[4:7], v[176:179], v[218:221], v[4:7]
	s_barrier
; #define PG8_STAGE(bufoff, gbase, voff) do { _Pragma("unroll") for (int _i = 0; _i < 2; ++_i) \
;         __builtin_amdgcn_global_load_lds((const unsigned*)((const char*)(gbase) + (voff)[_i]), (PG8_LAS unsigned*)(lds + (bufoff) + ldsw + _i * 8192), 16, 0, 0); } while (0)
; #define PG8_LDA(dst, b, h) do { _Pragma("unroll") for (int m = 0; m < 4; ++m) _Pragma("unroll") for (int k = 0; k < 2; ++k) dst[m][k] = *(const PG8_LAS bf16x8*)(lds + PG8_SA(b, h) + aoff + m * 2048 + k * 1024); } while (0)
; #define PG8_LDB(dst, b, h) do { _Pragma("unroll") for (int n = 0; n < 2; ++n) _Pragma("unroll") for (int k = 0; k < 2; ++k) dst[n][k] = *(const PG8_LAS bf16x8*)(lds + PG8_SB(b, h) + boff + n * 2048 + k * 1024); } while (0)
; #define PG8_MMA(ai, bj, At, Bt) do { __builtin_amdgcn_s_setprio(1); _Pragma("unroll") for (int m = 0; m < 4; ++m) _Pragma("unroll") for (int n = 0; n < 2; ++n) _Pragma("unroll") for (int k = 0; k < 2; ++k) \
;         acc[ai][bj][m][n] = __builtin_amdgcn_mfma_f32_16x16x32_bf16(Bt[n][k], At[m][k], acc[ai][bj][m][n], 0, 0, 0); __builtin_amdgcn_s_setprio(0); } while (0)
; #define PG8_WAIT_V(n) asm volatile("s_waitcnt vmcnt(" #n ")" ::: "memory")
; #define PG8_WAIT_L(n) asm volatile("s_waitcnt lgkmcnt(" #n ")" ::: "memory")
; #define PG8_BAR __builtin_amdgcn_s_barrier()
; #define PG8_SCHED __builtin_amdgcn_sched_barrier(0)
;     ...
;             PG8_LDB(B0, 1, 0); PG8_LDB(B1, 1, 1); PG8_SCHED; PG8_LDA(At, 1, 0); PG8_STAGE(PG8_SA(0, 1), a2 + hstep, voffA);
;             PG8_WAIT_V(8); PG8_WAIT_L(0); PG8_BAR; PG8_MMA(0, 0, At, B0); PG8_MMA(0, 1, At, B1); PG8_BAR; PG8_SCHED;
;             PG8_LDA(At, 1, 1); PG8_STAGE(PG8_SB(1, 0), b3, voffB); PG8_STAGE(PG8_SB(1, 1), b3 + hstep, voffB); PG8_STAGE(PG8_SA(1, 0), a3, voffA);
	s_setprio 0
	s_add_i32 s48, 0, 0x18000
	s_add_i32 s49, 0, 0x1c000
	ds_read_b128 v[132:135], v251 offset:32768
	ds_read_b128 v[146:149], v251 offset:33792
	ds_read_b128 v[150:153], v251 offset:34816
	ds_read_b128 v[154:157], v251 offset:35840
	ds_read_b128 v[158:161], v251 offset:49152
	ds_read_b128 v[162:165], v251 offset:50176
	ds_read_b128 v[166:169], v251 offset:51200
	ds_read_b128 v[176:179], v251 offset:52224
	s_add_u32 s50, s50, 0x20000
	s_addc_u32 s51, s51, 0
	s_mov_b32 m0, s68
	v_lshl_add_u64 v[224:225], s[50:51], 0, v[140:141]
	ds_read_b128 v[180:183], v174 offset:32768
	ds_read_b128 v[184:187], v174 offset:33792
	ds_read_b128 v[188:191], v174 offset:34816
	ds_read_b128 v[192:195], v174 offset:35840
	ds_read_b128 v[196:199], v174 offset:36864
	ds_read_b128 v[210:213], v174 offset:37888
	ds_read_b128 v[214:217], v174 offset:38912
	ds_read_b128 v[218:221], v174 offset:39936
	global_load_lds_dwordx4 v[224:225], off
	v_lshl_add_u64 v[224:225], s[50:51], 0, v[138:139]
	s_mov_b32 m0, s69
	s_nop 0
	global_load_lds_dwordx4 v[224:225], off
	s_waitcnt vmcnt(8)
	s_waitcnt lgkmcnt(0)
	s_setprio 1
	s_barrier
	v_mfma_f32_16x16x32_bf16 v[128:131], v[132:135], v[180:183], v[128:131]
	v_mfma_f32_16x16x32_bf16 v[124:127], v[150:153], v[180:183], v[124:127]
	v_mfma_f32_16x16x32_bf16 v[116:119], v[132:135], v[188:191], v[116:119]
	v_mfma_f32_16x16x32_bf16 v[108:111], v[150:153], v[188:191], v[108:111]
	v_mfma_f32_16x16x32_bf16 v[100:103], v[132:135], v[196:199], v[100:103]
	v_mfma_f32_16x16x32_bf16 v[92:95], v[150:153], v[196:199], v[92:95]
	v_mfma_f32_16x16x32_bf16 v[84:87], v[132:135], v[214:217], v[84:87]
	v_mfma_f32_16x16x32_bf16 v[76:79], v[150:153], v[214:217], v[76:79]
	v_mfma_f32_16x16x32_bf16 v[128:131], v[146:149], v[184:187], v[128:131]
	v_mfma_f32_16x16x32_bf16 v[124:127], v[154:157], v[184:187], v[124:127]
	v_mfma_f32_16x16x32_bf16 v[116:119], v[146:149], v[192:195], v[116:119]
	v_mfma_f32_16x16x32_bf16 v[108:111], v[154:157], v[192:195], v[108:111]
	v_mfma_f32_16x16x32_bf16 v[100:103], v[146:149], v[210:213], v[100:103]
	v_mfma_f32_16x16x32_bf16 v[92:95], v[154:157], v[210:213], v[92:95]
	v_mfma_f32_16x16x32_bf16 v[84:87], v[146:149], v[218:221], v[84:87]
	v_mfma_f32_16x16x32_bf16 v[76:79], v[154:157], v[218:221], v[76:79]
	s_setprio 0
	s_setprio 1
	v_mfma_f32_16x16x32_bf16 v[120:123], v[158:161], v[180:183], v[120:123]
	v_mfma_f32_16x16x32_bf16 v[112:115], v[166:169], v[180:183], v[112:115]
	v_mfma_f32_16x16x32_bf16 v[104:107], v[158:161], v[188:191], v[104:107]
	v_mfma_f32_16x16x32_bf16 v[96:99], v[166:169], v[188:191], v[96:99]
	v_mfma_f32_16x16x32_bf16 v[88:91], v[158:161], v[196:199], v[88:91]
	v_mfma_f32_16x16x32_bf16 v[80:83], v[166:169], v[196:199], v[80:83]
	v_mfma_f32_16x16x32_bf16 v[72:75], v[158:161], v[214:217], v[72:75]
	v_mfma_f32_16x16x32_bf16 v[68:71], v[166:169], v[214:217], v[68:71]
	v_mfma_f32_16x16x32_bf16 v[120:123], v[162:165], v[184:187], v[120:123]
	v_mfma_f32_16x16x32_bf16 v[112:115], v[176:179], v[184:187], v[112:115]
	v_mfma_f32_16x16x32_bf16 v[104:107], v[162:165], v[192:195], v[104:107]
	v_mfma_f32_16x16x32_bf16 v[96:99], v[176:179], v[192:195], v[96:99]
	v_mfma_f32_16x16x32_bf16 v[88:91], v[162:165], v[210:213], v[88:91]
	v_mfma_f32_16x16x32_bf16 v[80:83], v[176:179], v[210:213], v[80:83]
	v_mfma_f32_16x16x32_bf16 v[72:75], v[162:165], v[218:221], v[72:75]
	v_mfma_f32_16x16x32_bf16 v[68:71], v[176:179], v[218:221], v[68:71]
	s_barrier
	s_setprio 0
	s_add_i32 s48, s48, s61
	v_lshl_add_u64 v[170:171], v[170:171], 0, s[66:67]
	s_mov_b32 m0, s48
	ds_read_b128 v[180:183], v174 offset:49152
	ds_read_b128 v[184:187], v174 offset:50176
	ds_read_b128 v[188:191], v174 offset:51200
	ds_read_b128 v[192:195], v174 offset:52224
	ds_read_b128 v[196:199], v174 offset:53248
	ds_read_b128 v[210:213], v174 offset:54272
	ds_read_b128 v[214:217], v174 offset:55296
	ds_read_b128 v[218:221], v174 offset:56320
	global_load_lds_dwordx4 v[170:171], off
	s_add_i32 m0, s48, 0x2000
	s_add_u32 s24, s24, 0x20080
	v_lshl_add_u64 v[170:171], v[206:207], 0, s[66:67]
	s_addc_u32 s25, s25, 0
	s_add_i32 s48, s49, s61
	global_load_lds_dwordx4 v[170:171], off
	v_lshl_add_u64 v[170:171], s[24:25], 0, v[200:201]
	s_mov_b32 m0, s48
	s_nop 0
	global_load_lds_dwordx4 v[170:171], off
	v_lshl_add_u64 v[170:171], s[24:25], 0, v[136:137]
	s_add_i32 m0, s48, 0x2000
	s_nop 0
	global_load_lds_dwordx4 v[170:171], off
	v_lshl_add_u64 v[170:171], v[208:209], 0, s[66:67]
	s_mov_b32 m0, s71
	s_nop 0
	global_load_lds_dwordx4 v[170:171], off
	v_lshl_add_u64 v[170:171], v[222:223], 0, s[66:67]
	s_mov_b32 m0, s73
	s_nop 0
	global_load_lds_dwordx4 v[170:171], off
	s_waitcnt vmcnt(8)
	s_waitcnt lgkmcnt(0)
	s_setprio 1
	s_barrier
; #define PG8_G __attribute__((address_space(1)))
; __device__ __forceinline__ u32x4 pack8bf(const f32x4 a, const f32x4 b) { u32x4 w; w.x = cvt_pk_bf16(a[0], a[1]); w.y = cvt_pk_bf16(a[2], a[3]); w.z = cvt_pk_bf16(b[0], b[1]); w.w = cvt_pk_bf16(b[2], b[3]); return w; }
; #define PG8_WAIT_V(n) asm volatile("s_waitcnt vmcnt(" #n ")" ::: "memory")
; #define PG8_WAIT_L(n) asm volatile("s_waitcnt lgkmcnt(" #n ")" ::: "memory")
; #define PG8_BAR __builtin_amdgcn_s_barrier()
;     __device__ __forceinline__ void operator()(const f32x4 (&acc)[2][2][4][2], const Unit& u, int wr, int wc, int fr_, int fq_, int ui) const {
;         int fr = fr_, fq = fq_; asm volatile("" : "+v"(fr), "+v"(fq));
;         const int row0 = u.pm * BM + wr * 64 + fr;
;         float r[2][4]; load_rs(r, rsl, wr, fr);
;         if (u.pn < 8) {
;             const int col0 = u.pn * BM + wc * 32 + 8 * fq;
; #pragma unroll
;             for (int ai = 0; ai < 2; ++ai)
; #pragma unroll
;                 for (int m = 0; m < 4; ++m) { bf16_t* rowp = Q + (size_t)(row0 + ai * HALF + m * 16) * 3072 + col0;
; #pragma unroll
;                     for (int bj = 0; bj < 2; ++bj) *(PG8_G u32x4*)(rowp + bj * HALF) = pack8bf(acc[ai][bj][m][0] * r[ai][m], acc[ai][bj][m][1] * r[ai][m]); }
;         } else {
;             const int head = 4 * (u.pn - 8) + wc, i0 = 8 * fq;
; #pragma unroll
;             for (int ai = 0; ai < 2; ++ai)
; #pragma unroll
;                 for (int m = 0; m < 4; ++m) { const int row = row0 + ai * HALF + m * 16;
;                     const f32x4 c0 = *(const PG8_G f32x4*)(cosT + (size_t)row * 32 + i0), c1 = *(const PG8_G f32x4*)(cosT + (size_t)row * 32 + i0 + 4);
;                     const f32x4 s0 = *(const PG8_G f32x4*)(sinT + (size_t)row * 32 + i0), s1 = *(const PG8_G f32x4*)(sinT + (size_t)row * 32 + i0 + 4);
;                     const f32x4 x1a = acc[ai][0][m][0] * r[ai][m], x1b = acc[ai][0][m][1] * r[ai][m], x2a = acc[ai][1][m][0] * r[ai][m], x2b = acc[ai][1][m][1] * r[ai][m];
;     ...
;             PG8_WAIT_V(8); PG8_WAIT_L(0); PG8_BAR; PG8_MMA(0, 0, At, B0); PG8_MMA(0, 1, At, B1); PG8_BAR; PG8_SCHED;
;             PG8_LDA(At, 1, 1); PG8_STAGE(PG8_SB(1, 0), b3, voffB); PG8_STAGE(PG8_SB(1, 1), b3 + hstep, voffB); PG8_STAGE(PG8_SA(1, 0), a3, voffA);
;             PG8_WAIT_V(8); PG8_WAIT_L(0); PG8_BAR; PG8_MMA(1, 0, At, B0); PG8_MMA(1, 1, At, B1); PG8_BAR; PG8_SCHED;
	v_mfma_f32_16x16x32_bf16 v[64:67], v[132:135], v[180:183], v[64:67]
	v_mfma_f32_16x16x32_bf16 v[60:63], v[150:153], v[180:183], v[60:63]
	v_mfma_f32_16x16x32_bf16 v[52:55], v[132:135], v[188:191], v[52:55]
	v_mfma_f32_16x16x32_bf16 v[44:47], v[150:153], v[188:191], v[44:47]
	v_mfma_f32_16x16x32_bf16 v[36:39], v[132:135], v[196:199], v[36:39]
	v_mfma_f32_16x16x32_bf16 v[28:31], v[150:153], v[196:199], v[28:31]
	v_mfma_f32_16x16x32_bf16 v[20:23], v[132:135], v[214:217], v[20:23]
	v_mfma_f32_16x16x32_bf16 v[12:15], v[150:153], v[214:217], v[12:15]
	v_mfma_f32_16x16x32_bf16 v[64:67], v[146:149], v[184:187], v[64:67]
	v_mfma_f32_16x16x32_bf16 v[60:63], v[154:157], v[184:187], v[60:63]
	v_mfma_f32_16x16x32_bf16 v[52:55], v[146:149], v[192:195], v[52:55]
	v_mfma_f32_16x16x32_bf16 v[44:47], v[154:157], v[192:195], v[44:47]
	v_mfma_f32_16x16x32_bf16 v[36:39], v[146:149], v[210:213], v[36:39]
	v_mfma_f32_16x16x32_bf16 v[28:31], v[154:157], v[210:213], v[28:31]
	v_mfma_f32_16x16x32_bf16 v[20:23], v[146:149], v[218:221], v[20:23]
	v_mfma_f32_16x16x32_bf16 v[12:15], v[154:157], v[218:221], v[12:15]
	s_setprio 0
	s_setprio 1
	v_mfma_f32_16x16x32_bf16 v[56:59], v[158:161], v[180:183], v[56:59]
	v_mfma_f32_16x16x32_bf16 v[48:51], v[166:169], v[180:183], v[48:51]
	v_mfma_f32_16x16x32_bf16 v[40:43], v[158:161], v[188:191], v[40:43]
	v_mfma_f32_16x16x32_bf16 v[32:35], v[166:169], v[188:191], v[32:35]
	v_mfma_f32_16x16x32_bf16 v[24:27], v[158:161], v[196:199], v[24:27]
	v_mfma_f32_16x16x32_bf16 v[16:19], v[166:169], v[196:199], v[16:19]
	v_mfma_f32_16x16x32_bf16 v[8:11], v[158:161], v[214:217], v[8:11]
	v_mfma_f32_16x16x32_bf16 v[4:7], v[166:169], v[214:217], v[4:7]
	v_mfma_f32_16x16x32_bf16 v[56:59], v[162:165], v[184:187], v[56:59]
	v_mfma_f32_16x16x32_bf16 v[48:51], v[176:179], v[184:187], v[48:51]
	v_mfma_f32_16x16x32_bf16 v[40:43], v[162:165], v[192:195], v[40:43]
	v_mfma_f32_16x16x32_bf16 v[32:35], v[176:179], v[192:195], v[32:35]
	v_mfma_f32_16x16x32_bf16 v[24:27], v[162:165], v[210:213], v[24:27]
	v_mfma_f32_16x16x32_bf16 v[16:19], v[176:179], v[210:213], v[16:19]
	v_mfma_f32_16x16x32_bf16 v[8:11], v[162:165], v[218:221], v[8:11]
	v_mfma_f32_16x16x32_bf16 v[4:7], v[176:179], v[218:221], v[4:7]
	s_barrier
	s_setprio 0
	s_add_i32 s54, s54, 2
	s_add_u32 s52, s52, 0x100
	s_addc_u32 s53, s53, 0
	s_add_u32 s14, s14, 0x100
	s_addc_u32 s15, s15, 0
	s_cmp_gt_u32 s54, 5
	s_cbranch_scc0 .LBB0_301
	v_mov_b32_e32 v132, v3
	v_mov_b32_e32 v133, v172
	v_readlane_b32 s14, v254, 30
	v_add_u32_e32 v146, s1, v132
	v_lshl_add_u32 v132, v132, 2, s78
	ds_read2_b32 v[164:165], v132 offset1:16
	ds_read2_b32 v[158:159], v132 offset0:32 offset1:48
	ds_read2_b32 v[152:153], v132 offset0:128 offset1:144
	ds_read2_b32 v[148:149], v132 offset0:160 offset1:176
	s_add_i32 s14, s20, s14
	s_lshl_b32 s20, s14, 8
	s_cmp_gt_u32 s14, 7
	v_lshlrev_b32_e32 v168, 3, v133
	v_ashrrev_i32_e32 v147, 31, v146
	s_mov_b64 s[14:15], -1
	v_add_u32_e32 v166, 16, v146
	v_add_u32_e32 v162, 32, v146
	v_add_u32_e32 v160, 48, v146
	v_add_u32_e32 v156, 0x80, v146
	v_add_u32_e32 v154, 0x90, v146
	v_add_u32_e32 v150, 0xa0, v146
	s_cbranch_scc0 .LBB0_304
	v_ashrrev_i32_e32 v169, 31, v168
	v_lshlrev_b64 v[180:181], 7, v[146:147]
	v_lshl_add_u64 v[132:133], s[38:39], 0, v[180:181]
	v_lshlrev_b64 v[170:171], 2, v[168:169]
	v_lshl_add_u64 v[180:181], s[40:41], 0, v[180:181]
	v_lshl_add_u64 v[176:177], v[132:133], 0, v[170:171]
	v_lshl_add_u64 v[184:185], v[180:181], 0, v[170:171]
	global_load_dwordx4 v[132:135], v[176:177], off offset:16
	s_nop 0
	global_load_dwordx4 v[176:179], v[176:177], off
	s_nop 0
	global_load_dwordx4 v[180:183], v[184:185], off offset:16
	s_nop 0
	global_load_dwordx4 v[184:187], v[184:185], off
	s_waitcnt lgkmcnt(0)
	v_pk_mul_f32 v[188:189], v[130:131], v[164:165] op_sel_hi:[1,0]
	v_pk_mul_f32 v[196:197], v[122:123], v[164:165] op_sel_hi:[1,0]
	v_pk_mul_f32 v[190:191], v[128:129], v[164:165] op_sel_hi:[1,0]
	v_pk_mul_f32 v[194:195], v[124:125], v[164:165] op_sel_hi:[1,0]
	v_pk_mul_f32 v[198:199], v[120:121], v[164:165] op_sel_hi:[1,0]
	v_pk_mul_f32 v[208:209], v[112:113], v[164:165] op_sel_hi:[1,0]
	v_pk_mul_f32 v[192:193], v[126:127], v[164:165] op_sel_hi:[1,0]
	v_pk_mul_f32 v[206:207], v[114:115], v[164:165] op_sel_hi:[1,0]
	s_add_i32 s44, s0, s20
	s_mov_b64 s[48:49], 0x1000
	v_ashrrev_i32_e32 v167, 31, v166
	v_ashrrev_i32_e32 v163, 31, v162
	v_ashrrev_i32_e32 v161, 31, v160
	v_ashrrev_i32_e32 v157, 31, v156
	v_ashrrev_i32_e32 v155, 31, v154
	v_ashrrev_i32_e32 v151, 31, v150
	s_waitcnt vmcnt(0)
; #define PG8_G __attribute__((address_space(1)))
; __device__ __forceinline__ u32x4 pack8bf(const f32x4 a, const f32x4 b) { u32x4 w; w.x = cvt_pk_bf16(a[0], a[1]); w.y = cvt_pk_bf16(a[2], a[3]); w.z = cvt_pk_bf16(b[0], b[1]); w.w = cvt_pk_bf16(b[2], b[3]); return w; }
;     __device__ __forceinline__ void operator()(const f32x4 (&acc)[2][2][4][2], const Unit& u, int wr, int wc, int fr_, int fq_, int ui) const {
;     ...
; #pragma unroll
;             for (int ai = 0; ai < 2; ++ai)
; #pragma unroll
;                 for (int m = 0; m < 4; ++m) { const int row = row0 + ai * HALF + m * 16;
;                     const f32x4 c0 = *(const PG8_G f32x4*)(cosT + (size_t)row * 32 + i0), c1 = *(const PG8_G f32x4*)(cosT + (size_t)row * 32 + i0 + 4);
;                     const f32x4 s0 = *(const PG8_G f32x4*)(sinT + (size_t)row * 32 + i0), s1 = *(const PG8_G f32x4*)(sinT + (size_t)row * 32 + i0 + 4);
;                     const f32x4 x1a = acc[ai][0][m][0] * r[ai][m], x1b = acc[ai][0][m][1] * r[ai][m], x2a = acc[ai][1][m][0] * r[ai][m], x2b = acc[ai][1][m][1] * r[ai][m];
;                     const f32x4 y1a = x1a * c0 - x2a * s0, y1b = x1b * c1 - x2b * s1, y2a = x2a * c0 + x1a * s0, y2b = x2b * c1 + x1b * s1;
;                     bf16_t* dst = Q + (size_t)row * 3072 + 2048 + head * 64 + i0;
;                     *(PG8_G u32x4*)dst = pack8bf(y1a, y1b); *(PG8_G u32x4*)(dst + 32) = pack8bf(y2a, y2b); }
	v_pk_mul_f32 v[216:217], v[208:209], v[180:181]
	v_pk_mul_f32 v[210:211], v[196:197], v[186:187]
	v_pk_mul_f32 v[186:187], v[188:189], v[186:187]
	v_pk_mul_f32 v[212:213], v[198:199], v[184:185]
	v_pk_fma_f32 v[210:211], v[188:189], v[178:179], v[210:211] neg_lo:[0,0,1] neg_hi:[0,0,1]
	v_pk_mul_f32 v[184:185], v[190:191], v[184:185]
	v_pk_fma_f32 v[186:187], v[196:197], v[178:179], v[186:187]
	v_pk_mul_f32 v[178:179], v[194:195], v[180:181]
	v_pk_fma_f32 v[212:213], v[190:191], v[176:177], v[212:213] neg_lo:[0,0,1] neg_hi:[0,0,1]
	v_pk_mul_f32 v[214:215], v[206:207], v[182:183]
	v_pk_fma_f32 v[216:217], v[194:195], v[132:133], v[216:217] neg_lo:[0,0,1] neg_hi:[0,0,1]
	v_pk_fma_f32 v[184:185], v[198:199], v[176:177], v[184:185]
	v_pk_mul_f32 v[176:177], v[192:193], v[182:183]
	v_pk_fma_f32 v[182:183], v[208:209], v[132:133], v[178:179]
	v_mov_b64_e32 v[132:133], s[10:11]
	v_pk_fma_f32 v[214:215], v[192:193], v[134:135], v[214:215] neg_lo:[0,0,1] neg_hi:[0,0,1]
	v_pk_fma_f32 v[180:181], v[206:207], v[134:135], v[176:177]
	v_mad_i64_i32 v[134:135], s[14:15], v146, s26, v[132:133]
	s_lshl_b64 s[14:15], s[44:45], 1
	s_nop 0
	v_lshl_add_u64 v[176:177], v[134:135], 0, s[14:15]
	v_lshlrev_b64 v[134:135], 1, v[168:169]
	v_lshl_add_u64 v[188:189], v[176:177], 0, v[134:135]
	v_lshl_add_u64 v[190:191], v[188:189], 0, s[48:49]
	v_add_co_u32_e32 v188, vcc, s27, v188
	v_cvt_pk_bf16_f32 v176, v212, v213
	v_cvt_pk_bf16_f32 v177, v210, v211
	v_cvt_pk_bf16_f32 v178, v216, v217
	v_cvt_pk_bf16_f32 v179, v214, v215
	s_nop 1
	v_addc_co_u32_e32 v189, vcc, 0, v189, vcc
	global_store_dwordx4 v[188:189], v[176:179], off
	v_mov_b32_e32 v192, v165
	v_pk_mul_f32 v[194:195], v[118:119], v[192:193] op_sel_hi:[1,0]
	v_cvt_pk_bf16_f32 v176, v184, v185
	v_cvt_pk_bf16_f32 v177, v186, v187
	v_lshlrev_b64 v[184:185], 7, v[166:167]
	v_cvt_pk_bf16_f32 v178, v182, v183
	v_cvt_pk_bf16_f32 v179, v180, v181
	global_store_dwordx4 v[190:191], v[176:179], off offset:64
	v_pk_mul_f32 v[196:197], v[116:117], v[192:193] op_sel_hi:[1,0]
	v_pk_mul_f32 v[198:199], v[110:111], v[192:193] op_sel_hi:[1,0]
	v_lshl_add_u64 v[176:177], s[38:39], 0, v[184:185]
	v_lshl_add_u64 v[184:185], s[40:41], 0, v[184:185]
	v_lshl_add_u64 v[180:181], v[176:177], 0, v[170:171]
	v_lshl_add_u64 v[188:189], v[184:185], 0, v[170:171]
	global_load_dwordx4 v[176:179], v[180:181], off offset:16
	s_nop 0
	global_load_dwordx4 v[180:183], v[180:181], off
	s_nop 0
	global_load_dwordx4 v[184:187], v[188:189], off offset:16
	s_nop 0
	global_load_dwordx4 v[188:191], v[188:189], off
	v_pk_mul_f32 v[206:207], v[108:109], v[192:193] op_sel_hi:[1,0]
	v_pk_mul_f32 v[208:209], v[106:107], v[192:193] op_sel_hi:[1,0]
	v_pk_mul_f32 v[210:211], v[104:105], v[192:193] op_sel_hi:[1,0]
	v_pk_mul_f32 v[212:213], v[98:99], v[192:193] op_sel_hi:[1,0]
	v_pk_mul_f32 v[192:193], v[96:97], v[192:193] op_sel_hi:[1,0]
	s_waitcnt vmcnt(1)
	v_pk_mul_f32 v[218:219], v[212:213], v[186:187]
	v_pk_mul_f32 v[220:221], v[192:193], v[184:185]
	v_pk_mul_f32 v[184:185], v[206:207], v[184:185]
	v_pk_fma_f32 v[220:221], v[206:207], v[176:177], v[220:221] neg_lo:[0,0,1] neg_hi:[0,0,1]
	v_pk_fma_f32 v[184:185], v[192:193], v[176:177], v[184:185]
	v_mad_i64_i32 v[176:177], s[24:25], v166, s26, v[132:133]
	s_waitcnt vmcnt(0)
	v_pk_mul_f32 v[216:217], v[210:211], v[188:189]
	v_pk_mul_f32 v[188:189], v[196:197], v[188:189]
	v_lshl_add_u64 v[176:177], v[176:177], 0, s[14:15]
	v_pk_mul_f32 v[214:215], v[208:209], v[190:191]
	v_pk_fma_f32 v[216:217], v[196:197], v[180:181], v[216:217] neg_lo:[0,0,1] neg_hi:[0,0,1]
	v_pk_mul_f32 v[190:191], v[194:195], v[190:191]
	v_pk_fma_f32 v[180:181], v[210:211], v[180:181], v[188:189]
	v_lshl_add_u64 v[188:189], v[176:177], 0, v[134:135]
	v_pk_fma_f32 v[214:215], v[194:195], v[182:183], v[214:215] neg_lo:[0,0,1] neg_hi:[0,0,1]
	v_pk_fma_f32 v[182:183], v[208:209], v[182:183], v[190:191]
	v_pk_mul_f32 v[186:187], v[198:199], v[186:187]
	v_lshl_add_u64 v[190:191], v[188:189], 0, s[48:49]
	v_add_co_u32_e32 v188, vcc, s27, v188
	v_pk_fma_f32 v[218:219], v[198:199], v[178:179], v[218:219] neg_lo:[0,0,1] neg_hi:[0,0,1]
	v_pk_fma_f32 v[186:187], v[212:213], v[178:179], v[186:187]
	v_cvt_pk_bf16_f32 v176, v216, v217
	v_cvt_pk_bf16_f32 v177, v214, v215
	v_cvt_pk_bf16_f32 v178, v220, v221
	v_addc_co_u32_e32 v189, vcc, 0, v189, vcc
	v_cvt_pk_bf16_f32 v179, v218, v219
	global_store_dwordx4 v[188:189], v[176:179], off
	v_pk_mul_f32 v[198:199], v[92:93], v[158:159] op_sel_hi:[1,0]
	v_pk_mul_f32 v[212:213], v[80:81], v[158:159] op_sel_hi:[1,0]
	v_cvt_pk_bf16_f32 v176, v180, v181
	v_cvt_pk_bf16_f32 v177, v182, v183
	v_cvt_pk_bf16_f32 v178, v184, v185
	v_lshlrev_b64 v[184:185], 7, v[162:163]
	v_cvt_pk_bf16_f32 v179, v186, v187
	global_store_dwordx4 v[190:191], v[176:179], off offset:64
	v_pk_mul_f32 v[194:195], v[100:101], v[158:159] op_sel_hi:[1,0]
	v_pk_mul_f32 v[208:209], v[88:89], v[158:159] op_sel_hi:[1,0]
	v_lshl_add_u64 v[176:177], s[38:39], 0, v[184:185]
	v_lshl_add_u64 v[184:185], s[40:41], 0, v[184:185]
	v_lshl_add_u64 v[180:181], v[176:177], 0, v[170:171]
	v_lshl_add_u64 v[188:189], v[184:185], 0, v[170:171]
	global_load_dwordx4 v[176:179], v[180:181], off offset:16
	s_nop 0
	global_load_dwordx4 v[180:183], v[180:181], off
	s_nop 0
	global_load_dwordx4 v[184:187], v[188:189], off offset:16
	s_nop 0
	global_load_dwordx4 v[188:191], v[188:189], off
	v_pk_mul_f32 v[192:193], v[102:103], v[158:159] op_sel_hi:[1,0]
	v_pk_mul_f32 v[206:207], v[90:91], v[158:159] op_sel_hi:[1,0]
	v_pk_mul_f32 v[196:197], v[94:95], v[158:159] op_sel_hi:[1,0]
	v_pk_mul_f32 v[210:211], v[82:83], v[158:159] op_sel_hi:[1,0]
	s_waitcnt vmcnt(1)
; #define PG8_G __attribute__((address_space(1)))
; __device__ __forceinline__ u32x4 pack8bf(const f32x4 a, const f32x4 b) { u32x4 w; w.x = cvt_pk_bf16(a[0], a[1]); w.y = cvt_pk_bf16(a[2], a[3]); w.z = cvt_pk_bf16(b[0], b[1]); w.w = cvt_pk_bf16(b[2], b[3]); return w; }
;     __device__ __forceinline__ void operator()(const f32x4 (&acc)[2][2][4][2], const Unit& u, int wr, int wc, int fr_, int fq_, int ui) const {
;     ...
; #pragma unroll
;             for (int ai = 0; ai < 2; ++ai)
; #pragma unroll
;                 for (int m = 0; m < 4; ++m) { const int row = row0 + ai * HALF + m * 16;
;                     const f32x4 c0 = *(const PG8_G f32x4*)(cosT + (size_t)row * 32 + i0), c1 = *(const PG8_G f32x4*)(cosT + (size_t)row * 32 + i0 + 4);
;                     const f32x4 s0 = *(const PG8_G f32x4*)(sinT + (size_t)row * 32 + i0), s1 = *(const PG8_G f32x4*)(sinT + (size_t)row * 32 + i0 + 4);
;                     const f32x4 x1a = acc[ai][0][m][0] * r[ai][m], x1b = acc[ai][0][m][1] * r[ai][m], x2a = acc[ai][1][m][0] * r[ai][m], x2b = acc[ai][1][m][1] * r[ai][m];
;                     const f32x4 y1a = x1a * c0 - x2a * s0, y1b = x1b * c1 - x2b * s1, y2a = x2a * c0 + x1a * s0, y2b = x2b * c1 + x1b * s1;
;                     bf16_t* dst = Q + (size_t)row * 3072 + 2048 + head * 64 + i0;
;                     *(PG8_G u32x4*)dst = pack8bf(y1a, y1b); *(PG8_G u32x4*)(dst + 32) = pack8bf(y2a, y2b); }
	v_pk_mul_f32 v[220:221], v[212:213], v[184:185]
	v_pk_mul_f32 v[184:185], v[198:199], v[184:185]
	v_pk_fma_f32 v[220:221], v[198:199], v[176:177], v[220:221] neg_lo:[0,0,1] neg_hi:[0,0,1]
	v_pk_fma_f32 v[184:185], v[212:213], v[176:177], v[184:185]
	v_mad_i64_i32 v[176:177], s[24:25], v162, s26, v[132:133]
	s_waitcnt vmcnt(0)
	v_pk_mul_f32 v[216:217], v[208:209], v[188:189]
	v_pk_mul_f32 v[188:189], v[194:195], v[188:189]
	v_lshl_add_u64 v[176:177], v[176:177], 0, s[14:15]
	v_pk_mul_f32 v[214:215], v[206:207], v[190:191]
	v_pk_fma_f32 v[216:217], v[194:195], v[180:181], v[216:217] neg_lo:[0,0,1] neg_hi:[0,0,1]
	v_pk_mul_f32 v[190:191], v[192:193], v[190:191]
	v_pk_fma_f32 v[180:181], v[208:209], v[180:181], v[188:189]
	v_lshl_add_u64 v[188:189], v[176:177], 0, v[134:135]
	v_pk_fma_f32 v[214:215], v[192:193], v[182:183], v[214:215] neg_lo:[0,0,1] neg_hi:[0,0,1]
	v_pk_mul_f32 v[218:219], v[210:211], v[186:187]
	v_pk_fma_f32 v[182:183], v[206:207], v[182:183], v[190:191]
	v_pk_mul_f32 v[186:187], v[196:197], v[186:187]
	v_lshl_add_u64 v[190:191], v[188:189], 0, s[48:49]
	v_add_co_u32_e32 v188, vcc, s27, v188
	v_pk_fma_f32 v[218:219], v[196:197], v[178:179], v[218:219] neg_lo:[0,0,1] neg_hi:[0,0,1]
	v_pk_fma_f32 v[186:187], v[210:211], v[178:179], v[186:187]
	v_cvt_pk_bf16_f32 v176, v216, v217
	v_cvt_pk_bf16_f32 v177, v214, v215
	v_cvt_pk_bf16_f32 v178, v220, v221
	v_addc_co_u32_e32 v189, vcc, 0, v189, vcc
	v_cvt_pk_bf16_f32 v179, v218, v219
	global_store_dwordx4 v[188:189], v[176:179], off
	v_mov_b32_e32 v192, v159
	v_pk_mul_f32 v[194:195], v[86:87], v[192:193] op_sel_hi:[1,0]
	v_cvt_pk_bf16_f32 v176, v180, v181
	v_cvt_pk_bf16_f32 v177, v182, v183
	v_cvt_pk_bf16_f32 v178, v184, v185
	v_lshlrev_b64 v[184:185], 7, v[160:161]
	v_cvt_pk_bf16_f32 v179, v186, v187
	global_store_dwordx4 v[190:191], v[176:179], off offset:64
	v_pk_mul_f32 v[196:197], v[84:85], v[192:193] op_sel_hi:[1,0]
	v_pk_mul_f32 v[198:199], v[78:79], v[192:193] op_sel_hi:[1,0]
	v_lshl_add_u64 v[176:177], s[38:39], 0, v[184:185]
	v_lshl_add_u64 v[184:185], s[40:41], 0, v[184:185]
	v_lshl_add_u64 v[180:181], v[176:177], 0, v[170:171]
	v_lshl_add_u64 v[188:189], v[184:185], 0, v[170:171]
	global_load_dwordx4 v[176:179], v[180:181], off offset:16
	s_nop 0
	global_load_dwordx4 v[180:183], v[180:181], off
	s_nop 0
	global_load_dwordx4 v[184:187], v[188:189], off offset:16
	s_nop 0
	global_load_dwordx4 v[188:191], v[188:189], off
	v_pk_mul_f32 v[206:207], v[76:77], v[192:193] op_sel_hi:[1,0]
	v_pk_mul_f32 v[208:209], v[74:75], v[192:193] op_sel_hi:[1,0]
	v_pk_mul_f32 v[210:211], v[72:73], v[192:193] op_sel_hi:[1,0]
	v_pk_mul_f32 v[212:213], v[70:71], v[192:193] op_sel_hi:[1,0]
	v_pk_mul_f32 v[192:193], v[68:69], v[192:193] op_sel_hi:[1,0]
	s_waitcnt vmcnt(1)
	v_pk_mul_f32 v[218:219], v[212:213], v[186:187]
	v_pk_mul_f32 v[220:221], v[192:193], v[184:185]
	v_pk_mul_f32 v[184:185], v[206:207], v[184:185]
	v_pk_fma_f32 v[220:221], v[206:207], v[176:177], v[220:221] neg_lo:[0,0,1] neg_hi:[0,0,1]
	v_pk_fma_f32 v[184:185], v[192:193], v[176:177], v[184:185]
	v_mad_i64_i32 v[176:177], s[24:25], v160, s26, v[132:133]
	s_waitcnt vmcnt(0)
	v_pk_mul_f32 v[216:217], v[210:211], v[188:189]
	v_pk_mul_f32 v[188:189], v[196:197], v[188:189]
	v_lshl_add_u64 v[176:177], v[176:177], 0, s[14:15]
	v_pk_mul_f32 v[214:215], v[208:209], v[190:191]
	v_pk_fma_f32 v[216:217], v[196:197], v[180:181], v[216:217] neg_lo:[0,0,1] neg_hi:[0,0,1]
	v_pk_mul_f32 v[190:191], v[194:195], v[190:191]
	v_pk_fma_f32 v[180:181], v[210:211], v[180:181], v[188:189]
	v_lshl_add_u64 v[188:189], v[176:177], 0, v[134:135]
	v_pk_fma_f32 v[214:215], v[194:195], v[182:183], v[214:215] neg_lo:[0,0,1] neg_hi:[0,0,1]
	v_pk_fma_f32 v[182:183], v[208:209], v[182:183], v[190:191]
	v_pk_mul_f32 v[186:187], v[198:199], v[186:187]
	v_lshl_add_u64 v[190:191], v[188:189], 0, s[48:49]
	v_add_co_u32_e32 v188, vcc, s27, v188
	v_pk_fma_f32 v[218:219], v[198:199], v[178:179], v[218:219] neg_lo:[0,0,1] neg_hi:[0,0,1]
	v_pk_fma_f32 v[186:187], v[212:213], v[178:179], v[186:187]
	v_cvt_pk_bf16_f32 v176, v216, v217
	v_cvt_pk_bf16_f32 v177, v214, v215
	v_cvt_pk_bf16_f32 v178, v220, v221
	v_addc_co_u32_e32 v189, vcc, 0, v189, vcc
	v_cvt_pk_bf16_f32 v179, v218, v219
	global_store_dwordx4 v[188:189], v[176:179], off
	v_pk_mul_f32 v[198:199], v[60:61], v[152:153] op_sel_hi:[1,0]
	v_pk_mul_f32 v[212:213], v[48:49], v[152:153] op_sel_hi:[1,0]
	v_cvt_pk_bf16_f32 v176, v180, v181
	v_cvt_pk_bf16_f32 v177, v182, v183
	v_cvt_pk_bf16_f32 v178, v184, v185
	v_lshlrev_b64 v[184:185], 7, v[156:157]
	v_cvt_pk_bf16_f32 v179, v186, v187
	global_store_dwordx4 v[190:191], v[176:179], off offset:64
	v_pk_mul_f32 v[194:195], v[64:65], v[152:153] op_sel_hi:[1,0]
	v_pk_mul_f32 v[208:209], v[56:57], v[152:153] op_sel_hi:[1,0]
	v_lshl_add_u64 v[176:177], s[38:39], 0, v[184:185]
	v_lshl_add_u64 v[184:185], s[40:41], 0, v[184:185]
	v_lshl_add_u64 v[180:181], v[176:177], 0, v[170:171]
	v_lshl_add_u64 v[188:189], v[184:185], 0, v[170:171]
	global_load_dwordx4 v[176:179], v[180:181], off offset:16
	s_nop 0
	global_load_dwordx4 v[180:183], v[180:181], off
	s_nop 0
	global_load_dwordx4 v[184:187], v[188:189], off offset:16
	s_nop 0
	global_load_dwordx4 v[188:191], v[188:189], off
	v_pk_mul_f32 v[192:193], v[66:67], v[152:153] op_sel_hi:[1,0]
	v_pk_mul_f32 v[206:207], v[58:59], v[152:153] op_sel_hi:[1,0]
	v_pk_mul_f32 v[196:197], v[62:63], v[152:153] op_sel_hi:[1,0]
	v_pk_mul_f32 v[210:211], v[50:51], v[152:153] op_sel_hi:[1,0]
	s_waitcnt vmcnt(1)
; #define PG8_G __attribute__((address_space(1)))
; __device__ __forceinline__ u32x4 pack8bf(const f32x4 a, const f32x4 b) { u32x4 w; w.x = cvt_pk_bf16(a[0], a[1]); w.y = cvt_pk_bf16(a[2], a[3]); w.z = cvt_pk_bf16(b[0], b[1]); w.w = cvt_pk_bf16(b[2], b[3]); return w; }
;     __device__ __forceinline__ void operator()(const f32x4 (&acc)[2][2][4][2], const Unit& u, int wr, int wc, int fr_, int fq_, int ui) const {
;     ...
; #pragma unroll
;             for (int ai = 0; ai < 2; ++ai)
; #pragma unroll
;                 for (int m = 0; m < 4; ++m) { const int row = row0 + ai * HALF + m * 16;
;                     const f32x4 c0 = *(const PG8_G f32x4*)(cosT + (size_t)row * 32 + i0), c1 = *(const PG8_G f32x4*)(cosT + (size_t)row * 32 + i0 + 4);
;                     const f32x4 s0 = *(const PG8_G f32x4*)(sinT + (size_t)row * 32 + i0), s1 = *(const PG8_G f32x4*)(sinT + (size_t)row * 32 + i0 + 4);
;                     const f32x4 x1a = acc[ai][0][m][0] * r[ai][m], x1b = acc[ai][0][m][1] * r[ai][m], x2a = acc[ai][1][m][0] * r[ai][m], x2b = acc[ai][1][m][1] * r[ai][m];
;                     const f32x4 y1a = x1a * c0 - x2a * s0, y1b = x1b * c1 - x2b * s1, y2a = x2a * c0 + x1a * s0, y2b = x2b * c1 + x1b * s1;
;                     bf16_t* dst = Q + (size_t)row * 3072 + 2048 + head * 64 + i0;
;                     *(PG8_G u32x4*)dst = pack8bf(y1a, y1b); *(PG8_G u32x4*)(dst + 32) = pack8bf(y2a, y2b); }
	v_pk_mul_f32 v[220:221], v[212:213], v[184:185]
	v_pk_mul_f32 v[184:185], v[198:199], v[184:185]
	v_pk_fma_f32 v[220:221], v[198:199], v[176:177], v[220:221] neg_lo:[0,0,1] neg_hi:[0,0,1]
	v_pk_fma_f32 v[184:185], v[212:213], v[176:177], v[184:185]
	v_mad_i64_i32 v[176:177], s[24:25], v156, s26, v[132:133]
	s_waitcnt vmcnt(0)
	v_pk_mul_f32 v[216:217], v[208:209], v[188:189]
	v_pk_mul_f32 v[188:189], v[194:195], v[188:189]
	v_lshl_add_u64 v[176:177], v[176:177], 0, s[14:15]
	v_pk_mul_f32 v[214:215], v[206:207], v[190:191]
	v_pk_fma_f32 v[216:217], v[194:195], v[180:181], v[216:217] neg_lo:[0,0,1] neg_hi:[0,0,1]
	v_pk_mul_f32 v[190:191], v[192:193], v[190:191]
	v_pk_fma_f32 v[180:181], v[208:209], v[180:181], v[188:189]
	v_lshl_add_u64 v[188:189], v[176:177], 0, v[134:135]
	v_pk_fma_f32 v[214:215], v[192:193], v[182:183], v[214:215] neg_lo:[0,0,1] neg_hi:[0,0,1]
	v_pk_mul_f32 v[218:219], v[210:211], v[186:187]
	v_pk_fma_f32 v[182:183], v[206:207], v[182:183], v[190:191]
	v_pk_mul_f32 v[186:187], v[196:197], v[186:187]
	v_lshl_add_u64 v[190:191], v[188:189], 0, s[48:49]
	v_add_co_u32_e32 v188, vcc, s27, v188
	v_pk_fma_f32 v[218:219], v[196:197], v[178:179], v[218:219] neg_lo:[0,0,1] neg_hi:[0,0,1]
	v_pk_fma_f32 v[186:187], v[210:211], v[178:179], v[186:187]
	v_cvt_pk_bf16_f32 v176, v216, v217
	v_cvt_pk_bf16_f32 v177, v214, v215
	v_cvt_pk_bf16_f32 v178, v220, v221
	v_addc_co_u32_e32 v189, vcc, 0, v189, vcc
	v_cvt_pk_bf16_f32 v179, v218, v219
	global_store_dwordx4 v[188:189], v[176:179], off
	v_mov_b32_e32 v192, v153
	v_pk_mul_f32 v[194:195], v[54:55], v[192:193] op_sel_hi:[1,0]
	v_cvt_pk_bf16_f32 v176, v180, v181
	v_cvt_pk_bf16_f32 v177, v182, v183
	v_cvt_pk_bf16_f32 v178, v184, v185
	v_lshlrev_b64 v[184:185], 7, v[154:155]
	v_cvt_pk_bf16_f32 v179, v186, v187
	global_store_dwordx4 v[190:191], v[176:179], off offset:64
	v_pk_mul_f32 v[196:197], v[52:53], v[192:193] op_sel_hi:[1,0]
	v_pk_mul_f32 v[198:199], v[46:47], v[192:193] op_sel_hi:[1,0]
	v_lshl_add_u64 v[176:177], s[38:39], 0, v[184:185]
	v_lshl_add_u64 v[184:185], s[40:41], 0, v[184:185]
	v_lshl_add_u64 v[180:181], v[176:177], 0, v[170:171]
	v_lshl_add_u64 v[188:189], v[184:185], 0, v[170:171]
	global_load_dwordx4 v[176:179], v[180:181], off offset:16
	s_nop 0
	global_load_dwordx4 v[180:183], v[180:181], off
	s_nop 0
	global_load_dwordx4 v[184:187], v[188:189], off offset:16
	s_nop 0
	global_load_dwordx4 v[188:191], v[188:189], off
	v_pk_mul_f32 v[206:207], v[44:45], v[192:193] op_sel_hi:[1,0]
	v_pk_mul_f32 v[208:209], v[42:43], v[192:193] op_sel_hi:[1,0]
	v_pk_mul_f32 v[210:211], v[40:41], v[192:193] op_sel_hi:[1,0]
	v_pk_mul_f32 v[212:213], v[34:35], v[192:193] op_sel_hi:[1,0]
	v_pk_mul_f32 v[192:193], v[32:33], v[192:193] op_sel_hi:[1,0]
	s_waitcnt vmcnt(1)
	v_pk_mul_f32 v[218:219], v[212:213], v[186:187]
	v_pk_mul_f32 v[220:221], v[192:193], v[184:185]
	v_pk_mul_f32 v[184:185], v[206:207], v[184:185]
	v_pk_fma_f32 v[220:221], v[206:207], v[176:177], v[220:221] neg_lo:[0,0,1] neg_hi:[0,0,1]
	v_pk_fma_f32 v[184:185], v[192:193], v[176:177], v[184:185]
	v_mad_i64_i32 v[176:177], s[24:25], v154, s26, v[132:133]
	s_waitcnt vmcnt(0)
	v_pk_mul_f32 v[216:217], v[210:211], v[188:189]
	v_pk_mul_f32 v[188:189], v[196:197], v[188:189]
	v_lshl_add_u64 v[176:177], v[176:177], 0, s[14:15]
	v_pk_mul_f32 v[214:215], v[208:209], v[190:191]
	v_pk_fma_f32 v[216:217], v[196:197], v[180:181], v[216:217] neg_lo:[0,0,1] neg_hi:[0,0,1]
	v_pk_mul_f32 v[190:191], v[194:195], v[190:191]
	v_pk_fma_f32 v[180:181], v[210:211], v[180:181], v[188:189]
	v_lshl_add_u64 v[188:189], v[176:177], 0, v[134:135]
	v_pk_fma_f32 v[214:215], v[194:195], v[182:183], v[214:215] neg_lo:[0,0,1] neg_hi:[0,0,1]
	v_pk_fma_f32 v[182:183], v[208:209], v[182:183], v[190:191]
	v_pk_mul_f32 v[186:187], v[198:199], v[186:187]
	v_lshl_add_u64 v[190:191], v[188:189], 0, s[48:49]
	v_add_co_u32_e32 v188, vcc, s27, v188
	v_pk_fma_f32 v[218:219], v[198:199], v[178:179], v[218:219] neg_lo:[0,0,1] neg_hi:[0,0,1]
	v_pk_fma_f32 v[186:187], v[212:213], v[178:179], v[186:187]
	v_cvt_pk_bf16_f32 v176, v216, v217
	v_cvt_pk_bf16_f32 v177, v214, v215
	v_cvt_pk_bf16_f32 v178, v220, v221
	v_addc_co_u32_e32 v189, vcc, 0, v189, vcc
	v_cvt_pk_bf16_f32 v179, v218, v219
	global_store_dwordx4 v[188:189], v[176:179], off
	v_pk_mul_f32 v[198:199], v[28:29], v[148:149] op_sel_hi:[1,0]
	v_pk_mul_f32 v[212:213], v[16:17], v[148:149] op_sel_hi:[1,0]
	v_cvt_pk_bf16_f32 v176, v180, v181
	v_cvt_pk_bf16_f32 v177, v182, v183
	v_cvt_pk_bf16_f32 v178, v184, v185
	v_lshlrev_b64 v[184:185], 7, v[150:151]
	v_cvt_pk_bf16_f32 v179, v186, v187
	global_store_dwordx4 v[190:191], v[176:179], off offset:64
	v_pk_mul_f32 v[194:195], v[36:37], v[148:149] op_sel_hi:[1,0]
	v_pk_mul_f32 v[208:209], v[24:25], v[148:149] op_sel_hi:[1,0]
	v_lshl_add_u64 v[176:177], s[38:39], 0, v[184:185]
	v_lshl_add_u64 v[184:185], s[40:41], 0, v[184:185]
	v_lshl_add_u64 v[180:181], v[176:177], 0, v[170:171]
	v_lshl_add_u64 v[188:189], v[184:185], 0, v[170:171]
	global_load_dwordx4 v[176:179], v[180:181], off offset:16
	s_nop 0
	global_load_dwordx4 v[180:183], v[180:181], off
	s_nop 0
	global_load_dwordx4 v[184:187], v[188:189], off offset:16
	s_nop 0
	global_load_dwordx4 v[188:191], v[188:189], off
	v_pk_mul_f32 v[192:193], v[38:39], v[148:149] op_sel_hi:[1,0]
	v_pk_mul_f32 v[206:207], v[26:27], v[148:149] op_sel_hi:[1,0]
	v_pk_mul_f32 v[196:197], v[30:31], v[148:149] op_sel_hi:[1,0]
	v_pk_mul_f32 v[210:211], v[18:19], v[148:149] op_sel_hi:[1,0]
	s_waitcnt vmcnt(1)
; #define PG8_G __attribute__((address_space(1)))
; __device__ __forceinline__ u32x4 pack8bf(const f32x4 a, const f32x4 b) { u32x4 w; w.x = cvt_pk_bf16(a[0], a[1]); w.y = cvt_pk_bf16(a[2], a[3]); w.z = cvt_pk_bf16(b[0], b[1]); w.w = cvt_pk_bf16(b[2], b[3]); return w; }
;     __device__ __forceinline__ void operator()(const f32x4 (&acc)[2][2][4][2], const Unit& u, int wr, int wc, int fr_, int fq_, int ui) const {
;     ...
; #pragma unroll
;             for (int ai = 0; ai < 2; ++ai)
; #pragma unroll
;                 for (int m = 0; m < 4; ++m) { const int row = row0 + ai * HALF + m * 16;
;                     const f32x4 c0 = *(const PG8_G f32x4*)(cosT + (size_t)row * 32 + i0), c1 = *(const PG8_G f32x4*)(cosT + (size_t)row * 32 + i0 + 4);
;                     const f32x4 s0 = *(const PG8_G f32x4*)(sinT + (size_t)row * 32 + i0), s1 = *(const PG8_G f32x4*)(sinT + (size_t)row * 32 + i0 + 4);
;                     const f32x4 x1a = acc[ai][0][m][0] * r[ai][m], x1b = acc[ai][0][m][1] * r[ai][m], x2a = acc[ai][1][m][0] * r[ai][m], x2b = acc[ai][1][m][1] * r[ai][m];
;                     const f32x4 y1a = x1a * c0 - x2a * s0, y1b = x1b * c1 - x2b * s1, y2a = x2a * c0 + x1a * s0, y2b = x2b * c1 + x1b * s1;
;                     bf16_t* dst = Q + (size_t)row * 3072 + 2048 + head * 64 + i0;
;                     *(PG8_G u32x4*)dst = pack8bf(y1a, y1b); *(PG8_G u32x4*)(dst + 32) = pack8bf(y2a, y2b); }
	v_pk_mul_f32 v[220:221], v[212:213], v[184:185]
	v_pk_mul_f32 v[184:185], v[198:199], v[184:185]
	v_pk_fma_f32 v[220:221], v[198:199], v[176:177], v[220:221] neg_lo:[0,0,1] neg_hi:[0,0,1]
	v_pk_fma_f32 v[184:185], v[212:213], v[176:177], v[184:185]
	v_mad_i64_i32 v[176:177], s[24:25], v150, s26, v[132:133]
	s_waitcnt vmcnt(0)
	v_pk_mul_f32 v[216:217], v[208:209], v[188:189]
	v_pk_mul_f32 v[188:189], v[194:195], v[188:189]
	v_lshl_add_u64 v[176:177], v[176:177], 0, s[14:15]
	v_pk_mul_f32 v[214:215], v[206:207], v[190:191]
	v_pk_fma_f32 v[216:217], v[194:195], v[180:181], v[216:217] neg_lo:[0,0,1] neg_hi:[0,0,1]
	v_pk_mul_f32 v[190:191], v[192:193], v[190:191]
	v_pk_fma_f32 v[180:181], v[208:209], v[180:181], v[188:189]
	v_lshl_add_u64 v[188:189], v[176:177], 0, v[134:135]
	v_pk_fma_f32 v[214:215], v[192:193], v[182:183], v[214:215] neg_lo:[0,0,1] neg_hi:[0,0,1]
	v_pk_mul_f32 v[218:219], v[210:211], v[186:187]
	v_pk_fma_f32 v[182:183], v[206:207], v[182:183], v[190:191]
	v_pk_mul_f32 v[186:187], v[196:197], v[186:187]
	v_lshl_add_u64 v[190:191], v[188:189], 0, s[48:49]
	v_add_co_u32_e32 v188, vcc, s27, v188
	v_add_u32_e32 v192, 0xb0, v146
	v_pk_fma_f32 v[218:219], v[196:197], v[178:179], v[218:219] neg_lo:[0,0,1] neg_hi:[0,0,1]
	v_pk_fma_f32 v[186:187], v[210:211], v[178:179], v[186:187]
	v_cvt_pk_bf16_f32 v176, v216, v217
	v_cvt_pk_bf16_f32 v177, v214, v215
	v_cvt_pk_bf16_f32 v178, v220, v221
	v_addc_co_u32_e32 v189, vcc, 0, v189, vcc
	v_ashrrev_i32_e32 v193, 31, v192
	v_cvt_pk_bf16_f32 v179, v218, v219
	global_store_dwordx4 v[188:189], v[176:179], off
	v_mad_i64_i32 v[132:133], s[24:25], v192, s26, v[132:133]
	s_nop 0
	v_cvt_pk_bf16_f32 v176, v180, v181
	v_cvt_pk_bf16_f32 v177, v182, v183
	v_cvt_pk_bf16_f32 v178, v184, v185
	v_lshlrev_b64 v[184:185], 7, v[192:193]
	v_cvt_pk_bf16_f32 v179, v186, v187
	global_store_dwordx4 v[190:191], v[176:179], off offset:64
	v_lshl_add_u64 v[132:133], v[132:133], 0, s[14:15]
	s_mov_b64 s[14:15], 0x1040
	v_lshl_add_u64 v[176:177], s[38:39], 0, v[184:185]
	v_lshl_add_u64 v[184:185], s[40:41], 0, v[184:185]
	v_lshl_add_u64 v[180:181], v[176:177], 0, v[170:171]
	v_lshl_add_u64 v[170:171], v[184:185], 0, v[170:171]
	global_load_dwordx4 v[176:179], v[180:181], off offset:16
	s_nop 0
	global_load_dwordx4 v[180:183], v[180:181], off
	s_nop 0
	global_load_dwordx4 v[184:187], v[170:171], off offset:16
	global_load_dwordx4 v[188:191], v[170:171], off
	v_mov_b32_e32 v170, v149
	v_pk_mul_f32 v[194:195], v[22:23], v[170:171] op_sel_hi:[1,0]
	v_pk_mul_f32 v[196:197], v[20:21], v[170:171] op_sel_hi:[1,0]
	v_pk_mul_f32 v[198:199], v[14:15], v[170:171] op_sel_hi:[1,0]
	v_pk_mul_f32 v[206:207], v[12:13], v[170:171] op_sel_hi:[1,0]
	v_pk_mul_f32 v[208:209], v[10:11], v[170:171] op_sel_hi:[1,0]
	v_pk_mul_f32 v[210:211], v[8:9], v[170:171] op_sel_hi:[1,0]
	v_pk_mul_f32 v[212:213], v[6:7], v[170:171] op_sel_hi:[1,0]
	v_pk_mul_f32 v[170:171], v[4:5], v[170:171] op_sel_hi:[1,0]
	s_waitcnt vmcnt(1)
	v_pk_mul_f32 v[218:219], v[212:213], v[186:187]
	v_pk_mul_f32 v[220:221], v[170:171], v[184:185]
	v_pk_mul_f32 v[184:185], v[206:207], v[184:185]
	v_pk_fma_f32 v[220:221], v[206:207], v[176:177], v[220:221] neg_lo:[0,0,1] neg_hi:[0,0,1]
	v_pk_fma_f32 v[170:171], v[170:171], v[176:177], v[184:185]
	v_lshl_add_u64 v[176:177], v[132:133], 0, v[134:135]
	s_waitcnt vmcnt(0)
	v_pk_mul_f32 v[214:215], v[208:209], v[190:191]
	v_pk_mul_f32 v[216:217], v[210:211], v[188:189]
	v_add_co_u32_e32 v184, vcc, s27, v176
	v_pk_fma_f32 v[214:215], v[194:195], v[182:183], v[214:215] neg_lo:[0,0,1] neg_hi:[0,0,1]
	v_pk_fma_f32 v[216:217], v[196:197], v[180:181], v[216:217] neg_lo:[0,0,1] neg_hi:[0,0,1]
	v_pk_fma_f32 v[218:219], v[198:199], v[178:179], v[218:219] neg_lo:[0,0,1] neg_hi:[0,0,1]
	v_pk_mul_f32 v[190:191], v[194:195], v[190:191]
	v_pk_mul_f32 v[188:189], v[196:197], v[188:189]
	v_pk_mul_f32 v[186:187], v[198:199], v[186:187]
	v_cvt_pk_bf16_f32 v132, v216, v217
	v_cvt_pk_bf16_f32 v133, v214, v215
	v_cvt_pk_bf16_f32 v134, v220, v221
	v_cvt_pk_bf16_f32 v135, v218, v219
	v_addc_co_u32_e32 v185, vcc, 0, v177, vcc
	v_pk_fma_f32 v[182:183], v[208:209], v[182:183], v[190:191]
	v_pk_fma_f32 v[180:181], v[210:211], v[180:181], v[188:189]
	v_pk_fma_f32 v[178:179], v[212:213], v[178:179], v[186:187]
	global_store_dwordx4 v[184:185], v[132:135], off
	s_nop 1
	v_cvt_pk_bf16_f32 v132, v180, v181
	v_cvt_pk_bf16_f32 v133, v182, v183
	v_cvt_pk_bf16_f32 v134, v170, v171
	v_cvt_pk_bf16_f32 v135, v178, v179
	v_lshl_add_u64 v[170:171], v[176:177], 0, s[14:15]
	s_mov_b64 s[14:15], 0

;     __device__ __forceinline__ bool next(int i, Unit& u) const { if (i >= n) return false; u.pm = pm; u.pn = pn0 + i; return true; }
;     __device__ __forceinline__ bool next(int i, Unit& u) const { if (i) return false; u.pm = pm; u.pn = pn; return true; }
; #define PG8_STAGE(bufoff, gbase, voff) do { _Pragma("unroll") for (int _i = 0; _i < 2; ++_i) \
;         __builtin_amdgcn_global_load_lds((const unsigned*)((const char*)(gbase) + (voff)[_i]), (PG8_LAS unsigned*)(lds + (bufoff) + ldsw + _i * 8192), 16, 0, 0); } while (0)
; #define PG8_LDA(dst, b, h) do { _Pragma("unroll") for (int m = 0; m < 4; ++m) _Pragma("unroll") for (int k = 0; k < 2; ++k) dst[m][k] = *(const PG8_LAS bf16x8*)(lds + PG8_SA(b, h) + aoff + m * 2048 + k * 1024); } while (0)
; #define PG8_LDB(dst, b, h) do { _Pragma("unroll") for (int n = 0; n < 2; ++n) _Pragma("unroll") for (int k = 0; k < 2; ++k) dst[n][k] = *(const PG8_LAS bf16x8*)(lds + PG8_SB(b, h) + boff + n * 2048 + k * 1024); } while (0)
; #define PG8_SCHED __builtin_amdgcn_sched_barrier(0)
;     ...
;         const bool has_next = S.next(ui + 1, nxt);
;         const char* nA = has_next ? (const char*)g.A + (size_t)nxt.pm * tstep : cA; const char* nB = has_next ? (const char*)g.Bt + (size_t)nxt.pn * tstep : cB;
;         for (int t = 0; t < nt; t += 2) {
;             const bool last = (t == nt - 2);
;             const char* a1 = cA + (size_t)(t + 1) * kstep;
;             const char* a2 = last ? nA : cA + (size_t)(t + 2) * kstep; const char* b2 = last ? nB : cB + (size_t)(t + 2) * kstep;
;             const char* a3 = a2 + kstep; const char* b3 = b2 + kstep;
;             if (last && has_next) S.a_ready(nxt);
;             if (t == 0) E.pre_issue(pre, cur, tid, ui); else if (t == 2) E.pre_finish(pre, tid, ui);
;             if constexpr (SP2) {
;             PG8_LDB(B0, 0, 0); PG8_LDB(B1, 0, 1); PG8_SCHED; PG8_LDA(At, 0, 0); PG8_STAGE(PG8_SA(1, 1), a1 + hstep, voffA);
;     ...
;         for (int a = 0; a < 2; ++a)
; #pragma unroll
;             for (int b = 0; b < 2; ++b)
; #pragma unroll
;                 for (int m = 0; m < 4; ++m)
; #pragma unroll
;                     for (int n = 0; n < 2; ++n) acc[a][b][m][n] = (f32x4){0.f, 0.f, 0.f, 0.f};
;         cur = nxt; cA = nA; cB = nB; ++ui;
.LBB0_453:
	s_ashr_i32 s25, s24, 31
	s_lshl_b64 s[50:51], s[24:25], 20
	s_add_u32 s50, s58, s50
	s_addc_u32 s51, s59, s51
	s_and_b64 s[60:61], s[6:7], exec
	s_cselect_b32 s25, s51, s69
	s_cselect_b32 s76, s50, s68
	s_ashr_i32 s15, s14, 31
	s_lshl_b64 s[60:61], s[14:15], 20
	s_add_u32 s60, s1, s60
	s_addc_u32 s61, s4, s61
	s_and_b64 s[70:71], s[6:7], exec
	s_cselect_b32 s15, s61, s63
	s_cselect_b32 s77, s60, s62
	s_add_u32 s78, s62, 0x100
	s_addc_u32 s79, s63, 0
	s_add_u32 s62, s68, 0x80080
	v_mov_b32_e32 v4, 0
	s_addc_u32 s63, s69, 0
	s_mov_b32 s81, -2
	v_mov_b32_e32 v5, v4
	v_mov_b32_e32 v6, v4
	v_mov_b32_e32 v7, v4
	v_mov_b32_e32 v8, v4
	v_mov_b32_e32 v9, v4
	v_mov_b32_e32 v10, v4
	v_mov_b32_e32 v11, v4
	v_mov_b32_e32 v20, v4
	v_mov_b32_e32 v21, v4
	v_mov_b32_e32 v22, v4
	v_mov_b32_e32 v23, v4
	v_mov_b32_e32 v24, v4
	v_mov_b32_e32 v25, v4
	v_mov_b32_e32 v26, v4
	v_mov_b32_e32 v27, v4
	v_mov_b32_e32 v36, v4
	v_mov_b32_e32 v37, v4
	v_mov_b32_e32 v38, v4
	v_mov_b32_e32 v39, v4
	v_mov_b32_e32 v40, v4
	v_mov_b32_e32 v41, v4
	v_mov_b32_e32 v42, v4
	v_mov_b32_e32 v43, v4
	v_mov_b32_e32 v52, v4
	v_mov_b32_e32 v53, v4
	v_mov_b32_e32 v54, v4
	v_mov_b32_e32 v55, v4
	v_mov_b32_e32 v56, v4
	v_mov_b32_e32 v57, v4
	v_mov_b32_e32 v58, v4
	v_mov_b32_e32 v59, v4
	v_mov_b32_e32 v12, v4
	v_mov_b32_e32 v13, v4
	v_mov_b32_e32 v14, v4
	v_mov_b32_e32 v15, v4
	v_mov_b32_e32 v16, v4
	v_mov_b32_e32 v17, v4
	v_mov_b32_e32 v18, v4
	v_mov_b32_e32 v19, v4
	v_mov_b32_e32 v28, v4
	v_mov_b32_e32 v29, v4
	v_mov_b32_e32 v30, v4
	v_mov_b32_e32 v31, v4
	v_mov_b32_e32 v32, v4
	v_mov_b32_e32 v33, v4
	v_mov_b32_e32 v34, v4
	v_mov_b32_e32 v35, v4
	v_mov_b32_e32 v44, v4
	v_mov_b32_e32 v45, v4
	v_mov_b32_e32 v46, v4
	v_mov_b32_e32 v47, v4
	v_mov_b32_e32 v48, v4
	v_mov_b32_e32 v49, v4
	v_mov_b32_e32 v50, v4
	v_mov_b32_e32 v51, v4
	v_mov_b32_e32 v60, v4
	v_mov_b32_e32 v61, v4
	v_mov_b32_e32 v62, v4
	v_mov_b32_e32 v63, v4
	v_mov_b32_e32 v64, v4
	v_mov_b32_e32 v65, v4
	v_mov_b32_e32 v66, v4
	v_mov_b32_e32 v67, v4
	v_mov_b32_e32 v68, v4
	v_mov_b32_e32 v69, v4
	v_mov_b32_e32 v70, v4
	v_mov_b32_e32 v71, v4
	v_mov_b32_e32 v72, v4
	v_mov_b32_e32 v73, v4
	v_mov_b32_e32 v74, v4
	v_mov_b32_e32 v75, v4
	v_mov_b32_e32 v84, v4
	v_mov_b32_e32 v85, v4
	v_mov_b32_e32 v86, v4
	v_mov_b32_e32 v87, v4
	v_mov_b32_e32 v88, v4
	v_mov_b32_e32 v89, v4
	v_mov_b32_e32 v90, v4
	v_mov_b32_e32 v91, v4
	v_mov_b32_e32 v100, v4
	v_mov_b32_e32 v101, v4
	v_mov_b32_e32 v102, v4
	v_mov_b32_e32 v103, v4
	v_mov_b32_e32 v104, v4
	v_mov_b32_e32 v105, v4
	v_mov_b32_e32 v106, v4
	v_mov_b32_e32 v107, v4
	v_mov_b32_e32 v124, v4
	v_mov_b32_e32 v125, v4
	v_mov_b32_e32 v126, v4
	v_mov_b32_e32 v127, v4
	v_mov_b32_e32 v132, v4
	v_mov_b32_e32 v133, v4
	v_mov_b32_e32 v134, v4
	v_mov_b32_e32 v135, v4
	v_mov_b32_e32 v76, v4
	v_mov_b32_e32 v77, v4
	v_mov_b32_e32 v78, v4
	v_mov_b32_e32 v79, v4
	v_mov_b32_e32 v80, v4
	v_mov_b32_e32 v81, v4
	v_mov_b32_e32 v82, v4
	v_mov_b32_e32 v83, v4
	v_mov_b32_e32 v92, v4
	v_mov_b32_e32 v93, v4
	v_mov_b32_e32 v94, v4
	v_mov_b32_e32 v95, v4
	v_mov_b32_e32 v96, v4
	v_mov_b32_e32 v97, v4
	v_mov_b32_e32 v98, v4
	v_mov_b32_e32 v99, v4
	v_mov_b32_e32 v116, v4
	v_mov_b32_e32 v117, v4
	v_mov_b32_e32 v118, v4
	v_mov_b32_e32 v119, v4
	v_mov_b32_e32 v120, v4
	v_mov_b32_e32 v121, v4
	v_mov_b32_e32 v122, v4
	v_mov_b32_e32 v123, v4
	v_mov_b32_e32 v140, v4
	v_mov_b32_e32 v141, v4
	v_mov_b32_e32 v142, v4
	v_mov_b32_e32 v143, v4
	v_mov_b32_e32 v144, v4
	v_mov_b32_e32 v145, v4
	v_mov_b32_e32 v146, v4
	v_mov_b32_e32 v147, v4
	v_add_u32_e32 v251, 0x10000, v233
.LBB0_454:
	s_add_u32 s48, s62, 0xfff80080
	s_addc_u32 s49, s63, -1
	s_add_i32 s82, 0, 0x10000
	s_cmp_eq_u32 s81, 28
	s_cselect_b32 s71, s25, s49
	s_cselect_b32 s70, s76, s48
	s_cselect_b32 s69, s15, s79
	s_cselect_b32 s68, s77, s78
	s_add_i32 s48, 0, 0x14000
	ds_read_b128 v[108:111], v251
	ds_read_b128 v[112:115], v251 offset:1024
	ds_read_b128 v[128:131], v251 offset:2048
	ds_read_b128 v[136:139], v251 offset:3072
	ds_read_b128 v[148:151], v251 offset:16384
	ds_read_b128 v[152:155], v251 offset:17408
	ds_read_b128 v[156:159], v251 offset:18432
	ds_read_b128 v[160:163], v251 offset:19456
	v_lshl_add_u64 v[198:199], s[62:63], 0, v[196:197]
	s_add_i32 m0, s20, 0xc000
	ds_read_b128 v[164:167], v234
	ds_read_b128 v[168:171], v234 offset:1024
	ds_read_b128 v[172:175], v234 offset:2048
	ds_read_b128 v[176:179], v234 offset:3072
	ds_read_b128 v[180:183], v234 offset:4096
	ds_read_b128 v[184:187], v234 offset:5120
	ds_read_b128 v[206:209], v234 offset:6144
	ds_read_b128 v[210:213], v234 offset:7168
	global_load_lds_dwordx4 v[198:199], off
	v_lshl_add_u64 v[198:199], s[62:63], 0, v[194:195]
	s_add_i32 m0, s20, 0xe000
	s_nop 0
	global_load_lds_dwordx4 v[198:199], off
	s_waitcnt vmcnt(8)
	s_waitcnt lgkmcnt(0)
	s_setprio 1
	s_barrier
; #define PG8_STAGE(bufoff, gbase, voff) do { _Pragma("unroll") for (int _i = 0; _i < 2; ++_i) \
;         __builtin_amdgcn_global_load_lds((const unsigned*)((const char*)(gbase) + (voff)[_i]), (PG8_LAS unsigned*)(lds + (bufoff) + ldsw + _i * 8192), 16, 0, 0); } while (0)
; #define PG8_LDA(dst, b, h) do { _Pragma("unroll") for (int m = 0; m < 4; ++m) _Pragma("unroll") for (int k = 0; k < 2; ++k) dst[m][k] = *(const PG8_LAS bf16x8*)(lds + PG8_SA(b, h) + aoff + m * 2048 + k * 1024); } while (0)
; #define PG8_MMA(ai, bj, At, Bt) do { __builtin_amdgcn_s_setprio(1); _Pragma("unroll") for (int m = 0; m < 4; ++m) _Pragma("unroll") for (int n = 0; n < 2; ++n) _Pragma("unroll") for (int k = 0; k < 2; ++k) \
;         acc[ai][bj][m][n] = __builtin_amdgcn_mfma_f32_16x16x32_bf16(Bt[n][k], At[m][k], acc[ai][bj][m][n], 0, 0, 0); __builtin_amdgcn_s_setprio(0); } while (0)
; #define PG8_WAIT_V(n) asm volatile("s_waitcnt vmcnt(" #n ")" ::: "memory")
; #define PG8_WAIT_L(n) asm volatile("s_waitcnt lgkmcnt(" #n ")" ::: "memory")
; #define PG8_BAR __builtin_amdgcn_s_barrier()
; #define PG8_SCHED __builtin_amdgcn_sched_barrier(0)
;     ...
;             PG8_WAIT_V(8); PG8_WAIT_L(0); PG8_BAR; PG8_MMA(0, 0, At, B0); PG8_MMA(0, 1, At, B1); PG8_BAR; PG8_SCHED;
;             PG8_LDA(At, 0, 1); PG8_STAGE(PG8_SB(0, 0), b2, voffB); PG8_STAGE(PG8_SB(0, 1), b2 + hstep, voffB); PG8_STAGE(PG8_SA(0, 0), a2, voffA);
;             PG8_WAIT_V(8); PG8_WAIT_L(0); PG8_BAR; PG8_MMA(1, 0, At, B0); PG8_MMA(1, 1, At, B1); PG8_BAR; PG8_SCHED;
	v_mfma_f32_16x16x32_bf16 v[144:147], v[108:111], v[164:167], v[144:147]
	v_mfma_f32_16x16x32_bf16 v[140:143], v[128:131], v[164:167], v[140:143]
	v_mfma_f32_16x16x32_bf16 v[120:123], v[108:111], v[172:175], v[120:123]
	v_mfma_f32_16x16x32_bf16 v[116:119], v[128:131], v[172:175], v[116:119]
	v_mfma_f32_16x16x32_bf16 v[96:99], v[108:111], v[180:183], v[96:99]
	v_mfma_f32_16x16x32_bf16 v[92:95], v[128:131], v[180:183], v[92:95]
	v_mfma_f32_16x16x32_bf16 v[80:83], v[108:111], v[206:209], v[80:83]
	v_mfma_f32_16x16x32_bf16 v[76:79], v[128:131], v[206:209], v[76:79]
	v_mfma_f32_16x16x32_bf16 v[144:147], v[112:115], v[168:171], v[144:147]
	v_mfma_f32_16x16x32_bf16 v[140:143], v[136:139], v[168:171], v[140:143]
	v_mfma_f32_16x16x32_bf16 v[120:123], v[112:115], v[176:179], v[120:123]
	v_mfma_f32_16x16x32_bf16 v[116:119], v[136:139], v[176:179], v[116:119]
	v_mfma_f32_16x16x32_bf16 v[96:99], v[112:115], v[184:187], v[96:99]
	v_mfma_f32_16x16x32_bf16 v[92:95], v[136:139], v[184:187], v[92:95]
	v_mfma_f32_16x16x32_bf16 v[80:83], v[112:115], v[210:213], v[80:83]
	v_mfma_f32_16x16x32_bf16 v[76:79], v[136:139], v[210:213], v[76:79]
	s_setprio 0
	s_setprio 1
	v_mfma_f32_16x16x32_bf16 v[132:135], v[148:151], v[164:167], v[132:135]
	v_mfma_f32_16x16x32_bf16 v[124:127], v[156:159], v[164:167], v[124:127]
	v_mfma_f32_16x16x32_bf16 v[104:107], v[148:151], v[172:175], v[104:107]
	v_mfma_f32_16x16x32_bf16 v[100:103], v[156:159], v[172:175], v[100:103]
	v_mfma_f32_16x16x32_bf16 v[88:91], v[148:151], v[180:183], v[88:91]
	v_mfma_f32_16x16x32_bf16 v[84:87], v[156:159], v[180:183], v[84:87]
	v_mfma_f32_16x16x32_bf16 v[72:75], v[148:151], v[206:209], v[72:75]
	v_mfma_f32_16x16x32_bf16 v[68:71], v[156:159], v[206:209], v[68:71]
	v_mfma_f32_16x16x32_bf16 v[132:135], v[152:155], v[168:171], v[132:135]
	v_mfma_f32_16x16x32_bf16 v[124:127], v[160:163], v[168:171], v[124:127]
	v_mfma_f32_16x16x32_bf16 v[104:107], v[152:155], v[176:179], v[104:107]
	v_mfma_f32_16x16x32_bf16 v[100:103], v[160:163], v[176:179], v[100:103]
	v_mfma_f32_16x16x32_bf16 v[88:91], v[152:155], v[184:187], v[88:91]
	v_mfma_f32_16x16x32_bf16 v[84:87], v[160:163], v[184:187], v[84:87]
	v_mfma_f32_16x16x32_bf16 v[72:75], v[152:155], v[210:213], v[72:75]
	v_mfma_f32_16x16x32_bf16 v[68:71], v[160:163], v[210:213], v[68:71]
	s_barrier
	s_setprio 0
	s_add_i32 s49, s82, s5
	v_lshl_add_u64 v[198:199], s[68:69], 0, v[200:201]
	s_mov_b32 m0, s49
	ds_read_b128 v[164:167], v234 offset:16384
	ds_read_b128 v[168:171], v234 offset:17408
	ds_read_b128 v[172:175], v234 offset:18432
	ds_read_b128 v[176:179], v234 offset:19456
	ds_read_b128 v[180:183], v234 offset:20480
	ds_read_b128 v[184:187], v234 offset:21504
	ds_read_b128 v[206:209], v234 offset:22528
	ds_read_b128 v[210:213], v234 offset:23552
	global_load_lds_dwordx4 v[198:199], off
	s_add_i32 m0, s49, 0x2000
	s_add_u32 s82, s68, 0x80000
	v_lshl_add_u64 v[214:215], s[68:69], 0, v[188:189]
	s_addc_u32 s83, s69, 0
	s_add_i32 s48, s48, s5
	global_load_lds_dwordx4 v[214:215], off
	v_lshl_add_u64 v[216:217], s[82:83], 0, v[200:201]
	s_mov_b32 m0, s48
	v_lshl_add_u64 v[218:219], s[70:71], 0, v[190:191]
	global_load_lds_dwordx4 v[216:217], off
	v_lshl_add_u64 v[216:217], s[82:83], 0, v[188:189]
	s_add_i32 m0, s48, 0x2000
	s_nop 0
	global_load_lds_dwordx4 v[216:217], off
	v_lshl_add_u64 v[216:217], s[70:71], 0, v[192:193]
	s_mov_b32 m0, s20
	s_nop 0
	global_load_lds_dwordx4 v[216:217], off
	s_mov_b32 m0, s21
	s_nop 0
	global_load_lds_dwordx4 v[218:219], off
	s_waitcnt vmcnt(8)
	s_waitcnt lgkmcnt(0)
	s_setprio 1
	s_barrier
	v_mfma_f32_16x16x32_bf16 v[64:67], v[108:111], v[164:167], v[64:67]
	v_mfma_f32_16x16x32_bf16 v[60:63], v[128:131], v[164:167], v[60:63]
	v_mfma_f32_16x16x32_bf16 v[48:51], v[108:111], v[172:175], v[48:51]
	v_mfma_f32_16x16x32_bf16 v[44:47], v[128:131], v[172:175], v[44:47]
	v_mfma_f32_16x16x32_bf16 v[32:35], v[108:111], v[180:183], v[32:35]
	v_mfma_f32_16x16x32_bf16 v[28:31], v[128:131], v[180:183], v[28:31]
	v_mfma_f32_16x16x32_bf16 v[16:19], v[108:111], v[206:209], v[16:19]
	v_mfma_f32_16x16x32_bf16 v[12:15], v[128:131], v[206:209], v[12:15]
	v_mfma_f32_16x16x32_bf16 v[64:67], v[112:115], v[168:171], v[64:67]
	v_mfma_f32_16x16x32_bf16 v[60:63], v[136:139], v[168:171], v[60:63]
	v_mfma_f32_16x16x32_bf16 v[48:51], v[112:115], v[176:179], v[48:51]
	v_mfma_f32_16x16x32_bf16 v[44:47], v[136:139], v[176:179], v[44:47]
	v_mfma_f32_16x16x32_bf16 v[32:35], v[112:115], v[184:187], v[32:35]
	v_mfma_f32_16x16x32_bf16 v[28:31], v[136:139], v[184:187], v[28:31]
	v_mfma_f32_16x16x32_bf16 v[16:19], v[112:115], v[210:213], v[16:19]
	v_mfma_f32_16x16x32_bf16 v[12:15], v[136:139], v[210:213], v[12:15]
	s_setprio 0
	s_setprio 1
	v_mfma_f32_16x16x32_bf16 v[56:59], v[148:151], v[164:167], v[56:59]
	v_mfma_f32_16x16x32_bf16 v[52:55], v[156:159], v[164:167], v[52:55]
	v_mfma_f32_16x16x32_bf16 v[40:43], v[148:151], v[172:175], v[40:43]
	v_mfma_f32_16x16x32_bf16 v[36:39], v[156:159], v[172:175], v[36:39]
	v_mfma_f32_16x16x32_bf16 v[24:27], v[148:151], v[180:183], v[24:27]
	v_mfma_f32_16x16x32_bf16 v[20:23], v[156:159], v[180:183], v[20:23]
	v_mfma_f32_16x16x32_bf16 v[8:11], v[148:151], v[206:209], v[8:11]
	v_mfma_f32_16x16x32_bf16 v[4:7], v[156:159], v[206:209], v[4:7]
	v_mfma_f32_16x16x32_bf16 v[56:59], v[152:155], v[168:171], v[56:59]
	v_mfma_f32_16x16x32_bf16 v[52:55], v[160:163], v[168:171], v[52:55]
	v_mfma_f32_16x16x32_bf16 v[40:43], v[152:155], v[176:179], v[40:43]
	v_mfma_f32_16x16x32_bf16 v[36:39], v[160:163], v[176:179], v[36:39]
	v_mfma_f32_16x16x32_bf16 v[24:27], v[152:155], v[184:187], v[24:27]
	v_mfma_f32_16x16x32_bf16 v[20:23], v[160:163], v[184:187], v[20:23]
	v_mfma_f32_16x16x32_bf16 v[8:11], v[152:155], v[210:213], v[8:11]
	v_mfma_f32_16x16x32_bf16 v[4:7], v[160:163], v[210:213], v[4:7]
	s_barrier
; #define PG8_STAGE(bufoff, gbase, voff) do { _Pragma("unroll") for (int _i = 0; _i < 2; ++_i) \
;         __builtin_amdgcn_global_load_lds((const unsigned*)((const char*)(gbase) + (voff)[_i]), (PG8_LAS unsigned*)(lds + (bufoff) + ldsw + _i * 8192), 16, 0, 0); } while (0)
; #define PG8_LDA(dst, b, h) do { _Pragma("unroll") for (int m = 0; m < 4; ++m) _Pragma("unroll") for (int k = 0; k < 2; ++k) dst[m][k] = *(const PG8_LAS bf16x8*)(lds + PG8_SA(b, h) + aoff + m * 2048 + k * 1024); } while (0)
; #define PG8_LDB(dst, b, h) do { _Pragma("unroll") for (int n = 0; n < 2; ++n) _Pragma("unroll") for (int k = 0; k < 2; ++k) dst[n][k] = *(const PG8_LAS bf16x8*)(lds + PG8_SB(b, h) + boff + n * 2048 + k * 1024); } while (0)
; #define PG8_MMA(ai, bj, At, Bt) do { __builtin_amdgcn_s_setprio(1); _Pragma("unroll") for (int m = 0; m < 4; ++m) _Pragma("unroll") for (int n = 0; n < 2; ++n) _Pragma("unroll") for (int k = 0; k < 2; ++k) \
;         acc[ai][bj][m][n] = __builtin_amdgcn_mfma_f32_16x16x32_bf16(Bt[n][k], At[m][k], acc[ai][bj][m][n], 0, 0, 0); __builtin_amdgcn_s_setprio(0); } while (0)
; #define PG8_WAIT_V(n) asm volatile("s_waitcnt vmcnt(" #n ")" ::: "memory")
; #define PG8_WAIT_L(n) asm volatile("s_waitcnt lgkmcnt(" #n ")" ::: "memory")
; #define PG8_BAR __builtin_amdgcn_s_barrier()
; #define PG8_SCHED __builtin_amdgcn_sched_barrier(0)
;     ...
;             PG8_LDB(B0, 1, 0); PG8_LDB(B1, 1, 1); PG8_SCHED; PG8_LDA(At, 1, 0); PG8_STAGE(PG8_SA(0, 1), a2 + hstep, voffA);
;             PG8_WAIT_V(8); PG8_WAIT_L(0); PG8_BAR; PG8_MMA(0, 0, At, B0); PG8_MMA(0, 1, At, B1); PG8_BAR; PG8_SCHED;
	s_setprio 0
	s_add_i32 s48, 0, 0x18000
	s_add_i32 s49, 0, 0x1c000
	ds_read_b128 v[108:111], v251 offset:32768
	ds_read_b128 v[112:115], v251 offset:33792
	ds_read_b128 v[128:131], v251 offset:34816
	ds_read_b128 v[136:139], v251 offset:35840
	ds_read_b128 v[148:151], v251 offset:49152
	ds_read_b128 v[152:155], v251 offset:50176
	ds_read_b128 v[156:159], v251 offset:51200
	ds_read_b128 v[160:163], v251 offset:52224
	s_add_u32 s70, s70, 0x80000
	s_addc_u32 s71, s71, 0
	s_mov_b32 m0, s23
	v_lshl_add_u64 v[220:221], s[70:71], 0, v[192:193]
	ds_read_b128 v[164:167], v234 offset:32768
	ds_read_b128 v[168:171], v234 offset:33792
	ds_read_b128 v[172:175], v234 offset:34816
	ds_read_b128 v[176:179], v234 offset:35840
	ds_read_b128 v[180:183], v234 offset:36864
	ds_read_b128 v[184:187], v234 offset:37888
	ds_read_b128 v[206:209], v234 offset:38912
	ds_read_b128 v[210:213], v234 offset:39936
	global_load_lds_dwordx4 v[220:221], off
	v_lshl_add_u64 v[220:221], s[70:71], 0, v[190:191]
	s_mov_b32 m0, s42
	s_nop 0
	global_load_lds_dwordx4 v[220:221], off
	s_waitcnt vmcnt(8)
	s_waitcnt lgkmcnt(0)
	s_setprio 1
	s_barrier
	v_mfma_f32_16x16x32_bf16 v[144:147], v[108:111], v[164:167], v[144:147]
	v_mfma_f32_16x16x32_bf16 v[140:143], v[128:131], v[164:167], v[140:143]
	v_mfma_f32_16x16x32_bf16 v[120:123], v[108:111], v[172:175], v[120:123]
	v_mfma_f32_16x16x32_bf16 v[116:119], v[128:131], v[172:175], v[116:119]
	v_mfma_f32_16x16x32_bf16 v[96:99], v[108:111], v[180:183], v[96:99]
	v_mfma_f32_16x16x32_bf16 v[92:95], v[128:131], v[180:183], v[92:95]
	v_mfma_f32_16x16x32_bf16 v[80:83], v[108:111], v[206:209], v[80:83]
	v_mfma_f32_16x16x32_bf16 v[76:79], v[128:131], v[206:209], v[76:79]
	v_mfma_f32_16x16x32_bf16 v[144:147], v[112:115], v[168:171], v[144:147]
	v_mfma_f32_16x16x32_bf16 v[140:143], v[136:139], v[168:171], v[140:143]
	v_mfma_f32_16x16x32_bf16 v[120:123], v[112:115], v[176:179], v[120:123]
	v_mfma_f32_16x16x32_bf16 v[116:119], v[136:139], v[176:179], v[116:119]
	v_mfma_f32_16x16x32_bf16 v[96:99], v[112:115], v[184:187], v[96:99]
	v_mfma_f32_16x16x32_bf16 v[92:95], v[136:139], v[184:187], v[92:95]
	v_mfma_f32_16x16x32_bf16 v[80:83], v[112:115], v[210:213], v[80:83]
	v_mfma_f32_16x16x32_bf16 v[76:79], v[136:139], v[210:213], v[76:79]
	s_setprio 0
	s_setprio 1
	v_mfma_f32_16x16x32_bf16 v[132:135], v[148:151], v[164:167], v[132:135]
	v_mfma_f32_16x16x32_bf16 v[124:127], v[156:159], v[164:167], v[124:127]
	v_mfma_f32_16x16x32_bf16 v[104:107], v[148:151], v[172:175], v[104:107]
	v_mfma_f32_16x16x32_bf16 v[100:103], v[156:159], v[172:175], v[100:103]
	v_mfma_f32_16x16x32_bf16 v[88:91], v[148:151], v[180:183], v[88:91]
	v_mfma_f32_16x16x32_bf16 v[84:87], v[156:159], v[180:183], v[84:87]
	v_mfma_f32_16x16x32_bf16 v[72:75], v[148:151], v[206:209], v[72:75]
	v_mfma_f32_16x16x32_bf16 v[68:71], v[156:159], v[206:209], v[68:71]
	v_mfma_f32_16x16x32_bf16 v[132:135], v[152:155], v[168:171], v[132:135]
	v_mfma_f32_16x16x32_bf16 v[124:127], v[160:163], v[168:171], v[124:127]
	v_mfma_f32_16x16x32_bf16 v[104:107], v[152:155], v[176:179], v[104:107]
	v_mfma_f32_16x16x32_bf16 v[100:103], v[160:163], v[176:179], v[100:103]
	v_mfma_f32_16x16x32_bf16 v[88:91], v[152:155], v[184:187], v[88:91]
	v_mfma_f32_16x16x32_bf16 v[84:87], v[160:163], v[184:187], v[84:87]
	v_mfma_f32_16x16x32_bf16 v[72:75], v[152:155], v[210:213], v[72:75]
	v_mfma_f32_16x16x32_bf16 v[68:71], v[160:163], v[210:213], v[68:71]
	s_barrier
; #define PG8_STAGE(bufoff, gbase, voff) do { _Pragma("unroll") for (int _i = 0; _i < 2; ++_i) \
;         __builtin_amdgcn_global_load_lds((const unsigned*)((const char*)(gbase) + (voff)[_i]), (PG8_LAS unsigned*)(lds + (bufoff) + ldsw + _i * 8192), 16, 0, 0); } while (0)
; #define PG8_LDA(dst, b, h) do { _Pragma("unroll") for (int m = 0; m < 4; ++m) _Pragma("unroll") for (int k = 0; k < 2; ++k) dst[m][k] = *(const PG8_LAS bf16x8*)(lds + PG8_SA(b, h) + aoff + m * 2048 + k * 1024); } while (0)
; #define PG8_MMA(ai, bj, At, Bt) do { __builtin_amdgcn_s_setprio(1); _Pragma("unroll") for (int m = 0; m < 4; ++m) _Pragma("unroll") for (int n = 0; n < 2; ++n) _Pragma("unroll") for (int k = 0; k < 2; ++k) \
;         acc[ai][bj][m][n] = __builtin_amdgcn_mfma_f32_16x16x32_bf16(Bt[n][k], At[m][k], acc[ai][bj][m][n], 0, 0, 0); __builtin_amdgcn_s_setprio(0); } while (0)
; #define PG8_WAIT_V(n) asm volatile("s_waitcnt vmcnt(" #n ")" ::: "memory")
; #define PG8_WAIT_L(n) asm volatile("s_waitcnt lgkmcnt(" #n ")" ::: "memory")
; #define PG8_BAR __builtin_amdgcn_s_barrier()
; #define PG8_SCHED __builtin_amdgcn_sched_barrier(0)
;     ...
;             PG8_LDA(At, 1, 1); PG8_STAGE(PG8_SB(1, 0), b3, voffB); PG8_STAGE(PG8_SB(1, 1), b3 + hstep, voffB); PG8_STAGE(PG8_SA(1, 0), a3, voffA);
;             PG8_WAIT_V(8); PG8_WAIT_L(0); PG8_BAR; PG8_MMA(1, 0, At, B0); PG8_MMA(1, 1, At, B1); PG8_BAR; PG8_SCHED;
;     ...
;         if constexpr (ALIGN_EPI) { if (wr == 0) PG8_BAR; }
	s_setprio 0
	s_add_i32 s48, s48, s5
	v_lshl_add_u64 v[198:199], v[198:199], 0, s[66:67]
	s_mov_b32 m0, s48
	ds_read_b128 v[164:167], v234 offset:49152
	ds_read_b128 v[168:171], v234 offset:50176
	ds_read_b128 v[172:175], v234 offset:51200
	ds_read_b128 v[176:179], v234 offset:52224
	ds_read_b128 v[180:183], v234 offset:53248
	ds_read_b128 v[184:187], v234 offset:54272
	ds_read_b128 v[206:209], v234 offset:55296
	ds_read_b128 v[210:213], v234 offset:56320
	global_load_lds_dwordx4 v[198:199], off
	s_add_i32 m0, s48, 0x2000
	s_add_u32 s68, s68, 0x80080
	v_lshl_add_u64 v[198:199], v[214:215], 0, s[66:67]
	s_addc_u32 s69, s69, 0
	s_add_i32 s48, s49, s5
	global_load_lds_dwordx4 v[198:199], off
	v_lshl_add_u64 v[198:199], s[68:69], 0, v[200:201]
	s_mov_b32 m0, s48
	s_nop 0
	global_load_lds_dwordx4 v[198:199], off
	v_lshl_add_u64 v[198:199], s[68:69], 0, v[188:189]
	s_add_i32 m0, s48, 0x2000
	s_nop 0
	global_load_lds_dwordx4 v[198:199], off
	v_lshl_add_u64 v[198:199], v[216:217], 0, s[66:67]
	s_mov_b32 m0, s55
	s_nop 0
	global_load_lds_dwordx4 v[198:199], off
	v_lshl_add_u64 v[198:199], v[218:219], 0, s[66:67]
	s_mov_b32 m0, s56
	s_nop 0
	global_load_lds_dwordx4 v[198:199], off
	s_waitcnt vmcnt(8)
	s_waitcnt lgkmcnt(0)
	s_setprio 1
	s_barrier
	v_mfma_f32_16x16x32_bf16 v[64:67], v[108:111], v[164:167], v[64:67]
	v_mfma_f32_16x16x32_bf16 v[60:63], v[128:131], v[164:167], v[60:63]
	v_mfma_f32_16x16x32_bf16 v[48:51], v[108:111], v[172:175], v[48:51]
	v_mfma_f32_16x16x32_bf16 v[44:47], v[128:131], v[172:175], v[44:47]
	v_mfma_f32_16x16x32_bf16 v[32:35], v[108:111], v[180:183], v[32:35]
	v_mfma_f32_16x16x32_bf16 v[28:31], v[128:131], v[180:183], v[28:31]
	v_mfma_f32_16x16x32_bf16 v[16:19], v[108:111], v[206:209], v[16:19]
	v_mfma_f32_16x16x32_bf16 v[12:15], v[128:131], v[206:209], v[12:15]
	v_mfma_f32_16x16x32_bf16 v[64:67], v[112:115], v[168:171], v[64:67]
	v_mfma_f32_16x16x32_bf16 v[60:63], v[136:139], v[168:171], v[60:63]
	v_mfma_f32_16x16x32_bf16 v[48:51], v[112:115], v[176:179], v[48:51]
	v_mfma_f32_16x16x32_bf16 v[44:47], v[136:139], v[176:179], v[44:47]
	v_mfma_f32_16x16x32_bf16 v[32:35], v[112:115], v[184:187], v[32:35]
	v_mfma_f32_16x16x32_bf16 v[28:31], v[136:139], v[184:187], v[28:31]
	v_mfma_f32_16x16x32_bf16 v[16:19], v[112:115], v[210:213], v[16:19]
	v_mfma_f32_16x16x32_bf16 v[12:15], v[136:139], v[210:213], v[12:15]
	s_setprio 0
	s_setprio 1
	v_mfma_f32_16x16x32_bf16 v[56:59], v[148:151], v[164:167], v[56:59]
	v_mfma_f32_16x16x32_bf16 v[52:55], v[156:159], v[164:167], v[52:55]
	v_mfma_f32_16x16x32_bf16 v[40:43], v[148:151], v[172:175], v[40:43]
	v_mfma_f32_16x16x32_bf16 v[36:39], v[156:159], v[172:175], v[36:39]
	v_mfma_f32_16x16x32_bf16 v[24:27], v[148:151], v[180:183], v[24:27]
	v_mfma_f32_16x16x32_bf16 v[20:23], v[156:159], v[180:183], v[20:23]
	v_mfma_f32_16x16x32_bf16 v[8:11], v[148:151], v[206:209], v[8:11]
	v_mfma_f32_16x16x32_bf16 v[4:7], v[156:159], v[206:209], v[4:7]
	v_mfma_f32_16x16x32_bf16 v[56:59], v[152:155], v[168:171], v[56:59]
	v_mfma_f32_16x16x32_bf16 v[52:55], v[160:163], v[168:171], v[52:55]
	v_mfma_f32_16x16x32_bf16 v[40:43], v[152:155], v[176:179], v[40:43]
	v_mfma_f32_16x16x32_bf16 v[36:39], v[160:163], v[176:179], v[36:39]
	v_mfma_f32_16x16x32_bf16 v[24:27], v[152:155], v[184:187], v[24:27]
	v_mfma_f32_16x16x32_bf16 v[20:23], v[160:163], v[184:187], v[20:23]
	v_mfma_f32_16x16x32_bf16 v[8:11], v[152:155], v[210:213], v[8:11]
	v_mfma_f32_16x16x32_bf16 v[4:7], v[160:163], v[210:213], v[4:7]
	s_barrier
	s_setprio 0
	s_add_i32 s81, s81, 2
	s_add_u32 s78, s78, 0x100
	s_addc_u32 s79, s79, 0
	s_add_u32 s62, s62, 0x100
	s_addc_u32 s63, s63, 0
	s_cmp_gt_u32 s81, 29
	s_cbranch_scc0 .LBB0_454
	s_and_b64 vcc, exec, s[12:13]
	s_cbranch_vccz .LBB0_457
	s_barrier

;     __device__ __forceinline__ bool next(int i, Unit& u) const { if (i >= n) return false; u.pm = pm; u.pn = pn0 + i; return true; }
;     __device__ __forceinline__ bool next(int i, Unit& u) const { if (i) return false; u.pm = pm; u.pn = pn; return true; }
; #define PG8_STAGE(bufoff, gbase, voff) do { _Pragma("unroll") for (int _i = 0; _i < 2; ++_i) \
;         __builtin_amdgcn_global_load_lds((const unsigned*)((const char*)(gbase) + (voff)[_i]), (PG8_LAS unsigned*)(lds + (bufoff) + ldsw + _i * 8192), 16, 0, 0); } while (0)
; #define PG8_LDA(dst, b, h) do { _Pragma("unroll") for (int m = 0; m < 4; ++m) _Pragma("unroll") for (int k = 0; k < 2; ++k) dst[m][k] = *(const PG8_LAS bf16x8*)(lds + PG8_SA(b, h) + aoff + m * 2048 + k * 1024); } while (0)
; #define PG8_LDB(dst, b, h) do { _Pragma("unroll") for (int n = 0; n < 2; ++n) _Pragma("unroll") for (int k = 0; k < 2; ++k) dst[n][k] = *(const PG8_LAS bf16x8*)(lds + PG8_SB(b, h) + boff + n * 2048 + k * 1024); } while (0)
; #define PG8_SCHED __builtin_amdgcn_sched_barrier(0)
;     ...
;         const bool has_next = S.next(ui + 1, nxt);
;         const char* nA = has_next ? (const char*)g.A + (size_t)nxt.pm * tstep : cA; const char* nB = has_next ? (const char*)g.Bt + (size_t)nxt.pn * tstep : cB;
;         for (int t = 0; t < nt; t += 2) {
;             const bool last = (t == nt - 2);
;             const char* a1 = cA + (size_t)(t + 1) * kstep;
;             const char* a2 = last ? nA : cA + (size_t)(t + 2) * kstep; const char* b2 = last ? nB : cB + (size_t)(t + 2) * kstep;
;             const char* a3 = a2 + kstep; const char* b3 = b2 + kstep;
;             if (last && has_next) S.a_ready(nxt);
;             if (t == 0) E.pre_issue(pre, cur, tid, ui); else if (t == 2) E.pre_finish(pre, tid, ui);
;             if constexpr (SP2) {
;             PG8_LDB(B0, 0, 0); PG8_LDB(B1, 0, 1); PG8_SCHED; PG8_LDA(At, 0, 0); PG8_STAGE(PG8_SA(1, 1), a1 + hstep, voffA);
;     ...
;         for (int a = 0; a < 2; ++a)
; #pragma unroll
;             for (int b = 0; b < 2; ++b)
; #pragma unroll
;                 for (int m = 0; m < 4; ++m)
; #pragma unroll
;                     for (int n = 0; n < 2; ++n) acc[a][b][m][n] = (f32x4){0.f, 0.f, 0.f, 0.f};
;         cur = nxt; cA = nA; cB = nB; ++ui;
.LBB0_541:
	s_ashr_i32 s25, s24, 31
	s_lshl_b64 s[14:15], s[24:25], 20
	s_add_u32 s90, s36, s14
	s_addc_u32 s91, s37, s15
	s_and_b64 s[14:15], s[8:9], exec
	s_cselect_b32 s25, s91, s11
	s_cselect_b32 s69, s90, s10
	s_ashr_i32 s89, s88, 31
	s_lshl_b64 s[14:15], s[88:89], 20
	s_add_u32 s94, s6, s14
	s_addc_u32 s95, s7, s15
	s_and_b64 s[14:15], s[8:9], exec
	s_cselect_b32 s76, s95, s13
	s_cselect_b32 s77, s94, s12
	s_add_u32 s10, s10, 0x80080
	s_addc_u32 s11, s11, 0
	s_add_u32 s82, s12, 0x100
	v_mov_b32_e32 v12, 0
	s_addc_u32 s83, s13, 0
	s_mov_b32 s89, -2
	v_mov_b32_e32 v13, v12
	v_mov_b32_e32 v14, v12
	v_mov_b32_e32 v15, v12
	v_mov_b32_e32 v16, v12
	v_mov_b32_e32 v17, v12
	v_mov_b32_e32 v18, v12
	v_mov_b32_e32 v19, v12
	v_mov_b32_e32 v24, v12
	v_mov_b32_e32 v25, v12
	v_mov_b32_e32 v26, v12
	v_mov_b32_e32 v27, v12
	v_mov_b32_e32 v84, v12
	v_mov_b32_e32 v85, v12
	v_mov_b32_e32 v86, v12
	v_mov_b32_e32 v87, v12
	v_mov_b32_e32 v28, v12
	v_mov_b32_e32 v29, v12
	v_mov_b32_e32 v30, v12
	v_mov_b32_e32 v31, v12
	v_mov_b32_e32 v88, v12
	v_mov_b32_e32 v89, v12
	v_mov_b32_e32 v90, v12
	v_mov_b32_e32 v91, v12
	v_mov_b32_e32 v32, v12
	v_mov_b32_e32 v33, v12
	v_mov_b32_e32 v34, v12
	v_mov_b32_e32 v35, v12
	v_mov_b32_e32 v102, v12
	v_mov_b32_e32 v103, v12
	v_mov_b32_e32 v104, v12
	v_mov_b32_e32 v105, v12
	v_mov_b32_e32 v20, v12
	v_mov_b32_e32 v21, v12
	v_mov_b32_e32 v22, v12
	v_mov_b32_e32 v23, v12
	v_mov_b32_e32 v80, v12
	v_mov_b32_e32 v81, v12
	v_mov_b32_e32 v82, v12
	v_mov_b32_e32 v83, v12
	v_mov_b32_e32 v36, v12
	v_mov_b32_e32 v37, v12
	v_mov_b32_e32 v38, v12
	v_mov_b32_e32 v39, v12
	v_mov_b32_e32 v138, v12
	v_mov_b32_e32 v139, v12
	v_mov_b32_e32 v140, v12
	v_mov_b32_e32 v141, v12
	v_mov_b32_e32 v40, v12
	v_mov_b32_e32 v41, v12
	v_mov_b32_e32 v42, v12
	v_mov_b32_e32 v43, v12
	v_mov_b32_e32 v142, v12
	v_mov_b32_e32 v143, v12
	v_mov_b32_e32 v144, v12
	v_mov_b32_e32 v145, v12
	v_mov_b32_e32 v44, v12
	v_mov_b32_e32 v45, v12
	v_mov_b32_e32 v46, v12
	v_mov_b32_e32 v47, v12
	v_mov_b32_e32 v146, v12
	v_mov_b32_e32 v147, v12
	v_mov_b32_e32 v148, v12
	v_mov_b32_e32 v149, v12
	v_mov_b32_e32 v68, v12
	v_mov_b32_e32 v69, v12
	v_mov_b32_e32 v70, v12
	v_mov_b32_e32 v71, v12
	v_mov_b32_e32 v92, v12
	v_mov_b32_e32 v93, v12
	v_mov_b32_e32 v94, v12
	v_mov_b32_e32 v95, v12
	v_mov_b32_e32 v48, v12
	v_mov_b32_e32 v49, v12
	v_mov_b32_e32 v50, v12
	v_mov_b32_e32 v51, v12
	v_mov_b32_e32 v150, v12
	v_mov_b32_e32 v151, v12
	v_mov_b32_e32 v152, v12
	v_mov_b32_e32 v153, v12
	v_mov_b32_e32 v52, v12
	v_mov_b32_e32 v53, v12
	v_mov_b32_e32 v54, v12
	v_mov_b32_e32 v55, v12
	v_mov_b32_e32 v154, v12
	v_mov_b32_e32 v155, v12
	v_mov_b32_e32 v156, v12
	v_mov_b32_e32 v157, v12
	v_mov_b32_e32 v64, v12
	v_mov_b32_e32 v65, v12
	v_mov_b32_e32 v66, v12
	v_mov_b32_e32 v67, v12
	v_mov_b32_e32 v8, v12
	v_mov_b32_e32 v9, v12
	v_mov_b32_e32 v10, v12
	v_mov_b32_e32 v11, v12
	v_mov_b32_e32 v76, v12
	v_mov_b32_e32 v77, v12
	v_mov_b32_e32 v78, v12
	v_mov_b32_e32 v79, v12
	v_mov_b32_e32 v96, v12
	v_mov_b32_e32 v97, v12
	v_mov_b32_e32 v98, v12
	v_mov_b32_e32 v99, v12
	v_mov_b32_e32 v56, v12
	v_mov_b32_e32 v57, v12
	v_mov_b32_e32 v58, v12
	v_mov_b32_e32 v59, v12
	v_mov_b32_e32 v158, v12
	v_mov_b32_e32 v159, v12
	v_mov_b32_e32 v160, v12
	v_mov_b32_e32 v161, v12
	v_mov_b32_e32 v60, v12
	v_mov_b32_e32 v61, v12
	v_mov_b32_e32 v62, v12
	v_mov_b32_e32 v63, v12
	v_mov_b32_e32 v162, v12
	v_mov_b32_e32 v163, v12
	v_mov_b32_e32 v164, v12
	v_mov_b32_e32 v165, v12
	v_mov_b32_e32 v72, v12
	v_mov_b32_e32 v73, v12
	v_mov_b32_e32 v74, v12
	v_mov_b32_e32 v75, v12
	v_mov_b32_e32 v4, v12
	v_mov_b32_e32 v5, v12
	v_mov_b32_e32 v6, v12
	v_mov_b32_e32 v7, v12
	v_add_u32_e32 v251, 0x10000, v221
.LBB0_542:
	s_add_u32 s12, s10, 0xfff80080
	s_addc_u32 s13, s11, -1
	s_add_i32 s48, 0, 0x10000
	s_cmp_eq_u32 s89, 28
	s_cselect_b32 s15, s25, s13
	s_cselect_b32 s14, s69, s12
	s_cselect_b32 s13, s76, s83
	s_cselect_b32 s12, s77, s82
	s_add_i32 s49, 0, 0x14000
	ds_read_b128 v[106:109], v251
	ds_read_b128 v[110:113], v251 offset:1024
	ds_read_b128 v[114:117], v251 offset:2048
	ds_read_b128 v[118:121], v251 offset:3072
	ds_read_b128 v[122:125], v251 offset:16384
	ds_read_b128 v[126:129], v251 offset:17408
	ds_read_b128 v[130:133], v251 offset:18432
	ds_read_b128 v[134:137], v251 offset:19456
	v_lshl_add_u64 v[100:101], s[10:11], 0, v[190:191]
	s_add_i32 m0, s1, 0xc000
	ds_read_b128 v[166:169], v222
	ds_read_b128 v[170:173], v222 offset:1024
	ds_read_b128 v[174:177], v222 offset:2048
	ds_read_b128 v[178:181], v222 offset:3072
	ds_read_b128 v[194:197], v222 offset:4096
	ds_read_b128 v[206:209], v222 offset:5120
	ds_read_b128 v[210:213], v222 offset:6144
	ds_read_b128 v[214:217], v222 offset:7168
	global_load_lds_dwordx4 v[100:101], off
	v_lshl_add_u64 v[100:101], s[10:11], 0, v[192:193]
	s_add_i32 m0, s1, 0xe000
	s_nop 0
	global_load_lds_dwordx4 v[100:101], off
	s_waitcnt vmcnt(8)
	s_waitcnt lgkmcnt(0)
	s_setprio 1
	s_barrier
; #define PG8_STAGE(bufoff, gbase, voff) do { _Pragma("unroll") for (int _i = 0; _i < 2; ++_i) \
;         __builtin_amdgcn_global_load_lds((const unsigned*)((const char*)(gbase) + (voff)[_i]), (PG8_LAS unsigned*)(lds + (bufoff) + ldsw + _i * 8192), 16, 0, 0); } while (0)
; #define PG8_LDA(dst, b, h) do { _Pragma("unroll") for (int m = 0; m < 4; ++m) _Pragma("unroll") for (int k = 0; k < 2; ++k) dst[m][k] = *(const PG8_LAS bf16x8*)(lds + PG8_SA(b, h) + aoff + m * 2048 + k * 1024); } while (0)
; #define PG8_MMA(ai, bj, At, Bt) do { __builtin_amdgcn_s_setprio(1); _Pragma("unroll") for (int m = 0; m < 4; ++m) _Pragma("unroll") for (int n = 0; n < 2; ++n) _Pragma("unroll") for (int k = 0; k < 2; ++k) \
;         acc[ai][bj][m][n] = __builtin_amdgcn_mfma_f32_16x16x32_bf16(Bt[n][k], At[m][k], acc[ai][bj][m][n], 0, 0, 0); __builtin_amdgcn_s_setprio(0); } while (0)
; #define PG8_WAIT_V(n) asm volatile("s_waitcnt vmcnt(" #n ")" ::: "memory")
; #define PG8_WAIT_L(n) asm volatile("s_waitcnt lgkmcnt(" #n ")" ::: "memory")
; #define PG8_BAR __builtin_amdgcn_s_barrier()
; #define PG8_SCHED __builtin_amdgcn_sched_barrier(0)
;     ...
;             PG8_WAIT_V(8); PG8_WAIT_L(0); PG8_BAR; PG8_MMA(0, 0, At, B0); PG8_MMA(0, 1, At, B1); PG8_BAR; PG8_SCHED;
;             PG8_LDA(At, 0, 1); PG8_STAGE(PG8_SB(0, 0), b2, voffB); PG8_STAGE(PG8_SB(0, 1), b2 + hstep, voffB); PG8_STAGE(PG8_SA(0, 0), a2, voffA);
;             PG8_WAIT_V(8); PG8_WAIT_L(0); PG8_BAR; PG8_MMA(1, 0, At, B0); PG8_MMA(1, 1, At, B1); PG8_BAR; PG8_SCHED;
	v_mfma_f32_16x16x32_bf16 v[4:7], v[106:109], v[166:169], v[4:7]
	v_mfma_f32_16x16x32_bf16 v[72:75], v[114:117], v[166:169], v[72:75]
	v_mfma_f32_16x16x32_bf16 v[162:165], v[106:109], v[174:177], v[162:165]
	v_mfma_f32_16x16x32_bf16 v[60:63], v[114:117], v[174:177], v[60:63]
	v_mfma_f32_16x16x32_bf16 v[158:161], v[106:109], v[194:197], v[158:161]
	v_mfma_f32_16x16x32_bf16 v[56:59], v[114:117], v[194:197], v[56:59]
	v_mfma_f32_16x16x32_bf16 v[96:99], v[106:109], v[210:213], v[96:99]
	v_mfma_f32_16x16x32_bf16 v[76:79], v[114:117], v[210:213], v[76:79]
	v_mfma_f32_16x16x32_bf16 v[4:7], v[110:113], v[170:173], v[4:7]
	v_mfma_f32_16x16x32_bf16 v[72:75], v[118:121], v[170:173], v[72:75]
	v_mfma_f32_16x16x32_bf16 v[162:165], v[110:113], v[178:181], v[162:165]
	v_mfma_f32_16x16x32_bf16 v[60:63], v[118:121], v[178:181], v[60:63]
	v_mfma_f32_16x16x32_bf16 v[158:161], v[110:113], v[206:209], v[158:161]
	v_mfma_f32_16x16x32_bf16 v[56:59], v[118:121], v[206:209], v[56:59]
	v_mfma_f32_16x16x32_bf16 v[96:99], v[110:113], v[214:217], v[96:99]
	v_mfma_f32_16x16x32_bf16 v[76:79], v[118:121], v[214:217], v[76:79]
	s_setprio 0
	s_setprio 1
	v_mfma_f32_16x16x32_bf16 v[8:11], v[122:125], v[166:169], v[8:11]
	v_mfma_f32_16x16x32_bf16 v[64:67], v[130:133], v[166:169], v[64:67]
	v_mfma_f32_16x16x32_bf16 v[154:157], v[122:125], v[174:177], v[154:157]
	v_mfma_f32_16x16x32_bf16 v[52:55], v[130:133], v[174:177], v[52:55]
	v_mfma_f32_16x16x32_bf16 v[150:153], v[122:125], v[194:197], v[150:153]
	v_mfma_f32_16x16x32_bf16 v[48:51], v[130:133], v[194:197], v[48:51]
	v_mfma_f32_16x16x32_bf16 v[92:95], v[122:125], v[210:213], v[92:95]
	v_mfma_f32_16x16x32_bf16 v[68:71], v[130:133], v[210:213], v[68:71]
	v_mfma_f32_16x16x32_bf16 v[8:11], v[126:129], v[170:173], v[8:11]
	v_mfma_f32_16x16x32_bf16 v[64:67], v[134:137], v[170:173], v[64:67]
	v_mfma_f32_16x16x32_bf16 v[154:157], v[126:129], v[178:181], v[154:157]
	v_mfma_f32_16x16x32_bf16 v[52:55], v[134:137], v[178:181], v[52:55]
	v_mfma_f32_16x16x32_bf16 v[150:153], v[126:129], v[206:209], v[150:153]
	v_mfma_f32_16x16x32_bf16 v[48:51], v[134:137], v[206:209], v[48:51]
	v_mfma_f32_16x16x32_bf16 v[92:95], v[126:129], v[214:217], v[92:95]
	v_mfma_f32_16x16x32_bf16 v[68:71], v[134:137], v[214:217], v[68:71]
	s_barrier
	s_setprio 0
	s_add_i32 s48, s48, s0
	v_lshl_add_u64 v[198:199], s[12:13], 0, v[186:187]
	s_mov_b32 m0, s48
	ds_read_b128 v[166:169], v222 offset:16384
	ds_read_b128 v[170:173], v222 offset:17408
	ds_read_b128 v[174:177], v222 offset:18432
	ds_read_b128 v[178:181], v222 offset:19456
	ds_read_b128 v[194:197], v222 offset:20480
	ds_read_b128 v[206:209], v222 offset:21504
	ds_read_b128 v[210:213], v222 offset:22528
	ds_read_b128 v[214:217], v222 offset:23552
	global_load_lds_dwordx4 v[198:199], off
	s_add_i32 m0, s48, 0x2000
	s_add_u32 vcc_lo, s12, 0x80000
	v_lshl_add_u64 v[218:219], s[12:13], 0, v[182:183]
	s_addc_u32 vcc_hi, s13, 0
	s_add_i32 s48, s49, s0
	global_load_lds_dwordx4 v[218:219], off
	v_lshl_add_u64 v[100:101], vcc, 0, v[186:187]
	s_mov_b32 m0, s48
	v_lshl_add_u64 v[224:225], s[14:15], 0, v[188:189]
	global_load_lds_dwordx4 v[100:101], off
	v_lshl_add_u64 v[100:101], vcc, 0, v[182:183]
	s_add_i32 m0, s48, 0x2000
	v_lshl_add_u64 v[232:233], s[14:15], 0, v[184:185]
	global_load_lds_dwordx4 v[100:101], off
	s_mov_b32 m0, s1
	s_nop 0
	global_load_lds_dwordx4 v[224:225], off
	s_mov_b32 m0, s4
	s_nop 0
	global_load_lds_dwordx4 v[232:233], off
	s_waitcnt vmcnt(8)
	s_waitcnt lgkmcnt(0)
	s_setprio 1
	s_barrier
	v_mfma_f32_16x16x32_bf16 v[146:149], v[106:109], v[166:169], v[146:149]
	v_mfma_f32_16x16x32_bf16 v[44:47], v[114:117], v[166:169], v[44:47]
	v_mfma_f32_16x16x32_bf16 v[142:145], v[106:109], v[174:177], v[142:145]
	v_mfma_f32_16x16x32_bf16 v[40:43], v[114:117], v[174:177], v[40:43]
	v_mfma_f32_16x16x32_bf16 v[138:141], v[106:109], v[194:197], v[138:141]
	v_mfma_f32_16x16x32_bf16 v[36:39], v[114:117], v[194:197], v[36:39]
	v_mfma_f32_16x16x32_bf16 v[80:83], v[106:109], v[210:213], v[80:83]
	v_mfma_f32_16x16x32_bf16 v[20:23], v[114:117], v[210:213], v[20:23]
	v_mfma_f32_16x16x32_bf16 v[146:149], v[110:113], v[170:173], v[146:149]
	v_mfma_f32_16x16x32_bf16 v[44:47], v[118:121], v[170:173], v[44:47]
	v_mfma_f32_16x16x32_bf16 v[142:145], v[110:113], v[178:181], v[142:145]
	v_mfma_f32_16x16x32_bf16 v[40:43], v[118:121], v[178:181], v[40:43]
	v_mfma_f32_16x16x32_bf16 v[138:141], v[110:113], v[206:209], v[138:141]
	v_mfma_f32_16x16x32_bf16 v[36:39], v[118:121], v[206:209], v[36:39]
	v_mfma_f32_16x16x32_bf16 v[80:83], v[110:113], v[214:217], v[80:83]
	v_mfma_f32_16x16x32_bf16 v[20:23], v[118:121], v[214:217], v[20:23]
	s_setprio 0
	s_setprio 1
	v_mfma_f32_16x16x32_bf16 v[100:103], v[122:125], v[166:169], v[102:105]
	v_mfma_f32_16x16x32_bf16 v[32:35], v[130:133], v[166:169], v[32:35]
	v_mfma_f32_16x16x32_bf16 v[88:91], v[122:125], v[174:177], v[88:91]
	v_mfma_f32_16x16x32_bf16 v[28:31], v[130:133], v[174:177], v[28:31]
	v_mfma_f32_16x16x32_bf16 v[84:87], v[122:125], v[194:197], v[84:87]
	v_mfma_f32_16x16x32_bf16 v[24:27], v[130:133], v[194:197], v[24:27]
	v_mfma_f32_16x16x32_bf16 v[16:19], v[122:125], v[210:213], v[16:19]
	v_mfma_f32_16x16x32_bf16 v[12:15], v[130:133], v[210:213], v[12:15]
	v_mfma_f32_16x16x32_bf16 v[100:103], v[126:129], v[170:173], v[100:103]
	v_mfma_f32_16x16x32_bf16 v[32:35], v[134:137], v[170:173], v[32:35]
	v_mfma_f32_16x16x32_bf16 v[88:91], v[126:129], v[178:181], v[88:91]
	v_mfma_f32_16x16x32_bf16 v[28:31], v[134:137], v[178:181], v[28:31]
	v_mfma_f32_16x16x32_bf16 v[84:87], v[126:129], v[206:209], v[84:87]
	v_mfma_f32_16x16x32_bf16 v[24:27], v[134:137], v[206:209], v[24:27]
	v_mfma_f32_16x16x32_bf16 v[16:19], v[126:129], v[214:217], v[16:19]
	v_mfma_f32_16x16x32_bf16 v[12:15], v[134:137], v[214:217], v[12:15]
	s_barrier
; #define PG8_STAGE(bufoff, gbase, voff) do { _Pragma("unroll") for (int _i = 0; _i < 2; ++_i) \
;         __builtin_amdgcn_global_load_lds((const unsigned*)((const char*)(gbase) + (voff)[_i]), (PG8_LAS unsigned*)(lds + (bufoff) + ldsw + _i * 8192), 16, 0, 0); } while (0)
; #define PG8_LDA(dst, b, h) do { _Pragma("unroll") for (int m = 0; m < 4; ++m) _Pragma("unroll") for (int k = 0; k < 2; ++k) dst[m][k] = *(const PG8_LAS bf16x8*)(lds + PG8_SA(b, h) + aoff + m * 2048 + k * 1024); } while (0)
; #define PG8_LDB(dst, b, h) do { _Pragma("unroll") for (int n = 0; n < 2; ++n) _Pragma("unroll") for (int k = 0; k < 2; ++k) dst[n][k] = *(const PG8_LAS bf16x8*)(lds + PG8_SB(b, h) + boff + n * 2048 + k * 1024); } while (0)
; #define PG8_MMA(ai, bj, At, Bt) do { __builtin_amdgcn_s_setprio(1); _Pragma("unroll") for (int m = 0; m < 4; ++m) _Pragma("unroll") for (int n = 0; n < 2; ++n) _Pragma("unroll") for (int k = 0; k < 2; ++k) \
;         acc[ai][bj][m][n] = __builtin_amdgcn_mfma_f32_16x16x32_bf16(Bt[n][k], At[m][k], acc[ai][bj][m][n], 0, 0, 0); __builtin_amdgcn_s_setprio(0); } while (0)
; #define PG8_WAIT_V(n) asm volatile("s_waitcnt vmcnt(" #n ")" ::: "memory")
; #define PG8_WAIT_L(n) asm volatile("s_waitcnt lgkmcnt(" #n ")" ::: "memory")
; #define PG8_BAR __builtin_amdgcn_s_barrier()
; #define PG8_SCHED __builtin_amdgcn_sched_barrier(0)
;     ...
;             PG8_LDB(B0, 1, 0); PG8_LDB(B1, 1, 1); PG8_SCHED; PG8_LDA(At, 1, 0); PG8_STAGE(PG8_SA(0, 1), a2 + hstep, voffA);
;             PG8_WAIT_V(8); PG8_WAIT_L(0); PG8_BAR; PG8_MMA(0, 0, At, B0); PG8_MMA(0, 1, At, B1); PG8_BAR; PG8_SCHED;
	s_setprio 0
	s_add_i32 s48, 0, 0x18000
	s_add_i32 s49, 0, 0x1c000
	ds_read_b128 v[104:107], v251 offset:32768
	ds_read_b128 v[108:111], v251 offset:33792
	ds_read_b128 v[112:115], v251 offset:34816
	ds_read_b128 v[116:119], v251 offset:35840
	ds_read_b128 v[120:123], v251 offset:49152
	ds_read_b128 v[124:127], v251 offset:50176
	ds_read_b128 v[128:131], v251 offset:51200
	ds_read_b128 v[132:135], v251 offset:52224
	s_add_u32 s14, s14, 0x80000
	s_addc_u32 s15, s15, 0
	s_mov_b32 m0, s5
	v_lshl_add_u64 v[136:137], s[14:15], 0, v[188:189]
	ds_read_b128 v[166:169], v222 offset:32768
	ds_read_b128 v[170:173], v222 offset:33792
	ds_read_b128 v[174:177], v222 offset:34816
	ds_read_b128 v[178:181], v222 offset:35840
	ds_read_b128 v[194:197], v222 offset:36864
	ds_read_b128 v[206:209], v222 offset:37888
	ds_read_b128 v[210:213], v222 offset:38912
	ds_read_b128 v[214:217], v222 offset:39936
	global_load_lds_dwordx4 v[136:137], off
	v_lshl_add_u64 v[136:137], s[14:15], 0, v[184:185]
	s_mov_b32 m0, s44
	s_nop 0
	global_load_lds_dwordx4 v[136:137], off
	s_waitcnt vmcnt(8)
	s_waitcnt lgkmcnt(0)
	s_setprio 1
	s_barrier
	v_mfma_f32_16x16x32_bf16 v[4:7], v[104:107], v[166:169], v[4:7]
	v_mfma_f32_16x16x32_bf16 v[72:75], v[112:115], v[166:169], v[72:75]
	v_mfma_f32_16x16x32_bf16 v[162:165], v[104:107], v[174:177], v[162:165]
	v_mfma_f32_16x16x32_bf16 v[60:63], v[112:115], v[174:177], v[60:63]
	v_mfma_f32_16x16x32_bf16 v[158:161], v[104:107], v[194:197], v[158:161]
	v_mfma_f32_16x16x32_bf16 v[56:59], v[112:115], v[194:197], v[56:59]
	v_mfma_f32_16x16x32_bf16 v[96:99], v[104:107], v[210:213], v[96:99]
	v_mfma_f32_16x16x32_bf16 v[76:79], v[112:115], v[210:213], v[76:79]
	v_mfma_f32_16x16x32_bf16 v[4:7], v[108:111], v[170:173], v[4:7]
	v_mfma_f32_16x16x32_bf16 v[72:75], v[116:119], v[170:173], v[72:75]
	v_mfma_f32_16x16x32_bf16 v[162:165], v[108:111], v[178:181], v[162:165]
	v_mfma_f32_16x16x32_bf16 v[60:63], v[116:119], v[178:181], v[60:63]
	v_mfma_f32_16x16x32_bf16 v[158:161], v[108:111], v[206:209], v[158:161]
	v_mfma_f32_16x16x32_bf16 v[56:59], v[116:119], v[206:209], v[56:59]
	v_mfma_f32_16x16x32_bf16 v[96:99], v[108:111], v[214:217], v[96:99]
	v_mfma_f32_16x16x32_bf16 v[76:79], v[116:119], v[214:217], v[76:79]
	s_setprio 0
	s_setprio 1
	v_mfma_f32_16x16x32_bf16 v[8:11], v[120:123], v[166:169], v[8:11]
	v_mfma_f32_16x16x32_bf16 v[64:67], v[128:131], v[166:169], v[64:67]
	v_mfma_f32_16x16x32_bf16 v[154:157], v[120:123], v[174:177], v[154:157]
	v_mfma_f32_16x16x32_bf16 v[52:55], v[128:131], v[174:177], v[52:55]
	v_mfma_f32_16x16x32_bf16 v[150:153], v[120:123], v[194:197], v[150:153]
	v_mfma_f32_16x16x32_bf16 v[48:51], v[128:131], v[194:197], v[48:51]
	v_mfma_f32_16x16x32_bf16 v[92:95], v[120:123], v[210:213], v[92:95]
	v_mfma_f32_16x16x32_bf16 v[68:71], v[128:131], v[210:213], v[68:71]
	v_mfma_f32_16x16x32_bf16 v[8:11], v[124:127], v[170:173], v[8:11]
	v_mfma_f32_16x16x32_bf16 v[64:67], v[132:135], v[170:173], v[64:67]
	v_mfma_f32_16x16x32_bf16 v[154:157], v[124:127], v[178:181], v[154:157]
	v_mfma_f32_16x16x32_bf16 v[52:55], v[132:135], v[178:181], v[52:55]
	v_mfma_f32_16x16x32_bf16 v[150:153], v[124:127], v[206:209], v[150:153]
	v_mfma_f32_16x16x32_bf16 v[48:51], v[132:135], v[206:209], v[48:51]
	v_mfma_f32_16x16x32_bf16 v[92:95], v[124:127], v[214:217], v[92:95]
	v_mfma_f32_16x16x32_bf16 v[68:71], v[132:135], v[214:217], v[68:71]
	s_barrier
; #define PG8_STAGE(bufoff, gbase, voff) do { _Pragma("unroll") for (int _i = 0; _i < 2; ++_i) \
;         __builtin_amdgcn_global_load_lds((const unsigned*)((const char*)(gbase) + (voff)[_i]), (PG8_LAS unsigned*)(lds + (bufoff) + ldsw + _i * 8192), 16, 0, 0); } while (0)
; #define PG8_LDA(dst, b, h) do { _Pragma("unroll") for (int m = 0; m < 4; ++m) _Pragma("unroll") for (int k = 0; k < 2; ++k) dst[m][k] = *(const PG8_LAS bf16x8*)(lds + PG8_SA(b, h) + aoff + m * 2048 + k * 1024); } while (0)
; #define PG8_MMA(ai, bj, At, Bt) do { __builtin_amdgcn_s_setprio(1); _Pragma("unroll") for (int m = 0; m < 4; ++m) _Pragma("unroll") for (int n = 0; n < 2; ++n) _Pragma("unroll") for (int k = 0; k < 2; ++k) \
;         acc[ai][bj][m][n] = __builtin_amdgcn_mfma_f32_16x16x32_bf16(Bt[n][k], At[m][k], acc[ai][bj][m][n], 0, 0, 0); __builtin_amdgcn_s_setprio(0); } while (0)
; #define PG8_WAIT_V(n) asm volatile("s_waitcnt vmcnt(" #n ")" ::: "memory")
; #define PG8_WAIT_L(n) asm volatile("s_waitcnt lgkmcnt(" #n ")" ::: "memory")
; #define PG8_BAR __builtin_amdgcn_s_barrier()
; #define PG8_SCHED __builtin_amdgcn_sched_barrier(0)
;     ...
;             PG8_LDA(At, 1, 1); PG8_STAGE(PG8_SB(1, 0), b3, voffB); PG8_STAGE(PG8_SB(1, 1), b3 + hstep, voffB); PG8_STAGE(PG8_SA(1, 0), a3, voffA);
;             PG8_WAIT_V(8); PG8_WAIT_L(0); PG8_BAR; PG8_MMA(1, 0, At, B0); PG8_MMA(1, 1, At, B1); PG8_BAR; PG8_SCHED;
;     ...
;         if constexpr (ALIGN_EPI) { if (wr == 0) PG8_BAR; }
	s_setprio 0
	s_add_i32 s14, s48, s0
	v_lshl_add_u64 v[136:137], v[198:199], 0, s[66:67]
	s_mov_b32 m0, s14
	ds_read_b128 v[166:169], v222 offset:49152
	ds_read_b128 v[170:173], v222 offset:50176
	ds_read_b128 v[174:177], v222 offset:51200
	ds_read_b128 v[178:181], v222 offset:52224
	ds_read_b128 v[194:197], v222 offset:53248
	ds_read_b128 v[206:209], v222 offset:54272
	ds_read_b128 v[210:213], v222 offset:55296
	ds_read_b128 v[214:217], v222 offset:56320
	global_load_lds_dwordx4 v[136:137], off
	s_add_i32 m0, s14, 0x2000
	s_add_u32 s12, s12, 0x80080
	v_lshl_add_u64 v[136:137], v[218:219], 0, s[66:67]
	s_addc_u32 s13, s13, 0
	s_add_i32 s14, s49, s0
	global_load_lds_dwordx4 v[136:137], off
	v_lshl_add_u64 v[136:137], s[12:13], 0, v[186:187]
	s_mov_b32 m0, s14
	s_nop 0
	global_load_lds_dwordx4 v[136:137], off
	v_lshl_add_u64 v[136:137], s[12:13], 0, v[182:183]
	s_add_i32 m0, s14, 0x2000
	s_nop 0
	global_load_lds_dwordx4 v[136:137], off
	v_lshl_add_u64 v[136:137], v[224:225], 0, s[66:67]
	s_mov_b32 m0, s81
	s_nop 0
	global_load_lds_dwordx4 v[136:137], off
	v_lshl_add_u64 v[136:137], v[232:233], 0, s[66:67]
	s_mov_b32 m0, s42
	s_nop 0
	global_load_lds_dwordx4 v[136:137], off
	s_waitcnt vmcnt(8)
	s_waitcnt lgkmcnt(0)
	s_setprio 1
	s_barrier
	v_mfma_f32_16x16x32_bf16 v[146:149], v[104:107], v[166:169], v[146:149]
	v_mfma_f32_16x16x32_bf16 v[44:47], v[112:115], v[166:169], v[44:47]
	v_mfma_f32_16x16x32_bf16 v[142:145], v[104:107], v[174:177], v[142:145]
	v_mfma_f32_16x16x32_bf16 v[40:43], v[112:115], v[174:177], v[40:43]
	v_mfma_f32_16x16x32_bf16 v[136:139], v[104:107], v[194:197], v[138:141]
	v_mfma_f32_16x16x32_bf16 v[36:39], v[112:115], v[194:197], v[36:39]
	v_mfma_f32_16x16x32_bf16 v[80:83], v[104:107], v[210:213], v[80:83]
	v_mfma_f32_16x16x32_bf16 v[20:23], v[112:115], v[210:213], v[20:23]
	v_mfma_f32_16x16x32_bf16 v[146:149], v[108:111], v[170:173], v[146:149]
	v_mfma_f32_16x16x32_bf16 v[44:47], v[116:119], v[170:173], v[44:47]
	v_mfma_f32_16x16x32_bf16 v[142:145], v[108:111], v[178:181], v[142:145]
	v_mfma_f32_16x16x32_bf16 v[40:43], v[116:119], v[178:181], v[40:43]
	v_mfma_f32_16x16x32_bf16 v[138:141], v[108:111], v[206:209], v[136:139]
	v_mfma_f32_16x16x32_bf16 v[36:39], v[116:119], v[206:209], v[36:39]
	v_mfma_f32_16x16x32_bf16 v[80:83], v[108:111], v[214:217], v[80:83]
	v_mfma_f32_16x16x32_bf16 v[20:23], v[116:119], v[214:217], v[20:23]
	s_setprio 0
	s_setprio 1
	v_mfma_f32_16x16x32_bf16 v[100:103], v[120:123], v[166:169], v[100:103]
	v_mfma_f32_16x16x32_bf16 v[32:35], v[128:131], v[166:169], v[32:35]
	v_mfma_f32_16x16x32_bf16 v[88:91], v[120:123], v[174:177], v[88:91]
	v_mfma_f32_16x16x32_bf16 v[28:31], v[128:131], v[174:177], v[28:31]
	v_mfma_f32_16x16x32_bf16 v[84:87], v[120:123], v[194:197], v[84:87]
	v_mfma_f32_16x16x32_bf16 v[24:27], v[128:131], v[194:197], v[24:27]
	v_mfma_f32_16x16x32_bf16 v[16:19], v[120:123], v[210:213], v[16:19]
	v_mfma_f32_16x16x32_bf16 v[12:15], v[128:131], v[210:213], v[12:15]
	v_mfma_f32_16x16x32_bf16 v[102:105], v[124:127], v[170:173], v[100:103]
	v_mfma_f32_16x16x32_bf16 v[32:35], v[132:135], v[170:173], v[32:35]
	v_mfma_f32_16x16x32_bf16 v[88:91], v[124:127], v[178:181], v[88:91]
	v_mfma_f32_16x16x32_bf16 v[28:31], v[132:135], v[178:181], v[28:31]
	v_mfma_f32_16x16x32_bf16 v[84:87], v[124:127], v[206:209], v[84:87]
	v_mfma_f32_16x16x32_bf16 v[24:27], v[132:135], v[206:209], v[24:27]
	v_mfma_f32_16x16x32_bf16 v[16:19], v[124:127], v[214:217], v[16:19]
	v_mfma_f32_16x16x32_bf16 v[12:15], v[132:135], v[214:217], v[12:15]
	s_barrier
	s_setprio 0
	s_add_i32 s89, s89, 2
	s_add_u32 s10, s10, 0x100
	s_addc_u32 s11, s11, 0
	s_add_u32 s82, s82, 0x100
	s_addc_u32 s83, s83, 0
	s_cmp_gt_u32 s89, 29
	s_cbranch_scc0 .LBB0_542
	s_and_b64 vcc, exec, s[70:71]
	s_cbranch_vccz .LBB0_545
	s_barrier

;     __device__ __forceinline__ bool next(int i, Unit& u) const { if (i >= n) return false; u.pm = pm; u.pn = pn0 + i; return true; }
;     __device__ __forceinline__ bool next(int i, Unit& u) const { if (i) return false; u.pm = pm; u.pn = pn; return true; }
; #define PG8_STAGE(bufoff, gbase, voff) do { _Pragma("unroll") for (int _i = 0; _i < 2; ++_i) \
;         __builtin_amdgcn_global_load_lds((const unsigned*)((const char*)(gbase) + (voff)[_i]), (PG8_LAS unsigned*)(lds + (bufoff) + ldsw + _i * 8192), 16, 0, 0); } while (0)
; #define PG8_LDA(dst, b, h) do { _Pragma("unroll") for (int m = 0; m < 4; ++m) _Pragma("unroll") for (int k = 0; k < 2; ++k) dst[m][k] = *(const PG8_LAS bf16x8*)(lds + PG8_SA(b, h) + aoff + m * 2048 + k * 1024); } while (0)
; #define PG8_LDB(dst, b, h) do { _Pragma("unroll") for (int n = 0; n < 2; ++n) _Pragma("unroll") for (int k = 0; k < 2; ++k) dst[n][k] = *(const PG8_LAS bf16x8*)(lds + PG8_SB(b, h) + boff + n * 2048 + k * 1024); } while (0)
; #define PG8_WAIT_V(n) asm volatile("s_waitcnt vmcnt(" #n ")" ::: "memory")
; #define PG8_BAR __builtin_amdgcn_s_barrier()
;     ...
;         const bool has_next = S.next(ui + 1, nxt);
;         const char* nA = has_next ? (const char*)g.A + (size_t)nxt.pm * tstep : cA; const char* nB = has_next ? (const char*)g.Bt + (size_t)nxt.pn * tstep : cB;
;         for (int t = 0; t < nt; t += 2) {
;             const bool last = (t == nt - 2);
;             const char* a1 = cA + (size_t)(t + 1) * kstep;
;             const char* a2 = last ? nA : cA + (size_t)(t + 2) * kstep; const char* b2 = last ? nB : cB + (size_t)(t + 2) * kstep;
;             const char* a3 = a2 + kstep; const char* b3 = b2 + kstep;
;             if (last && has_next) S.a_ready(nxt);
;             if (t == 0) E.pre_issue(pre, cur, tid, ui); else if (t == 2) E.pre_finish(pre, tid, ui);
;             if constexpr (SP2) {
;             PG8_LDB(B0, 0, 0); PG8_LDB(B1, 0, 1); PG8_SCHED; PG8_LDA(At, 0, 0); PG8_STAGE(PG8_SA(1, 1), a1 + hstep, voffA);
;             PG8_WAIT_V(8); PG8_WAIT_L(0); PG8_BAR; PG8_MMA(0, 0, At, B0); PG8_MMA(0, 1, At, B1); PG8_BAR; PG8_SCHED;
;     ...
;         for (int a = 0; a < 2; ++a)
; #pragma unroll
;             for (int b = 0; b < 2; ++b)
; #pragma unroll
;                 for (int m = 0; m < 4; ++m)
; #pragma unroll
;                     for (int n = 0; n < 2; ++n) acc[a][b][m][n] = (f32x4){0.f, 0.f, 0.f, 0.f};
.LBB0_666:
	s_add_u32 s73, s68, 0x100
	v_mov_b32_e32 v4, 0
	s_addc_u32 s75, s69, 0
	s_mov_b32 s78, -2
	v_mov_b32_e32 v5, v4
	v_mov_b32_e32 v6, v4
	v_mov_b32_e32 v7, v4
	v_mov_b32_e32 v8, v4
	v_mov_b32_e32 v9, v4
	v_mov_b32_e32 v10, v4
	v_mov_b32_e32 v11, v4
	v_mov_b32_e32 v20, v4
	v_mov_b32_e32 v21, v4
	v_mov_b32_e32 v22, v4
	v_mov_b32_e32 v23, v4
	s_waitcnt vmcnt(0)
	v_mov_b32_e32 v24, v4
	v_mov_b32_e32 v25, v4
	v_mov_b32_e32 v26, v4
	v_mov_b32_e32 v27, v4
	v_mov_b32_e32 v36, v4
	v_mov_b32_e32 v37, v4
	v_mov_b32_e32 v38, v4
	v_mov_b32_e32 v39, v4
	v_mov_b32_e32 v40, v4
	v_mov_b32_e32 v41, v4
	v_mov_b32_e32 v42, v4
	v_mov_b32_e32 v43, v4
	v_mov_b32_e32 v52, v4
	v_mov_b32_e32 v53, v4
	v_mov_b32_e32 v54, v4
	v_mov_b32_e32 v55, v4
	v_mov_b32_e32 v56, v4
	v_mov_b32_e32 v57, v4
	v_mov_b32_e32 v58, v4
	v_mov_b32_e32 v59, v4
	v_mov_b32_e32 v12, v4
	v_mov_b32_e32 v13, v4
	v_mov_b32_e32 v14, v4
	v_mov_b32_e32 v15, v4
	v_mov_b32_e32 v16, v4
	v_mov_b32_e32 v17, v4
	v_mov_b32_e32 v18, v4
	v_mov_b32_e32 v19, v4
	v_mov_b32_e32 v28, v4
	v_mov_b32_e32 v29, v4
	v_mov_b32_e32 v30, v4
	v_mov_b32_e32 v31, v4
	v_mov_b32_e32 v32, v4
	v_mov_b32_e32 v33, v4
	v_mov_b32_e32 v34, v4
	v_mov_b32_e32 v35, v4
	v_mov_b32_e32 v44, v4
	v_mov_b32_e32 v45, v4
	v_mov_b32_e32 v46, v4
	v_mov_b32_e32 v47, v4
	v_mov_b32_e32 v48, v4
	v_mov_b32_e32 v49, v4
	v_mov_b32_e32 v50, v4
	v_mov_b32_e32 v51, v4
	v_mov_b32_e32 v60, v4
	v_mov_b32_e32 v61, v4
	v_mov_b32_e32 v62, v4
	v_mov_b32_e32 v63, v4
	v_mov_b32_e32 v64, v4
	v_mov_b32_e32 v65, v4
	v_mov_b32_e32 v66, v4
	v_mov_b32_e32 v67, v4
	v_mov_b32_e32 v68, v4
	v_mov_b32_e32 v69, v4
	v_mov_b32_e32 v70, v4
	v_mov_b32_e32 v71, v4
	v_mov_b32_e32 v72, v4
	v_mov_b32_e32 v73, v4
	v_mov_b32_e32 v74, v4
	v_mov_b32_e32 v75, v4
	v_mov_b32_e32 v84, v4
	v_mov_b32_e32 v85, v4
	v_mov_b32_e32 v86, v4
	v_mov_b32_e32 v87, v4
	v_mov_b32_e32 v88, v4
	v_mov_b32_e32 v89, v4
	v_mov_b32_e32 v90, v4
	v_mov_b32_e32 v91, v4
	v_mov_b32_e32 v100, v4
	v_mov_b32_e32 v101, v4
	v_mov_b32_e32 v102, v4
	v_mov_b32_e32 v103, v4
	v_mov_b32_e32 v104, v4
	v_mov_b32_e32 v105, v4
	v_mov_b32_e32 v106, v4
	v_mov_b32_e32 v107, v4
	v_mov_b32_e32 v124, v4
	v_mov_b32_e32 v125, v4
	v_mov_b32_e32 v126, v4
	v_mov_b32_e32 v127, v4
	v_mov_b32_e32 v132, v4
	v_mov_b32_e32 v133, v4
	v_mov_b32_e32 v134, v4
	v_mov_b32_e32 v135, v4
	v_mov_b32_e32 v76, v4
	v_mov_b32_e32 v77, v4
	v_mov_b32_e32 v78, v4
	v_mov_b32_e32 v79, v4
	v_mov_b32_e32 v80, v4
	v_mov_b32_e32 v81, v4
	v_mov_b32_e32 v82, v4
	v_mov_b32_e32 v83, v4
	v_mov_b32_e32 v92, v4
	v_mov_b32_e32 v93, v4
	v_mov_b32_e32 v94, v4
	v_mov_b32_e32 v95, v4
	v_mov_b32_e32 v96, v4
	v_mov_b32_e32 v97, v4
	v_mov_b32_e32 v98, v4
	v_mov_b32_e32 v99, v4
	v_mov_b32_e32 v116, v4
	v_mov_b32_e32 v117, v4
	v_mov_b32_e32 v118, v4
	v_mov_b32_e32 v119, v4
	v_mov_b32_e32 v120, v4
	v_mov_b32_e32 v121, v4
	v_mov_b32_e32 v122, v4
	v_mov_b32_e32 v123, v4
	v_mov_b32_e32 v140, v4
	v_mov_b32_e32 v141, v4
	v_mov_b32_e32 v142, v4
	v_mov_b32_e32 v143, v4
	v_mov_b32_e32 v144, v4
	v_mov_b32_e32 v145, v4
	v_mov_b32_e32 v146, v4
	v_mov_b32_e32 v147, v4
	v_add_u32_e32 v251, 0x10000, v233
.LBB0_667:
	s_add_u32 s68, s62, 0x100
	s_addc_u32 s69, s63, 0
	s_add_i32 s48, 0, 0x10000
	s_cmpk_eq_i32 s78, 0x54
	s_cselect_b32 s77, s11, s69
	s_cselect_b32 s76, s10, s68
	s_cselect_b32 s71, s61, s75
	s_cselect_b32 s70, s60, s73
	s_add_i32 s49, 0, 0x14000
	ds_read_b128 v[108:111], v251
	ds_read_b128 v[112:115], v251 offset:1024
	ds_read_b128 v[128:131], v251 offset:2048
	ds_read_b128 v[136:139], v251 offset:3072
	ds_read_b128 v[148:151], v251 offset:16384
	ds_read_b128 v[152:155], v251 offset:17408
	ds_read_b128 v[156:159], v251 offset:18432
	ds_read_b128 v[160:163], v251 offset:19456
	v_lshl_add_u64 v[198:199], s[62:63], 0, v[196:197]
	s_add_i32 m0, s6, 0xc000
	ds_read_b128 v[164:167], v234
	ds_read_b128 v[168:171], v234 offset:1024
	ds_read_b128 v[172:175], v234 offset:2048
	ds_read_b128 v[176:179], v234 offset:3072
	ds_read_b128 v[180:183], v234 offset:4096
	ds_read_b128 v[184:187], v234 offset:5120
	ds_read_b128 v[206:209], v234 offset:6144
	ds_read_b128 v[210:213], v234 offset:7168
	global_load_lds_dwordx4 v[198:199], off
	v_lshl_add_u64 v[198:199], s[62:63], 0, v[194:195]
	s_add_i32 m0, s6, 0xe000
	s_nop 0
	global_load_lds_dwordx4 v[198:199], off
	s_waitcnt vmcnt(8)
	s_waitcnt lgkmcnt(0)
	s_setprio 1
	s_barrier
	v_mfma_f32_16x16x32_bf16 v[144:147], v[108:111], v[164:167], v[144:147]
	v_mfma_f32_16x16x32_bf16 v[140:143], v[128:131], v[164:167], v[140:143]
	v_mfma_f32_16x16x32_bf16 v[120:123], v[108:111], v[172:175], v[120:123]
	v_mfma_f32_16x16x32_bf16 v[116:119], v[128:131], v[172:175], v[116:119]
	v_mfma_f32_16x16x32_bf16 v[96:99], v[108:111], v[180:183], v[96:99]
	v_mfma_f32_16x16x32_bf16 v[92:95], v[128:131], v[180:183], v[92:95]
	v_mfma_f32_16x16x32_bf16 v[80:83], v[108:111], v[206:209], v[80:83]
	v_mfma_f32_16x16x32_bf16 v[76:79], v[128:131], v[206:209], v[76:79]
	v_mfma_f32_16x16x32_bf16 v[144:147], v[112:115], v[168:171], v[144:147]
	v_mfma_f32_16x16x32_bf16 v[140:143], v[136:139], v[168:171], v[140:143]
	v_mfma_f32_16x16x32_bf16 v[120:123], v[112:115], v[176:179], v[120:123]
	v_mfma_f32_16x16x32_bf16 v[116:119], v[136:139], v[176:179], v[116:119]
	v_mfma_f32_16x16x32_bf16 v[96:99], v[112:115], v[184:187], v[96:99]
	v_mfma_f32_16x16x32_bf16 v[92:95], v[136:139], v[184:187], v[92:95]
	v_mfma_f32_16x16x32_bf16 v[80:83], v[112:115], v[210:213], v[80:83]
	v_mfma_f32_16x16x32_bf16 v[76:79], v[136:139], v[210:213], v[76:79]
	s_setprio 0
	s_setprio 1
	v_mfma_f32_16x16x32_bf16 v[132:135], v[148:151], v[164:167], v[132:135]
	v_mfma_f32_16x16x32_bf16 v[124:127], v[156:159], v[164:167], v[124:127]
	v_mfma_f32_16x16x32_bf16 v[104:107], v[148:151], v[172:175], v[104:107]
	v_mfma_f32_16x16x32_bf16 v[100:103], v[156:159], v[172:175], v[100:103]
	v_mfma_f32_16x16x32_bf16 v[88:91], v[148:151], v[180:183], v[88:91]
	v_mfma_f32_16x16x32_bf16 v[84:87], v[156:159], v[180:183], v[84:87]
	v_mfma_f32_16x16x32_bf16 v[72:75], v[148:151], v[206:209], v[72:75]
	v_mfma_f32_16x16x32_bf16 v[68:71], v[156:159], v[206:209], v[68:71]
	v_mfma_f32_16x16x32_bf16 v[132:135], v[152:155], v[168:171], v[132:135]
	v_mfma_f32_16x16x32_bf16 v[124:127], v[160:163], v[168:171], v[124:127]
	v_mfma_f32_16x16x32_bf16 v[104:107], v[152:155], v[176:179], v[104:107]
	v_mfma_f32_16x16x32_bf16 v[100:103], v[160:163], v[176:179], v[100:103]
	v_mfma_f32_16x16x32_bf16 v[88:91], v[152:155], v[184:187], v[88:91]
	v_mfma_f32_16x16x32_bf16 v[84:87], v[160:163], v[184:187], v[84:87]
	v_mfma_f32_16x16x32_bf16 v[72:75], v[152:155], v[210:213], v[72:75]
	v_mfma_f32_16x16x32_bf16 v[68:71], v[160:163], v[210:213], v[68:71]
	s_barrier
; #define PG8_STAGE(bufoff, gbase, voff) do { _Pragma("unroll") for (int _i = 0; _i < 2; ++_i) \
;         __builtin_amdgcn_global_load_lds((const unsigned*)((const char*)(gbase) + (voff)[_i]), (PG8_LAS unsigned*)(lds + (bufoff) + ldsw + _i * 8192), 16, 0, 0); } while (0)
; #define PG8_LDA(dst, b, h) do { _Pragma("unroll") for (int m = 0; m < 4; ++m) _Pragma("unroll") for (int k = 0; k < 2; ++k) dst[m][k] = *(const PG8_LAS bf16x8*)(lds + PG8_SA(b, h) + aoff + m * 2048 + k * 1024); } while (0)
; #define PG8_LDB(dst, b, h) do { _Pragma("unroll") for (int n = 0; n < 2; ++n) _Pragma("unroll") for (int k = 0; k < 2; ++k) dst[n][k] = *(const PG8_LAS bf16x8*)(lds + PG8_SB(b, h) + boff + n * 2048 + k * 1024); } while (0)
; #define PG8_MMA(ai, bj, At, Bt) do { __builtin_amdgcn_s_setprio(1); _Pragma("unroll") for (int m = 0; m < 4; ++m) _Pragma("unroll") for (int n = 0; n < 2; ++n) _Pragma("unroll") for (int k = 0; k < 2; ++k) \
;         acc[ai][bj][m][n] = __builtin_amdgcn_mfma_f32_16x16x32_bf16(Bt[n][k], At[m][k], acc[ai][bj][m][n], 0, 0, 0); __builtin_amdgcn_s_setprio(0); } while (0)
; #define PG8_WAIT_V(n) asm volatile("s_waitcnt vmcnt(" #n ")" ::: "memory")
; #define PG8_WAIT_L(n) asm volatile("s_waitcnt lgkmcnt(" #n ")" ::: "memory")
; #define PG8_BAR __builtin_amdgcn_s_barrier()
; #define PG8_SCHED __builtin_amdgcn_sched_barrier(0)
;     ...
;             PG8_WAIT_V(8); PG8_WAIT_L(0); PG8_BAR; PG8_MMA(0, 0, At, B0); PG8_MMA(0, 1, At, B1); PG8_BAR; PG8_SCHED;
;             PG8_LDA(At, 0, 1); PG8_STAGE(PG8_SB(0, 0), b2, voffB); PG8_STAGE(PG8_SB(0, 1), b2 + hstep, voffB); PG8_STAGE(PG8_SA(0, 0), a2, voffA);
;             PG8_WAIT_V(8); PG8_WAIT_L(0); PG8_BAR; PG8_MMA(1, 0, At, B0); PG8_MMA(1, 1, At, B1); PG8_BAR; PG8_SCHED;
;             PG8_LDB(B0, 1, 0); PG8_LDB(B1, 1, 1); PG8_SCHED; PG8_LDA(At, 1, 0); PG8_STAGE(PG8_SA(0, 1), a2 + hstep, voffA);
;             PG8_WAIT_V(8); PG8_WAIT_L(0); PG8_BAR; PG8_MMA(0, 0, At, B0); PG8_MMA(0, 1, At, B1); PG8_BAR; PG8_SCHED;
	s_setprio 0
	s_add_i32 s48, s48, s5
	v_lshl_add_u64 v[198:199], s[70:71], 0, v[200:201]
	s_mov_b32 m0, s48
	ds_read_b128 v[164:167], v234 offset:16384
	ds_read_b128 v[168:171], v234 offset:17408
	ds_read_b128 v[172:175], v234 offset:18432
	ds_read_b128 v[176:179], v234 offset:19456
	ds_read_b128 v[180:183], v234 offset:20480
	ds_read_b128 v[184:187], v234 offset:21504
	ds_read_b128 v[206:209], v234 offset:22528
	ds_read_b128 v[210:213], v234 offset:23552
	global_load_lds_dwordx4 v[198:199], off
	s_add_i32 m0, s48, 0x2000
	s_add_u32 s62, s70, 0x160000
	v_lshl_add_u64 v[214:215], s[70:71], 0, v[188:189]
	s_addc_u32 s63, s71, 0
	s_add_i32 s48, s49, s5
	global_load_lds_dwordx4 v[214:215], off
	v_lshl_add_u64 v[216:217], s[62:63], 0, v[200:201]
	s_mov_b32 m0, s48
	v_lshl_add_u64 v[218:219], s[76:77], 0, v[190:191]
	global_load_lds_dwordx4 v[216:217], off
	v_lshl_add_u64 v[216:217], s[62:63], 0, v[188:189]
	s_add_i32 m0, s48, 0x2000
	s_nop 0
	global_load_lds_dwordx4 v[216:217], off
	v_lshl_add_u64 v[216:217], s[76:77], 0, v[192:193]
	s_mov_b32 m0, s6
	s_nop 0
	global_load_lds_dwordx4 v[216:217], off
	s_mov_b32 m0, s7
	s_nop 0
	global_load_lds_dwordx4 v[218:219], off
	s_waitcnt vmcnt(8)
	s_waitcnt lgkmcnt(0)
	s_setprio 1
	s_barrier
	v_mfma_f32_16x16x32_bf16 v[64:67], v[108:111], v[164:167], v[64:67]
	v_mfma_f32_16x16x32_bf16 v[60:63], v[128:131], v[164:167], v[60:63]
	v_mfma_f32_16x16x32_bf16 v[48:51], v[108:111], v[172:175], v[48:51]
	v_mfma_f32_16x16x32_bf16 v[44:47], v[128:131], v[172:175], v[44:47]
	v_mfma_f32_16x16x32_bf16 v[32:35], v[108:111], v[180:183], v[32:35]
	v_mfma_f32_16x16x32_bf16 v[28:31], v[128:131], v[180:183], v[28:31]
	v_mfma_f32_16x16x32_bf16 v[16:19], v[108:111], v[206:209], v[16:19]
	v_mfma_f32_16x16x32_bf16 v[12:15], v[128:131], v[206:209], v[12:15]
	v_mfma_f32_16x16x32_bf16 v[64:67], v[112:115], v[168:171], v[64:67]
	v_mfma_f32_16x16x32_bf16 v[60:63], v[136:139], v[168:171], v[60:63]
	v_mfma_f32_16x16x32_bf16 v[48:51], v[112:115], v[176:179], v[48:51]
	v_mfma_f32_16x16x32_bf16 v[44:47], v[136:139], v[176:179], v[44:47]
	v_mfma_f32_16x16x32_bf16 v[32:35], v[112:115], v[184:187], v[32:35]
	v_mfma_f32_16x16x32_bf16 v[28:31], v[136:139], v[184:187], v[28:31]
	v_mfma_f32_16x16x32_bf16 v[16:19], v[112:115], v[210:213], v[16:19]
	v_mfma_f32_16x16x32_bf16 v[12:15], v[136:139], v[210:213], v[12:15]
	s_setprio 0
	s_setprio 1
	v_mfma_f32_16x16x32_bf16 v[56:59], v[148:151], v[164:167], v[56:59]
	v_mfma_f32_16x16x32_bf16 v[52:55], v[156:159], v[164:167], v[52:55]
	v_mfma_f32_16x16x32_bf16 v[40:43], v[148:151], v[172:175], v[40:43]
	v_mfma_f32_16x16x32_bf16 v[36:39], v[156:159], v[172:175], v[36:39]
	v_mfma_f32_16x16x32_bf16 v[24:27], v[148:151], v[180:183], v[24:27]
	v_mfma_f32_16x16x32_bf16 v[20:23], v[156:159], v[180:183], v[20:23]
	v_mfma_f32_16x16x32_bf16 v[8:11], v[148:151], v[206:209], v[8:11]
	v_mfma_f32_16x16x32_bf16 v[4:7], v[156:159], v[206:209], v[4:7]
	v_mfma_f32_16x16x32_bf16 v[56:59], v[152:155], v[168:171], v[56:59]
	v_mfma_f32_16x16x32_bf16 v[52:55], v[160:163], v[168:171], v[52:55]
	v_mfma_f32_16x16x32_bf16 v[40:43], v[152:155], v[176:179], v[40:43]
	v_mfma_f32_16x16x32_bf16 v[36:39], v[160:163], v[176:179], v[36:39]
	v_mfma_f32_16x16x32_bf16 v[24:27], v[152:155], v[184:187], v[24:27]
	v_mfma_f32_16x16x32_bf16 v[20:23], v[160:163], v[184:187], v[20:23]
	v_mfma_f32_16x16x32_bf16 v[8:11], v[152:155], v[210:213], v[8:11]
	v_mfma_f32_16x16x32_bf16 v[4:7], v[160:163], v[210:213], v[4:7]
	s_barrier
	s_setprio 0
	s_add_i32 s48, 0, 0x18000
	s_add_i32 s49, 0, 0x1c000
	ds_read_b128 v[108:111], v251 offset:32768
	ds_read_b128 v[112:115], v251 offset:33792
	ds_read_b128 v[128:131], v251 offset:34816
	ds_read_b128 v[136:139], v251 offset:35840
	ds_read_b128 v[148:151], v251 offset:49152
	ds_read_b128 v[152:155], v251 offset:50176
	ds_read_b128 v[156:159], v251 offset:51200
	ds_read_b128 v[160:163], v251 offset:52224
	s_add_u32 s62, s76, 0x160000
	s_addc_u32 s63, s77, 0
	s_mov_b32 m0, s20
	v_lshl_add_u64 v[220:221], s[62:63], 0, v[192:193]
	ds_read_b128 v[164:167], v234 offset:32768
	ds_read_b128 v[168:171], v234 offset:33792
	ds_read_b128 v[172:175], v234 offset:34816
	ds_read_b128 v[176:179], v234 offset:35840
	ds_read_b128 v[180:183], v234 offset:36864
	ds_read_b128 v[184:187], v234 offset:37888
	ds_read_b128 v[206:209], v234 offset:38912
	ds_read_b128 v[210:213], v234 offset:39936
	global_load_lds_dwordx4 v[220:221], off
	v_lshl_add_u64 v[220:221], s[62:63], 0, v[190:191]
	s_mov_b32 m0, s21
	s_nop 0
	global_load_lds_dwordx4 v[220:221], off
	s_waitcnt vmcnt(8)
	s_waitcnt lgkmcnt(0)
	s_setprio 1
	s_barrier
; #define PG8_STAGE(bufoff, gbase, voff) do { _Pragma("unroll") for (int _i = 0; _i < 2; ++_i) \
;         __builtin_amdgcn_global_load_lds((const unsigned*)((const char*)(gbase) + (voff)[_i]), (PG8_LAS unsigned*)(lds + (bufoff) + ldsw + _i * 8192), 16, 0, 0); } while (0)
; #define PG8_LDA(dst, b, h) do { _Pragma("unroll") for (int m = 0; m < 4; ++m) _Pragma("unroll") for (int k = 0; k < 2; ++k) dst[m][k] = *(const PG8_LAS bf16x8*)(lds + PG8_SA(b, h) + aoff + m * 2048 + k * 1024); } while (0)
; #define PG8_MMA(ai, bj, At, Bt) do { __builtin_amdgcn_s_setprio(1); _Pragma("unroll") for (int m = 0; m < 4; ++m) _Pragma("unroll") for (int n = 0; n < 2; ++n) _Pragma("unroll") for (int k = 0; k < 2; ++k) \
;         acc[ai][bj][m][n] = __builtin_amdgcn_mfma_f32_16x16x32_bf16(Bt[n][k], At[m][k], acc[ai][bj][m][n], 0, 0, 0); __builtin_amdgcn_s_setprio(0); } while (0)
; #define PG8_WAIT_V(n) asm volatile("s_waitcnt vmcnt(" #n ")" ::: "memory")
; #define PG8_WAIT_L(n) asm volatile("s_waitcnt lgkmcnt(" #n ")" ::: "memory")
; #define PG8_BAR __builtin_amdgcn_s_barrier()
; #define PG8_SCHED __builtin_amdgcn_sched_barrier(0)
;     ...
;             PG8_WAIT_V(8); PG8_WAIT_L(0); PG8_BAR; PG8_MMA(0, 0, At, B0); PG8_MMA(0, 1, At, B1); PG8_BAR; PG8_SCHED;
;             PG8_LDA(At, 1, 1); PG8_STAGE(PG8_SB(1, 0), b3, voffB); PG8_STAGE(PG8_SB(1, 1), b3 + hstep, voffB); PG8_STAGE(PG8_SA(1, 0), a3, voffA);
;             PG8_WAIT_V(8); PG8_WAIT_L(0); PG8_BAR; PG8_MMA(1, 0, At, B0); PG8_MMA(1, 1, At, B1); PG8_BAR; PG8_SCHED;
;     ...
;         if constexpr (ALIGN_EPI) { if (wr == 0) PG8_BAR; }
	v_mfma_f32_16x16x32_bf16 v[144:147], v[108:111], v[164:167], v[144:147]
	v_mfma_f32_16x16x32_bf16 v[140:143], v[128:131], v[164:167], v[140:143]
	v_mfma_f32_16x16x32_bf16 v[120:123], v[108:111], v[172:175], v[120:123]
	v_mfma_f32_16x16x32_bf16 v[116:119], v[128:131], v[172:175], v[116:119]
	v_mfma_f32_16x16x32_bf16 v[96:99], v[108:111], v[180:183], v[96:99]
	v_mfma_f32_16x16x32_bf16 v[92:95], v[128:131], v[180:183], v[92:95]
	v_mfma_f32_16x16x32_bf16 v[80:83], v[108:111], v[206:209], v[80:83]
	v_mfma_f32_16x16x32_bf16 v[76:79], v[128:131], v[206:209], v[76:79]
	v_mfma_f32_16x16x32_bf16 v[144:147], v[112:115], v[168:171], v[144:147]
	v_mfma_f32_16x16x32_bf16 v[140:143], v[136:139], v[168:171], v[140:143]
	v_mfma_f32_16x16x32_bf16 v[120:123], v[112:115], v[176:179], v[120:123]
	v_mfma_f32_16x16x32_bf16 v[116:119], v[136:139], v[176:179], v[116:119]
	v_mfma_f32_16x16x32_bf16 v[96:99], v[112:115], v[184:187], v[96:99]
	v_mfma_f32_16x16x32_bf16 v[92:95], v[136:139], v[184:187], v[92:95]
	v_mfma_f32_16x16x32_bf16 v[80:83], v[112:115], v[210:213], v[80:83]
	v_mfma_f32_16x16x32_bf16 v[76:79], v[136:139], v[210:213], v[76:79]
	s_setprio 0
	s_setprio 1
	v_mfma_f32_16x16x32_bf16 v[132:135], v[148:151], v[164:167], v[132:135]
	v_mfma_f32_16x16x32_bf16 v[124:127], v[156:159], v[164:167], v[124:127]
	v_mfma_f32_16x16x32_bf16 v[104:107], v[148:151], v[172:175], v[104:107]
	v_mfma_f32_16x16x32_bf16 v[100:103], v[156:159], v[172:175], v[100:103]
	v_mfma_f32_16x16x32_bf16 v[88:91], v[148:151], v[180:183], v[88:91]
	v_mfma_f32_16x16x32_bf16 v[84:87], v[156:159], v[180:183], v[84:87]
	v_mfma_f32_16x16x32_bf16 v[72:75], v[148:151], v[206:209], v[72:75]
	v_mfma_f32_16x16x32_bf16 v[68:71], v[156:159], v[206:209], v[68:71]
	v_mfma_f32_16x16x32_bf16 v[132:135], v[152:155], v[168:171], v[132:135]
	v_mfma_f32_16x16x32_bf16 v[124:127], v[160:163], v[168:171], v[124:127]
	v_mfma_f32_16x16x32_bf16 v[104:107], v[152:155], v[176:179], v[104:107]
	v_mfma_f32_16x16x32_bf16 v[100:103], v[160:163], v[176:179], v[100:103]
	v_mfma_f32_16x16x32_bf16 v[88:91], v[152:155], v[184:187], v[88:91]
	v_mfma_f32_16x16x32_bf16 v[84:87], v[160:163], v[184:187], v[84:87]
	v_mfma_f32_16x16x32_bf16 v[72:75], v[152:155], v[210:213], v[72:75]
	v_mfma_f32_16x16x32_bf16 v[68:71], v[160:163], v[210:213], v[68:71]
	s_barrier
	s_setprio 0
	s_add_i32 s48, s48, s5
	v_lshl_add_u64 v[198:199], v[198:199], 0, s[66:67]
	s_mov_b32 m0, s48
	ds_read_b128 v[164:167], v234 offset:49152
	ds_read_b128 v[168:171], v234 offset:50176
	ds_read_b128 v[172:175], v234 offset:51200
	ds_read_b128 v[176:179], v234 offset:52224
	ds_read_b128 v[180:183], v234 offset:53248
	ds_read_b128 v[184:187], v234 offset:54272
	ds_read_b128 v[206:209], v234 offset:55296
	ds_read_b128 v[210:213], v234 offset:56320
	global_load_lds_dwordx4 v[198:199], off
	s_add_i32 m0, s48, 0x2000
	s_add_u32 s62, s70, 0x160080
	v_lshl_add_u64 v[198:199], v[214:215], 0, s[66:67]
	s_addc_u32 s63, s71, 0
	s_add_i32 s48, s49, s5
	global_load_lds_dwordx4 v[198:199], off
	v_lshl_add_u64 v[198:199], s[62:63], 0, v[200:201]
	s_mov_b32 m0, s48
	s_nop 0
	global_load_lds_dwordx4 v[198:199], off
	v_lshl_add_u64 v[198:199], s[62:63], 0, v[188:189]
	s_add_i32 m0, s48, 0x2000
	s_nop 0
	global_load_lds_dwordx4 v[198:199], off
	v_lshl_add_u64 v[198:199], v[216:217], 0, s[66:67]
	s_mov_b32 m0, s53
	s_nop 0
	global_load_lds_dwordx4 v[198:199], off
	v_lshl_add_u64 v[198:199], v[218:219], 0, s[66:67]
	s_mov_b32 m0, s54
	s_nop 0
	global_load_lds_dwordx4 v[198:199], off
	s_waitcnt vmcnt(8)
	s_waitcnt lgkmcnt(0)
	s_setprio 1
	s_barrier
	v_mfma_f32_16x16x32_bf16 v[64:67], v[108:111], v[164:167], v[64:67]
	v_mfma_f32_16x16x32_bf16 v[60:63], v[128:131], v[164:167], v[60:63]
	v_mfma_f32_16x16x32_bf16 v[48:51], v[108:111], v[172:175], v[48:51]
	v_mfma_f32_16x16x32_bf16 v[44:47], v[128:131], v[172:175], v[44:47]
	v_mfma_f32_16x16x32_bf16 v[32:35], v[108:111], v[180:183], v[32:35]
	v_mfma_f32_16x16x32_bf16 v[28:31], v[128:131], v[180:183], v[28:31]
	v_mfma_f32_16x16x32_bf16 v[16:19], v[108:111], v[206:209], v[16:19]
	v_mfma_f32_16x16x32_bf16 v[12:15], v[128:131], v[206:209], v[12:15]
	v_mfma_f32_16x16x32_bf16 v[64:67], v[112:115], v[168:171], v[64:67]
	v_mfma_f32_16x16x32_bf16 v[60:63], v[136:139], v[168:171], v[60:63]
	v_mfma_f32_16x16x32_bf16 v[48:51], v[112:115], v[176:179], v[48:51]
	v_mfma_f32_16x16x32_bf16 v[44:47], v[136:139], v[176:179], v[44:47]
	v_mfma_f32_16x16x32_bf16 v[32:35], v[112:115], v[184:187], v[32:35]
	v_mfma_f32_16x16x32_bf16 v[28:31], v[136:139], v[184:187], v[28:31]
	v_mfma_f32_16x16x32_bf16 v[16:19], v[112:115], v[210:213], v[16:19]
	v_mfma_f32_16x16x32_bf16 v[12:15], v[136:139], v[210:213], v[12:15]
	s_setprio 0
	s_setprio 1
	v_mfma_f32_16x16x32_bf16 v[56:59], v[148:151], v[164:167], v[56:59]
	v_mfma_f32_16x16x32_bf16 v[52:55], v[156:159], v[164:167], v[52:55]
	v_mfma_f32_16x16x32_bf16 v[40:43], v[148:151], v[172:175], v[40:43]
	v_mfma_f32_16x16x32_bf16 v[36:39], v[156:159], v[172:175], v[36:39]
	v_mfma_f32_16x16x32_bf16 v[24:27], v[148:151], v[180:183], v[24:27]
	v_mfma_f32_16x16x32_bf16 v[20:23], v[156:159], v[180:183], v[20:23]
	v_mfma_f32_16x16x32_bf16 v[8:11], v[148:151], v[206:209], v[8:11]
	v_mfma_f32_16x16x32_bf16 v[4:7], v[156:159], v[206:209], v[4:7]
	v_mfma_f32_16x16x32_bf16 v[56:59], v[152:155], v[168:171], v[56:59]
	v_mfma_f32_16x16x32_bf16 v[52:55], v[160:163], v[168:171], v[52:55]
	v_mfma_f32_16x16x32_bf16 v[40:43], v[152:155], v[176:179], v[40:43]
	v_mfma_f32_16x16x32_bf16 v[36:39], v[160:163], v[176:179], v[36:39]
	v_mfma_f32_16x16x32_bf16 v[24:27], v[152:155], v[184:187], v[24:27]
	v_mfma_f32_16x16x32_bf16 v[20:23], v[160:163], v[184:187], v[20:23]
	v_mfma_f32_16x16x32_bf16 v[8:11], v[152:155], v[210:213], v[8:11]
	v_mfma_f32_16x16x32_bf16 v[4:7], v[160:163], v[210:213], v[4:7]
	s_barrier
	s_setprio 0
	s_add_i32 s78, s78, 2
	s_add_u32 s73, s73, 0x100
	s_addc_u32 s75, s75, 0
	s_cmpk_gt_u32 s78, 0x55
	s_mov_b64 s[62:63], s[68:69]
	s_cbranch_scc0 .LBB0_667
	s_and_b64 vcc, exec, s[24:25]
	s_cbranch_vccz .LBB0_670
	s_barrier

;     __device__ __forceinline__ bool next(int i, Unit& u) const { if (i >= n) return false; u.pm = pm; u.pn = pn0 + i; return true; }
;     __device__ __forceinline__ bool next(int i, Unit& u) const { if (i) return false; u.pm = pm; u.pn = pn; return true; }
; #define PG8_STAGE(bufoff, gbase, voff) do { _Pragma("unroll") for (int _i = 0; _i < 2; ++_i) \
;         __builtin_amdgcn_global_load_lds((const unsigned*)((const char*)(gbase) + (voff)[_i]), (PG8_LAS unsigned*)(lds + (bufoff) + ldsw + _i * 8192), 16, 0, 0); } while (0)
; #define PG8_LDA(dst, b, h) do { _Pragma("unroll") for (int m = 0; m < 4; ++m) _Pragma("unroll") for (int k = 0; k < 2; ++k) dst[m][k] = *(const PG8_LAS bf16x8*)(lds + PG8_SA(b, h) + aoff + m * 2048 + k * 1024); } while (0)
; #define PG8_LDB(dst, b, h) do { _Pragma("unroll") for (int n = 0; n < 2; ++n) _Pragma("unroll") for (int k = 0; k < 2; ++k) dst[n][k] = *(const PG8_LAS bf16x8*)(lds + PG8_SB(b, h) + boff + n * 2048 + k * 1024); } while (0)
; #define PG8_WAIT_V(n) asm volatile("s_waitcnt vmcnt(" #n ")" ::: "memory")
; #define PG8_BAR __builtin_amdgcn_s_barrier()
;     ...
;         const bool has_next = S.next(ui + 1, nxt);
;         const char* nA = has_next ? (const char*)g.A + (size_t)nxt.pm * tstep : cA; const char* nB = has_next ? (const char*)g.Bt + (size_t)nxt.pn * tstep : cB;
;         for (int t = 0; t < nt; t += 2) {
;             const bool last = (t == nt - 2);
;             const char* a1 = cA + (size_t)(t + 1) * kstep;
;             const char* a2 = last ? nA : cA + (size_t)(t + 2) * kstep; const char* b2 = last ? nB : cB + (size_t)(t + 2) * kstep;
;             const char* a3 = a2 + kstep; const char* b3 = b2 + kstep;
;             if (last && has_next) S.a_ready(nxt);
;             if (t == 0) E.pre_issue(pre, cur, tid, ui); else if (t == 2) E.pre_finish(pre, tid, ui);
;             if constexpr (SP2) {
;             PG8_LDB(B0, 0, 0); PG8_LDB(B1, 0, 1); PG8_SCHED; PG8_LDA(At, 0, 0); PG8_STAGE(PG8_SA(1, 1), a1 + hstep, voffA);
;             PG8_WAIT_V(8); PG8_WAIT_L(0); PG8_BAR; PG8_MMA(0, 0, At, B0); PG8_MMA(0, 1, At, B1); PG8_BAR; PG8_SCHED;
;     ...
;         for (int a = 0; a < 2; ++a)
; #pragma unroll
;             for (int b = 0; b < 2; ++b)
; #pragma unroll
;                 for (int m = 0; m < 4; ++m)
; #pragma unroll
;                     for (int n = 0; n < 2; ++n) acc[a][b][m][n] = (f32x4){0.f, 0.f, 0.f, 0.f};
.LBB0_752:
	s_ashr_i32 s61, s60, 31
	s_lshl_b64 s[54:55], s[60:61], 20
	s_add_u32 s62, s36, s54
	s_addc_u32 s63, s37, s55
	s_and_b64 s[54:55], s[8:9], exec
	s_cselect_b32 s53, s63, s69
	s_cselect_b32 s54, s62, s68
	s_ashr_i32 s25, s24, 31
	s_lshl_b64 s[58:59], s[24:25], 20
	s_add_u32 s70, s81, s58
	s_addc_u32 s71, s6, s59
	s_and_b64 s[58:59], s[8:9], exec
	s_cselect_b32 s25, s71, s77
	s_cselect_b32 s55, s70, s76
	s_add_u32 s68, s68, 0x80080
	s_addc_u32 s69, s69, 0
	s_add_u32 s56, s76, 0x100
	v_mov_b32_e32 v4, 0
	s_addc_u32 s58, s77, 0
	s_mov_b32 s59, -2
	v_mov_b32_e32 v5, v4
	v_mov_b32_e32 v6, v4
	v_mov_b32_e32 v7, v4
	v_mov_b32_e32 v8, v4
	v_mov_b32_e32 v9, v4
	v_mov_b32_e32 v10, v4
	v_mov_b32_e32 v11, v4
	v_mov_b32_e32 v16, v4
	v_mov_b32_e32 v17, v4
	v_mov_b32_e32 v18, v4
	v_mov_b32_e32 v19, v4
	s_waitcnt vmcnt(0)
	v_mov_b32_e32 v24, v4
	v_mov_b32_e32 v25, v4
	v_mov_b32_e32 v26, v4
	v_mov_b32_e32 v27, v4
	v_mov_b32_e32 v32, v4
	v_mov_b32_e32 v33, v4
	v_mov_b32_e32 v34, v4
	v_mov_b32_e32 v35, v4
	v_mov_b32_e32 v40, v4
	v_mov_b32_e32 v41, v4
	v_mov_b32_e32 v42, v4
	v_mov_b32_e32 v43, v4
	v_mov_b32_e32 v48, v4
	v_mov_b32_e32 v49, v4
	v_mov_b32_e32 v50, v4
	v_mov_b32_e32 v51, v4
	v_mov_b32_e32 v56, v4
	v_mov_b32_e32 v57, v4
	v_mov_b32_e32 v58, v4
	v_mov_b32_e32 v59, v4
	v_mov_b32_e32 v12, v4
	v_mov_b32_e32 v13, v4
	v_mov_b32_e32 v14, v4
	v_mov_b32_e32 v15, v4
	v_mov_b32_e32 v20, v4
	v_mov_b32_e32 v21, v4
	v_mov_b32_e32 v22, v4
	v_mov_b32_e32 v23, v4
	v_mov_b32_e32 v28, v4
	v_mov_b32_e32 v29, v4
	v_mov_b32_e32 v30, v4
	v_mov_b32_e32 v31, v4
	v_mov_b32_e32 v36, v4
	v_mov_b32_e32 v37, v4
	v_mov_b32_e32 v38, v4
	v_mov_b32_e32 v39, v4
	v_mov_b32_e32 v44, v4
	v_mov_b32_e32 v45, v4
	v_mov_b32_e32 v46, v4
	v_mov_b32_e32 v47, v4
	v_mov_b32_e32 v52, v4
	v_mov_b32_e32 v53, v4
	v_mov_b32_e32 v54, v4
	v_mov_b32_e32 v55, v4
	v_mov_b32_e32 v60, v4
	v_mov_b32_e32 v61, v4
	v_mov_b32_e32 v62, v4
	v_mov_b32_e32 v63, v4
	v_mov_b32_e32 v64, v4
	v_mov_b32_e32 v65, v4
	v_mov_b32_e32 v66, v4
	v_mov_b32_e32 v67, v4
	v_mov_b32_e32 v68, v4
	v_mov_b32_e32 v69, v4
	v_mov_b32_e32 v70, v4
	v_mov_b32_e32 v71, v4
	v_mov_b32_e32 v72, v4
	v_mov_b32_e32 v73, v4
	v_mov_b32_e32 v74, v4
	v_mov_b32_e32 v75, v4
	v_mov_b32_e32 v80, v4
	v_mov_b32_e32 v81, v4
	v_mov_b32_e32 v82, v4
	v_mov_b32_e32 v83, v4
	v_mov_b32_e32 v88, v4
	v_mov_b32_e32 v89, v4
	v_mov_b32_e32 v90, v4
	v_mov_b32_e32 v91, v4
	v_mov_b32_e32 v96, v4
	v_mov_b32_e32 v97, v4
	v_mov_b32_e32 v98, v4
	v_mov_b32_e32 v99, v4
	v_mov_b32_e32 v104, v4
	v_mov_b32_e32 v105, v4
	v_mov_b32_e32 v106, v4
	v_mov_b32_e32 v107, v4
	v_mov_b32_e32 v112, v4
	v_mov_b32_e32 v113, v4
	v_mov_b32_e32 v114, v4
	v_mov_b32_e32 v115, v4
	v_mov_b32_e32 v120, v4
	v_mov_b32_e32 v121, v4
	v_mov_b32_e32 v122, v4
	v_mov_b32_e32 v123, v4
	v_mov_b32_e32 v76, v4
	v_mov_b32_e32 v77, v4
	v_mov_b32_e32 v78, v4
	v_mov_b32_e32 v79, v4
	v_mov_b32_e32 v84, v4
	v_mov_b32_e32 v85, v4
	v_mov_b32_e32 v86, v4
	v_mov_b32_e32 v87, v4
	v_mov_b32_e32 v92, v4
	v_mov_b32_e32 v93, v4
	v_mov_b32_e32 v94, v4
	v_mov_b32_e32 v95, v4
	v_mov_b32_e32 v100, v4
	v_mov_b32_e32 v101, v4
	v_mov_b32_e32 v102, v4
	v_mov_b32_e32 v103, v4
	v_mov_b32_e32 v108, v4
	v_mov_b32_e32 v109, v4
	v_mov_b32_e32 v110, v4
	v_mov_b32_e32 v111, v4
	v_mov_b32_e32 v116, v4
	v_mov_b32_e32 v117, v4
	v_mov_b32_e32 v118, v4
	v_mov_b32_e32 v119, v4
	v_mov_b32_e32 v124, v4
	v_mov_b32_e32 v125, v4
	v_mov_b32_e32 v126, v4
	v_mov_b32_e32 v127, v4
	v_mov_b32_e32 v128, v4
	v_mov_b32_e32 v129, v4
	v_mov_b32_e32 v130, v4
	v_mov_b32_e32 v131, v4
	s_waitcnt lgkmcnt(0)
	v_add_u32_e32 v251, 0x10000, v145
.LBB0_753:
	s_add_u32 s48, s68, 0xfff80080
	s_addc_u32 s49, s69, -1
	s_add_i32 s61, 0, 0x10000
	s_cmp_eq_u32 s59, 28
	s_cselect_b32 s79, s53, s49
	s_cselect_b32 s78, s54, s48
	s_cselect_b32 s77, s25, s58
	s_cselect_b32 s76, s55, s56
	s_add_i32 s48, 0, 0x14000
	ds_read_b128 v[132:135], v251
	ds_read_b128 v[158:161], v251 offset:1024
	ds_read_b128 v[162:165], v251 offset:2048
	ds_read_b128 v[166:169], v251 offset:3072
	ds_read_b128 v[170:173], v251 offset:16384
	ds_read_b128 v[176:179], v251 offset:17408
	ds_read_b128 v[180:183], v251 offset:18432
	ds_read_b128 v[184:187], v251 offset:19456
	v_lshl_add_u64 v[232:233], s[68:69], 0, v[150:151]
	s_add_i32 m0, s1, 0xc000
	ds_read_b128 v[188:191], v175
	ds_read_b128 v[192:195], v175 offset:1024
	ds_read_b128 v[196:199], v175 offset:2048
	ds_read_b128 v[206:209], v175 offset:3072
	ds_read_b128 v[210:213], v175 offset:4096
	ds_read_b128 v[214:217], v175 offset:5120
	ds_read_b128 v[218:221], v175 offset:6144
	ds_read_b128 v[222:225], v175 offset:7168
	global_load_lds_dwordx4 v[232:233], off
	v_lshl_add_u64 v[232:233], s[68:69], 0, v[152:153]
	s_add_i32 m0, s1, 0xe000
	s_nop 0
	global_load_lds_dwordx4 v[232:233], off
	s_waitcnt vmcnt(8)
	s_waitcnt lgkmcnt(0)
	s_setprio 1
	s_barrier
; #define PG8_STAGE(bufoff, gbase, voff) do { _Pragma("unroll") for (int _i = 0; _i < 2; ++_i) \
;         __builtin_amdgcn_global_load_lds((const unsigned*)((const char*)(gbase) + (voff)[_i]), (PG8_LAS unsigned*)(lds + (bufoff) + ldsw + _i * 8192), 16, 0, 0); } while (0)
; #define PG8_LDA(dst, b, h) do { _Pragma("unroll") for (int m = 0; m < 4; ++m) _Pragma("unroll") for (int k = 0; k < 2; ++k) dst[m][k] = *(const PG8_LAS bf16x8*)(lds + PG8_SA(b, h) + aoff + m * 2048 + k * 1024); } while (0)
; #define PG8_MMA(ai, bj, At, Bt) do { __builtin_amdgcn_s_setprio(1); _Pragma("unroll") for (int m = 0; m < 4; ++m) _Pragma("unroll") for (int n = 0; n < 2; ++n) _Pragma("unroll") for (int k = 0; k < 2; ++k) \
;         acc[ai][bj][m][n] = __builtin_amdgcn_mfma_f32_16x16x32_bf16(Bt[n][k], At[m][k], acc[ai][bj][m][n], 0, 0, 0); __builtin_amdgcn_s_setprio(0); } while (0)
; #define PG8_WAIT_V(n) asm volatile("s_waitcnt vmcnt(" #n ")" ::: "memory")
; #define PG8_WAIT_L(n) asm volatile("s_waitcnt lgkmcnt(" #n ")" ::: "memory")
; #define PG8_BAR __builtin_amdgcn_s_barrier()
; #define PG8_SCHED __builtin_amdgcn_sched_barrier(0)
;     ...
;             PG8_WAIT_V(8); PG8_WAIT_L(0); PG8_BAR; PG8_MMA(0, 0, At, B0); PG8_MMA(0, 1, At, B1); PG8_BAR; PG8_SCHED;
;             PG8_LDA(At, 0, 1); PG8_STAGE(PG8_SB(0, 0), b2, voffB); PG8_STAGE(PG8_SB(0, 1), b2 + hstep, voffB); PG8_STAGE(PG8_SA(0, 0), a2, voffA);
;             PG8_WAIT_V(8); PG8_WAIT_L(0); PG8_BAR; PG8_MMA(1, 0, At, B0); PG8_MMA(1, 1, At, B1); PG8_BAR; PG8_SCHED;
	v_mfma_f32_16x16x32_bf16 v[128:131], v[132:135], v[188:191], v[128:131]
	v_mfma_f32_16x16x32_bf16 v[124:127], v[162:165], v[188:191], v[124:127]
	v_mfma_f32_16x16x32_bf16 v[116:119], v[132:135], v[196:199], v[116:119]
	v_mfma_f32_16x16x32_bf16 v[108:111], v[162:165], v[196:199], v[108:111]
	v_mfma_f32_16x16x32_bf16 v[100:103], v[132:135], v[210:213], v[100:103]
	v_mfma_f32_16x16x32_bf16 v[92:95], v[162:165], v[210:213], v[92:95]
	v_mfma_f32_16x16x32_bf16 v[84:87], v[132:135], v[218:221], v[84:87]
	v_mfma_f32_16x16x32_bf16 v[76:79], v[162:165], v[218:221], v[76:79]
	v_mfma_f32_16x16x32_bf16 v[128:131], v[158:161], v[192:195], v[128:131]
	v_mfma_f32_16x16x32_bf16 v[124:127], v[166:169], v[192:195], v[124:127]
	v_mfma_f32_16x16x32_bf16 v[116:119], v[158:161], v[206:209], v[116:119]
	v_mfma_f32_16x16x32_bf16 v[108:111], v[166:169], v[206:209], v[108:111]
	v_mfma_f32_16x16x32_bf16 v[100:103], v[158:161], v[214:217], v[100:103]
	v_mfma_f32_16x16x32_bf16 v[92:95], v[166:169], v[214:217], v[92:95]
	v_mfma_f32_16x16x32_bf16 v[84:87], v[158:161], v[222:225], v[84:87]
	v_mfma_f32_16x16x32_bf16 v[76:79], v[166:169], v[222:225], v[76:79]
	s_setprio 0
	s_setprio 1
	v_mfma_f32_16x16x32_bf16 v[120:123], v[170:173], v[188:191], v[120:123]
	v_mfma_f32_16x16x32_bf16 v[112:115], v[180:183], v[188:191], v[112:115]
	v_mfma_f32_16x16x32_bf16 v[104:107], v[170:173], v[196:199], v[104:107]
	v_mfma_f32_16x16x32_bf16 v[96:99], v[180:183], v[196:199], v[96:99]
	v_mfma_f32_16x16x32_bf16 v[88:91], v[170:173], v[210:213], v[88:91]
	v_mfma_f32_16x16x32_bf16 v[80:83], v[180:183], v[210:213], v[80:83]
	v_mfma_f32_16x16x32_bf16 v[72:75], v[170:173], v[218:221], v[72:75]
	v_mfma_f32_16x16x32_bf16 v[68:71], v[180:183], v[218:221], v[68:71]
	v_mfma_f32_16x16x32_bf16 v[120:123], v[176:179], v[192:195], v[120:123]
	v_mfma_f32_16x16x32_bf16 v[112:115], v[184:187], v[192:195], v[112:115]
	v_mfma_f32_16x16x32_bf16 v[104:107], v[176:179], v[206:209], v[104:107]
	v_mfma_f32_16x16x32_bf16 v[96:99], v[184:187], v[206:209], v[96:99]
	v_mfma_f32_16x16x32_bf16 v[88:91], v[176:179], v[214:217], v[88:91]
	v_mfma_f32_16x16x32_bf16 v[80:83], v[184:187], v[214:217], v[80:83]
	v_mfma_f32_16x16x32_bf16 v[72:75], v[176:179], v[222:225], v[72:75]
	v_mfma_f32_16x16x32_bf16 v[68:71], v[184:187], v[222:225], v[68:71]
	s_barrier
	s_setprio 0
	s_add_i32 s49, s61, s0
	v_lshl_add_u64 v[232:233], s[76:77], 0, v[140:141]
	s_mov_b32 m0, s49
	ds_read_b128 v[188:191], v175 offset:16384
	ds_read_b128 v[192:195], v175 offset:17408
	ds_read_b128 v[196:199], v175 offset:18432
	ds_read_b128 v[206:209], v175 offset:19456
	ds_read_b128 v[210:213], v175 offset:20480
	ds_read_b128 v[214:217], v175 offset:21504
	ds_read_b128 v[218:221], v175 offset:22528
	ds_read_b128 v[222:225], v175 offset:23552
	global_load_lds_dwordx4 v[232:233], off
	s_add_i32 m0, s49, 0x2000
	s_add_u32 s82, s76, 0x80000
	v_lshl_add_u64 v[234:235], s[76:77], 0, v[136:137]
	s_addc_u32 s83, s77, 0
	s_add_i32 s48, s48, s0
	global_load_lds_dwordx4 v[234:235], off
	v_lshl_add_u64 v[236:237], s[82:83], 0, v[140:141]
	s_mov_b32 m0, s48
	v_lshl_add_u64 v[238:239], s[78:79], 0, v[138:139]
	global_load_lds_dwordx4 v[236:237], off
	v_lshl_add_u64 v[236:237], s[82:83], 0, v[136:137]
	s_add_i32 m0, s48, 0x2000
	s_nop 0
	global_load_lds_dwordx4 v[236:237], off
	v_lshl_add_u64 v[236:237], s[78:79], 0, v[142:143]
	s_mov_b32 m0, s1
	s_nop 0
	global_load_lds_dwordx4 v[236:237], off
	s_mov_b32 m0, s4
	s_nop 0
	global_load_lds_dwordx4 v[238:239], off
	s_waitcnt vmcnt(8)
	s_waitcnt lgkmcnt(0)
	s_setprio 1
	s_barrier
	v_mfma_f32_16x16x32_bf16 v[64:67], v[132:135], v[188:191], v[64:67]
	v_mfma_f32_16x16x32_bf16 v[60:63], v[162:165], v[188:191], v[60:63]
	v_mfma_f32_16x16x32_bf16 v[52:55], v[132:135], v[196:199], v[52:55]
	v_mfma_f32_16x16x32_bf16 v[44:47], v[162:165], v[196:199], v[44:47]
	v_mfma_f32_16x16x32_bf16 v[36:39], v[132:135], v[210:213], v[36:39]
	v_mfma_f32_16x16x32_bf16 v[28:31], v[162:165], v[210:213], v[28:31]
	v_mfma_f32_16x16x32_bf16 v[20:23], v[132:135], v[218:221], v[20:23]
	v_mfma_f32_16x16x32_bf16 v[12:15], v[162:165], v[218:221], v[12:15]
	v_mfma_f32_16x16x32_bf16 v[64:67], v[158:161], v[192:195], v[64:67]
	v_mfma_f32_16x16x32_bf16 v[60:63], v[166:169], v[192:195], v[60:63]
	v_mfma_f32_16x16x32_bf16 v[52:55], v[158:161], v[206:209], v[52:55]
	v_mfma_f32_16x16x32_bf16 v[44:47], v[166:169], v[206:209], v[44:47]
	v_mfma_f32_16x16x32_bf16 v[36:39], v[158:161], v[214:217], v[36:39]
	v_mfma_f32_16x16x32_bf16 v[28:31], v[166:169], v[214:217], v[28:31]
	v_mfma_f32_16x16x32_bf16 v[20:23], v[158:161], v[222:225], v[20:23]
	v_mfma_f32_16x16x32_bf16 v[12:15], v[166:169], v[222:225], v[12:15]
	s_setprio 0
	s_setprio 1
	v_mfma_f32_16x16x32_bf16 v[56:59], v[170:173], v[188:191], v[56:59]
	v_mfma_f32_16x16x32_bf16 v[48:51], v[180:183], v[188:191], v[48:51]
	v_mfma_f32_16x16x32_bf16 v[40:43], v[170:173], v[196:199], v[40:43]
	v_mfma_f32_16x16x32_bf16 v[32:35], v[180:183], v[196:199], v[32:35]
	v_mfma_f32_16x16x32_bf16 v[24:27], v[170:173], v[210:213], v[24:27]
	v_mfma_f32_16x16x32_bf16 v[16:19], v[180:183], v[210:213], v[16:19]
	v_mfma_f32_16x16x32_bf16 v[8:11], v[170:173], v[218:221], v[8:11]
	v_mfma_f32_16x16x32_bf16 v[4:7], v[180:183], v[218:221], v[4:7]
	v_mfma_f32_16x16x32_bf16 v[56:59], v[176:179], v[192:195], v[56:59]
	v_mfma_f32_16x16x32_bf16 v[48:51], v[184:187], v[192:195], v[48:51]
	v_mfma_f32_16x16x32_bf16 v[40:43], v[176:179], v[206:209], v[40:43]
	v_mfma_f32_16x16x32_bf16 v[32:35], v[184:187], v[206:209], v[32:35]
	v_mfma_f32_16x16x32_bf16 v[24:27], v[176:179], v[214:217], v[24:27]
	v_mfma_f32_16x16x32_bf16 v[16:19], v[184:187], v[214:217], v[16:19]
	v_mfma_f32_16x16x32_bf16 v[8:11], v[176:179], v[222:225], v[8:11]
	v_mfma_f32_16x16x32_bf16 v[4:7], v[184:187], v[222:225], v[4:7]
	s_barrier
; #define PG8_STAGE(bufoff, gbase, voff) do { _Pragma("unroll") for (int _i = 0; _i < 2; ++_i) \
;         __builtin_amdgcn_global_load_lds((const unsigned*)((const char*)(gbase) + (voff)[_i]), (PG8_LAS unsigned*)(lds + (bufoff) + ldsw + _i * 8192), 16, 0, 0); } while (0)
; #define PG8_LDA(dst, b, h) do { _Pragma("unroll") for (int m = 0; m < 4; ++m) _Pragma("unroll") for (int k = 0; k < 2; ++k) dst[m][k] = *(const PG8_LAS bf16x8*)(lds + PG8_SA(b, h) + aoff + m * 2048 + k * 1024); } while (0)
; #define PG8_LDB(dst, b, h) do { _Pragma("unroll") for (int n = 0; n < 2; ++n) _Pragma("unroll") for (int k = 0; k < 2; ++k) dst[n][k] = *(const PG8_LAS bf16x8*)(lds + PG8_SB(b, h) + boff + n * 2048 + k * 1024); } while (0)
; #define PG8_MMA(ai, bj, At, Bt) do { __builtin_amdgcn_s_setprio(1); _Pragma("unroll") for (int m = 0; m < 4; ++m) _Pragma("unroll") for (int n = 0; n < 2; ++n) _Pragma("unroll") for (int k = 0; k < 2; ++k) \
;         acc[ai][bj][m][n] = __builtin_amdgcn_mfma_f32_16x16x32_bf16(Bt[n][k], At[m][k], acc[ai][bj][m][n], 0, 0, 0); __builtin_amdgcn_s_setprio(0); } while (0)
; #define PG8_WAIT_V(n) asm volatile("s_waitcnt vmcnt(" #n ")" ::: "memory")
; #define PG8_WAIT_L(n) asm volatile("s_waitcnt lgkmcnt(" #n ")" ::: "memory")
; #define PG8_BAR __builtin_amdgcn_s_barrier()
; #define PG8_SCHED __builtin_amdgcn_sched_barrier(0)
;     ...
;             PG8_LDB(B0, 1, 0); PG8_LDB(B1, 1, 1); PG8_SCHED; PG8_LDA(At, 1, 0); PG8_STAGE(PG8_SA(0, 1), a2 + hstep, voffA);
;             PG8_WAIT_V(8); PG8_WAIT_L(0); PG8_BAR; PG8_MMA(0, 0, At, B0); PG8_MMA(0, 1, At, B1); PG8_BAR; PG8_SCHED;
	s_setprio 0
	s_add_i32 s48, 0, 0x18000
	s_add_i32 s49, 0, 0x1c000
	ds_read_b128 v[132:135], v251 offset:32768
	ds_read_b128 v[158:161], v251 offset:33792
	ds_read_b128 v[162:165], v251 offset:34816
	ds_read_b128 v[166:169], v251 offset:35840
	ds_read_b128 v[170:173], v251 offset:49152
	ds_read_b128 v[176:179], v251 offset:50176
	ds_read_b128 v[180:183], v251 offset:51200
	ds_read_b128 v[184:187], v251 offset:52224
	s_add_u32 s78, s78, 0x80000
	s_addc_u32 s79, s79, 0
	s_mov_b32 m0, s5
	v_lshl_add_u64 v[240:241], s[78:79], 0, v[142:143]
	ds_read_b128 v[188:191], v175 offset:32768
	ds_read_b128 v[192:195], v175 offset:33792
	ds_read_b128 v[196:199], v175 offset:34816
	ds_read_b128 v[206:209], v175 offset:35840
	ds_read_b128 v[210:213], v175 offset:36864
	ds_read_b128 v[214:217], v175 offset:37888
	ds_read_b128 v[218:221], v175 offset:38912
	ds_read_b128 v[222:225], v175 offset:39936
	global_load_lds_dwordx4 v[240:241], off
	v_lshl_add_u64 v[240:241], s[78:79], 0, v[138:139]
	s_mov_b32 m0, s7
	s_nop 0
	global_load_lds_dwordx4 v[240:241], off
	s_waitcnt vmcnt(8)
	s_waitcnt lgkmcnt(0)
	s_setprio 1
	s_barrier
	v_mfma_f32_16x16x32_bf16 v[128:131], v[132:135], v[188:191], v[128:131]
	v_mfma_f32_16x16x32_bf16 v[124:127], v[162:165], v[188:191], v[124:127]
	v_mfma_f32_16x16x32_bf16 v[116:119], v[132:135], v[196:199], v[116:119]
	v_mfma_f32_16x16x32_bf16 v[108:111], v[162:165], v[196:199], v[108:111]
	v_mfma_f32_16x16x32_bf16 v[100:103], v[132:135], v[210:213], v[100:103]
	v_mfma_f32_16x16x32_bf16 v[92:95], v[162:165], v[210:213], v[92:95]
	v_mfma_f32_16x16x32_bf16 v[84:87], v[132:135], v[218:221], v[84:87]
	v_mfma_f32_16x16x32_bf16 v[76:79], v[162:165], v[218:221], v[76:79]
	v_mfma_f32_16x16x32_bf16 v[128:131], v[158:161], v[192:195], v[128:131]
	v_mfma_f32_16x16x32_bf16 v[124:127], v[166:169], v[192:195], v[124:127]
	v_mfma_f32_16x16x32_bf16 v[116:119], v[158:161], v[206:209], v[116:119]
	v_mfma_f32_16x16x32_bf16 v[108:111], v[166:169], v[206:209], v[108:111]
	v_mfma_f32_16x16x32_bf16 v[100:103], v[158:161], v[214:217], v[100:103]
	v_mfma_f32_16x16x32_bf16 v[92:95], v[166:169], v[214:217], v[92:95]
	v_mfma_f32_16x16x32_bf16 v[84:87], v[158:161], v[222:225], v[84:87]
	v_mfma_f32_16x16x32_bf16 v[76:79], v[166:169], v[222:225], v[76:79]
	s_setprio 0
	s_setprio 1
	v_mfma_f32_16x16x32_bf16 v[120:123], v[170:173], v[188:191], v[120:123]
	v_mfma_f32_16x16x32_bf16 v[112:115], v[180:183], v[188:191], v[112:115]
	v_mfma_f32_16x16x32_bf16 v[104:107], v[170:173], v[196:199], v[104:107]
	v_mfma_f32_16x16x32_bf16 v[96:99], v[180:183], v[196:199], v[96:99]
	v_mfma_f32_16x16x32_bf16 v[88:91], v[170:173], v[210:213], v[88:91]
	v_mfma_f32_16x16x32_bf16 v[80:83], v[180:183], v[210:213], v[80:83]
	v_mfma_f32_16x16x32_bf16 v[72:75], v[170:173], v[218:221], v[72:75]
	v_mfma_f32_16x16x32_bf16 v[68:71], v[180:183], v[218:221], v[68:71]
	v_mfma_f32_16x16x32_bf16 v[120:123], v[176:179], v[192:195], v[120:123]
	v_mfma_f32_16x16x32_bf16 v[112:115], v[184:187], v[192:195], v[112:115]
	v_mfma_f32_16x16x32_bf16 v[104:107], v[176:179], v[206:209], v[104:107]
	v_mfma_f32_16x16x32_bf16 v[96:99], v[184:187], v[206:209], v[96:99]
	v_mfma_f32_16x16x32_bf16 v[88:91], v[176:179], v[214:217], v[88:91]
	v_mfma_f32_16x16x32_bf16 v[80:83], v[184:187], v[214:217], v[80:83]
	v_mfma_f32_16x16x32_bf16 v[72:75], v[176:179], v[222:225], v[72:75]
	v_mfma_f32_16x16x32_bf16 v[68:71], v[184:187], v[222:225], v[68:71]
	s_barrier
; #define PG8_STAGE(bufoff, gbase, voff) do { _Pragma("unroll") for (int _i = 0; _i < 2; ++_i) \
;         __builtin_amdgcn_global_load_lds((const unsigned*)((const char*)(gbase) + (voff)[_i]), (PG8_LAS unsigned*)(lds + (bufoff) + ldsw + _i * 8192), 16, 0, 0); } while (0)
; #define PG8_LDA(dst, b, h) do { _Pragma("unroll") for (int m = 0; m < 4; ++m) _Pragma("unroll") for (int k = 0; k < 2; ++k) dst[m][k] = *(const PG8_LAS bf16x8*)(lds + PG8_SA(b, h) + aoff + m * 2048 + k * 1024); } while (0)
; #define PG8_MMA(ai, bj, At, Bt) do { __builtin_amdgcn_s_setprio(1); _Pragma("unroll") for (int m = 0; m < 4; ++m) _Pragma("unroll") for (int n = 0; n < 2; ++n) _Pragma("unroll") for (int k = 0; k < 2; ++k) \
;         acc[ai][bj][m][n] = __builtin_amdgcn_mfma_f32_16x16x32_bf16(Bt[n][k], At[m][k], acc[ai][bj][m][n], 0, 0, 0); __builtin_amdgcn_s_setprio(0); } while (0)
; #define PG8_WAIT_V(n) asm volatile("s_waitcnt vmcnt(" #n ")" ::: "memory")
; #define PG8_WAIT_L(n) asm volatile("s_waitcnt lgkmcnt(" #n ")" ::: "memory")
; #define PG8_BAR __builtin_amdgcn_s_barrier()
; #define PG8_SCHED __builtin_amdgcn_sched_barrier(0)
;     ...
;             PG8_WAIT_V(8); PG8_WAIT_L(0); PG8_BAR; PG8_MMA(0, 0, At, B0); PG8_MMA(0, 1, At, B1); PG8_BAR; PG8_SCHED;
;             PG8_LDA(At, 1, 1); PG8_STAGE(PG8_SB(1, 0), b3, voffB); PG8_STAGE(PG8_SB(1, 1), b3 + hstep, voffB); PG8_STAGE(PG8_SA(1, 0), a3, voffA);
;             PG8_WAIT_V(8); PG8_WAIT_L(0); PG8_BAR; PG8_MMA(1, 0, At, B0); PG8_MMA(1, 1, At, B1); PG8_BAR; PG8_SCHED;
;     ...
;         if constexpr (ALIGN_EPI) { if (wr == 0) PG8_BAR; }
	s_setprio 0
	s_add_i32 s48, s48, s0
	v_lshl_add_u64 v[232:233], v[232:233], 0, s[66:67]
	s_mov_b32 m0, s48
	ds_read_b128 v[188:191], v175 offset:49152
	ds_read_b128 v[192:195], v175 offset:50176
	ds_read_b128 v[196:199], v175 offset:51200
	ds_read_b128 v[206:209], v175 offset:52224
	ds_read_b128 v[210:213], v175 offset:53248
	ds_read_b128 v[214:217], v175 offset:54272
	ds_read_b128 v[218:221], v175 offset:55296
	ds_read_b128 v[222:225], v175 offset:56320
	global_load_lds_dwordx4 v[232:233], off
	s_add_i32 m0, s48, 0x2000
	s_add_u32 s76, s76, 0x80080
	v_lshl_add_u64 v[232:233], v[234:235], 0, s[66:67]
	s_addc_u32 s77, s77, 0
	s_add_i32 s48, s49, s0
	global_load_lds_dwordx4 v[232:233], off
	v_lshl_add_u64 v[232:233], s[76:77], 0, v[140:141]
	s_mov_b32 m0, s48
	s_nop 0
	global_load_lds_dwordx4 v[232:233], off
	v_lshl_add_u64 v[232:233], s[76:77], 0, v[136:137]
	s_add_i32 m0, s48, 0x2000
	s_nop 0
	global_load_lds_dwordx4 v[232:233], off
	v_lshl_add_u64 v[232:233], v[236:237], 0, s[66:67]
	s_mov_b32 m0, s21
	s_nop 0
	global_load_lds_dwordx4 v[232:233], off
	v_lshl_add_u64 v[232:233], v[238:239], 0, s[66:67]
	s_mov_b32 m0, s23
	s_nop 0
	global_load_lds_dwordx4 v[232:233], off
	s_waitcnt vmcnt(8)
	s_waitcnt lgkmcnt(0)
	s_setprio 1
	s_barrier
	v_mfma_f32_16x16x32_bf16 v[64:67], v[132:135], v[188:191], v[64:67]
	v_mfma_f32_16x16x32_bf16 v[60:63], v[162:165], v[188:191], v[60:63]
	v_mfma_f32_16x16x32_bf16 v[52:55], v[132:135], v[196:199], v[52:55]
	v_mfma_f32_16x16x32_bf16 v[44:47], v[162:165], v[196:199], v[44:47]
	v_mfma_f32_16x16x32_bf16 v[36:39], v[132:135], v[210:213], v[36:39]
	v_mfma_f32_16x16x32_bf16 v[28:31], v[162:165], v[210:213], v[28:31]
	v_mfma_f32_16x16x32_bf16 v[20:23], v[132:135], v[218:221], v[20:23]
	v_mfma_f32_16x16x32_bf16 v[12:15], v[162:165], v[218:221], v[12:15]
	v_mfma_f32_16x16x32_bf16 v[64:67], v[158:161], v[192:195], v[64:67]
	v_mfma_f32_16x16x32_bf16 v[60:63], v[166:169], v[192:195], v[60:63]
	v_mfma_f32_16x16x32_bf16 v[52:55], v[158:161], v[206:209], v[52:55]
	v_mfma_f32_16x16x32_bf16 v[44:47], v[166:169], v[206:209], v[44:47]
	v_mfma_f32_16x16x32_bf16 v[36:39], v[158:161], v[214:217], v[36:39]
	v_mfma_f32_16x16x32_bf16 v[28:31], v[166:169], v[214:217], v[28:31]
	v_mfma_f32_16x16x32_bf16 v[20:23], v[158:161], v[222:225], v[20:23]
	v_mfma_f32_16x16x32_bf16 v[12:15], v[166:169], v[222:225], v[12:15]
	s_setprio 0
	s_setprio 1
	v_mfma_f32_16x16x32_bf16 v[56:59], v[170:173], v[188:191], v[56:59]
	v_mfma_f32_16x16x32_bf16 v[48:51], v[180:183], v[188:191], v[48:51]
	v_mfma_f32_16x16x32_bf16 v[40:43], v[170:173], v[196:199], v[40:43]
	v_mfma_f32_16x16x32_bf16 v[32:35], v[180:183], v[196:199], v[32:35]
	v_mfma_f32_16x16x32_bf16 v[24:27], v[170:173], v[210:213], v[24:27]
	v_mfma_f32_16x16x32_bf16 v[16:19], v[180:183], v[210:213], v[16:19]
	v_mfma_f32_16x16x32_bf16 v[8:11], v[170:173], v[218:221], v[8:11]
	v_mfma_f32_16x16x32_bf16 v[4:7], v[180:183], v[218:221], v[4:7]
	v_mfma_f32_16x16x32_bf16 v[56:59], v[176:179], v[192:195], v[56:59]
	v_mfma_f32_16x16x32_bf16 v[48:51], v[184:187], v[192:195], v[48:51]
	v_mfma_f32_16x16x32_bf16 v[40:43], v[176:179], v[206:209], v[40:43]
	v_mfma_f32_16x16x32_bf16 v[32:35], v[184:187], v[206:209], v[32:35]
	v_mfma_f32_16x16x32_bf16 v[24:27], v[176:179], v[214:217], v[24:27]
	v_mfma_f32_16x16x32_bf16 v[16:19], v[184:187], v[214:217], v[16:19]
	v_mfma_f32_16x16x32_bf16 v[8:11], v[176:179], v[222:225], v[8:11]
	v_mfma_f32_16x16x32_bf16 v[4:7], v[184:187], v[222:225], v[4:7]
	s_barrier
	s_setprio 0
	s_add_i32 s59, s59, 2
	s_add_u32 s68, s68, 0x100
	s_addc_u32 s69, s69, 0
	s_add_u32 s56, s56, 0x100
	s_addc_u32 s58, s58, 0
	s_cmp_gt_u32 s59, 29
	s_cbranch_scc0 .LBB0_753
	s_and_b64 vcc, exec, s[12:13]
	s_cbranch_vccz .LBB0_756
	s_barrier

;     __device__ __forceinline__ bool next(int i, Unit& u) const { if (i >= n) return false; u.pm = pm; u.pn = pn0 + i; return true; }
;     __device__ __forceinline__ bool next(int i, Unit& u) const { if (i) return false; u.pm = pm; u.pn = pn; return true; }
; #define PG8_STAGE(bufoff, gbase, voff) do { _Pragma("unroll") for (int _i = 0; _i < 2; ++_i) \
;         __builtin_amdgcn_global_load_lds((const unsigned*)((const char*)(gbase) + (voff)[_i]), (PG8_LAS unsigned*)(lds + (bufoff) + ldsw + _i * 8192), 16, 0, 0); } while (0)
; #define PG8_LDA(dst, b, h) do { _Pragma("unroll") for (int m = 0; m < 4; ++m) _Pragma("unroll") for (int k = 0; k < 2; ++k) dst[m][k] = *(const PG8_LAS bf16x8*)(lds + PG8_SA(b, h) + aoff + m * 2048 + k * 1024); } while (0)
; #define PG8_LDB(dst, b, h) do { _Pragma("unroll") for (int n = 0; n < 2; ++n) _Pragma("unroll") for (int k = 0; k < 2; ++k) dst[n][k] = *(const PG8_LAS bf16x8*)(lds + PG8_SB(b, h) + boff + n * 2048 + k * 1024); } while (0)
; #define PG8_WAIT_V(n) asm volatile("s_waitcnt vmcnt(" #n ")" ::: "memory")
; #define PG8_BAR __builtin_amdgcn_s_barrier()
;     ...
;         const bool has_next = S.next(ui + 1, nxt);
;         const char* nA = has_next ? (const char*)g.A + (size_t)nxt.pm * tstep : cA; const char* nB = has_next ? (const char*)g.Bt + (size_t)nxt.pn * tstep : cB;
;         for (int t = 0; t < nt; t += 2) {
;             const bool last = (t == nt - 2);
;             const char* a1 = cA + (size_t)(t + 1) * kstep;
;             const char* a2 = last ? nA : cA + (size_t)(t + 2) * kstep; const char* b2 = last ? nB : cB + (size_t)(t + 2) * kstep;
;             const char* a3 = a2 + kstep; const char* b3 = b2 + kstep;
;             if (last && has_next) S.a_ready(nxt);
;             if (t == 0) E.pre_issue(pre, cur, tid, ui); else if (t == 2) E.pre_finish(pre, tid, ui);
;             if constexpr (SP2) {
;             PG8_LDB(B0, 0, 0); PG8_LDB(B1, 0, 1); PG8_SCHED; PG8_LDA(At, 0, 0); PG8_STAGE(PG8_SA(1, 1), a1 + hstep, voffA);
;             PG8_WAIT_V(8); PG8_WAIT_L(0); PG8_BAR; PG8_MMA(0, 0, At, B0); PG8_MMA(0, 1, At, B1); PG8_BAR; PG8_SCHED;
;     ...
;         for (int a = 0; a < 2; ++a)
; #pragma unroll
;             for (int b = 0; b < 2; ++b)
; #pragma unroll
;                 for (int m = 0; m < 4; ++m)
; #pragma unroll
;                     for (int n = 0; n < 2; ++n) acc[a][b][m][n] = (f32x4){0.f, 0.f, 0.f, 0.f};
.LBB0_997:
	s_ashr_i32 s51, s50, 31
	s_lshl_b64 s[60:61], s[50:51], 20
	s_add_u32 s60, s7, s60
	s_addc_u32 s61, s82, s61
	s_and_b64 s[62:63], s[8:9], exec
	s_cselect_b32 s51, s61, s71
	s_cselect_b32 s59, s60, s70
	s_ashr_i32 s25, s24, 31
	s_lshl_b64 s[62:63], s[24:25], 20
	s_add_u32 s62, s1, s62
	s_addc_u32 s63, s4, s63
	s_and_b64 s[76:77], s[8:9], exec
	s_cselect_b32 s25, s63, s69
	s_cselect_b32 s73, s62, s68
	s_add_u32 s75, s68, 0x100
	s_addc_u32 s78, s69, 0
	s_add_u32 s68, s70, 0x80080
	v_mov_b32_e32 v4, 0
	s_addc_u32 s69, s71, 0
	s_mov_b32 s79, -2
	v_mov_b32_e32 v5, v4
	v_mov_b32_e32 v6, v4
	v_mov_b32_e32 v7, v4
	v_mov_b32_e32 v8, v4
	v_mov_b32_e32 v9, v4
	v_mov_b32_e32 v10, v4
	v_mov_b32_e32 v11, v4
	v_mov_b32_e32 v20, v4
	v_mov_b32_e32 v21, v4
	v_mov_b32_e32 v22, v4
	v_mov_b32_e32 v23, v4
	v_mov_b32_e32 v24, v4
	v_mov_b32_e32 v25, v4
	v_mov_b32_e32 v26, v4
	v_mov_b32_e32 v27, v4
	v_mov_b32_e32 v36, v4
	v_mov_b32_e32 v37, v4
	v_mov_b32_e32 v38, v4
	v_mov_b32_e32 v39, v4
	v_mov_b32_e32 v40, v4
	v_mov_b32_e32 v41, v4
	v_mov_b32_e32 v42, v4
	v_mov_b32_e32 v43, v4
	v_mov_b32_e32 v52, v4
	v_mov_b32_e32 v53, v4
	v_mov_b32_e32 v54, v4
	v_mov_b32_e32 v55, v4
	v_mov_b32_e32 v56, v4
	v_mov_b32_e32 v57, v4
	v_mov_b32_e32 v58, v4
	v_mov_b32_e32 v59, v4
	v_mov_b32_e32 v12, v4
	v_mov_b32_e32 v13, v4
	v_mov_b32_e32 v14, v4
	v_mov_b32_e32 v15, v4
	v_mov_b32_e32 v16, v4
	v_mov_b32_e32 v17, v4
	v_mov_b32_e32 v18, v4
	v_mov_b32_e32 v19, v4
	v_mov_b32_e32 v28, v4
	v_mov_b32_e32 v29, v4
	v_mov_b32_e32 v30, v4
	v_mov_b32_e32 v31, v4
	v_mov_b32_e32 v32, v4
	v_mov_b32_e32 v33, v4
	v_mov_b32_e32 v34, v4
	v_mov_b32_e32 v35, v4
	v_mov_b32_e32 v44, v4
	v_mov_b32_e32 v45, v4
	v_mov_b32_e32 v46, v4
	v_mov_b32_e32 v47, v4
	v_mov_b32_e32 v48, v4
	v_mov_b32_e32 v49, v4
	v_mov_b32_e32 v50, v4
	v_mov_b32_e32 v51, v4
	v_mov_b32_e32 v60, v4
	v_mov_b32_e32 v61, v4
	v_mov_b32_e32 v62, v4
	v_mov_b32_e32 v63, v4
	v_mov_b32_e32 v64, v4
	v_mov_b32_e32 v65, v4
	v_mov_b32_e32 v66, v4
	v_mov_b32_e32 v67, v4
	v_mov_b32_e32 v68, v4
	v_mov_b32_e32 v69, v4
	v_mov_b32_e32 v70, v4
	v_mov_b32_e32 v71, v4
	v_mov_b32_e32 v72, v4
	v_mov_b32_e32 v73, v4
	v_mov_b32_e32 v74, v4
	v_mov_b32_e32 v75, v4
	v_mov_b32_e32 v84, v4
	v_mov_b32_e32 v85, v4
	v_mov_b32_e32 v86, v4
	v_mov_b32_e32 v87, v4
	v_mov_b32_e32 v88, v4
	v_mov_b32_e32 v89, v4
	v_mov_b32_e32 v90, v4
	v_mov_b32_e32 v91, v4
	v_mov_b32_e32 v100, v4
	v_mov_b32_e32 v101, v4
	v_mov_b32_e32 v102, v4
	v_mov_b32_e32 v103, v4
	v_mov_b32_e32 v104, v4
	v_mov_b32_e32 v105, v4
	v_mov_b32_e32 v106, v4
	v_mov_b32_e32 v107, v4
	v_mov_b32_e32 v124, v4
	v_mov_b32_e32 v125, v4
	v_mov_b32_e32 v126, v4
	v_mov_b32_e32 v127, v4
	v_mov_b32_e32 v132, v4
	v_mov_b32_e32 v133, v4
	v_mov_b32_e32 v134, v4
	v_mov_b32_e32 v135, v4
	v_mov_b32_e32 v76, v4
	v_mov_b32_e32 v77, v4
	v_mov_b32_e32 v78, v4
	v_mov_b32_e32 v79, v4
	v_mov_b32_e32 v80, v4
	v_mov_b32_e32 v81, v4
	v_mov_b32_e32 v82, v4
	v_mov_b32_e32 v83, v4
	v_mov_b32_e32 v92, v4
	v_mov_b32_e32 v93, v4
	v_mov_b32_e32 v94, v4
	v_mov_b32_e32 v95, v4
	v_mov_b32_e32 v96, v4
	v_mov_b32_e32 v97, v4
	v_mov_b32_e32 v98, v4
	v_mov_b32_e32 v99, v4
	v_mov_b32_e32 v116, v4
	v_mov_b32_e32 v117, v4
	v_mov_b32_e32 v118, v4
	v_mov_b32_e32 v119, v4
	v_mov_b32_e32 v120, v4
	v_mov_b32_e32 v121, v4
	v_mov_b32_e32 v122, v4
	v_mov_b32_e32 v123, v4
	v_mov_b32_e32 v140, v4
	v_mov_b32_e32 v141, v4
	v_mov_b32_e32 v142, v4
	v_mov_b32_e32 v143, v4
	v_mov_b32_e32 v144, v4
	v_mov_b32_e32 v145, v4
	s_waitcnt vmcnt(0)
	v_mov_b32_e32 v146, v4
	v_mov_b32_e32 v147, v4
	v_add_u32_e32 v251, 0x10000, v233
.LBB0_998:
	s_add_u32 s48, s68, 0xfff80080
	s_addc_u32 s49, s69, -1
	s_add_i32 s81, 0, 0x10000
	s_cmp_eq_u32 s79, 28
	s_cselect_b32 s77, s51, s49
	s_cselect_b32 s76, s59, s48
	s_cselect_b32 s71, s25, s78
	s_cselect_b32 s70, s73, s75
	s_add_i32 s48, 0, 0x14000
	ds_read_b128 v[108:111], v251
	ds_read_b128 v[112:115], v251 offset:1024
	ds_read_b128 v[128:131], v251 offset:2048
	ds_read_b128 v[136:139], v251 offset:3072
	ds_read_b128 v[148:151], v251 offset:16384
	ds_read_b128 v[152:155], v251 offset:17408
	ds_read_b128 v[156:159], v251 offset:18432
	ds_read_b128 v[160:163], v251 offset:19456
	v_lshl_add_u64 v[198:199], s[68:69], 0, v[196:197]
	s_add_i32 m0, s6, 0xc000
	ds_read_b128 v[164:167], v234
	ds_read_b128 v[168:171], v234 offset:1024
	ds_read_b128 v[172:175], v234 offset:2048
	ds_read_b128 v[176:179], v234 offset:3072
	ds_read_b128 v[180:183], v234 offset:4096
	ds_read_b128 v[184:187], v234 offset:5120
	ds_read_b128 v[206:209], v234 offset:6144
	ds_read_b128 v[210:213], v234 offset:7168
	global_load_lds_dwordx4 v[198:199], off
	v_lshl_add_u64 v[198:199], s[68:69], 0, v[194:195]
	s_add_i32 m0, s6, 0xe000
	s_nop 0
	global_load_lds_dwordx4 v[198:199], off
	s_waitcnt vmcnt(8)
	s_waitcnt lgkmcnt(0)
	s_setprio 1
	s_barrier
; #define PG8_STAGE(bufoff, gbase, voff) do { _Pragma("unroll") for (int _i = 0; _i < 2; ++_i) \
;         __builtin_amdgcn_global_load_lds((const unsigned*)((const char*)(gbase) + (voff)[_i]), (PG8_LAS unsigned*)(lds + (bufoff) + ldsw + _i * 8192), 16, 0, 0); } while (0)
; #define PG8_LDA(dst, b, h) do { _Pragma("unroll") for (int m = 0; m < 4; ++m) _Pragma("unroll") for (int k = 0; k < 2; ++k) dst[m][k] = *(const PG8_LAS bf16x8*)(lds + PG8_SA(b, h) + aoff + m * 2048 + k * 1024); } while (0)
; #define PG8_MMA(ai, bj, At, Bt) do { __builtin_amdgcn_s_setprio(1); _Pragma("unroll") for (int m = 0; m < 4; ++m) _Pragma("unroll") for (int n = 0; n < 2; ++n) _Pragma("unroll") for (int k = 0; k < 2; ++k) \
;         acc[ai][bj][m][n] = __builtin_amdgcn_mfma_f32_16x16x32_bf16(Bt[n][k], At[m][k], acc[ai][bj][m][n], 0, 0, 0); __builtin_amdgcn_s_setprio(0); } while (0)
; #define PG8_WAIT_V(n) asm volatile("s_waitcnt vmcnt(" #n ")" ::: "memory")
; #define PG8_WAIT_L(n) asm volatile("s_waitcnt lgkmcnt(" #n ")" ::: "memory")
; #define PG8_BAR __builtin_amdgcn_s_barrier()
; #define PG8_SCHED __builtin_amdgcn_sched_barrier(0)
;     ...
;             PG8_WAIT_V(8); PG8_WAIT_L(0); PG8_BAR; PG8_MMA(0, 0, At, B0); PG8_MMA(0, 1, At, B1); PG8_BAR; PG8_SCHED;
;             PG8_LDA(At, 0, 1); PG8_STAGE(PG8_SB(0, 0), b2, voffB); PG8_STAGE(PG8_SB(0, 1), b2 + hstep, voffB); PG8_STAGE(PG8_SA(0, 0), a2, voffA);
;             PG8_WAIT_V(8); PG8_WAIT_L(0); PG8_BAR; PG8_MMA(1, 0, At, B0); PG8_MMA(1, 1, At, B1); PG8_BAR; PG8_SCHED;
	v_mfma_f32_16x16x32_bf16 v[144:147], v[108:111], v[164:167], v[144:147]
	v_mfma_f32_16x16x32_bf16 v[140:143], v[128:131], v[164:167], v[140:143]
	v_mfma_f32_16x16x32_bf16 v[120:123], v[108:111], v[172:175], v[120:123]
	v_mfma_f32_16x16x32_bf16 v[116:119], v[128:131], v[172:175], v[116:119]
	v_mfma_f32_16x16x32_bf16 v[96:99], v[108:111], v[180:183], v[96:99]
	v_mfma_f32_16x16x32_bf16 v[92:95], v[128:131], v[180:183], v[92:95]
	v_mfma_f32_16x16x32_bf16 v[80:83], v[108:111], v[206:209], v[80:83]
	v_mfma_f32_16x16x32_bf16 v[76:79], v[128:131], v[206:209], v[76:79]
	v_mfma_f32_16x16x32_bf16 v[144:147], v[112:115], v[168:171], v[144:147]
	v_mfma_f32_16x16x32_bf16 v[140:143], v[136:139], v[168:171], v[140:143]
	v_mfma_f32_16x16x32_bf16 v[120:123], v[112:115], v[176:179], v[120:123]
	v_mfma_f32_16x16x32_bf16 v[116:119], v[136:139], v[176:179], v[116:119]
	v_mfma_f32_16x16x32_bf16 v[96:99], v[112:115], v[184:187], v[96:99]
	v_mfma_f32_16x16x32_bf16 v[92:95], v[136:139], v[184:187], v[92:95]
	v_mfma_f32_16x16x32_bf16 v[80:83], v[112:115], v[210:213], v[80:83]
	v_mfma_f32_16x16x32_bf16 v[76:79], v[136:139], v[210:213], v[76:79]
	s_setprio 0
	s_setprio 1
	v_mfma_f32_16x16x32_bf16 v[132:135], v[148:151], v[164:167], v[132:135]
	v_mfma_f32_16x16x32_bf16 v[124:127], v[156:159], v[164:167], v[124:127]
	v_mfma_f32_16x16x32_bf16 v[104:107], v[148:151], v[172:175], v[104:107]
	v_mfma_f32_16x16x32_bf16 v[100:103], v[156:159], v[172:175], v[100:103]
	v_mfma_f32_16x16x32_bf16 v[88:91], v[148:151], v[180:183], v[88:91]
	v_mfma_f32_16x16x32_bf16 v[84:87], v[156:159], v[180:183], v[84:87]
	v_mfma_f32_16x16x32_bf16 v[72:75], v[148:151], v[206:209], v[72:75]
	v_mfma_f32_16x16x32_bf16 v[68:71], v[156:159], v[206:209], v[68:71]
	v_mfma_f32_16x16x32_bf16 v[132:135], v[152:155], v[168:171], v[132:135]
	v_mfma_f32_16x16x32_bf16 v[124:127], v[160:163], v[168:171], v[124:127]
	v_mfma_f32_16x16x32_bf16 v[104:107], v[152:155], v[176:179], v[104:107]
	v_mfma_f32_16x16x32_bf16 v[100:103], v[160:163], v[176:179], v[100:103]
	v_mfma_f32_16x16x32_bf16 v[88:91], v[152:155], v[184:187], v[88:91]
	v_mfma_f32_16x16x32_bf16 v[84:87], v[160:163], v[184:187], v[84:87]
	v_mfma_f32_16x16x32_bf16 v[72:75], v[152:155], v[210:213], v[72:75]
	v_mfma_f32_16x16x32_bf16 v[68:71], v[160:163], v[210:213], v[68:71]
	s_barrier
	s_setprio 0
	s_add_i32 s49, s81, s5
	v_lshl_add_u64 v[198:199], s[70:71], 0, v[200:201]
	s_mov_b32 m0, s49
	ds_read_b128 v[164:167], v234 offset:16384
	ds_read_b128 v[168:171], v234 offset:17408
	ds_read_b128 v[172:175], v234 offset:18432
	ds_read_b128 v[176:179], v234 offset:19456
	ds_read_b128 v[180:183], v234 offset:20480
	ds_read_b128 v[184:187], v234 offset:21504
	ds_read_b128 v[206:209], v234 offset:22528
	ds_read_b128 v[210:213], v234 offset:23552
	global_load_lds_dwordx4 v[198:199], off
	s_add_i32 m0, s49, 0x2000
	s_add_u32 s84, s70, 0x80000
	v_lshl_add_u64 v[214:215], s[70:71], 0, v[188:189]
	s_addc_u32 s85, s71, 0
	s_add_i32 s48, s48, s5
	global_load_lds_dwordx4 v[214:215], off
	v_lshl_add_u64 v[216:217], s[84:85], 0, v[200:201]
	s_mov_b32 m0, s48
	v_lshl_add_u64 v[218:219], s[76:77], 0, v[190:191]
	global_load_lds_dwordx4 v[216:217], off
	v_lshl_add_u64 v[216:217], s[84:85], 0, v[188:189]
	s_add_i32 m0, s48, 0x2000
	s_nop 0
	global_load_lds_dwordx4 v[216:217], off
	v_lshl_add_u64 v[216:217], s[76:77], 0, v[192:193]
	s_mov_b32 m0, s6
	s_nop 0
	global_load_lds_dwordx4 v[216:217], off
	s_mov_b32 m0, s20
	s_nop 0
	global_load_lds_dwordx4 v[218:219], off
	s_waitcnt vmcnt(8)
	s_waitcnt lgkmcnt(0)
	s_setprio 1
	s_barrier
	v_mfma_f32_16x16x32_bf16 v[64:67], v[108:111], v[164:167], v[64:67]
	v_mfma_f32_16x16x32_bf16 v[60:63], v[128:131], v[164:167], v[60:63]
	v_mfma_f32_16x16x32_bf16 v[48:51], v[108:111], v[172:175], v[48:51]
	v_mfma_f32_16x16x32_bf16 v[44:47], v[128:131], v[172:175], v[44:47]
	v_mfma_f32_16x16x32_bf16 v[32:35], v[108:111], v[180:183], v[32:35]
	v_mfma_f32_16x16x32_bf16 v[28:31], v[128:131], v[180:183], v[28:31]
	v_mfma_f32_16x16x32_bf16 v[16:19], v[108:111], v[206:209], v[16:19]
	v_mfma_f32_16x16x32_bf16 v[12:15], v[128:131], v[206:209], v[12:15]
	v_mfma_f32_16x16x32_bf16 v[64:67], v[112:115], v[168:171], v[64:67]
	v_mfma_f32_16x16x32_bf16 v[60:63], v[136:139], v[168:171], v[60:63]
	v_mfma_f32_16x16x32_bf16 v[48:51], v[112:115], v[176:179], v[48:51]
	v_mfma_f32_16x16x32_bf16 v[44:47], v[136:139], v[176:179], v[44:47]
	v_mfma_f32_16x16x32_bf16 v[32:35], v[112:115], v[184:187], v[32:35]
	v_mfma_f32_16x16x32_bf16 v[28:31], v[136:139], v[184:187], v[28:31]
	v_mfma_f32_16x16x32_bf16 v[16:19], v[112:115], v[210:213], v[16:19]
	v_mfma_f32_16x16x32_bf16 v[12:15], v[136:139], v[210:213], v[12:15]
	s_setprio 0
	s_setprio 1
	v_mfma_f32_16x16x32_bf16 v[56:59], v[148:151], v[164:167], v[56:59]
	v_mfma_f32_16x16x32_bf16 v[52:55], v[156:159], v[164:167], v[52:55]
	v_mfma_f32_16x16x32_bf16 v[40:43], v[148:151], v[172:175], v[40:43]
	v_mfma_f32_16x16x32_bf16 v[36:39], v[156:159], v[172:175], v[36:39]
	v_mfma_f32_16x16x32_bf16 v[24:27], v[148:151], v[180:183], v[24:27]
	v_mfma_f32_16x16x32_bf16 v[20:23], v[156:159], v[180:183], v[20:23]
	v_mfma_f32_16x16x32_bf16 v[8:11], v[148:151], v[206:209], v[8:11]
	v_mfma_f32_16x16x32_bf16 v[4:7], v[156:159], v[206:209], v[4:7]
	v_mfma_f32_16x16x32_bf16 v[56:59], v[152:155], v[168:171], v[56:59]
	v_mfma_f32_16x16x32_bf16 v[52:55], v[160:163], v[168:171], v[52:55]
	v_mfma_f32_16x16x32_bf16 v[40:43], v[152:155], v[176:179], v[40:43]
	v_mfma_f32_16x16x32_bf16 v[36:39], v[160:163], v[176:179], v[36:39]
	v_mfma_f32_16x16x32_bf16 v[24:27], v[152:155], v[184:187], v[24:27]
	v_mfma_f32_16x16x32_bf16 v[20:23], v[160:163], v[184:187], v[20:23]
	v_mfma_f32_16x16x32_bf16 v[8:11], v[152:155], v[210:213], v[8:11]
	v_mfma_f32_16x16x32_bf16 v[4:7], v[160:163], v[210:213], v[4:7]
	s_barrier
; #define PG8_STAGE(bufoff, gbase, voff) do { _Pragma("unroll") for (int _i = 0; _i < 2; ++_i) \
;         __builtin_amdgcn_global_load_lds((const unsigned*)((const char*)(gbase) + (voff)[_i]), (PG8_LAS unsigned*)(lds + (bufoff) + ldsw + _i * 8192), 16, 0, 0); } while (0)
; #define PG8_LDA(dst, b, h) do { _Pragma("unroll") for (int m = 0; m < 4; ++m) _Pragma("unroll") for (int k = 0; k < 2; ++k) dst[m][k] = *(const PG8_LAS bf16x8*)(lds + PG8_SA(b, h) + aoff + m * 2048 + k * 1024); } while (0)
; #define PG8_LDB(dst, b, h) do { _Pragma("unroll") for (int n = 0; n < 2; ++n) _Pragma("unroll") for (int k = 0; k < 2; ++k) dst[n][k] = *(const PG8_LAS bf16x8*)(lds + PG8_SB(b, h) + boff + n * 2048 + k * 1024); } while (0)
; #define PG8_MMA(ai, bj, At, Bt) do { __builtin_amdgcn_s_setprio(1); _Pragma("unroll") for (int m = 0; m < 4; ++m) _Pragma("unroll") for (int n = 0; n < 2; ++n) _Pragma("unroll") for (int k = 0; k < 2; ++k) \
;         acc[ai][bj][m][n] = __builtin_amdgcn_mfma_f32_16x16x32_bf16(Bt[n][k], At[m][k], acc[ai][bj][m][n], 0, 0, 0); __builtin_amdgcn_s_setprio(0); } while (0)
; #define PG8_WAIT_V(n) asm volatile("s_waitcnt vmcnt(" #n ")" ::: "memory")
; #define PG8_WAIT_L(n) asm volatile("s_waitcnt lgkmcnt(" #n ")" ::: "memory")
; #define PG8_BAR __builtin_amdgcn_s_barrier()
; #define PG8_SCHED __builtin_amdgcn_sched_barrier(0)
;     ...
;             PG8_LDB(B0, 1, 0); PG8_LDB(B1, 1, 1); PG8_SCHED; PG8_LDA(At, 1, 0); PG8_STAGE(PG8_SA(0, 1), a2 + hstep, voffA);
;             PG8_WAIT_V(8); PG8_WAIT_L(0); PG8_BAR; PG8_MMA(0, 0, At, B0); PG8_MMA(0, 1, At, B1); PG8_BAR; PG8_SCHED;
	s_setprio 0
	s_add_i32 s48, 0, 0x18000
	s_add_i32 s49, 0, 0x1c000
	ds_read_b128 v[108:111], v251 offset:32768
	ds_read_b128 v[112:115], v251 offset:33792
	ds_read_b128 v[128:131], v251 offset:34816
	ds_read_b128 v[136:139], v251 offset:35840
	ds_read_b128 v[148:151], v251 offset:49152
	ds_read_b128 v[152:155], v251 offset:50176
	ds_read_b128 v[156:159], v251 offset:51200
	ds_read_b128 v[160:163], v251 offset:52224
	s_add_u32 s76, s76, 0x80000
	s_addc_u32 s77, s77, 0
	s_mov_b32 m0, s21
	v_lshl_add_u64 v[220:221], s[76:77], 0, v[192:193]
	ds_read_b128 v[164:167], v234 offset:32768
	ds_read_b128 v[168:171], v234 offset:33792
	ds_read_b128 v[172:175], v234 offset:34816
	ds_read_b128 v[176:179], v234 offset:35840
	ds_read_b128 v[180:183], v234 offset:36864
	ds_read_b128 v[184:187], v234 offset:37888
	ds_read_b128 v[206:209], v234 offset:38912
	ds_read_b128 v[210:213], v234 offset:39936
	global_load_lds_dwordx4 v[220:221], off
	v_lshl_add_u64 v[220:221], s[76:77], 0, v[190:191]
	s_mov_b32 m0, s23
	s_nop 0
	global_load_lds_dwordx4 v[220:221], off
	s_waitcnt vmcnt(8)
	s_waitcnt lgkmcnt(0)
	s_setprio 1
	s_barrier
	v_mfma_f32_16x16x32_bf16 v[144:147], v[108:111], v[164:167], v[144:147]
	v_mfma_f32_16x16x32_bf16 v[140:143], v[128:131], v[164:167], v[140:143]
	v_mfma_f32_16x16x32_bf16 v[120:123], v[108:111], v[172:175], v[120:123]
	v_mfma_f32_16x16x32_bf16 v[116:119], v[128:131], v[172:175], v[116:119]
	v_mfma_f32_16x16x32_bf16 v[96:99], v[108:111], v[180:183], v[96:99]
	v_mfma_f32_16x16x32_bf16 v[92:95], v[128:131], v[180:183], v[92:95]
	v_mfma_f32_16x16x32_bf16 v[80:83], v[108:111], v[206:209], v[80:83]
	v_mfma_f32_16x16x32_bf16 v[76:79], v[128:131], v[206:209], v[76:79]
	v_mfma_f32_16x16x32_bf16 v[144:147], v[112:115], v[168:171], v[144:147]
	v_mfma_f32_16x16x32_bf16 v[140:143], v[136:139], v[168:171], v[140:143]
	v_mfma_f32_16x16x32_bf16 v[120:123], v[112:115], v[176:179], v[120:123]
	v_mfma_f32_16x16x32_bf16 v[116:119], v[136:139], v[176:179], v[116:119]
	v_mfma_f32_16x16x32_bf16 v[96:99], v[112:115], v[184:187], v[96:99]
	v_mfma_f32_16x16x32_bf16 v[92:95], v[136:139], v[184:187], v[92:95]
	v_mfma_f32_16x16x32_bf16 v[80:83], v[112:115], v[210:213], v[80:83]
	v_mfma_f32_16x16x32_bf16 v[76:79], v[136:139], v[210:213], v[76:79]
	s_setprio 0
	s_setprio 1
	v_mfma_f32_16x16x32_bf16 v[132:135], v[148:151], v[164:167], v[132:135]
	v_mfma_f32_16x16x32_bf16 v[124:127], v[156:159], v[164:167], v[124:127]
	v_mfma_f32_16x16x32_bf16 v[104:107], v[148:151], v[172:175], v[104:107]
	v_mfma_f32_16x16x32_bf16 v[100:103], v[156:159], v[172:175], v[100:103]
	v_mfma_f32_16x16x32_bf16 v[88:91], v[148:151], v[180:183], v[88:91]
	v_mfma_f32_16x16x32_bf16 v[84:87], v[156:159], v[180:183], v[84:87]
	v_mfma_f32_16x16x32_bf16 v[72:75], v[148:151], v[206:209], v[72:75]
	v_mfma_f32_16x16x32_bf16 v[68:71], v[156:159], v[206:209], v[68:71]
	v_mfma_f32_16x16x32_bf16 v[132:135], v[152:155], v[168:171], v[132:135]
	v_mfma_f32_16x16x32_bf16 v[124:127], v[160:163], v[168:171], v[124:127]
	v_mfma_f32_16x16x32_bf16 v[104:107], v[152:155], v[176:179], v[104:107]
	v_mfma_f32_16x16x32_bf16 v[100:103], v[160:163], v[176:179], v[100:103]
	v_mfma_f32_16x16x32_bf16 v[88:91], v[152:155], v[184:187], v[88:91]
	v_mfma_f32_16x16x32_bf16 v[84:87], v[160:163], v[184:187], v[84:87]
	v_mfma_f32_16x16x32_bf16 v[72:75], v[152:155], v[210:213], v[72:75]
	v_mfma_f32_16x16x32_bf16 v[68:71], v[160:163], v[210:213], v[68:71]
	s_barrier
; #define PG8_STAGE(bufoff, gbase, voff) do { _Pragma("unroll") for (int _i = 0; _i < 2; ++_i) \
;         __builtin_amdgcn_global_load_lds((const unsigned*)((const char*)(gbase) + (voff)[_i]), (PG8_LAS unsigned*)(lds + (bufoff) + ldsw + _i * 8192), 16, 0, 0); } while (0)
; #define PG8_LDA(dst, b, h) do { _Pragma("unroll") for (int m = 0; m < 4; ++m) _Pragma("unroll") for (int k = 0; k < 2; ++k) dst[m][k] = *(const PG8_LAS bf16x8*)(lds + PG8_SA(b, h) + aoff + m * 2048 + k * 1024); } while (0)
; #define PG8_MMA(ai, bj, At, Bt) do { __builtin_amdgcn_s_setprio(1); _Pragma("unroll") for (int m = 0; m < 4; ++m) _Pragma("unroll") for (int n = 0; n < 2; ++n) _Pragma("unroll") for (int k = 0; k < 2; ++k) \
;         acc[ai][bj][m][n] = __builtin_amdgcn_mfma_f32_16x16x32_bf16(Bt[n][k], At[m][k], acc[ai][bj][m][n], 0, 0, 0); __builtin_amdgcn_s_setprio(0); } while (0)
; #define PG8_WAIT_V(n) asm volatile("s_waitcnt vmcnt(" #n ")" ::: "memory")
; #define PG8_WAIT_L(n) asm volatile("s_waitcnt lgkmcnt(" #n ")" ::: "memory")
; #define PG8_BAR __builtin_amdgcn_s_barrier()
; #define PG8_SCHED __builtin_amdgcn_sched_barrier(0)
;     ...
;             PG8_WAIT_V(8); PG8_WAIT_L(0); PG8_BAR; PG8_MMA(0, 0, At, B0); PG8_MMA(0, 1, At, B1); PG8_BAR; PG8_SCHED;
;             PG8_LDA(At, 1, 1); PG8_STAGE(PG8_SB(1, 0), b3, voffB); PG8_STAGE(PG8_SB(1, 1), b3 + hstep, voffB); PG8_STAGE(PG8_SA(1, 0), a3, voffA);
;             PG8_WAIT_V(8); PG8_WAIT_L(0); PG8_BAR; PG8_MMA(1, 0, At, B0); PG8_MMA(1, 1, At, B1); PG8_BAR; PG8_SCHED;
;     ...
;         if constexpr (ALIGN_EPI) { if (wr == 0) PG8_BAR; }
	s_setprio 0
	s_add_i32 s48, s48, s5
	v_lshl_add_u64 v[198:199], v[198:199], 0, s[66:67]
	s_mov_b32 m0, s48
	ds_read_b128 v[164:167], v234 offset:49152
	ds_read_b128 v[168:171], v234 offset:50176
	ds_read_b128 v[172:175], v234 offset:51200
	ds_read_b128 v[176:179], v234 offset:52224
	ds_read_b128 v[180:183], v234 offset:53248
	ds_read_b128 v[184:187], v234 offset:54272
	ds_read_b128 v[206:209], v234 offset:55296
	ds_read_b128 v[210:213], v234 offset:56320
	global_load_lds_dwordx4 v[198:199], off
	s_add_i32 m0, s48, 0x2000
	s_add_u32 s70, s70, 0x80080
	v_lshl_add_u64 v[198:199], v[214:215], 0, s[66:67]
	s_addc_u32 s71, s71, 0
	s_add_i32 s48, s49, s5
	global_load_lds_dwordx4 v[198:199], off
	v_lshl_add_u64 v[198:199], s[70:71], 0, v[200:201]
	s_mov_b32 m0, s48
	s_nop 0
	global_load_lds_dwordx4 v[198:199], off
	v_lshl_add_u64 v[198:199], s[70:71], 0, v[188:189]
	s_add_i32 m0, s48, 0x2000
	s_nop 0
	global_load_lds_dwordx4 v[198:199], off
	v_lshl_add_u64 v[198:199], v[216:217], 0, s[66:67]
	s_mov_b32 m0, s54
	s_nop 0
	global_load_lds_dwordx4 v[198:199], off
	v_lshl_add_u64 v[198:199], v[218:219], 0, s[66:67]
	s_mov_b32 m0, s55
	s_nop 0
	global_load_lds_dwordx4 v[198:199], off
	s_waitcnt vmcnt(8)
	s_waitcnt lgkmcnt(0)
	s_setprio 1
	s_barrier
	v_mfma_f32_16x16x32_bf16 v[64:67], v[108:111], v[164:167], v[64:67]
	v_mfma_f32_16x16x32_bf16 v[60:63], v[128:131], v[164:167], v[60:63]
	v_mfma_f32_16x16x32_bf16 v[48:51], v[108:111], v[172:175], v[48:51]
	v_mfma_f32_16x16x32_bf16 v[44:47], v[128:131], v[172:175], v[44:47]
	v_mfma_f32_16x16x32_bf16 v[32:35], v[108:111], v[180:183], v[32:35]
	v_mfma_f32_16x16x32_bf16 v[28:31], v[128:131], v[180:183], v[28:31]
	v_mfma_f32_16x16x32_bf16 v[16:19], v[108:111], v[206:209], v[16:19]
	v_mfma_f32_16x16x32_bf16 v[12:15], v[128:131], v[206:209], v[12:15]
	v_mfma_f32_16x16x32_bf16 v[64:67], v[112:115], v[168:171], v[64:67]
	v_mfma_f32_16x16x32_bf16 v[60:63], v[136:139], v[168:171], v[60:63]
	v_mfma_f32_16x16x32_bf16 v[48:51], v[112:115], v[176:179], v[48:51]
	v_mfma_f32_16x16x32_bf16 v[44:47], v[136:139], v[176:179], v[44:47]
	v_mfma_f32_16x16x32_bf16 v[32:35], v[112:115], v[184:187], v[32:35]
	v_mfma_f32_16x16x32_bf16 v[28:31], v[136:139], v[184:187], v[28:31]
	v_mfma_f32_16x16x32_bf16 v[16:19], v[112:115], v[210:213], v[16:19]
	v_mfma_f32_16x16x32_bf16 v[12:15], v[136:139], v[210:213], v[12:15]
	s_setprio 0
	s_setprio 1
	v_mfma_f32_16x16x32_bf16 v[56:59], v[148:151], v[164:167], v[56:59]
	v_mfma_f32_16x16x32_bf16 v[52:55], v[156:159], v[164:167], v[52:55]
	v_mfma_f32_16x16x32_bf16 v[40:43], v[148:151], v[172:175], v[40:43]
	v_mfma_f32_16x16x32_bf16 v[36:39], v[156:159], v[172:175], v[36:39]
	v_mfma_f32_16x16x32_bf16 v[24:27], v[148:151], v[180:183], v[24:27]
	v_mfma_f32_16x16x32_bf16 v[20:23], v[156:159], v[180:183], v[20:23]
	v_mfma_f32_16x16x32_bf16 v[8:11], v[148:151], v[206:209], v[8:11]
	v_mfma_f32_16x16x32_bf16 v[4:7], v[156:159], v[206:209], v[4:7]
	v_mfma_f32_16x16x32_bf16 v[56:59], v[152:155], v[168:171], v[56:59]
	v_mfma_f32_16x16x32_bf16 v[52:55], v[160:163], v[168:171], v[52:55]
	v_mfma_f32_16x16x32_bf16 v[40:43], v[152:155], v[176:179], v[40:43]
	v_mfma_f32_16x16x32_bf16 v[36:39], v[160:163], v[176:179], v[36:39]
	v_mfma_f32_16x16x32_bf16 v[24:27], v[152:155], v[184:187], v[24:27]
	v_mfma_f32_16x16x32_bf16 v[20:23], v[160:163], v[184:187], v[20:23]
	v_mfma_f32_16x16x32_bf16 v[8:11], v[152:155], v[210:213], v[8:11]
	v_mfma_f32_16x16x32_bf16 v[4:7], v[160:163], v[210:213], v[4:7]
	s_barrier
	s_setprio 0
	s_add_i32 s79, s79, 2
	s_add_u32 s75, s75, 0x100
	s_addc_u32 s78, s78, 0
	s_add_u32 s68, s68, 0x100
	s_addc_u32 s69, s69, 0
	s_cmp_gt_u32 s79, 29
	s_cbranch_scc0 .LBB0_998
	s_and_b64 vcc, exec, s[14:15]
	s_cbranch_vccz .LBB0_1001
	s_barrier

;     __device__ __forceinline__ bool next(int i, Unit& u) const { if (i >= n) return false; u.pm = pm; u.pn = pn0 + i; return true; }
;     __device__ __forceinline__ bool next(int i, Unit& u) const { if (i) return false; u.pm = pm; u.pn = pn; return true; }
; #define PG8_STAGE(bufoff, gbase, voff) do { _Pragma("unroll") for (int _i = 0; _i < 2; ++_i) \
;         __builtin_amdgcn_global_load_lds((const unsigned*)((const char*)(gbase) + (voff)[_i]), (PG8_LAS unsigned*)(lds + (bufoff) + ldsw + _i * 8192), 16, 0, 0); } while (0)
; #define PG8_LDA(dst, b, h) do { _Pragma("unroll") for (int m = 0; m < 4; ++m) _Pragma("unroll") for (int k = 0; k < 2; ++k) dst[m][k] = *(const PG8_LAS bf16x8*)(lds + PG8_SA(b, h) + aoff + m * 2048 + k * 1024); } while (0)
; #define PG8_LDB(dst, b, h) do { _Pragma("unroll") for (int n = 0; n < 2; ++n) _Pragma("unroll") for (int k = 0; k < 2; ++k) dst[n][k] = *(const PG8_LAS bf16x8*)(lds + PG8_SB(b, h) + boff + n * 2048 + k * 1024); } while (0)
; #define PG8_WAIT_V(n) asm volatile("s_waitcnt vmcnt(" #n ")" ::: "memory")
; #define PG8_BAR __builtin_amdgcn_s_barrier()
;     ...
;         const bool has_next = S.next(ui + 1, nxt);
;         const char* nA = has_next ? (const char*)g.A + (size_t)nxt.pm * tstep : cA; const char* nB = has_next ? (const char*)g.Bt + (size_t)nxt.pn * tstep : cB;
;         for (int t = 0; t < nt; t += 2) {
;             const bool last = (t == nt - 2);
;             const char* a1 = cA + (size_t)(t + 1) * kstep;
;             const char* a2 = last ? nA : cA + (size_t)(t + 2) * kstep; const char* b2 = last ? nB : cB + (size_t)(t + 2) * kstep;
;             const char* a3 = a2 + kstep; const char* b3 = b2 + kstep;
;             if (last && has_next) S.a_ready(nxt);
;             if (t == 0) E.pre_issue(pre, cur, tid, ui); else if (t == 2) E.pre_finish(pre, tid, ui);
;             if constexpr (SP2) {
;             PG8_LDB(B0, 0, 0); PG8_LDB(B1, 0, 1); PG8_SCHED; PG8_LDA(At, 0, 0); PG8_STAGE(PG8_SA(1, 1), a1 + hstep, voffA);
;             PG8_WAIT_V(8); PG8_WAIT_L(0); PG8_BAR; PG8_MMA(0, 0, At, B0); PG8_MMA(0, 1, At, B1); PG8_BAR; PG8_SCHED;
;     ...
;         for (int a = 0; a < 2; ++a)
; #pragma unroll
;             for (int b = 0; b < 2; ++b)
; #pragma unroll
;                 for (int m = 0; m < 4; ++m)
; #pragma unroll
;                     for (int n = 0; n < 2; ++n) acc[a][b][m][n] = (f32x4){0.f, 0.f, 0.f, 0.f};
.LBB0_1085:
	s_ashr_i32 s97, s96, 31
	s_lshl_b64 s[12:13], s[96:97], 20
	s_add_u32 s90, s36, s12
	s_addc_u32 s91, s37, s13
	s_and_b64 s[12:13], s[6:7], exec
	s_cselect_b32 s69, s91, s9
	s_cselect_b32 s76, s90, s8
	s_ashr_i32 s89, s88, 31
	s_lshl_b64 s[12:13], s[88:89], 20
	s_add_u32 s94, s58, s12
	s_addc_u32 s95, s59, s13
	s_and_b64 s[12:13], s[6:7], exec
	s_cselect_b32 s77, s95, s11
	s_cselect_b32 s82, s94, s10
	s_add_u32 s8, s8, 0x80080
	s_addc_u32 s9, s9, 0
	s_add_u32 s83, s10, 0x100
	v_mov_b32_e32 v12, 0
	s_addc_u32 s89, s11, 0
	s_mov_b32 s97, -2
	v_mov_b32_e32 v13, v12
	v_mov_b32_e32 v14, v12
	v_mov_b32_e32 v15, v12
	v_mov_b32_e32 v16, v12
	v_mov_b32_e32 v17, v12
	v_mov_b32_e32 v18, v12
	v_mov_b32_e32 v19, v12
	v_mov_b32_e32 v24, v12
	v_mov_b32_e32 v25, v12
	v_mov_b32_e32 v26, v12
	v_mov_b32_e32 v27, v12
	v_mov_b32_e32 v84, v12
	v_mov_b32_e32 v85, v12
	v_mov_b32_e32 v86, v12
	v_mov_b32_e32 v87, v12
	v_mov_b32_e32 v28, v12
	v_mov_b32_e32 v29, v12
	v_mov_b32_e32 v30, v12
	v_mov_b32_e32 v31, v12
	v_mov_b32_e32 v88, v12
	v_mov_b32_e32 v89, v12
	v_mov_b32_e32 v90, v12
	v_mov_b32_e32 v91, v12
	v_mov_b32_e32 v32, v12
	v_mov_b32_e32 v33, v12
	v_mov_b32_e32 v34, v12
	v_mov_b32_e32 v35, v12
	v_mov_b32_e32 v102, v12
	v_mov_b32_e32 v103, v12
	v_mov_b32_e32 v104, v12
	v_mov_b32_e32 v105, v12
	v_mov_b32_e32 v20, v12
	v_mov_b32_e32 v21, v12
	v_mov_b32_e32 v22, v12
	v_mov_b32_e32 v23, v12
	v_mov_b32_e32 v80, v12
	v_mov_b32_e32 v81, v12
	v_mov_b32_e32 v82, v12
	v_mov_b32_e32 v83, v12
	v_mov_b32_e32 v36, v12
	v_mov_b32_e32 v37, v12
	v_mov_b32_e32 v38, v12
	v_mov_b32_e32 v39, v12
	v_mov_b32_e32 v138, v12
	v_mov_b32_e32 v139, v12
	v_mov_b32_e32 v140, v12
	v_mov_b32_e32 v141, v12
	v_mov_b32_e32 v40, v12
	v_mov_b32_e32 v41, v12
	v_mov_b32_e32 v42, v12
	v_mov_b32_e32 v43, v12
	v_mov_b32_e32 v142, v12
	v_mov_b32_e32 v143, v12
	v_mov_b32_e32 v144, v12
	v_mov_b32_e32 v145, v12
	v_mov_b32_e32 v44, v12
	v_mov_b32_e32 v45, v12
	v_mov_b32_e32 v46, v12
	v_mov_b32_e32 v47, v12
	v_mov_b32_e32 v146, v12
	v_mov_b32_e32 v147, v12
	v_mov_b32_e32 v148, v12
	v_mov_b32_e32 v149, v12
	v_mov_b32_e32 v68, v12
	v_mov_b32_e32 v69, v12
	v_mov_b32_e32 v70, v12
	v_mov_b32_e32 v71, v12
	v_mov_b32_e32 v92, v12
	v_mov_b32_e32 v93, v12
	v_mov_b32_e32 v94, v12
	v_mov_b32_e32 v95, v12
	v_mov_b32_e32 v48, v12
	v_mov_b32_e32 v49, v12
	v_mov_b32_e32 v50, v12
	v_mov_b32_e32 v51, v12
	v_mov_b32_e32 v150, v12
	v_mov_b32_e32 v151, v12
	v_mov_b32_e32 v152, v12
	v_mov_b32_e32 v153, v12
	v_mov_b32_e32 v52, v12
	v_mov_b32_e32 v53, v12
	v_mov_b32_e32 v54, v12
	v_mov_b32_e32 v55, v12
	v_mov_b32_e32 v154, v12
	v_mov_b32_e32 v155, v12
	v_mov_b32_e32 v156, v12
	v_mov_b32_e32 v157, v12
	v_mov_b32_e32 v64, v12
	v_mov_b32_e32 v65, v12
	v_mov_b32_e32 v66, v12
	v_mov_b32_e32 v67, v12
	v_mov_b32_e32 v8, v12
	v_mov_b32_e32 v9, v12
	v_mov_b32_e32 v10, v12
	v_mov_b32_e32 v11, v12
	v_mov_b32_e32 v76, v12
	v_mov_b32_e32 v77, v12
	v_mov_b32_e32 v78, v12
	v_mov_b32_e32 v79, v12
	v_mov_b32_e32 v96, v12
	v_mov_b32_e32 v97, v12
	v_mov_b32_e32 v98, v12
	v_mov_b32_e32 v99, v12
	v_mov_b32_e32 v56, v12
	v_mov_b32_e32 v57, v12
	v_mov_b32_e32 v58, v12
	v_mov_b32_e32 v59, v12
	v_mov_b32_e32 v158, v12
	v_mov_b32_e32 v159, v12
	v_mov_b32_e32 v160, v12
	v_mov_b32_e32 v161, v12
	v_mov_b32_e32 v60, v12
	v_mov_b32_e32 v61, v12
	v_mov_b32_e32 v62, v12
	v_mov_b32_e32 v63, v12
	v_mov_b32_e32 v162, v12
	v_mov_b32_e32 v163, v12
	v_mov_b32_e32 v164, v12
	v_mov_b32_e32 v165, v12
	v_mov_b32_e32 v72, v12
	v_mov_b32_e32 v73, v12
	v_mov_b32_e32 v74, v12
	v_mov_b32_e32 v75, v12
	v_mov_b32_e32 v4, v12
	v_mov_b32_e32 v5, v12
	v_mov_b32_e32 v6, v12
	v_mov_b32_e32 v7, v12
	v_add_u32_e32 v251, 0x10000, v221
.LBB0_1086:
	s_add_u32 s10, s8, 0xfff80080
	s_addc_u32 s11, s9, -1
	s_add_i32 s48, 0, 0x10000
	s_cmp_eq_u32 s97, 28
	s_cselect_b32 s13, s69, s11
	s_cselect_b32 s12, s76, s10
	s_cselect_b32 s11, s77, s89
	s_cselect_b32 s10, s82, s83
	s_add_i32 vcc_lo, 0, 0x14000
	ds_read_b128 v[106:109], v251
	ds_read_b128 v[110:113], v251 offset:1024
	ds_read_b128 v[114:117], v251 offset:2048
	ds_read_b128 v[118:121], v251 offset:3072
	ds_read_b128 v[122:125], v251 offset:16384
	ds_read_b128 v[126:129], v251 offset:17408
	ds_read_b128 v[130:133], v251 offset:18432
	ds_read_b128 v[134:137], v251 offset:19456
	v_lshl_add_u64 v[100:101], s[8:9], 0, v[190:191]
	s_add_i32 m0, s1, 0xc000
	ds_read_b128 v[166:169], v222
	ds_read_b128 v[170:173], v222 offset:1024
	ds_read_b128 v[174:177], v222 offset:2048
	ds_read_b128 v[178:181], v222 offset:3072
	ds_read_b128 v[194:197], v222 offset:4096
	ds_read_b128 v[206:209], v222 offset:5120
	ds_read_b128 v[210:213], v222 offset:6144
	ds_read_b128 v[214:217], v222 offset:7168
	global_load_lds_dwordx4 v[100:101], off
	v_lshl_add_u64 v[100:101], s[8:9], 0, v[192:193]
	s_add_i32 m0, s1, 0xe000
	s_nop 0
	global_load_lds_dwordx4 v[100:101], off
	s_waitcnt vmcnt(8)
	s_waitcnt lgkmcnt(0)
	s_setprio 1
	s_barrier
; #define PG8_STAGE(bufoff, gbase, voff) do { _Pragma("unroll") for (int _i = 0; _i < 2; ++_i) \
;         __builtin_amdgcn_global_load_lds((const unsigned*)((const char*)(gbase) + (voff)[_i]), (PG8_LAS unsigned*)(lds + (bufoff) + ldsw + _i * 8192), 16, 0, 0); } while (0)
; #define PG8_LDA(dst, b, h) do { _Pragma("unroll") for (int m = 0; m < 4; ++m) _Pragma("unroll") for (int k = 0; k < 2; ++k) dst[m][k] = *(const PG8_LAS bf16x8*)(lds + PG8_SA(b, h) + aoff + m * 2048 + k * 1024); } while (0)
; #define PG8_MMA(ai, bj, At, Bt) do { __builtin_amdgcn_s_setprio(1); _Pragma("unroll") for (int m = 0; m < 4; ++m) _Pragma("unroll") for (int n = 0; n < 2; ++n) _Pragma("unroll") for (int k = 0; k < 2; ++k) \
;         acc[ai][bj][m][n] = __builtin_amdgcn_mfma_f32_16x16x32_bf16(Bt[n][k], At[m][k], acc[ai][bj][m][n], 0, 0, 0); __builtin_amdgcn_s_setprio(0); } while (0)
; #define PG8_WAIT_V(n) asm volatile("s_waitcnt vmcnt(" #n ")" ::: "memory")
; #define PG8_WAIT_L(n) asm volatile("s_waitcnt lgkmcnt(" #n ")" ::: "memory")
; #define PG8_BAR __builtin_amdgcn_s_barrier()
; #define PG8_SCHED __builtin_amdgcn_sched_barrier(0)
;     ...
;             PG8_WAIT_V(8); PG8_WAIT_L(0); PG8_BAR; PG8_MMA(0, 0, At, B0); PG8_MMA(0, 1, At, B1); PG8_BAR; PG8_SCHED;
;             PG8_LDA(At, 0, 1); PG8_STAGE(PG8_SB(0, 0), b2, voffB); PG8_STAGE(PG8_SB(0, 1), b2 + hstep, voffB); PG8_STAGE(PG8_SA(0, 0), a2, voffA);
;             PG8_WAIT_V(8); PG8_WAIT_L(0); PG8_BAR; PG8_MMA(1, 0, At, B0); PG8_MMA(1, 1, At, B1); PG8_BAR; PG8_SCHED;
	v_mfma_f32_16x16x32_bf16 v[4:7], v[106:109], v[166:169], v[4:7]
	v_mfma_f32_16x16x32_bf16 v[72:75], v[114:117], v[166:169], v[72:75]
	v_mfma_f32_16x16x32_bf16 v[162:165], v[106:109], v[174:177], v[162:165]
	v_mfma_f32_16x16x32_bf16 v[60:63], v[114:117], v[174:177], v[60:63]
	v_mfma_f32_16x16x32_bf16 v[158:161], v[106:109], v[194:197], v[158:161]
	v_mfma_f32_16x16x32_bf16 v[56:59], v[114:117], v[194:197], v[56:59]
	v_mfma_f32_16x16x32_bf16 v[96:99], v[106:109], v[210:213], v[96:99]
	v_mfma_f32_16x16x32_bf16 v[76:79], v[114:117], v[210:213], v[76:79]
	v_mfma_f32_16x16x32_bf16 v[4:7], v[110:113], v[170:173], v[4:7]
	v_mfma_f32_16x16x32_bf16 v[72:75], v[118:121], v[170:173], v[72:75]
	v_mfma_f32_16x16x32_bf16 v[162:165], v[110:113], v[178:181], v[162:165]
	v_mfma_f32_16x16x32_bf16 v[60:63], v[118:121], v[178:181], v[60:63]
	v_mfma_f32_16x16x32_bf16 v[158:161], v[110:113], v[206:209], v[158:161]
	v_mfma_f32_16x16x32_bf16 v[56:59], v[118:121], v[206:209], v[56:59]
	v_mfma_f32_16x16x32_bf16 v[96:99], v[110:113], v[214:217], v[96:99]
	v_mfma_f32_16x16x32_bf16 v[76:79], v[118:121], v[214:217], v[76:79]
	s_setprio 0
	s_setprio 1
	v_mfma_f32_16x16x32_bf16 v[8:11], v[122:125], v[166:169], v[8:11]
	v_mfma_f32_16x16x32_bf16 v[64:67], v[130:133], v[166:169], v[64:67]
	v_mfma_f32_16x16x32_bf16 v[154:157], v[122:125], v[174:177], v[154:157]
	v_mfma_f32_16x16x32_bf16 v[52:55], v[130:133], v[174:177], v[52:55]
	v_mfma_f32_16x16x32_bf16 v[150:153], v[122:125], v[194:197], v[150:153]
	v_mfma_f32_16x16x32_bf16 v[48:51], v[130:133], v[194:197], v[48:51]
	v_mfma_f32_16x16x32_bf16 v[92:95], v[122:125], v[210:213], v[92:95]
	v_mfma_f32_16x16x32_bf16 v[68:71], v[130:133], v[210:213], v[68:71]
	v_mfma_f32_16x16x32_bf16 v[8:11], v[126:129], v[170:173], v[8:11]
	v_mfma_f32_16x16x32_bf16 v[64:67], v[134:137], v[170:173], v[64:67]
	v_mfma_f32_16x16x32_bf16 v[154:157], v[126:129], v[178:181], v[154:157]
	v_mfma_f32_16x16x32_bf16 v[52:55], v[134:137], v[178:181], v[52:55]
	v_mfma_f32_16x16x32_bf16 v[150:153], v[126:129], v[206:209], v[150:153]
	v_mfma_f32_16x16x32_bf16 v[48:51], v[134:137], v[206:209], v[48:51]
	v_mfma_f32_16x16x32_bf16 v[92:95], v[126:129], v[214:217], v[92:95]
	v_mfma_f32_16x16x32_bf16 v[68:71], v[134:137], v[214:217], v[68:71]
	s_barrier
	s_setprio 0
	s_add_i32 s48, s48, s0
	v_lshl_add_u64 v[198:199], s[10:11], 0, v[186:187]
	s_mov_b32 m0, s48
	ds_read_b128 v[166:169], v222 offset:16384
	ds_read_b128 v[170:173], v222 offset:17408
	ds_read_b128 v[174:177], v222 offset:18432
	ds_read_b128 v[178:181], v222 offset:19456
	ds_read_b128 v[194:197], v222 offset:20480
	ds_read_b128 v[206:209], v222 offset:21504
	ds_read_b128 v[210:213], v222 offset:22528
	ds_read_b128 v[214:217], v222 offset:23552
	global_load_lds_dwordx4 v[198:199], off
	s_add_i32 m0, s48, 0x2000
	s_add_u32 s48, s10, 0x80000
	v_lshl_add_u64 v[218:219], s[10:11], 0, v[182:183]
	s_addc_u32 s49, s11, 0
	s_add_i32 vcc_lo, vcc_lo, s0
	global_load_lds_dwordx4 v[218:219], off
	v_lshl_add_u64 v[100:101], s[48:49], 0, v[186:187]
	s_mov_b32 m0, vcc_lo
	v_lshl_add_u64 v[224:225], s[12:13], 0, v[188:189]
	global_load_lds_dwordx4 v[100:101], off
	v_lshl_add_u64 v[100:101], s[48:49], 0, v[182:183]
	s_add_i32 m0, vcc_lo, 0x2000
	v_lshl_add_u64 v[232:233], s[12:13], 0, v[184:185]
	global_load_lds_dwordx4 v[100:101], off
	s_mov_b32 m0, s1
	s_nop 0
	global_load_lds_dwordx4 v[224:225], off
	s_mov_b32 m0, s4
	s_nop 0
	global_load_lds_dwordx4 v[232:233], off
	s_waitcnt vmcnt(8)
	s_waitcnt lgkmcnt(0)
	s_setprio 1
	s_barrier
	v_mfma_f32_16x16x32_bf16 v[146:149], v[106:109], v[166:169], v[146:149]
	v_mfma_f32_16x16x32_bf16 v[44:47], v[114:117], v[166:169], v[44:47]
	v_mfma_f32_16x16x32_bf16 v[142:145], v[106:109], v[174:177], v[142:145]
	v_mfma_f32_16x16x32_bf16 v[40:43], v[114:117], v[174:177], v[40:43]
	v_mfma_f32_16x16x32_bf16 v[138:141], v[106:109], v[194:197], v[138:141]
	v_mfma_f32_16x16x32_bf16 v[36:39], v[114:117], v[194:197], v[36:39]
	v_mfma_f32_16x16x32_bf16 v[80:83], v[106:109], v[210:213], v[80:83]
	v_mfma_f32_16x16x32_bf16 v[20:23], v[114:117], v[210:213], v[20:23]
	v_mfma_f32_16x16x32_bf16 v[146:149], v[110:113], v[170:173], v[146:149]
	v_mfma_f32_16x16x32_bf16 v[44:47], v[118:121], v[170:173], v[44:47]
	v_mfma_f32_16x16x32_bf16 v[142:145], v[110:113], v[178:181], v[142:145]
	v_mfma_f32_16x16x32_bf16 v[40:43], v[118:121], v[178:181], v[40:43]
	v_mfma_f32_16x16x32_bf16 v[138:141], v[110:113], v[206:209], v[138:141]
	v_mfma_f32_16x16x32_bf16 v[36:39], v[118:121], v[206:209], v[36:39]
	v_mfma_f32_16x16x32_bf16 v[80:83], v[110:113], v[214:217], v[80:83]
	v_mfma_f32_16x16x32_bf16 v[20:23], v[118:121], v[214:217], v[20:23]
	s_setprio 0
	s_setprio 1
	v_mfma_f32_16x16x32_bf16 v[100:103], v[122:125], v[166:169], v[102:105]
	v_mfma_f32_16x16x32_bf16 v[32:35], v[130:133], v[166:169], v[32:35]
	v_mfma_f32_16x16x32_bf16 v[88:91], v[122:125], v[174:177], v[88:91]
	v_mfma_f32_16x16x32_bf16 v[28:31], v[130:133], v[174:177], v[28:31]
	v_mfma_f32_16x16x32_bf16 v[84:87], v[122:125], v[194:197], v[84:87]
	v_mfma_f32_16x16x32_bf16 v[24:27], v[130:133], v[194:197], v[24:27]
	v_mfma_f32_16x16x32_bf16 v[16:19], v[122:125], v[210:213], v[16:19]
	v_mfma_f32_16x16x32_bf16 v[12:15], v[130:133], v[210:213], v[12:15]
	v_mfma_f32_16x16x32_bf16 v[100:103], v[126:129], v[170:173], v[100:103]
	v_mfma_f32_16x16x32_bf16 v[32:35], v[134:137], v[170:173], v[32:35]
	v_mfma_f32_16x16x32_bf16 v[88:91], v[126:129], v[178:181], v[88:91]
	v_mfma_f32_16x16x32_bf16 v[28:31], v[134:137], v[178:181], v[28:31]
	v_mfma_f32_16x16x32_bf16 v[84:87], v[126:129], v[206:209], v[84:87]
	v_mfma_f32_16x16x32_bf16 v[24:27], v[134:137], v[206:209], v[24:27]
	v_mfma_f32_16x16x32_bf16 v[16:19], v[126:129], v[214:217], v[16:19]
	v_mfma_f32_16x16x32_bf16 v[12:15], v[134:137], v[214:217], v[12:15]
	s_barrier
; #define PG8_STAGE(bufoff, gbase, voff) do { _Pragma("unroll") for (int _i = 0; _i < 2; ++_i) \
;         __builtin_amdgcn_global_load_lds((const unsigned*)((const char*)(gbase) + (voff)[_i]), (PG8_LAS unsigned*)(lds + (bufoff) + ldsw + _i * 8192), 16, 0, 0); } while (0)
; #define PG8_LDA(dst, b, h) do { _Pragma("unroll") for (int m = 0; m < 4; ++m) _Pragma("unroll") for (int k = 0; k < 2; ++k) dst[m][k] = *(const PG8_LAS bf16x8*)(lds + PG8_SA(b, h) + aoff + m * 2048 + k * 1024); } while (0)
; #define PG8_LDB(dst, b, h) do { _Pragma("unroll") for (int n = 0; n < 2; ++n) _Pragma("unroll") for (int k = 0; k < 2; ++k) dst[n][k] = *(const PG8_LAS bf16x8*)(lds + PG8_SB(b, h) + boff + n * 2048 + k * 1024); } while (0)
; #define PG8_MMA(ai, bj, At, Bt) do { __builtin_amdgcn_s_setprio(1); _Pragma("unroll") for (int m = 0; m < 4; ++m) _Pragma("unroll") for (int n = 0; n < 2; ++n) _Pragma("unroll") for (int k = 0; k < 2; ++k) \
;         acc[ai][bj][m][n] = __builtin_amdgcn_mfma_f32_16x16x32_bf16(Bt[n][k], At[m][k], acc[ai][bj][m][n], 0, 0, 0); __builtin_amdgcn_s_setprio(0); } while (0)
; #define PG8_WAIT_V(n) asm volatile("s_waitcnt vmcnt(" #n ")" ::: "memory")
; #define PG8_WAIT_L(n) asm volatile("s_waitcnt lgkmcnt(" #n ")" ::: "memory")
; #define PG8_BAR __builtin_amdgcn_s_barrier()
; #define PG8_SCHED __builtin_amdgcn_sched_barrier(0)
;     ...
;             PG8_LDB(B0, 1, 0); PG8_LDB(B1, 1, 1); PG8_SCHED; PG8_LDA(At, 1, 0); PG8_STAGE(PG8_SA(0, 1), a2 + hstep, voffA);
;             PG8_WAIT_V(8); PG8_WAIT_L(0); PG8_BAR; PG8_MMA(0, 0, At, B0); PG8_MMA(0, 1, At, B1); PG8_BAR; PG8_SCHED;
	s_setprio 0
	s_add_i32 s48, 0, 0x18000
	s_add_i32 s49, 0, 0x1c000
	ds_read_b128 v[104:107], v251 offset:32768
	ds_read_b128 v[108:111], v251 offset:33792
	ds_read_b128 v[112:115], v251 offset:34816
	ds_read_b128 v[116:119], v251 offset:35840
	ds_read_b128 v[120:123], v251 offset:49152
	ds_read_b128 v[124:127], v251 offset:50176
	ds_read_b128 v[128:131], v251 offset:51200
	ds_read_b128 v[132:135], v251 offset:52224
	s_add_u32 s12, s12, 0x80000
	s_addc_u32 s13, s13, 0
	s_mov_b32 m0, s5
	v_lshl_add_u64 v[136:137], s[12:13], 0, v[188:189]
	ds_read_b128 v[166:169], v222 offset:32768
	ds_read_b128 v[170:173], v222 offset:33792
	ds_read_b128 v[174:177], v222 offset:34816
	ds_read_b128 v[178:181], v222 offset:35840
	ds_read_b128 v[194:197], v222 offset:36864
	ds_read_b128 v[206:209], v222 offset:37888
	ds_read_b128 v[210:213], v222 offset:38912
	ds_read_b128 v[214:217], v222 offset:39936
	global_load_lds_dwordx4 v[136:137], off
	v_lshl_add_u64 v[136:137], s[12:13], 0, v[184:185]
	s_mov_b32 m0, s44
	s_nop 0
	global_load_lds_dwordx4 v[136:137], off
	s_waitcnt vmcnt(8)
	s_waitcnt lgkmcnt(0)
	s_setprio 1
	s_barrier
	v_mfma_f32_16x16x32_bf16 v[4:7], v[104:107], v[166:169], v[4:7]
	v_mfma_f32_16x16x32_bf16 v[72:75], v[112:115], v[166:169], v[72:75]
	v_mfma_f32_16x16x32_bf16 v[162:165], v[104:107], v[174:177], v[162:165]
	v_mfma_f32_16x16x32_bf16 v[60:63], v[112:115], v[174:177], v[60:63]
	v_mfma_f32_16x16x32_bf16 v[158:161], v[104:107], v[194:197], v[158:161]
	v_mfma_f32_16x16x32_bf16 v[56:59], v[112:115], v[194:197], v[56:59]
	v_mfma_f32_16x16x32_bf16 v[96:99], v[104:107], v[210:213], v[96:99]
	v_mfma_f32_16x16x32_bf16 v[76:79], v[112:115], v[210:213], v[76:79]
	v_mfma_f32_16x16x32_bf16 v[4:7], v[108:111], v[170:173], v[4:7]
	v_mfma_f32_16x16x32_bf16 v[72:75], v[116:119], v[170:173], v[72:75]
	v_mfma_f32_16x16x32_bf16 v[162:165], v[108:111], v[178:181], v[162:165]
	v_mfma_f32_16x16x32_bf16 v[60:63], v[116:119], v[178:181], v[60:63]
	v_mfma_f32_16x16x32_bf16 v[158:161], v[108:111], v[206:209], v[158:161]
	v_mfma_f32_16x16x32_bf16 v[56:59], v[116:119], v[206:209], v[56:59]
	v_mfma_f32_16x16x32_bf16 v[96:99], v[108:111], v[214:217], v[96:99]
	v_mfma_f32_16x16x32_bf16 v[76:79], v[116:119], v[214:217], v[76:79]
	s_setprio 0
	s_setprio 1
	v_mfma_f32_16x16x32_bf16 v[8:11], v[120:123], v[166:169], v[8:11]
	v_mfma_f32_16x16x32_bf16 v[64:67], v[128:131], v[166:169], v[64:67]
	v_mfma_f32_16x16x32_bf16 v[154:157], v[120:123], v[174:177], v[154:157]
	v_mfma_f32_16x16x32_bf16 v[52:55], v[128:131], v[174:177], v[52:55]
	v_mfma_f32_16x16x32_bf16 v[150:153], v[120:123], v[194:197], v[150:153]
	v_mfma_f32_16x16x32_bf16 v[48:51], v[128:131], v[194:197], v[48:51]
	v_mfma_f32_16x16x32_bf16 v[92:95], v[120:123], v[210:213], v[92:95]
	v_mfma_f32_16x16x32_bf16 v[68:71], v[128:131], v[210:213], v[68:71]
	v_mfma_f32_16x16x32_bf16 v[8:11], v[124:127], v[170:173], v[8:11]
	v_mfma_f32_16x16x32_bf16 v[64:67], v[132:135], v[170:173], v[64:67]
	v_mfma_f32_16x16x32_bf16 v[154:157], v[124:127], v[178:181], v[154:157]
	v_mfma_f32_16x16x32_bf16 v[52:55], v[132:135], v[178:181], v[52:55]
	v_mfma_f32_16x16x32_bf16 v[150:153], v[124:127], v[206:209], v[150:153]
	v_mfma_f32_16x16x32_bf16 v[48:51], v[132:135], v[206:209], v[48:51]
	v_mfma_f32_16x16x32_bf16 v[92:95], v[124:127], v[214:217], v[92:95]
	v_mfma_f32_16x16x32_bf16 v[68:71], v[132:135], v[214:217], v[68:71]
	s_barrier
; #define PG8_STAGE(bufoff, gbase, voff) do { _Pragma("unroll") for (int _i = 0; _i < 2; ++_i) \
;         __builtin_amdgcn_global_load_lds((const unsigned*)((const char*)(gbase) + (voff)[_i]), (PG8_LAS unsigned*)(lds + (bufoff) + ldsw + _i * 8192), 16, 0, 0); } while (0)
; #define PG8_LDA(dst, b, h) do { _Pragma("unroll") for (int m = 0; m < 4; ++m) _Pragma("unroll") for (int k = 0; k < 2; ++k) dst[m][k] = *(const PG8_LAS bf16x8*)(lds + PG8_SA(b, h) + aoff + m * 2048 + k * 1024); } while (0)
; #define PG8_MMA(ai, bj, At, Bt) do { __builtin_amdgcn_s_setprio(1); _Pragma("unroll") for (int m = 0; m < 4; ++m) _Pragma("unroll") for (int n = 0; n < 2; ++n) _Pragma("unroll") for (int k = 0; k < 2; ++k) \
;         acc[ai][bj][m][n] = __builtin_amdgcn_mfma_f32_16x16x32_bf16(Bt[n][k], At[m][k], acc[ai][bj][m][n], 0, 0, 0); __builtin_amdgcn_s_setprio(0); } while (0)
; #define PG8_WAIT_V(n) asm volatile("s_waitcnt vmcnt(" #n ")" ::: "memory")
; #define PG8_WAIT_L(n) asm volatile("s_waitcnt lgkmcnt(" #n ")" ::: "memory")
; #define PG8_BAR __builtin_amdgcn_s_barrier()
; #define PG8_SCHED __builtin_amdgcn_sched_barrier(0)
;     ...
;             PG8_WAIT_V(8); PG8_WAIT_L(0); PG8_BAR; PG8_MMA(0, 0, At, B0); PG8_MMA(0, 1, At, B1); PG8_BAR; PG8_SCHED;
;             PG8_LDA(At, 1, 1); PG8_STAGE(PG8_SB(1, 0), b3, voffB); PG8_STAGE(PG8_SB(1, 1), b3 + hstep, voffB); PG8_STAGE(PG8_SA(1, 0), a3, voffA);
;             PG8_WAIT_V(8); PG8_WAIT_L(0); PG8_BAR; PG8_MMA(1, 0, At, B0); PG8_MMA(1, 1, At, B1); PG8_BAR; PG8_SCHED;
;     ...
;         if constexpr (ALIGN_EPI) { if (wr == 0) PG8_BAR; }
	s_setprio 0
	s_add_i32 s12, s48, s0
	v_lshl_add_u64 v[136:137], v[198:199], 0, s[66:67]
	s_mov_b32 m0, s12
	ds_read_b128 v[166:169], v222 offset:49152
	ds_read_b128 v[170:173], v222 offset:50176
	ds_read_b128 v[174:177], v222 offset:51200
	ds_read_b128 v[178:181], v222 offset:52224
	ds_read_b128 v[194:197], v222 offset:53248
	ds_read_b128 v[206:209], v222 offset:54272
	ds_read_b128 v[210:213], v222 offset:55296
	ds_read_b128 v[214:217], v222 offset:56320
	global_load_lds_dwordx4 v[136:137], off
	s_add_i32 m0, s12, 0x2000
	s_add_u32 s10, s10, 0x80080
	v_lshl_add_u64 v[136:137], v[218:219], 0, s[66:67]
	s_addc_u32 s11, s11, 0
	s_add_i32 s12, s49, s0
	global_load_lds_dwordx4 v[136:137], off
	v_lshl_add_u64 v[136:137], s[10:11], 0, v[186:187]
	s_mov_b32 m0, s12
	s_nop 0
	global_load_lds_dwordx4 v[136:137], off
	v_lshl_add_u64 v[136:137], s[10:11], 0, v[182:183]
	s_add_i32 m0, s12, 0x2000
	s_nop 0
	global_load_lds_dwordx4 v[136:137], off
	v_lshl_add_u64 v[136:137], v[224:225], 0, s[66:67]
	s_mov_b32 m0, s42
	s_nop 0
	global_load_lds_dwordx4 v[136:137], off
	v_lshl_add_u64 v[136:137], v[232:233], 0, s[66:67]
	s_mov_b32 m0, s55
	s_nop 0
	global_load_lds_dwordx4 v[136:137], off
	s_waitcnt vmcnt(8)
	s_waitcnt lgkmcnt(0)
	s_setprio 1
	s_barrier
	v_mfma_f32_16x16x32_bf16 v[146:149], v[104:107], v[166:169], v[146:149]
	v_mfma_f32_16x16x32_bf16 v[44:47], v[112:115], v[166:169], v[44:47]
	v_mfma_f32_16x16x32_bf16 v[142:145], v[104:107], v[174:177], v[142:145]
	v_mfma_f32_16x16x32_bf16 v[40:43], v[112:115], v[174:177], v[40:43]
	v_mfma_f32_16x16x32_bf16 v[136:139], v[104:107], v[194:197], v[138:141]
	v_mfma_f32_16x16x32_bf16 v[36:39], v[112:115], v[194:197], v[36:39]
	v_mfma_f32_16x16x32_bf16 v[80:83], v[104:107], v[210:213], v[80:83]
	v_mfma_f32_16x16x32_bf16 v[20:23], v[112:115], v[210:213], v[20:23]
	v_mfma_f32_16x16x32_bf16 v[146:149], v[108:111], v[170:173], v[146:149]
	v_mfma_f32_16x16x32_bf16 v[44:47], v[116:119], v[170:173], v[44:47]
	v_mfma_f32_16x16x32_bf16 v[142:145], v[108:111], v[178:181], v[142:145]
	v_mfma_f32_16x16x32_bf16 v[40:43], v[116:119], v[178:181], v[40:43]
	v_mfma_f32_16x16x32_bf16 v[138:141], v[108:111], v[206:209], v[136:139]
	v_mfma_f32_16x16x32_bf16 v[36:39], v[116:119], v[206:209], v[36:39]
	v_mfma_f32_16x16x32_bf16 v[80:83], v[108:111], v[214:217], v[80:83]
	v_mfma_f32_16x16x32_bf16 v[20:23], v[116:119], v[214:217], v[20:23]
	s_setprio 0
	s_setprio 1
	v_mfma_f32_16x16x32_bf16 v[100:103], v[120:123], v[166:169], v[100:103]
	v_mfma_f32_16x16x32_bf16 v[32:35], v[128:131], v[166:169], v[32:35]
	v_mfma_f32_16x16x32_bf16 v[88:91], v[120:123], v[174:177], v[88:91]
	v_mfma_f32_16x16x32_bf16 v[28:31], v[128:131], v[174:177], v[28:31]
	v_mfma_f32_16x16x32_bf16 v[84:87], v[120:123], v[194:197], v[84:87]
	v_mfma_f32_16x16x32_bf16 v[24:27], v[128:131], v[194:197], v[24:27]
	v_mfma_f32_16x16x32_bf16 v[16:19], v[120:123], v[210:213], v[16:19]
	v_mfma_f32_16x16x32_bf16 v[12:15], v[128:131], v[210:213], v[12:15]
	v_mfma_f32_16x16x32_bf16 v[102:105], v[124:127], v[170:173], v[100:103]
	v_mfma_f32_16x16x32_bf16 v[32:35], v[132:135], v[170:173], v[32:35]
	v_mfma_f32_16x16x32_bf16 v[88:91], v[124:127], v[178:181], v[88:91]
	v_mfma_f32_16x16x32_bf16 v[28:31], v[132:135], v[178:181], v[28:31]
	v_mfma_f32_16x16x32_bf16 v[84:87], v[124:127], v[206:209], v[84:87]
	v_mfma_f32_16x16x32_bf16 v[24:27], v[132:135], v[206:209], v[24:27]
	v_mfma_f32_16x16x32_bf16 v[16:19], v[124:127], v[214:217], v[16:19]
	v_mfma_f32_16x16x32_bf16 v[12:15], v[132:135], v[214:217], v[12:15]
	s_barrier
	s_setprio 0
	s_add_i32 s97, s97, 2
	s_add_u32 s8, s8, 0x100
	s_addc_u32 s9, s9, 0
	s_add_u32 s83, s83, 0x100
	s_addc_u32 s89, s89, 0
	s_cmp_gt_u32 s97, 29
	s_cbranch_scc0 .LBB0_1086
	s_and_b64 vcc, exec, s[70:71]
	s_cbranch_vccz .LBB0_1089
	s_barrier

;     __device__ __forceinline__ bool next(int i, Unit& u) const { if (i >= n) return false; u.pm = pm; u.pn = pn0 + i; return true; }
;     __device__ __forceinline__ bool next(int i, Unit& u) const { if (i) return false; u.pm = pm; u.pn = pn; return true; }
; #define PG8_STAGE(bufoff, gbase, voff) do { _Pragma("unroll") for (int _i = 0; _i < 2; ++_i) \
;         __builtin_amdgcn_global_load_lds((const unsigned*)((const char*)(gbase) + (voff)[_i]), (PG8_LAS unsigned*)(lds + (bufoff) + ldsw + _i * 8192), 16, 0, 0); } while (0)
; #define PG8_LDA(dst, b, h) do { _Pragma("unroll") for (int m = 0; m < 4; ++m) _Pragma("unroll") for (int k = 0; k < 2; ++k) dst[m][k] = *(const PG8_LAS bf16x8*)(lds + PG8_SA(b, h) + aoff + m * 2048 + k * 1024); } while (0)
; #define PG8_LDB(dst, b, h) do { _Pragma("unroll") for (int n = 0; n < 2; ++n) _Pragma("unroll") for (int k = 0; k < 2; ++k) dst[n][k] = *(const PG8_LAS bf16x8*)(lds + PG8_SB(b, h) + boff + n * 2048 + k * 1024); } while (0)
; #define PG8_WAIT_V(n) asm volatile("s_waitcnt vmcnt(" #n ")" ::: "memory")
; #define PG8_BAR __builtin_amdgcn_s_barrier()
;     ...
;         const bool has_next = S.next(ui + 1, nxt);
;         const char* nA = has_next ? (const char*)g.A + (size_t)nxt.pm * tstep : cA; const char* nB = has_next ? (const char*)g.Bt + (size_t)nxt.pn * tstep : cB;
;         for (int t = 0; t < nt; t += 2) {
;             const bool last = (t == nt - 2);
;             const char* a1 = cA + (size_t)(t + 1) * kstep;
;             const char* a2 = last ? nA : cA + (size_t)(t + 2) * kstep; const char* b2 = last ? nB : cB + (size_t)(t + 2) * kstep;
;             const char* a3 = a2 + kstep; const char* b3 = b2 + kstep;
;             if (last && has_next) S.a_ready(nxt);
;             if (t == 0) E.pre_issue(pre, cur, tid, ui); else if (t == 2) E.pre_finish(pre, tid, ui);
;             if constexpr (SP2) {
;             PG8_LDB(B0, 0, 0); PG8_LDB(B1, 0, 1); PG8_SCHED; PG8_LDA(At, 0, 0); PG8_STAGE(PG8_SA(1, 1), a1 + hstep, voffA);
;             PG8_WAIT_V(8); PG8_WAIT_L(0); PG8_BAR; PG8_MMA(0, 0, At, B0); PG8_MMA(0, 1, At, B1); PG8_BAR; PG8_SCHED;
;     ...
;         for (int a = 0; a < 2; ++a)
; #pragma unroll
;             for (int b = 0; b < 2; ++b)
; #pragma unroll
;                 for (int m = 0; m < 4; ++m)
; #pragma unroll
;                     for (int n = 0; n < 2; ++n) acc[a][b][m][n] = (f32x4){0.f, 0.f, 0.f, 0.f};
.LBB0_1211:
	s_add_u32 s77, s62, 0x100
	v_mov_b32_e32 v4, 0
	s_addc_u32 s78, s63, 0
	s_mov_b32 s79, -2
	v_mov_b32_e32 v5, v4
	v_mov_b32_e32 v6, v4
	v_mov_b32_e32 v7, v4
	v_mov_b32_e32 v8, v4
	v_mov_b32_e32 v9, v4
	v_mov_b32_e32 v10, v4
	v_mov_b32_e32 v11, v4
	v_mov_b32_e32 v20, v4
	v_mov_b32_e32 v21, v4
	v_mov_b32_e32 v22, v4
	v_mov_b32_e32 v23, v4
	s_waitcnt vmcnt(0)
	v_mov_b32_e32 v24, v4
	v_mov_b32_e32 v25, v4
	v_mov_b32_e32 v26, v4
	v_mov_b32_e32 v27, v4
	v_mov_b32_e32 v36, v4
	v_mov_b32_e32 v37, v4
	v_mov_b32_e32 v38, v4
	v_mov_b32_e32 v39, v4
	v_mov_b32_e32 v40, v4
	v_mov_b32_e32 v41, v4
	v_mov_b32_e32 v42, v4
	v_mov_b32_e32 v43, v4
	v_mov_b32_e32 v52, v4
	v_mov_b32_e32 v53, v4
	v_mov_b32_e32 v54, v4
	v_mov_b32_e32 v55, v4
	v_mov_b32_e32 v56, v4
	v_mov_b32_e32 v57, v4
	v_mov_b32_e32 v58, v4
	v_mov_b32_e32 v59, v4
	v_mov_b32_e32 v12, v4
	v_mov_b32_e32 v13, v4
	v_mov_b32_e32 v14, v4
	v_mov_b32_e32 v15, v4
	v_mov_b32_e32 v16, v4
	v_mov_b32_e32 v17, v4
	v_mov_b32_e32 v18, v4
	v_mov_b32_e32 v19, v4
	v_mov_b32_e32 v28, v4
	v_mov_b32_e32 v29, v4
	v_mov_b32_e32 v30, v4
	v_mov_b32_e32 v31, v4
	v_mov_b32_e32 v32, v4
	v_mov_b32_e32 v33, v4
	v_mov_b32_e32 v34, v4
	v_mov_b32_e32 v35, v4
	v_mov_b32_e32 v44, v4
	v_mov_b32_e32 v45, v4
	v_mov_b32_e32 v46, v4
	v_mov_b32_e32 v47, v4
	v_mov_b32_e32 v48, v4
	v_mov_b32_e32 v49, v4
	v_mov_b32_e32 v50, v4
	v_mov_b32_e32 v51, v4
	v_mov_b32_e32 v60, v4
	v_mov_b32_e32 v61, v4
	v_mov_b32_e32 v62, v4
	v_mov_b32_e32 v63, v4
	v_mov_b32_e32 v64, v4
	v_mov_b32_e32 v65, v4
	v_mov_b32_e32 v66, v4
	v_mov_b32_e32 v67, v4
	v_mov_b32_e32 v68, v4
	v_mov_b32_e32 v69, v4
	v_mov_b32_e32 v70, v4
	v_mov_b32_e32 v71, v4
	v_mov_b32_e32 v72, v4
	v_mov_b32_e32 v73, v4
	v_mov_b32_e32 v74, v4
	v_mov_b32_e32 v75, v4
	v_mov_b32_e32 v84, v4
	v_mov_b32_e32 v85, v4
	v_mov_b32_e32 v86, v4
	v_mov_b32_e32 v87, v4
	v_mov_b32_e32 v88, v4
	v_mov_b32_e32 v89, v4
	v_mov_b32_e32 v90, v4
	v_mov_b32_e32 v91, v4
	v_mov_b32_e32 v100, v4
	v_mov_b32_e32 v101, v4
	v_mov_b32_e32 v102, v4
	v_mov_b32_e32 v103, v4
	v_mov_b32_e32 v104, v4
	v_mov_b32_e32 v105, v4
	v_mov_b32_e32 v106, v4
	v_mov_b32_e32 v107, v4
	v_mov_b32_e32 v124, v4
	v_mov_b32_e32 v125, v4
	v_mov_b32_e32 v126, v4
	v_mov_b32_e32 v127, v4
	v_mov_b32_e32 v132, v4
	v_mov_b32_e32 v133, v4
	v_mov_b32_e32 v134, v4
	v_mov_b32_e32 v135, v4
	v_mov_b32_e32 v76, v4
	v_mov_b32_e32 v77, v4
	v_mov_b32_e32 v78, v4
	v_mov_b32_e32 v79, v4
	v_mov_b32_e32 v80, v4
	v_mov_b32_e32 v81, v4
	v_mov_b32_e32 v82, v4
	v_mov_b32_e32 v83, v4
	v_mov_b32_e32 v92, v4
	v_mov_b32_e32 v93, v4
	v_mov_b32_e32 v94, v4
	v_mov_b32_e32 v95, v4
	v_mov_b32_e32 v96, v4
	v_mov_b32_e32 v97, v4
	v_mov_b32_e32 v98, v4
	v_mov_b32_e32 v99, v4
	v_mov_b32_e32 v116, v4
	v_mov_b32_e32 v117, v4
	v_mov_b32_e32 v118, v4
	v_mov_b32_e32 v119, v4
	v_mov_b32_e32 v120, v4
	v_mov_b32_e32 v121, v4
	v_mov_b32_e32 v122, v4
	v_mov_b32_e32 v123, v4
	v_mov_b32_e32 v140, v4
	v_mov_b32_e32 v141, v4
	v_mov_b32_e32 v142, v4
	v_mov_b32_e32 v143, v4
	v_mov_b32_e32 v144, v4
	v_mov_b32_e32 v145, v4
	v_mov_b32_e32 v146, v4
	v_mov_b32_e32 v147, v4
	v_add_u32_e32 v251, 0x10000, v233
.LBB0_1212:
	s_add_u32 s62, s60, 0x100
	s_addc_u32 s63, s61, 0
	s_add_i32 s48, 0, 0x10000
	s_cmpk_eq_i32 s79, 0x54
	s_cselect_b32 s71, s9, s63
	s_cselect_b32 s70, s8, s62
	s_cselect_b32 s69, s25, s78
	s_cselect_b32 s68, s24, s77
	s_add_i32 s81, 0, 0x14000
	ds_read_b128 v[108:111], v251
	ds_read_b128 v[112:115], v251 offset:1024
	ds_read_b128 v[128:131], v251 offset:2048
	ds_read_b128 v[136:139], v251 offset:3072
	ds_read_b128 v[148:151], v251 offset:16384
	ds_read_b128 v[152:155], v251 offset:17408
	ds_read_b128 v[156:159], v251 offset:18432
	ds_read_b128 v[160:163], v251 offset:19456
	v_lshl_add_u64 v[198:199], s[60:61], 0, v[196:197]
	s_add_i32 m0, s5, 0xc000
	ds_read_b128 v[164:167], v234
	ds_read_b128 v[168:171], v234 offset:1024
	ds_read_b128 v[172:175], v234 offset:2048
	ds_read_b128 v[176:179], v234 offset:3072
	ds_read_b128 v[180:183], v234 offset:4096
	ds_read_b128 v[184:187], v234 offset:5120
	ds_read_b128 v[206:209], v234 offset:6144
	ds_read_b128 v[210:213], v234 offset:7168
	global_load_lds_dwordx4 v[198:199], off
	v_lshl_add_u64 v[198:199], s[60:61], 0, v[194:195]
	s_add_i32 m0, s5, 0xe000
	s_nop 0
	global_load_lds_dwordx4 v[198:199], off
	s_waitcnt vmcnt(8)
	s_waitcnt lgkmcnt(0)
	s_setprio 1
	s_barrier
	v_mfma_f32_16x16x32_bf16 v[144:147], v[108:111], v[164:167], v[144:147]
	v_mfma_f32_16x16x32_bf16 v[140:143], v[128:131], v[164:167], v[140:143]
	v_mfma_f32_16x16x32_bf16 v[120:123], v[108:111], v[172:175], v[120:123]
	v_mfma_f32_16x16x32_bf16 v[116:119], v[128:131], v[172:175], v[116:119]
	v_mfma_f32_16x16x32_bf16 v[96:99], v[108:111], v[180:183], v[96:99]
	v_mfma_f32_16x16x32_bf16 v[92:95], v[128:131], v[180:183], v[92:95]
	v_mfma_f32_16x16x32_bf16 v[80:83], v[108:111], v[206:209], v[80:83]
	v_mfma_f32_16x16x32_bf16 v[76:79], v[128:131], v[206:209], v[76:79]
	v_mfma_f32_16x16x32_bf16 v[144:147], v[112:115], v[168:171], v[144:147]
	v_mfma_f32_16x16x32_bf16 v[140:143], v[136:139], v[168:171], v[140:143]
	v_mfma_f32_16x16x32_bf16 v[120:123], v[112:115], v[176:179], v[120:123]
	v_mfma_f32_16x16x32_bf16 v[116:119], v[136:139], v[176:179], v[116:119]
	v_mfma_f32_16x16x32_bf16 v[96:99], v[112:115], v[184:187], v[96:99]
	v_mfma_f32_16x16x32_bf16 v[92:95], v[136:139], v[184:187], v[92:95]
	v_mfma_f32_16x16x32_bf16 v[80:83], v[112:115], v[210:213], v[80:83]
	v_mfma_f32_16x16x32_bf16 v[76:79], v[136:139], v[210:213], v[76:79]
	s_setprio 0
	s_setprio 1
	v_mfma_f32_16x16x32_bf16 v[132:135], v[148:151], v[164:167], v[132:135]
	v_mfma_f32_16x16x32_bf16 v[124:127], v[156:159], v[164:167], v[124:127]
	v_mfma_f32_16x16x32_bf16 v[104:107], v[148:151], v[172:175], v[104:107]
	v_mfma_f32_16x16x32_bf16 v[100:103], v[156:159], v[172:175], v[100:103]
	v_mfma_f32_16x16x32_bf16 v[88:91], v[148:151], v[180:183], v[88:91]
	v_mfma_f32_16x16x32_bf16 v[84:87], v[156:159], v[180:183], v[84:87]
	v_mfma_f32_16x16x32_bf16 v[72:75], v[148:151], v[206:209], v[72:75]
	v_mfma_f32_16x16x32_bf16 v[68:71], v[156:159], v[206:209], v[68:71]
	v_mfma_f32_16x16x32_bf16 v[132:135], v[152:155], v[168:171], v[132:135]
	v_mfma_f32_16x16x32_bf16 v[124:127], v[160:163], v[168:171], v[124:127]
	v_mfma_f32_16x16x32_bf16 v[104:107], v[152:155], v[176:179], v[104:107]
	v_mfma_f32_16x16x32_bf16 v[100:103], v[160:163], v[176:179], v[100:103]
	v_mfma_f32_16x16x32_bf16 v[88:91], v[152:155], v[184:187], v[88:91]
	v_mfma_f32_16x16x32_bf16 v[84:87], v[160:163], v[184:187], v[84:87]
	v_mfma_f32_16x16x32_bf16 v[72:75], v[152:155], v[210:213], v[72:75]
	v_mfma_f32_16x16x32_bf16 v[68:71], v[160:163], v[210:213], v[68:71]
	s_barrier
; #define PG8_STAGE(bufoff, gbase, voff) do { _Pragma("unroll") for (int _i = 0; _i < 2; ++_i) \
;         __builtin_amdgcn_global_load_lds((const unsigned*)((const char*)(gbase) + (voff)[_i]), (PG8_LAS unsigned*)(lds + (bufoff) + ldsw + _i * 8192), 16, 0, 0); } while (0)
; #define PG8_LDA(dst, b, h) do { _Pragma("unroll") for (int m = 0; m < 4; ++m) _Pragma("unroll") for (int k = 0; k < 2; ++k) dst[m][k] = *(const PG8_LAS bf16x8*)(lds + PG8_SA(b, h) + aoff + m * 2048 + k * 1024); } while (0)
; #define PG8_LDB(dst, b, h) do { _Pragma("unroll") for (int n = 0; n < 2; ++n) _Pragma("unroll") for (int k = 0; k < 2; ++k) dst[n][k] = *(const PG8_LAS bf16x8*)(lds + PG8_SB(b, h) + boff + n * 2048 + k * 1024); } while (0)
; #define PG8_MMA(ai, bj, At, Bt) do { __builtin_amdgcn_s_setprio(1); _Pragma("unroll") for (int m = 0; m < 4; ++m) _Pragma("unroll") for (int n = 0; n < 2; ++n) _Pragma("unroll") for (int k = 0; k < 2; ++k) \
;         acc[ai][bj][m][n] = __builtin_amdgcn_mfma_f32_16x16x32_bf16(Bt[n][k], At[m][k], acc[ai][bj][m][n], 0, 0, 0); __builtin_amdgcn_s_setprio(0); } while (0)
; #define PG8_WAIT_V(n) asm volatile("s_waitcnt vmcnt(" #n ")" ::: "memory")
; #define PG8_WAIT_L(n) asm volatile("s_waitcnt lgkmcnt(" #n ")" ::: "memory")
; #define PG8_BAR __builtin_amdgcn_s_barrier()
; #define PG8_SCHED __builtin_amdgcn_sched_barrier(0)
;     ...
;             PG8_WAIT_V(8); PG8_WAIT_L(0); PG8_BAR; PG8_MMA(0, 0, At, B0); PG8_MMA(0, 1, At, B1); PG8_BAR; PG8_SCHED;
;             PG8_LDA(At, 0, 1); PG8_STAGE(PG8_SB(0, 0), b2, voffB); PG8_STAGE(PG8_SB(0, 1), b2 + hstep, voffB); PG8_STAGE(PG8_SA(0, 0), a2, voffA);
;             PG8_WAIT_V(8); PG8_WAIT_L(0); PG8_BAR; PG8_MMA(1, 0, At, B0); PG8_MMA(1, 1, At, B1); PG8_BAR; PG8_SCHED;
;             PG8_LDB(B0, 1, 0); PG8_LDB(B1, 1, 1); PG8_SCHED; PG8_LDA(At, 1, 0); PG8_STAGE(PG8_SA(0, 1), a2 + hstep, voffA);
;             PG8_WAIT_V(8); PG8_WAIT_L(0); PG8_BAR; PG8_MMA(0, 0, At, B0); PG8_MMA(0, 1, At, B1); PG8_BAR; PG8_SCHED;
	s_setprio 0
	s_add_i32 s48, s48, s4
	v_lshl_add_u64 v[198:199], s[68:69], 0, v[200:201]
	s_mov_b32 m0, s48
	ds_read_b128 v[164:167], v234 offset:16384
	ds_read_b128 v[168:171], v234 offset:17408
	ds_read_b128 v[172:175], v234 offset:18432
	ds_read_b128 v[176:179], v234 offset:19456
	ds_read_b128 v[180:183], v234 offset:20480
	ds_read_b128 v[184:187], v234 offset:21504
	ds_read_b128 v[206:209], v234 offset:22528
	ds_read_b128 v[210:213], v234 offset:23552
	global_load_lds_dwordx4 v[198:199], off
	s_add_i32 m0, s48, 0x2000
	s_add_u32 s48, s68, 0x160000
	v_lshl_add_u64 v[214:215], s[68:69], 0, v[188:189]
	s_addc_u32 s49, s69, 0
	s_add_i32 s60, s81, s4
	global_load_lds_dwordx4 v[214:215], off
	v_lshl_add_u64 v[216:217], s[48:49], 0, v[200:201]
	s_mov_b32 m0, s60
	v_lshl_add_u64 v[218:219], s[70:71], 0, v[190:191]
	global_load_lds_dwordx4 v[216:217], off
	v_lshl_add_u64 v[216:217], s[48:49], 0, v[188:189]
	s_add_i32 m0, s60, 0x2000
	s_nop 0
	global_load_lds_dwordx4 v[216:217], off
	v_lshl_add_u64 v[216:217], s[70:71], 0, v[192:193]
	s_mov_b32 m0, s5
	s_nop 0
	global_load_lds_dwordx4 v[216:217], off
	s_mov_b32 m0, s20
	s_nop 0
	global_load_lds_dwordx4 v[218:219], off
	s_waitcnt vmcnt(8)
	s_waitcnt lgkmcnt(0)
	s_setprio 1
	s_barrier
	v_mfma_f32_16x16x32_bf16 v[64:67], v[108:111], v[164:167], v[64:67]
	v_mfma_f32_16x16x32_bf16 v[60:63], v[128:131], v[164:167], v[60:63]
	v_mfma_f32_16x16x32_bf16 v[48:51], v[108:111], v[172:175], v[48:51]
	v_mfma_f32_16x16x32_bf16 v[44:47], v[128:131], v[172:175], v[44:47]
	v_mfma_f32_16x16x32_bf16 v[32:35], v[108:111], v[180:183], v[32:35]
	v_mfma_f32_16x16x32_bf16 v[28:31], v[128:131], v[180:183], v[28:31]
	v_mfma_f32_16x16x32_bf16 v[16:19], v[108:111], v[206:209], v[16:19]
	v_mfma_f32_16x16x32_bf16 v[12:15], v[128:131], v[206:209], v[12:15]
	v_mfma_f32_16x16x32_bf16 v[64:67], v[112:115], v[168:171], v[64:67]
	v_mfma_f32_16x16x32_bf16 v[60:63], v[136:139], v[168:171], v[60:63]
	v_mfma_f32_16x16x32_bf16 v[48:51], v[112:115], v[176:179], v[48:51]
	v_mfma_f32_16x16x32_bf16 v[44:47], v[136:139], v[176:179], v[44:47]
	v_mfma_f32_16x16x32_bf16 v[32:35], v[112:115], v[184:187], v[32:35]
	v_mfma_f32_16x16x32_bf16 v[28:31], v[136:139], v[184:187], v[28:31]
	v_mfma_f32_16x16x32_bf16 v[16:19], v[112:115], v[210:213], v[16:19]
	v_mfma_f32_16x16x32_bf16 v[12:15], v[136:139], v[210:213], v[12:15]
	s_setprio 0
	s_setprio 1
	v_mfma_f32_16x16x32_bf16 v[56:59], v[148:151], v[164:167], v[56:59]
	v_mfma_f32_16x16x32_bf16 v[52:55], v[156:159], v[164:167], v[52:55]
	v_mfma_f32_16x16x32_bf16 v[40:43], v[148:151], v[172:175], v[40:43]
	v_mfma_f32_16x16x32_bf16 v[36:39], v[156:159], v[172:175], v[36:39]
	v_mfma_f32_16x16x32_bf16 v[24:27], v[148:151], v[180:183], v[24:27]
	v_mfma_f32_16x16x32_bf16 v[20:23], v[156:159], v[180:183], v[20:23]
	v_mfma_f32_16x16x32_bf16 v[8:11], v[148:151], v[206:209], v[8:11]
	v_mfma_f32_16x16x32_bf16 v[4:7], v[156:159], v[206:209], v[4:7]
	v_mfma_f32_16x16x32_bf16 v[56:59], v[152:155], v[168:171], v[56:59]
	v_mfma_f32_16x16x32_bf16 v[52:55], v[160:163], v[168:171], v[52:55]
	v_mfma_f32_16x16x32_bf16 v[40:43], v[152:155], v[176:179], v[40:43]
	v_mfma_f32_16x16x32_bf16 v[36:39], v[160:163], v[176:179], v[36:39]
	v_mfma_f32_16x16x32_bf16 v[24:27], v[152:155], v[184:187], v[24:27]
	v_mfma_f32_16x16x32_bf16 v[20:23], v[160:163], v[184:187], v[20:23]
	v_mfma_f32_16x16x32_bf16 v[8:11], v[152:155], v[210:213], v[8:11]
	v_mfma_f32_16x16x32_bf16 v[4:7], v[160:163], v[210:213], v[4:7]
	s_barrier
	s_setprio 0
	s_add_i32 s60, 0, 0x18000
	s_add_i32 s61, 0, 0x1c000
	ds_read_b128 v[108:111], v251 offset:32768
	ds_read_b128 v[112:115], v251 offset:33792
	ds_read_b128 v[128:131], v251 offset:34816
	ds_read_b128 v[136:139], v251 offset:35840
	ds_read_b128 v[148:151], v251 offset:49152
	ds_read_b128 v[152:155], v251 offset:50176
	ds_read_b128 v[156:159], v251 offset:51200
	ds_read_b128 v[160:163], v251 offset:52224
	s_add_u32 s48, s70, 0x160000
	s_addc_u32 s49, s71, 0
	s_mov_b32 m0, s21
	v_lshl_add_u64 v[220:221], s[48:49], 0, v[192:193]
	ds_read_b128 v[164:167], v234 offset:32768
	ds_read_b128 v[168:171], v234 offset:33792
	ds_read_b128 v[172:175], v234 offset:34816
	ds_read_b128 v[176:179], v234 offset:35840
	ds_read_b128 v[180:183], v234 offset:36864
	ds_read_b128 v[184:187], v234 offset:37888
	ds_read_b128 v[206:209], v234 offset:38912
	ds_read_b128 v[210:213], v234 offset:39936
	global_load_lds_dwordx4 v[220:221], off
	v_lshl_add_u64 v[220:221], s[48:49], 0, v[190:191]
	s_mov_b32 m0, s23
	s_nop 0
	global_load_lds_dwordx4 v[220:221], off
	s_waitcnt vmcnt(8)
	s_waitcnt lgkmcnt(0)
	s_setprio 1
	s_barrier
; #define PG8_STAGE(bufoff, gbase, voff) do { _Pragma("unroll") for (int _i = 0; _i < 2; ++_i) \
;         __builtin_amdgcn_global_load_lds((const unsigned*)((const char*)(gbase) + (voff)[_i]), (PG8_LAS unsigned*)(lds + (bufoff) + ldsw + _i * 8192), 16, 0, 0); } while (0)
; #define PG8_LDA(dst, b, h) do { _Pragma("unroll") for (int m = 0; m < 4; ++m) _Pragma("unroll") for (int k = 0; k < 2; ++k) dst[m][k] = *(const PG8_LAS bf16x8*)(lds + PG8_SA(b, h) + aoff + m * 2048 + k * 1024); } while (0)
; #define PG8_MMA(ai, bj, At, Bt) do { __builtin_amdgcn_s_setprio(1); _Pragma("unroll") for (int m = 0; m < 4; ++m) _Pragma("unroll") for (int n = 0; n < 2; ++n) _Pragma("unroll") for (int k = 0; k < 2; ++k) \
;         acc[ai][bj][m][n] = __builtin_amdgcn_mfma_f32_16x16x32_bf16(Bt[n][k], At[m][k], acc[ai][bj][m][n], 0, 0, 0); __builtin_amdgcn_s_setprio(0); } while (0)
; #define PG8_WAIT_V(n) asm volatile("s_waitcnt vmcnt(" #n ")" ::: "memory")
; #define PG8_WAIT_L(n) asm volatile("s_waitcnt lgkmcnt(" #n ")" ::: "memory")
; #define PG8_BAR __builtin_amdgcn_s_barrier()
; #define PG8_SCHED __builtin_amdgcn_sched_barrier(0)
;     ...
;             PG8_WAIT_V(8); PG8_WAIT_L(0); PG8_BAR; PG8_MMA(0, 0, At, B0); PG8_MMA(0, 1, At, B1); PG8_BAR; PG8_SCHED;
;             PG8_LDA(At, 1, 1); PG8_STAGE(PG8_SB(1, 0), b3, voffB); PG8_STAGE(PG8_SB(1, 1), b3 + hstep, voffB); PG8_STAGE(PG8_SA(1, 0), a3, voffA);
;             PG8_WAIT_V(8); PG8_WAIT_L(0); PG8_BAR; PG8_MMA(1, 0, At, B0); PG8_MMA(1, 1, At, B1); PG8_BAR; PG8_SCHED;
;     ...
;         if constexpr (ALIGN_EPI) { if (wr == 0) PG8_BAR; }
	v_mfma_f32_16x16x32_bf16 v[144:147], v[108:111], v[164:167], v[144:147]
	v_mfma_f32_16x16x32_bf16 v[140:143], v[128:131], v[164:167], v[140:143]
	v_mfma_f32_16x16x32_bf16 v[120:123], v[108:111], v[172:175], v[120:123]
	v_mfma_f32_16x16x32_bf16 v[116:119], v[128:131], v[172:175], v[116:119]
	v_mfma_f32_16x16x32_bf16 v[96:99], v[108:111], v[180:183], v[96:99]
	v_mfma_f32_16x16x32_bf16 v[92:95], v[128:131], v[180:183], v[92:95]
	v_mfma_f32_16x16x32_bf16 v[80:83], v[108:111], v[206:209], v[80:83]
	v_mfma_f32_16x16x32_bf16 v[76:79], v[128:131], v[206:209], v[76:79]
	v_mfma_f32_16x16x32_bf16 v[144:147], v[112:115], v[168:171], v[144:147]
	v_mfma_f32_16x16x32_bf16 v[140:143], v[136:139], v[168:171], v[140:143]
	v_mfma_f32_16x16x32_bf16 v[120:123], v[112:115], v[176:179], v[120:123]
	v_mfma_f32_16x16x32_bf16 v[116:119], v[136:139], v[176:179], v[116:119]
	v_mfma_f32_16x16x32_bf16 v[96:99], v[112:115], v[184:187], v[96:99]
	v_mfma_f32_16x16x32_bf16 v[92:95], v[136:139], v[184:187], v[92:95]
	v_mfma_f32_16x16x32_bf16 v[80:83], v[112:115], v[210:213], v[80:83]
	v_mfma_f32_16x16x32_bf16 v[76:79], v[136:139], v[210:213], v[76:79]
	s_setprio 0
	s_setprio 1
	v_mfma_f32_16x16x32_bf16 v[132:135], v[148:151], v[164:167], v[132:135]
	v_mfma_f32_16x16x32_bf16 v[124:127], v[156:159], v[164:167], v[124:127]
	v_mfma_f32_16x16x32_bf16 v[104:107], v[148:151], v[172:175], v[104:107]
	v_mfma_f32_16x16x32_bf16 v[100:103], v[156:159], v[172:175], v[100:103]
	v_mfma_f32_16x16x32_bf16 v[88:91], v[148:151], v[180:183], v[88:91]
	v_mfma_f32_16x16x32_bf16 v[84:87], v[156:159], v[180:183], v[84:87]
	v_mfma_f32_16x16x32_bf16 v[72:75], v[148:151], v[206:209], v[72:75]
	v_mfma_f32_16x16x32_bf16 v[68:71], v[156:159], v[206:209], v[68:71]
	v_mfma_f32_16x16x32_bf16 v[132:135], v[152:155], v[168:171], v[132:135]
	v_mfma_f32_16x16x32_bf16 v[124:127], v[160:163], v[168:171], v[124:127]
	v_mfma_f32_16x16x32_bf16 v[104:107], v[152:155], v[176:179], v[104:107]
	v_mfma_f32_16x16x32_bf16 v[100:103], v[160:163], v[176:179], v[100:103]
	v_mfma_f32_16x16x32_bf16 v[88:91], v[152:155], v[184:187], v[88:91]
	v_mfma_f32_16x16x32_bf16 v[84:87], v[160:163], v[184:187], v[84:87]
	v_mfma_f32_16x16x32_bf16 v[72:75], v[152:155], v[210:213], v[72:75]
	v_mfma_f32_16x16x32_bf16 v[68:71], v[160:163], v[210:213], v[68:71]
	s_barrier
	s_setprio 0
	s_add_i32 s48, s60, s4
	v_lshl_add_u64 v[198:199], v[198:199], 0, s[66:67]
	s_mov_b32 m0, s48
	ds_read_b128 v[164:167], v234 offset:49152
	ds_read_b128 v[168:171], v234 offset:50176
	ds_read_b128 v[172:175], v234 offset:51200
	ds_read_b128 v[176:179], v234 offset:52224
	ds_read_b128 v[180:183], v234 offset:53248
	ds_read_b128 v[184:187], v234 offset:54272
	ds_read_b128 v[206:209], v234 offset:55296
	ds_read_b128 v[210:213], v234 offset:56320
	global_load_lds_dwordx4 v[198:199], off
	s_add_i32 m0, s48, 0x2000
	s_add_u32 s48, s68, 0x160080
	v_lshl_add_u64 v[198:199], v[214:215], 0, s[66:67]
	s_addc_u32 s49, s69, 0
	s_add_i32 s60, s61, s4
	global_load_lds_dwordx4 v[198:199], off
	v_lshl_add_u64 v[198:199], s[48:49], 0, v[200:201]
	s_mov_b32 m0, s60
	s_nop 0
	global_load_lds_dwordx4 v[198:199], off
	v_lshl_add_u64 v[198:199], s[48:49], 0, v[188:189]
	s_add_i32 m0, s60, 0x2000
	s_nop 0
	global_load_lds_dwordx4 v[198:199], off
	v_lshl_add_u64 v[198:199], v[216:217], 0, s[66:67]
	s_mov_b32 m0, s54
	s_nop 0
	global_load_lds_dwordx4 v[198:199], off
	v_lshl_add_u64 v[198:199], v[218:219], 0, s[66:67]
	s_mov_b32 m0, s55
	s_nop 0
	global_load_lds_dwordx4 v[198:199], off
	s_waitcnt vmcnt(8)
	s_waitcnt lgkmcnt(0)
	s_setprio 1
	s_barrier
	v_mfma_f32_16x16x32_bf16 v[64:67], v[108:111], v[164:167], v[64:67]
	v_mfma_f32_16x16x32_bf16 v[60:63], v[128:131], v[164:167], v[60:63]
	v_mfma_f32_16x16x32_bf16 v[48:51], v[108:111], v[172:175], v[48:51]
	v_mfma_f32_16x16x32_bf16 v[44:47], v[128:131], v[172:175], v[44:47]
	v_mfma_f32_16x16x32_bf16 v[32:35], v[108:111], v[180:183], v[32:35]
	v_mfma_f32_16x16x32_bf16 v[28:31], v[128:131], v[180:183], v[28:31]
	v_mfma_f32_16x16x32_bf16 v[16:19], v[108:111], v[206:209], v[16:19]
	v_mfma_f32_16x16x32_bf16 v[12:15], v[128:131], v[206:209], v[12:15]
	v_mfma_f32_16x16x32_bf16 v[64:67], v[112:115], v[168:171], v[64:67]
	v_mfma_f32_16x16x32_bf16 v[60:63], v[136:139], v[168:171], v[60:63]
	v_mfma_f32_16x16x32_bf16 v[48:51], v[112:115], v[176:179], v[48:51]
	v_mfma_f32_16x16x32_bf16 v[44:47], v[136:139], v[176:179], v[44:47]
	v_mfma_f32_16x16x32_bf16 v[32:35], v[112:115], v[184:187], v[32:35]
	v_mfma_f32_16x16x32_bf16 v[28:31], v[136:139], v[184:187], v[28:31]
	v_mfma_f32_16x16x32_bf16 v[16:19], v[112:115], v[210:213], v[16:19]
	v_mfma_f32_16x16x32_bf16 v[12:15], v[136:139], v[210:213], v[12:15]
	s_setprio 0
	s_setprio 1
	v_mfma_f32_16x16x32_bf16 v[56:59], v[148:151], v[164:167], v[56:59]
	v_mfma_f32_16x16x32_bf16 v[52:55], v[156:159], v[164:167], v[52:55]
	v_mfma_f32_16x16x32_bf16 v[40:43], v[148:151], v[172:175], v[40:43]
	v_mfma_f32_16x16x32_bf16 v[36:39], v[156:159], v[172:175], v[36:39]
	v_mfma_f32_16x16x32_bf16 v[24:27], v[148:151], v[180:183], v[24:27]
	v_mfma_f32_16x16x32_bf16 v[20:23], v[156:159], v[180:183], v[20:23]
	v_mfma_f32_16x16x32_bf16 v[8:11], v[148:151], v[206:209], v[8:11]
	v_mfma_f32_16x16x32_bf16 v[4:7], v[156:159], v[206:209], v[4:7]
	v_mfma_f32_16x16x32_bf16 v[56:59], v[152:155], v[168:171], v[56:59]
	v_mfma_f32_16x16x32_bf16 v[52:55], v[160:163], v[168:171], v[52:55]
	v_mfma_f32_16x16x32_bf16 v[40:43], v[152:155], v[176:179], v[40:43]
	v_mfma_f32_16x16x32_bf16 v[36:39], v[160:163], v[176:179], v[36:39]
	v_mfma_f32_16x16x32_bf16 v[24:27], v[152:155], v[184:187], v[24:27]
	v_mfma_f32_16x16x32_bf16 v[20:23], v[160:163], v[184:187], v[20:23]
	v_mfma_f32_16x16x32_bf16 v[8:11], v[152:155], v[210:213], v[8:11]
	v_mfma_f32_16x16x32_bf16 v[4:7], v[160:163], v[210:213], v[4:7]
	s_barrier
	s_setprio 0
	s_add_i32 s79, s79, 2
	s_add_u32 s77, s77, 0x100
	s_addc_u32 s78, s78, 0
	s_cmpk_gt_u32 s79, 0x55
	s_mov_b64 s[60:61], s[62:63]
	s_cbranch_scc0 .LBB0_1212
	s_and_b64 vcc, exec, s[12:13]
	s_cbranch_vccz .LBB0_1215
	s_barrier

;     __device__ __forceinline__ bool next(int i, Unit& u) const { if (i >= n) return false; u.pm = pm; u.pn = pn0 + i; return true; }
;     __device__ __forceinline__ bool next(int i, Unit& u) const { if (i) return false; u.pm = pm; u.pn = pn; return true; }
; #define PG8_STAGE(bufoff, gbase, voff) do { _Pragma("unroll") for (int _i = 0; _i < 2; ++_i) \
;         __builtin_amdgcn_global_load_lds((const unsigned*)((const char*)(gbase) + (voff)[_i]), (PG8_LAS unsigned*)(lds + (bufoff) + ldsw + _i * 8192), 16, 0, 0); } while (0)
; #define PG8_LDA(dst, b, h) do { _Pragma("unroll") for (int m = 0; m < 4; ++m) _Pragma("unroll") for (int k = 0; k < 2; ++k) dst[m][k] = *(const PG8_LAS bf16x8*)(lds + PG8_SA(b, h) + aoff + m * 2048 + k * 1024); } while (0)
; #define PG8_LDB(dst, b, h) do { _Pragma("unroll") for (int n = 0; n < 2; ++n) _Pragma("unroll") for (int k = 0; k < 2; ++k) dst[n][k] = *(const PG8_LAS bf16x8*)(lds + PG8_SB(b, h) + boff + n * 2048 + k * 1024); } while (0)
; #define PG8_WAIT_V(n) asm volatile("s_waitcnt vmcnt(" #n ")" ::: "memory")
; #define PG8_BAR __builtin_amdgcn_s_barrier()
;     ...
;         const bool has_next = S.next(ui + 1, nxt);
;         const char* nA = has_next ? (const char*)g.A + (size_t)nxt.pm * tstep : cA; const char* nB = has_next ? (const char*)g.Bt + (size_t)nxt.pn * tstep : cB;
;         for (int t = 0; t < nt; t += 2) {
;             const bool last = (t == nt - 2);
;             const char* a1 = cA + (size_t)(t + 1) * kstep;
;             const char* a2 = last ? nA : cA + (size_t)(t + 2) * kstep; const char* b2 = last ? nB : cB + (size_t)(t + 2) * kstep;
;             const char* a3 = a2 + kstep; const char* b3 = b2 + kstep;
;             if (last && has_next) S.a_ready(nxt);
;             if (t == 0) E.pre_issue(pre, cur, tid, ui); else if (t == 2) E.pre_finish(pre, tid, ui);
;             if constexpr (SP2) {
;             PG8_LDB(B0, 0, 0); PG8_LDB(B1, 0, 1); PG8_SCHED; PG8_LDA(At, 0, 0); PG8_STAGE(PG8_SA(1, 1), a1 + hstep, voffA);
;             PG8_WAIT_V(8); PG8_WAIT_L(0); PG8_BAR; PG8_MMA(0, 0, At, B0); PG8_MMA(0, 1, At, B1); PG8_BAR; PG8_SCHED;
;     ...
;         for (int a = 0; a < 2; ++a)
; #pragma unroll
;             for (int b = 0; b < 2; ++b)
; #pragma unroll
;                 for (int m = 0; m < 4; ++m)
; #pragma unroll
;                     for (int n = 0; n < 2; ++n) acc[a][b][m][n] = (f32x4){0.f, 0.f, 0.f, 0.f};
.LBB0_1253:
	s_add_u32 s75, s60, 0x100
	v_mov_b32_e32 v4, 0
	s_addc_u32 s76, s61, 0
	s_mov_b32 s77, -2
	v_mov_b32_e32 v5, v4
	v_mov_b32_e32 v6, v4
	v_mov_b32_e32 v7, v4
	v_mov_b32_e32 v8, v4
	v_mov_b32_e32 v9, v4
	v_mov_b32_e32 v10, v4
	v_mov_b32_e32 v11, v4
	v_mov_b32_e32 v20, v4
	v_mov_b32_e32 v21, v4
	v_mov_b32_e32 v22, v4
	v_mov_b32_e32 v23, v4
	s_waitcnt vmcnt(0)
	v_mov_b32_e32 v24, v4
	v_mov_b32_e32 v25, v4
	v_mov_b32_e32 v26, v4
	v_mov_b32_e32 v27, v4
	v_mov_b32_e32 v36, v4
	v_mov_b32_e32 v37, v4
	v_mov_b32_e32 v38, v4
	v_mov_b32_e32 v39, v4
	v_mov_b32_e32 v40, v4
	v_mov_b32_e32 v41, v4
	v_mov_b32_e32 v42, v4
	v_mov_b32_e32 v43, v4
	v_mov_b32_e32 v52, v4
	v_mov_b32_e32 v53, v4
	v_mov_b32_e32 v54, v4
	v_mov_b32_e32 v55, v4
	v_mov_b32_e32 v56, v4
	v_mov_b32_e32 v57, v4
	v_mov_b32_e32 v58, v4
	v_mov_b32_e32 v59, v4
	v_mov_b32_e32 v12, v4
	v_mov_b32_e32 v13, v4
	v_mov_b32_e32 v14, v4
	v_mov_b32_e32 v15, v4
	v_mov_b32_e32 v16, v4
	v_mov_b32_e32 v17, v4
	v_mov_b32_e32 v18, v4
	v_mov_b32_e32 v19, v4
	v_mov_b32_e32 v28, v4
	v_mov_b32_e32 v29, v4
	v_mov_b32_e32 v30, v4
	v_mov_b32_e32 v31, v4
	v_mov_b32_e32 v32, v4
	v_mov_b32_e32 v33, v4
	v_mov_b32_e32 v34, v4
	v_mov_b32_e32 v35, v4
	v_mov_b32_e32 v44, v4
	v_mov_b32_e32 v45, v4
	v_mov_b32_e32 v46, v4
	v_mov_b32_e32 v47, v4
	v_mov_b32_e32 v48, v4
	v_mov_b32_e32 v49, v4
	v_mov_b32_e32 v50, v4
	v_mov_b32_e32 v51, v4
	v_mov_b32_e32 v60, v4
	v_mov_b32_e32 v61, v4
	v_mov_b32_e32 v62, v4
	v_mov_b32_e32 v63, v4
	v_mov_b32_e32 v64, v4
	v_mov_b32_e32 v65, v4
	v_mov_b32_e32 v66, v4
	v_mov_b32_e32 v67, v4
	v_mov_b32_e32 v68, v4
	v_mov_b32_e32 v69, v4
	v_mov_b32_e32 v70, v4
	v_mov_b32_e32 v71, v4
	v_mov_b32_e32 v72, v4
	v_mov_b32_e32 v73, v4
	v_mov_b32_e32 v74, v4
	v_mov_b32_e32 v75, v4
	v_mov_b32_e32 v84, v4
	v_mov_b32_e32 v85, v4
	v_mov_b32_e32 v86, v4
	v_mov_b32_e32 v87, v4
	v_mov_b32_e32 v88, v4
	v_mov_b32_e32 v89, v4
	v_mov_b32_e32 v90, v4
	v_mov_b32_e32 v91, v4
	v_mov_b32_e32 v100, v4
	v_mov_b32_e32 v101, v4
	v_mov_b32_e32 v102, v4
	v_mov_b32_e32 v103, v4
	v_mov_b32_e32 v104, v4
	v_mov_b32_e32 v105, v4
	v_mov_b32_e32 v106, v4
	v_mov_b32_e32 v107, v4
	v_mov_b32_e32 v124, v4
	v_mov_b32_e32 v125, v4
	v_mov_b32_e32 v126, v4
	v_mov_b32_e32 v127, v4
	v_mov_b32_e32 v132, v4
	v_mov_b32_e32 v133, v4
	v_mov_b32_e32 v134, v4
	v_mov_b32_e32 v135, v4
	v_mov_b32_e32 v76, v4
	v_mov_b32_e32 v77, v4
	v_mov_b32_e32 v78, v4
	v_mov_b32_e32 v79, v4
	v_mov_b32_e32 v80, v4
	v_mov_b32_e32 v81, v4
	v_mov_b32_e32 v82, v4
	v_mov_b32_e32 v83, v4
	v_mov_b32_e32 v92, v4
	v_mov_b32_e32 v93, v4
	v_mov_b32_e32 v94, v4
	v_mov_b32_e32 v95, v4
	v_mov_b32_e32 v96, v4
	v_mov_b32_e32 v97, v4
	v_mov_b32_e32 v98, v4
	v_mov_b32_e32 v99, v4
	v_mov_b32_e32 v116, v4
	v_mov_b32_e32 v117, v4
	v_mov_b32_e32 v118, v4
	v_mov_b32_e32 v119, v4
	v_mov_b32_e32 v120, v4
	v_mov_b32_e32 v121, v4
	v_mov_b32_e32 v122, v4
	v_mov_b32_e32 v123, v4
	v_mov_b32_e32 v140, v4
	v_mov_b32_e32 v141, v4
	v_mov_b32_e32 v142, v4
	v_mov_b32_e32 v143, v4
	v_mov_b32_e32 v144, v4
	v_mov_b32_e32 v145, v4
	v_mov_b32_e32 v146, v4
	v_mov_b32_e32 v147, v4
	v_add_u32_e32 v251, 0x10000, v233
.LBB0_1254:
	s_add_u32 s60, s50, 0x100
	s_addc_u32 s61, s51, 0
	s_add_i32 s48, 0, 0x10000
	s_cmpk_eq_i32 s77, 0x54
	s_cselect_b32 s69, s7, s61
	s_cselect_b32 s68, s6, s60
	s_cselect_b32 s63, s25, s76
	s_cselect_b32 s62, s24, s75
	s_add_i32 s78, 0, 0x14000
	ds_read_b128 v[108:111], v251
	ds_read_b128 v[112:115], v251 offset:1024
	ds_read_b128 v[128:131], v251 offset:2048
	ds_read_b128 v[136:139], v251 offset:3072
	ds_read_b128 v[148:151], v251 offset:16384
	ds_read_b128 v[152:155], v251 offset:17408
	ds_read_b128 v[156:159], v251 offset:18432
	ds_read_b128 v[160:163], v251 offset:19456
	v_lshl_add_u64 v[198:199], s[50:51], 0, v[196:197]
	s_add_i32 m0, s21, 0xc000
	ds_read_b128 v[164:167], v234
	ds_read_b128 v[168:171], v234 offset:1024
	ds_read_b128 v[172:175], v234 offset:2048
	ds_read_b128 v[176:179], v234 offset:3072
	ds_read_b128 v[180:183], v234 offset:4096
	ds_read_b128 v[184:187], v234 offset:5120
	ds_read_b128 v[206:209], v234 offset:6144
	ds_read_b128 v[210:213], v234 offset:7168
	global_load_lds_dwordx4 v[198:199], off
	v_lshl_add_u64 v[198:199], s[50:51], 0, v[194:195]
	s_add_i32 m0, s21, 0xe000
	s_nop 0
	global_load_lds_dwordx4 v[198:199], off
	s_waitcnt vmcnt(8)
	s_waitcnt lgkmcnt(0)
	s_setprio 1
	s_barrier
	v_mfma_f32_16x16x32_bf16 v[144:147], v[108:111], v[164:167], v[144:147]
	v_mfma_f32_16x16x32_bf16 v[140:143], v[128:131], v[164:167], v[140:143]
	v_mfma_f32_16x16x32_bf16 v[120:123], v[108:111], v[172:175], v[120:123]
	v_mfma_f32_16x16x32_bf16 v[116:119], v[128:131], v[172:175], v[116:119]
	v_mfma_f32_16x16x32_bf16 v[96:99], v[108:111], v[180:183], v[96:99]
	v_mfma_f32_16x16x32_bf16 v[92:95], v[128:131], v[180:183], v[92:95]
	v_mfma_f32_16x16x32_bf16 v[80:83], v[108:111], v[206:209], v[80:83]
	v_mfma_f32_16x16x32_bf16 v[76:79], v[128:131], v[206:209], v[76:79]
	v_mfma_f32_16x16x32_bf16 v[144:147], v[112:115], v[168:171], v[144:147]
	v_mfma_f32_16x16x32_bf16 v[140:143], v[136:139], v[168:171], v[140:143]
	v_mfma_f32_16x16x32_bf16 v[120:123], v[112:115], v[176:179], v[120:123]
	v_mfma_f32_16x16x32_bf16 v[116:119], v[136:139], v[176:179], v[116:119]
	v_mfma_f32_16x16x32_bf16 v[96:99], v[112:115], v[184:187], v[96:99]
	v_mfma_f32_16x16x32_bf16 v[92:95], v[136:139], v[184:187], v[92:95]
	v_mfma_f32_16x16x32_bf16 v[80:83], v[112:115], v[210:213], v[80:83]
	v_mfma_f32_16x16x32_bf16 v[76:79], v[136:139], v[210:213], v[76:79]
	s_setprio 0
	s_setprio 1
	v_mfma_f32_16x16x32_bf16 v[132:135], v[148:151], v[164:167], v[132:135]
	v_mfma_f32_16x16x32_bf16 v[124:127], v[156:159], v[164:167], v[124:127]
	v_mfma_f32_16x16x32_bf16 v[104:107], v[148:151], v[172:175], v[104:107]
	v_mfma_f32_16x16x32_bf16 v[100:103], v[156:159], v[172:175], v[100:103]
	v_mfma_f32_16x16x32_bf16 v[88:91], v[148:151], v[180:183], v[88:91]
	v_mfma_f32_16x16x32_bf16 v[84:87], v[156:159], v[180:183], v[84:87]
	v_mfma_f32_16x16x32_bf16 v[72:75], v[148:151], v[206:209], v[72:75]
	v_mfma_f32_16x16x32_bf16 v[68:71], v[156:159], v[206:209], v[68:71]
	v_mfma_f32_16x16x32_bf16 v[132:135], v[152:155], v[168:171], v[132:135]
	v_mfma_f32_16x16x32_bf16 v[124:127], v[160:163], v[168:171], v[124:127]
	v_mfma_f32_16x16x32_bf16 v[104:107], v[152:155], v[176:179], v[104:107]
	v_mfma_f32_16x16x32_bf16 v[100:103], v[160:163], v[176:179], v[100:103]
	v_mfma_f32_16x16x32_bf16 v[88:91], v[152:155], v[184:187], v[88:91]
	v_mfma_f32_16x16x32_bf16 v[84:87], v[160:163], v[184:187], v[84:87]
	v_mfma_f32_16x16x32_bf16 v[72:75], v[152:155], v[210:213], v[72:75]
	v_mfma_f32_16x16x32_bf16 v[68:71], v[160:163], v[210:213], v[68:71]
	s_barrier
; #define PG8_STAGE(bufoff, gbase, voff) do { _Pragma("unroll") for (int _i = 0; _i < 2; ++_i) \
;         __builtin_amdgcn_global_load_lds((const unsigned*)((const char*)(gbase) + (voff)[_i]), (PG8_LAS unsigned*)(lds + (bufoff) + ldsw + _i * 8192), 16, 0, 0); } while (0)
; #define PG8_LDA(dst, b, h) do { _Pragma("unroll") for (int m = 0; m < 4; ++m) _Pragma("unroll") for (int k = 0; k < 2; ++k) dst[m][k] = *(const PG8_LAS bf16x8*)(lds + PG8_SA(b, h) + aoff + m * 2048 + k * 1024); } while (0)
; #define PG8_LDB(dst, b, h) do { _Pragma("unroll") for (int n = 0; n < 2; ++n) _Pragma("unroll") for (int k = 0; k < 2; ++k) dst[n][k] = *(const PG8_LAS bf16x8*)(lds + PG8_SB(b, h) + boff + n * 2048 + k * 1024); } while (0)
; #define PG8_MMA(ai, bj, At, Bt) do { __builtin_amdgcn_s_setprio(1); _Pragma("unroll") for (int m = 0; m < 4; ++m) _Pragma("unroll") for (int n = 0; n < 2; ++n) _Pragma("unroll") for (int k = 0; k < 2; ++k) \
;         acc[ai][bj][m][n] = __builtin_amdgcn_mfma_f32_16x16x32_bf16(Bt[n][k], At[m][k], acc[ai][bj][m][n], 0, 0, 0); __builtin_amdgcn_s_setprio(0); } while (0)
; #define PG8_WAIT_V(n) asm volatile("s_waitcnt vmcnt(" #n ")" ::: "memory")
; #define PG8_WAIT_L(n) asm volatile("s_waitcnt lgkmcnt(" #n ")" ::: "memory")
; #define PG8_BAR __builtin_amdgcn_s_barrier()
; #define PG8_SCHED __builtin_amdgcn_sched_barrier(0)
;     ...
;             PG8_WAIT_V(8); PG8_WAIT_L(0); PG8_BAR; PG8_MMA(0, 0, At, B0); PG8_MMA(0, 1, At, B1); PG8_BAR; PG8_SCHED;
;             PG8_LDA(At, 0, 1); PG8_STAGE(PG8_SB(0, 0), b2, voffB); PG8_STAGE(PG8_SB(0, 1), b2 + hstep, voffB); PG8_STAGE(PG8_SA(0, 0), a2, voffA);
;             PG8_WAIT_V(8); PG8_WAIT_L(0); PG8_BAR; PG8_MMA(1, 0, At, B0); PG8_MMA(1, 1, At, B1); PG8_BAR; PG8_SCHED;
;             PG8_LDB(B0, 1, 0); PG8_LDB(B1, 1, 1); PG8_SCHED; PG8_LDA(At, 1, 0); PG8_STAGE(PG8_SA(0, 1), a2 + hstep, voffA);
;             PG8_WAIT_V(8); PG8_WAIT_L(0); PG8_BAR; PG8_MMA(0, 0, At, B0); PG8_MMA(0, 1, At, B1); PG8_BAR; PG8_SCHED;
	s_setprio 0
	s_add_i32 s48, s48, s20
	v_lshl_add_u64 v[198:199], s[62:63], 0, v[200:201]
	s_mov_b32 m0, s48
	ds_read_b128 v[164:167], v234 offset:16384
	ds_read_b128 v[168:171], v234 offset:17408
	ds_read_b128 v[172:175], v234 offset:18432
	ds_read_b128 v[176:179], v234 offset:19456
	ds_read_b128 v[180:183], v234 offset:20480
	ds_read_b128 v[184:187], v234 offset:21504
	ds_read_b128 v[206:209], v234 offset:22528
	ds_read_b128 v[210:213], v234 offset:23552
	global_load_lds_dwordx4 v[198:199], off
	s_add_i32 m0, s48, 0x2000
	s_add_u32 s48, s62, 0x160000
	v_lshl_add_u64 v[214:215], s[62:63], 0, v[188:189]
	s_addc_u32 s49, s63, 0
	s_add_i32 s50, s78, s20
	global_load_lds_dwordx4 v[214:215], off
	v_lshl_add_u64 v[216:217], s[48:49], 0, v[200:201]
	s_mov_b32 m0, s50
	v_lshl_add_u64 v[218:219], s[68:69], 0, v[190:191]
	global_load_lds_dwordx4 v[216:217], off
	v_lshl_add_u64 v[216:217], s[48:49], 0, v[188:189]
	s_add_i32 m0, s50, 0x2000
	s_nop 0
	global_load_lds_dwordx4 v[216:217], off
	v_lshl_add_u64 v[216:217], s[68:69], 0, v[192:193]
	s_mov_b32 m0, s21
	s_nop 0
	global_load_lds_dwordx4 v[216:217], off
	s_mov_b32 m0, s23
	s_nop 0
	global_load_lds_dwordx4 v[218:219], off
	s_waitcnt vmcnt(8)
	s_waitcnt lgkmcnt(0)
	s_setprio 1
	s_barrier
	v_mfma_f32_16x16x32_bf16 v[64:67], v[108:111], v[164:167], v[64:67]
	v_mfma_f32_16x16x32_bf16 v[60:63], v[128:131], v[164:167], v[60:63]
	v_mfma_f32_16x16x32_bf16 v[48:51], v[108:111], v[172:175], v[48:51]
	v_mfma_f32_16x16x32_bf16 v[44:47], v[128:131], v[172:175], v[44:47]
	v_mfma_f32_16x16x32_bf16 v[32:35], v[108:111], v[180:183], v[32:35]
	v_mfma_f32_16x16x32_bf16 v[28:31], v[128:131], v[180:183], v[28:31]
	v_mfma_f32_16x16x32_bf16 v[16:19], v[108:111], v[206:209], v[16:19]
	v_mfma_f32_16x16x32_bf16 v[12:15], v[128:131], v[206:209], v[12:15]
	v_mfma_f32_16x16x32_bf16 v[64:67], v[112:115], v[168:171], v[64:67]
	v_mfma_f32_16x16x32_bf16 v[60:63], v[136:139], v[168:171], v[60:63]
	v_mfma_f32_16x16x32_bf16 v[48:51], v[112:115], v[176:179], v[48:51]
	v_mfma_f32_16x16x32_bf16 v[44:47], v[136:139], v[176:179], v[44:47]
	v_mfma_f32_16x16x32_bf16 v[32:35], v[112:115], v[184:187], v[32:35]
	v_mfma_f32_16x16x32_bf16 v[28:31], v[136:139], v[184:187], v[28:31]
	v_mfma_f32_16x16x32_bf16 v[16:19], v[112:115], v[210:213], v[16:19]
	v_mfma_f32_16x16x32_bf16 v[12:15], v[136:139], v[210:213], v[12:15]
	s_setprio 0
	s_setprio 1
	v_mfma_f32_16x16x32_bf16 v[56:59], v[148:151], v[164:167], v[56:59]
	v_mfma_f32_16x16x32_bf16 v[52:55], v[156:159], v[164:167], v[52:55]
	v_mfma_f32_16x16x32_bf16 v[40:43], v[148:151], v[172:175], v[40:43]
	v_mfma_f32_16x16x32_bf16 v[36:39], v[156:159], v[172:175], v[36:39]
	v_mfma_f32_16x16x32_bf16 v[24:27], v[148:151], v[180:183], v[24:27]
	v_mfma_f32_16x16x32_bf16 v[20:23], v[156:159], v[180:183], v[20:23]
	v_mfma_f32_16x16x32_bf16 v[8:11], v[148:151], v[206:209], v[8:11]
	v_mfma_f32_16x16x32_bf16 v[4:7], v[156:159], v[206:209], v[4:7]
	v_mfma_f32_16x16x32_bf16 v[56:59], v[152:155], v[168:171], v[56:59]
	v_mfma_f32_16x16x32_bf16 v[52:55], v[160:163], v[168:171], v[52:55]
	v_mfma_f32_16x16x32_bf16 v[40:43], v[152:155], v[176:179], v[40:43]
	v_mfma_f32_16x16x32_bf16 v[36:39], v[160:163], v[176:179], v[36:39]
	v_mfma_f32_16x16x32_bf16 v[24:27], v[152:155], v[184:187], v[24:27]
	v_mfma_f32_16x16x32_bf16 v[20:23], v[160:163], v[184:187], v[20:23]
	v_mfma_f32_16x16x32_bf16 v[8:11], v[152:155], v[210:213], v[8:11]
	v_mfma_f32_16x16x32_bf16 v[4:7], v[160:163], v[210:213], v[4:7]
	s_barrier
	s_setprio 0
	s_add_i32 s50, 0, 0x18000
	s_add_i32 s51, 0, 0x1c000
	ds_read_b128 v[108:111], v251 offset:32768
	ds_read_b128 v[112:115], v251 offset:33792
	ds_read_b128 v[128:131], v251 offset:34816
	ds_read_b128 v[136:139], v251 offset:35840
	ds_read_b128 v[148:151], v251 offset:49152
	ds_read_b128 v[152:155], v251 offset:50176
	ds_read_b128 v[156:159], v251 offset:51200
	ds_read_b128 v[160:163], v251 offset:52224
	s_add_u32 s48, s68, 0x160000
	s_addc_u32 s49, s69, 0
	s_mov_b32 m0, s42
	v_lshl_add_u64 v[220:221], s[48:49], 0, v[192:193]
	ds_read_b128 v[164:167], v234 offset:32768
	ds_read_b128 v[168:171], v234 offset:33792
	ds_read_b128 v[172:175], v234 offset:34816
	ds_read_b128 v[176:179], v234 offset:35840
	ds_read_b128 v[180:183], v234 offset:36864
	ds_read_b128 v[184:187], v234 offset:37888
	ds_read_b128 v[206:209], v234 offset:38912
	ds_read_b128 v[210:213], v234 offset:39936
	global_load_lds_dwordx4 v[220:221], off
	v_lshl_add_u64 v[220:221], s[48:49], 0, v[190:191]
	s_mov_b32 m0, s52
	s_nop 0
	global_load_lds_dwordx4 v[220:221], off
	s_waitcnt vmcnt(8)
	s_waitcnt lgkmcnt(0)
	s_setprio 1
	s_barrier
; #define PG8_STAGE(bufoff, gbase, voff) do { _Pragma("unroll") for (int _i = 0; _i < 2; ++_i) \
;         __builtin_amdgcn_global_load_lds((const unsigned*)((const char*)(gbase) + (voff)[_i]), (PG8_LAS unsigned*)(lds + (bufoff) + ldsw + _i * 8192), 16, 0, 0); } while (0)
; #define PG8_LDA(dst, b, h) do { _Pragma("unroll") for (int m = 0; m < 4; ++m) _Pragma("unroll") for (int k = 0; k < 2; ++k) dst[m][k] = *(const PG8_LAS bf16x8*)(lds + PG8_SA(b, h) + aoff + m * 2048 + k * 1024); } while (0)
; #define PG8_MMA(ai, bj, At, Bt) do { __builtin_amdgcn_s_setprio(1); _Pragma("unroll") for (int m = 0; m < 4; ++m) _Pragma("unroll") for (int n = 0; n < 2; ++n) _Pragma("unroll") for (int k = 0; k < 2; ++k) \
;         acc[ai][bj][m][n] = __builtin_amdgcn_mfma_f32_16x16x32_bf16(Bt[n][k], At[m][k], acc[ai][bj][m][n], 0, 0, 0); __builtin_amdgcn_s_setprio(0); } while (0)
; #define PG8_WAIT_V(n) asm volatile("s_waitcnt vmcnt(" #n ")" ::: "memory")
; #define PG8_WAIT_L(n) asm volatile("s_waitcnt lgkmcnt(" #n ")" ::: "memory")
; #define PG8_BAR __builtin_amdgcn_s_barrier()
; #define PG8_SCHED __builtin_amdgcn_sched_barrier(0)
;     ...
;             PG8_WAIT_V(8); PG8_WAIT_L(0); PG8_BAR; PG8_MMA(0, 0, At, B0); PG8_MMA(0, 1, At, B1); PG8_BAR; PG8_SCHED;
;             PG8_LDA(At, 1, 1); PG8_STAGE(PG8_SB(1, 0), b3, voffB); PG8_STAGE(PG8_SB(1, 1), b3 + hstep, voffB); PG8_STAGE(PG8_SA(1, 0), a3, voffA);
;             PG8_WAIT_V(8); PG8_WAIT_L(0); PG8_BAR; PG8_MMA(1, 0, At, B0); PG8_MMA(1, 1, At, B1); PG8_BAR; PG8_SCHED;
;     ...
;         if constexpr (ALIGN_EPI) { if (wr == 0) PG8_BAR; }
	v_mfma_f32_16x16x32_bf16 v[144:147], v[108:111], v[164:167], v[144:147]
	v_mfma_f32_16x16x32_bf16 v[140:143], v[128:131], v[164:167], v[140:143]
	v_mfma_f32_16x16x32_bf16 v[120:123], v[108:111], v[172:175], v[120:123]
	v_mfma_f32_16x16x32_bf16 v[116:119], v[128:131], v[172:175], v[116:119]
	v_mfma_f32_16x16x32_bf16 v[96:99], v[108:111], v[180:183], v[96:99]
	v_mfma_f32_16x16x32_bf16 v[92:95], v[128:131], v[180:183], v[92:95]
	v_mfma_f32_16x16x32_bf16 v[80:83], v[108:111], v[206:209], v[80:83]
	v_mfma_f32_16x16x32_bf16 v[76:79], v[128:131], v[206:209], v[76:79]
	v_mfma_f32_16x16x32_bf16 v[144:147], v[112:115], v[168:171], v[144:147]
	v_mfma_f32_16x16x32_bf16 v[140:143], v[136:139], v[168:171], v[140:143]
	v_mfma_f32_16x16x32_bf16 v[120:123], v[112:115], v[176:179], v[120:123]
	v_mfma_f32_16x16x32_bf16 v[116:119], v[136:139], v[176:179], v[116:119]
	v_mfma_f32_16x16x32_bf16 v[96:99], v[112:115], v[184:187], v[96:99]
	v_mfma_f32_16x16x32_bf16 v[92:95], v[136:139], v[184:187], v[92:95]
	v_mfma_f32_16x16x32_bf16 v[80:83], v[112:115], v[210:213], v[80:83]
	v_mfma_f32_16x16x32_bf16 v[76:79], v[136:139], v[210:213], v[76:79]
	s_setprio 0
	s_setprio 1
	v_mfma_f32_16x16x32_bf16 v[132:135], v[148:151], v[164:167], v[132:135]
	v_mfma_f32_16x16x32_bf16 v[124:127], v[156:159], v[164:167], v[124:127]
	v_mfma_f32_16x16x32_bf16 v[104:107], v[148:151], v[172:175], v[104:107]
	v_mfma_f32_16x16x32_bf16 v[100:103], v[156:159], v[172:175], v[100:103]
	v_mfma_f32_16x16x32_bf16 v[88:91], v[148:151], v[180:183], v[88:91]
	v_mfma_f32_16x16x32_bf16 v[84:87], v[156:159], v[180:183], v[84:87]
	v_mfma_f32_16x16x32_bf16 v[72:75], v[148:151], v[206:209], v[72:75]
	v_mfma_f32_16x16x32_bf16 v[68:71], v[156:159], v[206:209], v[68:71]
	v_mfma_f32_16x16x32_bf16 v[132:135], v[152:155], v[168:171], v[132:135]
	v_mfma_f32_16x16x32_bf16 v[124:127], v[160:163], v[168:171], v[124:127]
	v_mfma_f32_16x16x32_bf16 v[104:107], v[152:155], v[176:179], v[104:107]
	v_mfma_f32_16x16x32_bf16 v[100:103], v[160:163], v[176:179], v[100:103]
	v_mfma_f32_16x16x32_bf16 v[88:91], v[152:155], v[184:187], v[88:91]
	v_mfma_f32_16x16x32_bf16 v[84:87], v[160:163], v[184:187], v[84:87]
	v_mfma_f32_16x16x32_bf16 v[72:75], v[152:155], v[210:213], v[72:75]
	v_mfma_f32_16x16x32_bf16 v[68:71], v[160:163], v[210:213], v[68:71]
	s_barrier
	s_setprio 0
	s_add_i32 s48, s50, s20
	v_lshl_add_u64 v[198:199], v[198:199], 0, s[66:67]
	s_mov_b32 m0, s48
	ds_read_b128 v[164:167], v234 offset:49152
	ds_read_b128 v[168:171], v234 offset:50176
	ds_read_b128 v[172:175], v234 offset:51200
	ds_read_b128 v[176:179], v234 offset:52224
	ds_read_b128 v[180:183], v234 offset:53248
	ds_read_b128 v[184:187], v234 offset:54272
	ds_read_b128 v[206:209], v234 offset:55296
	ds_read_b128 v[210:213], v234 offset:56320
	global_load_lds_dwordx4 v[198:199], off
	s_add_i32 m0, s48, 0x2000
	s_add_u32 s48, s62, 0x160080
	v_lshl_add_u64 v[198:199], v[214:215], 0, s[66:67]
	s_addc_u32 s49, s63, 0
	s_add_i32 s50, s51, s20
	global_load_lds_dwordx4 v[198:199], off
	v_lshl_add_u64 v[198:199], s[48:49], 0, v[200:201]
	s_mov_b32 m0, s50
	s_nop 0
	global_load_lds_dwordx4 v[198:199], off
	v_lshl_add_u64 v[198:199], s[48:49], 0, v[188:189]
	s_add_i32 m0, s50, 0x2000
	s_nop 0
	global_load_lds_dwordx4 v[198:199], off
	v_lshl_add_u64 v[198:199], v[216:217], 0, s[66:67]
	s_mov_b32 m0, s56
	s_nop 0
	global_load_lds_dwordx4 v[198:199], off
	v_lshl_add_u64 v[198:199], v[218:219], 0, s[66:67]
	s_mov_b32 m0, s58
	s_nop 0
	global_load_lds_dwordx4 v[198:199], off
	s_waitcnt vmcnt(8)
	s_waitcnt lgkmcnt(0)
	s_setprio 1
	s_barrier
	v_mfma_f32_16x16x32_bf16 v[64:67], v[108:111], v[164:167], v[64:67]
	v_mfma_f32_16x16x32_bf16 v[60:63], v[128:131], v[164:167], v[60:63]
	v_mfma_f32_16x16x32_bf16 v[48:51], v[108:111], v[172:175], v[48:51]
	v_mfma_f32_16x16x32_bf16 v[44:47], v[128:131], v[172:175], v[44:47]
	v_mfma_f32_16x16x32_bf16 v[32:35], v[108:111], v[180:183], v[32:35]
	v_mfma_f32_16x16x32_bf16 v[28:31], v[128:131], v[180:183], v[28:31]
	v_mfma_f32_16x16x32_bf16 v[16:19], v[108:111], v[206:209], v[16:19]
	v_mfma_f32_16x16x32_bf16 v[12:15], v[128:131], v[206:209], v[12:15]
	v_mfma_f32_16x16x32_bf16 v[64:67], v[112:115], v[168:171], v[64:67]
	v_mfma_f32_16x16x32_bf16 v[60:63], v[136:139], v[168:171], v[60:63]
	v_mfma_f32_16x16x32_bf16 v[48:51], v[112:115], v[176:179], v[48:51]
	v_mfma_f32_16x16x32_bf16 v[44:47], v[136:139], v[176:179], v[44:47]
	v_mfma_f32_16x16x32_bf16 v[32:35], v[112:115], v[184:187], v[32:35]
	v_mfma_f32_16x16x32_bf16 v[28:31], v[136:139], v[184:187], v[28:31]
	v_mfma_f32_16x16x32_bf16 v[16:19], v[112:115], v[210:213], v[16:19]
	v_mfma_f32_16x16x32_bf16 v[12:15], v[136:139], v[210:213], v[12:15]
	s_setprio 0
	s_setprio 1
	v_mfma_f32_16x16x32_bf16 v[56:59], v[148:151], v[164:167], v[56:59]
	v_mfma_f32_16x16x32_bf16 v[52:55], v[156:159], v[164:167], v[52:55]
	v_mfma_f32_16x16x32_bf16 v[40:43], v[148:151], v[172:175], v[40:43]
	v_mfma_f32_16x16x32_bf16 v[36:39], v[156:159], v[172:175], v[36:39]
	v_mfma_f32_16x16x32_bf16 v[24:27], v[148:151], v[180:183], v[24:27]
	v_mfma_f32_16x16x32_bf16 v[20:23], v[156:159], v[180:183], v[20:23]
	v_mfma_f32_16x16x32_bf16 v[8:11], v[148:151], v[206:209], v[8:11]
	v_mfma_f32_16x16x32_bf16 v[4:7], v[156:159], v[206:209], v[4:7]
	v_mfma_f32_16x16x32_bf16 v[56:59], v[152:155], v[168:171], v[56:59]
	v_mfma_f32_16x16x32_bf16 v[52:55], v[160:163], v[168:171], v[52:55]
	v_mfma_f32_16x16x32_bf16 v[40:43], v[152:155], v[176:179], v[40:43]
	v_mfma_f32_16x16x32_bf16 v[36:39], v[160:163], v[176:179], v[36:39]
	v_mfma_f32_16x16x32_bf16 v[24:27], v[152:155], v[184:187], v[24:27]
	v_mfma_f32_16x16x32_bf16 v[20:23], v[160:163], v[184:187], v[20:23]
	v_mfma_f32_16x16x32_bf16 v[8:11], v[152:155], v[210:213], v[8:11]
	v_mfma_f32_16x16x32_bf16 v[4:7], v[160:163], v[210:213], v[4:7]
	s_barrier
	s_setprio 0
	s_add_i32 s77, s77, 2
	s_add_u32 s75, s75, 0x100
	s_addc_u32 s76, s76, 0
	s_cmpk_gt_u32 s77, 0x55
	s_mov_b64 s[50:51], s[60:61]
	s_cbranch_scc0 .LBB0_1254
	s_and_b64 vcc, exec, s[12:13]
	s_cbranch_vccz .LBB0_1257
	s_barrier
